# removed the back-to-back s_setprio 0 / s_setprio 1 pair in the middle of each 32-MFMA block of the GEMM K-loops
# baseline (speedup 1.0000x reference)
.LBB0_410:
	ds_read_b128 v[154:157], v149
	ds_read_b128 v[158:161], v149 offset:1024
	ds_read_b128 v[162:165], v149 offset:2048
	ds_read_b128 v[166:169], v149 offset:3072
	ds_read_b128 v[170:173], v150
	ds_read_b128 v[174:177], v150 offset:1024
	ds_read_b128 v[178:181], v150 offset:2048
	ds_read_b128 v[182:185], v150 offset:3072
	s_add_u32 s30, s28, 0xfffc0080
	s_addc_u32 s31, s29, -1
	s_cmp_eq_u32 s71, 12
	s_cselect_b32 s35, s21, s31
	s_cselect_b32 s34, s61, s30
	s_cselect_b32 s31, s19, s70
	s_cselect_b32 s30, s62, s63
	v_lshl_add_u64 v[144:145], s[28:29], 0, v[136:137]
	s_add_i32 m0, s27, 0xc000
	ds_read_b128 v[186:189], v151
	ds_read_b128 v[190:193], v151 offset:1024
	ds_read_b128 v[196:199], v151 offset:2048
	ds_read_b128 v[200:203], v151 offset:3072
	ds_read_b128 v[204:207], v151 offset:4096
	ds_read_b128 v[208:211], v151 offset:5120
	ds_read_b128 v[212:215], v151 offset:6144
	ds_read_b128 v[216:219], v151 offset:7168
	global_load_lds_dwordx4 v[144:145], off
	v_lshl_add_u64 v[144:145], s[28:29], 0, v[138:139]
	s_add_i32 m0, s27, 0xe000
	s_nop 0
	global_load_lds_dwordx4 v[144:145], off
	s_waitcnt vmcnt(8)
	s_waitcnt lgkmcnt(0)
	s_barrier
	s_setprio 1
	s_waitcnt lgkmcnt(0)
	v_mfma_f32_16x16x32_bf16 v[116:119], v[154:157], v[186:189], v[116:119]
	v_mfma_f32_16x16x32_bf16 v[112:115], v[162:165], v[186:189], v[112:115]
	v_mfma_f32_16x16x32_bf16 v[100:103], v[154:157], v[196:199], v[100:103]
	v_mfma_f32_16x16x32_bf16 v[96:99], v[162:165], v[196:199], v[96:99]
	v_mfma_f32_16x16x32_bf16 v[84:87], v[154:157], v[204:207], v[84:87]
	v_mfma_f32_16x16x32_bf16 v[80:83], v[162:165], v[204:207], v[80:83]
	v_mfma_f32_16x16x32_bf16 v[68:71], v[154:157], v[212:215], v[68:71]
	v_mfma_f32_16x16x32_bf16 v[64:67], v[162:165], v[212:215], v[64:67]
	v_mfma_f32_16x16x32_bf16 v[116:119], v[158:161], v[190:193], v[116:119]
	v_mfma_f32_16x16x32_bf16 v[112:115], v[166:169], v[190:193], v[112:115]
	v_mfma_f32_16x16x32_bf16 v[100:103], v[158:161], v[200:203], v[100:103]
	v_mfma_f32_16x16x32_bf16 v[96:99], v[166:169], v[200:203], v[96:99]
	v_mfma_f32_16x16x32_bf16 v[84:87], v[158:161], v[208:211], v[84:87]
	v_mfma_f32_16x16x32_bf16 v[80:83], v[166:169], v[208:211], v[80:83]
	v_mfma_f32_16x16x32_bf16 v[68:71], v[158:161], v[216:219], v[68:71]
	v_mfma_f32_16x16x32_bf16 v[64:67], v[166:169], v[216:219], v[64:67]
	v_mfma_f32_16x16x32_bf16 v[124:127], v[170:173], v[186:189], v[124:127]
	v_mfma_f32_16x16x32_bf16 v[120:123], v[178:181], v[186:189], v[120:123]
	v_mfma_f32_16x16x32_bf16 v[108:111], v[170:173], v[196:199], v[108:111]
	v_mfma_f32_16x16x32_bf16 v[104:107], v[178:181], v[196:199], v[104:107]
	v_mfma_f32_16x16x32_bf16 v[92:95], v[170:173], v[204:207], v[92:95]
	v_mfma_f32_16x16x32_bf16 v[88:91], v[178:181], v[204:207], v[88:91]
	v_mfma_f32_16x16x32_bf16 v[76:79], v[170:173], v[212:215], v[76:79]
	v_mfma_f32_16x16x32_bf16 v[72:75], v[178:181], v[212:215], v[72:75]
	v_mfma_f32_16x16x32_bf16 v[124:127], v[174:177], v[190:193], v[124:127]
	v_mfma_f32_16x16x32_bf16 v[120:123], v[182:185], v[190:193], v[120:123]
	v_mfma_f32_16x16x32_bf16 v[108:111], v[174:177], v[200:203], v[108:111]
	v_mfma_f32_16x16x32_bf16 v[104:107], v[182:185], v[200:203], v[104:107]
	v_mfma_f32_16x16x32_bf16 v[92:95], v[174:177], v[208:211], v[92:95]
	v_mfma_f32_16x16x32_bf16 v[88:91], v[182:185], v[208:211], v[88:91]
	v_mfma_f32_16x16x32_bf16 v[76:79], v[174:177], v[216:219], v[76:79]
	v_mfma_f32_16x16x32_bf16 v[72:75], v[182:185], v[216:219], v[72:75]
	s_setprio 0
	s_barrier
	s_add_i32 s72, s54, s41
	v_lshl_add_u64 v[144:145], s[30:31], 0, v[132:133]
	s_mov_b32 m0, s72
	ds_read_b128 v[186:189], v151 offset:16384
	ds_read_b128 v[190:193], v151 offset:17408
	ds_read_b128 v[196:199], v151 offset:18432
	ds_read_b128 v[200:203], v151 offset:19456
	ds_read_b128 v[204:207], v151 offset:20480
	ds_read_b128 v[208:211], v151 offset:21504
	ds_read_b128 v[212:215], v151 offset:22528
	ds_read_b128 v[216:219], v151 offset:23552
	global_load_lds_dwordx4 v[144:145], off
	s_add_i32 m0, s72, 0x2000
	s_add_u32 s72, s30, 0x40000
	v_lshl_add_u64 v[220:221], s[30:31], 0, v[128:129]
	s_addc_u32 s73, s31, 0
	s_add_i32 s77, s55, s41
	global_load_lds_dwordx4 v[220:221], off
	v_lshl_add_u64 v[222:223], s[72:73], 0, v[132:133]
	s_mov_b32 m0, s77
	v_lshl_add_u64 v[224:225], s[34:35], 0, v[130:131]
	global_load_lds_dwordx4 v[222:223], off
	v_lshl_add_u64 v[222:223], s[72:73], 0, v[128:129]
	s_add_i32 m0, s77, 0x2000
	s_nop 0
	global_load_lds_dwordx4 v[222:223], off
	v_lshl_add_u64 v[222:223], s[34:35], 0, v[134:135]
	s_waitcnt vmcnt(6)
	s_waitcnt lgkmcnt(0)
	s_barrier
	s_setprio 1
	s_waitcnt lgkmcnt(0)
	v_mfma_f32_16x16x32_bf16 v[52:55], v[154:157], v[186:189], v[52:55]
	v_mfma_f32_16x16x32_bf16 v[48:51], v[162:165], v[186:189], v[48:51]
	v_mfma_f32_16x16x32_bf16 v[36:39], v[154:157], v[196:199], v[36:39]
	v_mfma_f32_16x16x32_bf16 v[32:35], v[162:165], v[196:199], v[32:35]
	v_mfma_f32_16x16x32_bf16 v[20:23], v[154:157], v[204:207], v[20:23]
	v_mfma_f32_16x16x32_bf16 v[16:19], v[162:165], v[204:207], v[16:19]
	v_mfma_f32_16x16x32_bf16 v[4:7], v[154:157], v[212:215], v[4:7]
	v_mfma_f32_16x16x32_bf16 v[0:3], v[162:165], v[212:215], v[0:3]
	v_mfma_f32_16x16x32_bf16 v[52:55], v[158:161], v[190:193], v[52:55]
	v_mfma_f32_16x16x32_bf16 v[48:51], v[166:169], v[190:193], v[48:51]
	v_mfma_f32_16x16x32_bf16 v[36:39], v[158:161], v[200:203], v[36:39]
	v_mfma_f32_16x16x32_bf16 v[32:35], v[166:169], v[200:203], v[32:35]
	v_mfma_f32_16x16x32_bf16 v[20:23], v[158:161], v[208:211], v[20:23]
	v_mfma_f32_16x16x32_bf16 v[16:19], v[166:169], v[208:211], v[16:19]
	v_mfma_f32_16x16x32_bf16 v[4:7], v[158:161], v[216:219], v[4:7]
	v_mfma_f32_16x16x32_bf16 v[0:3], v[166:169], v[216:219], v[0:3]
	v_mfma_f32_16x16x32_bf16 v[60:63], v[170:173], v[186:189], v[60:63]
	v_mfma_f32_16x16x32_bf16 v[56:59], v[178:181], v[186:189], v[56:59]
	v_mfma_f32_16x16x32_bf16 v[44:47], v[170:173], v[196:199], v[44:47]
	v_mfma_f32_16x16x32_bf16 v[40:43], v[178:181], v[196:199], v[40:43]
	v_mfma_f32_16x16x32_bf16 v[28:31], v[170:173], v[204:207], v[28:31]
	v_mfma_f32_16x16x32_bf16 v[24:27], v[178:181], v[204:207], v[24:27]
	v_mfma_f32_16x16x32_bf16 v[12:15], v[170:173], v[212:215], v[12:15]
	v_mfma_f32_16x16x32_bf16 v[8:11], v[178:181], v[212:215], v[8:11]
	v_mfma_f32_16x16x32_bf16 v[60:63], v[174:177], v[190:193], v[60:63]
	v_mfma_f32_16x16x32_bf16 v[56:59], v[182:185], v[190:193], v[56:59]
	v_mfma_f32_16x16x32_bf16 v[44:47], v[174:177], v[200:203], v[44:47]
	v_mfma_f32_16x16x32_bf16 v[40:43], v[182:185], v[200:203], v[40:43]
	v_mfma_f32_16x16x32_bf16 v[28:31], v[174:177], v[208:211], v[28:31]
	v_mfma_f32_16x16x32_bf16 v[24:27], v[182:185], v[208:211], v[24:27]
	v_mfma_f32_16x16x32_bf16 v[12:15], v[174:177], v[216:219], v[12:15]
	v_mfma_f32_16x16x32_bf16 v[8:11], v[182:185], v[216:219], v[8:11]
	s_setprio 0
	s_barrier
	s_add_i32 s72, 0, 0x18000
	v_add_u32_e32 v153, s72, v147
	s_add_i32 s73, 0, 0x1c000
	ds_read_b128 v[154:157], v153
	ds_read_b128 v[158:161], v153 offset:1024
	ds_read_b128 v[162:165], v153 offset:2048
	ds_read_b128 v[166:169], v153 offset:3072
	v_add_u32_e32 v153, s73, v147
	ds_read_b128 v[170:173], v153
	ds_read_b128 v[174:177], v153 offset:1024
	ds_read_b128 v[178:181], v153 offset:2048
	ds_read_b128 v[182:185], v153 offset:3072
	s_add_u32 s34, s34, 0x40000
	s_addc_u32 s35, s35, 0
	v_lshl_add_u64 v[226:227], s[34:35], 0, v[134:135]
	ds_read_b128 v[186:189], v151 offset:32768
	ds_read_b128 v[190:193], v151 offset:33792
	ds_read_b128 v[196:199], v151 offset:34816
	ds_read_b128 v[200:203], v151 offset:35840
	ds_read_b128 v[204:207], v151 offset:36864
	ds_read_b128 v[208:211], v151 offset:37888
	ds_read_b128 v[212:215], v151 offset:38912
	ds_read_b128 v[216:219], v151 offset:39936
	s_mov_b32 m0, s27
	s_nop 0
	global_load_lds_dwordx4 v[222:223], off
	s_mov_b32 m0, s43
	s_nop 0
	global_load_lds_dwordx4 v[224:225], off
	s_mov_b32 m0, s44
	s_nop 0
	global_load_lds_dwordx4 v[226:227], off
	v_lshl_add_u64 v[226:227], s[34:35], 0, v[130:131]
	s_mov_b32 m0, s45
	s_nop 0
	global_load_lds_dwordx4 v[226:227], off
	s_waitcnt vmcnt(8)
	s_waitcnt lgkmcnt(0)
	s_barrier
	s_setprio 1
	s_waitcnt lgkmcnt(0)
	v_mfma_f32_16x16x32_bf16 v[116:119], v[154:157], v[186:189], v[116:119]
	v_mfma_f32_16x16x32_bf16 v[112:115], v[162:165], v[186:189], v[112:115]
	v_mfma_f32_16x16x32_bf16 v[100:103], v[154:157], v[196:199], v[100:103]
	v_mfma_f32_16x16x32_bf16 v[96:99], v[162:165], v[196:199], v[96:99]
	v_mfma_f32_16x16x32_bf16 v[84:87], v[154:157], v[204:207], v[84:87]
	v_mfma_f32_16x16x32_bf16 v[80:83], v[162:165], v[204:207], v[80:83]
	v_mfma_f32_16x16x32_bf16 v[68:71], v[154:157], v[212:215], v[68:71]
	v_mfma_f32_16x16x32_bf16 v[64:67], v[162:165], v[212:215], v[64:67]
	v_mfma_f32_16x16x32_bf16 v[116:119], v[158:161], v[190:193], v[116:119]
	v_mfma_f32_16x16x32_bf16 v[112:115], v[166:169], v[190:193], v[112:115]
	v_mfma_f32_16x16x32_bf16 v[100:103], v[158:161], v[200:203], v[100:103]
	v_mfma_f32_16x16x32_bf16 v[96:99], v[166:169], v[200:203], v[96:99]
	v_mfma_f32_16x16x32_bf16 v[84:87], v[158:161], v[208:211], v[84:87]
	v_mfma_f32_16x16x32_bf16 v[80:83], v[166:169], v[208:211], v[80:83]
	v_mfma_f32_16x16x32_bf16 v[68:71], v[158:161], v[216:219], v[68:71]
	v_mfma_f32_16x16x32_bf16 v[64:67], v[166:169], v[216:219], v[64:67]
	v_mfma_f32_16x16x32_bf16 v[124:127], v[170:173], v[186:189], v[124:127]
	v_mfma_f32_16x16x32_bf16 v[120:123], v[178:181], v[186:189], v[120:123]
	v_mfma_f32_16x16x32_bf16 v[108:111], v[170:173], v[196:199], v[108:111]
	v_mfma_f32_16x16x32_bf16 v[104:107], v[178:181], v[196:199], v[104:107]
	v_mfma_f32_16x16x32_bf16 v[92:95], v[170:173], v[204:207], v[92:95]
	v_mfma_f32_16x16x32_bf16 v[88:91], v[178:181], v[204:207], v[88:91]
	v_mfma_f32_16x16x32_bf16 v[76:79], v[170:173], v[212:215], v[76:79]
	v_mfma_f32_16x16x32_bf16 v[72:75], v[178:181], v[212:215], v[72:75]
	v_mfma_f32_16x16x32_bf16 v[124:127], v[174:177], v[190:193], v[124:127]
	v_mfma_f32_16x16x32_bf16 v[120:123], v[182:185], v[190:193], v[120:123]
	v_mfma_f32_16x16x32_bf16 v[108:111], v[174:177], v[200:203], v[108:111]
	v_mfma_f32_16x16x32_bf16 v[104:107], v[182:185], v[200:203], v[104:107]
	v_mfma_f32_16x16x32_bf16 v[92:95], v[174:177], v[208:211], v[92:95]
	v_mfma_f32_16x16x32_bf16 v[88:91], v[182:185], v[208:211], v[88:91]
	v_mfma_f32_16x16x32_bf16 v[76:79], v[174:177], v[216:219], v[76:79]
	v_mfma_f32_16x16x32_bf16 v[72:75], v[182:185], v[216:219], v[72:75]
	s_setprio 0
	s_barrier
	s_add_i32 s34, s72, s41
	v_lshl_add_u64 v[144:145], v[144:145], 0, s[12:13]
	s_mov_b32 m0, s34
	ds_read_b128 v[186:189], v151 offset:49152
	ds_read_b128 v[190:193], v151 offset:50176
	ds_read_b128 v[196:199], v151 offset:51200
	ds_read_b128 v[200:203], v151 offset:52224
	ds_read_b128 v[204:207], v151 offset:53248
	ds_read_b128 v[208:211], v151 offset:54272
	ds_read_b128 v[212:215], v151 offset:55296
	ds_read_b128 v[216:219], v151 offset:56320
	global_load_lds_dwordx4 v[144:145], off
	s_add_i32 m0, s34, 0x2000
	s_add_u32 s30, s30, 0x40080
	v_lshl_add_u64 v[144:145], v[220:221], 0, s[12:13]
	s_addc_u32 s31, s31, 0
	s_add_i32 s34, s73, s41
	global_load_lds_dwordx4 v[144:145], off
	v_lshl_add_u64 v[144:145], s[30:31], 0, v[132:133]
	s_mov_b32 m0, s34
	s_nop 0
	global_load_lds_dwordx4 v[144:145], off
	v_lshl_add_u64 v[144:145], s[30:31], 0, v[128:129]
	s_add_i32 m0, s34, 0x2000
	s_nop 0
	global_load_lds_dwordx4 v[144:145], off
	s_waitcnt vmcnt(6)
	s_waitcnt lgkmcnt(0)
	s_barrier
	s_setprio 1
	s_waitcnt lgkmcnt(0)
	v_mfma_f32_16x16x32_bf16 v[52:55], v[154:157], v[186:189], v[52:55]
	v_mfma_f32_16x16x32_bf16 v[48:51], v[162:165], v[186:189], v[48:51]
	v_mfma_f32_16x16x32_bf16 v[36:39], v[154:157], v[196:199], v[36:39]
	v_mfma_f32_16x16x32_bf16 v[32:35], v[162:165], v[196:199], v[32:35]
	v_mfma_f32_16x16x32_bf16 v[20:23], v[154:157], v[204:207], v[20:23]
	v_mfma_f32_16x16x32_bf16 v[16:19], v[162:165], v[204:207], v[16:19]
	v_mfma_f32_16x16x32_bf16 v[4:7], v[154:157], v[212:215], v[4:7]
	v_mfma_f32_16x16x32_bf16 v[0:3], v[162:165], v[212:215], v[0:3]
	v_mfma_f32_16x16x32_bf16 v[52:55], v[158:161], v[190:193], v[52:55]
	v_mfma_f32_16x16x32_bf16 v[48:51], v[166:169], v[190:193], v[48:51]
	v_mfma_f32_16x16x32_bf16 v[36:39], v[158:161], v[200:203], v[36:39]
	v_mfma_f32_16x16x32_bf16 v[32:35], v[166:169], v[200:203], v[32:35]
	v_mfma_f32_16x16x32_bf16 v[20:23], v[158:161], v[208:211], v[20:23]
	v_mfma_f32_16x16x32_bf16 v[16:19], v[166:169], v[208:211], v[16:19]
	v_mfma_f32_16x16x32_bf16 v[4:7], v[158:161], v[216:219], v[4:7]
	v_mfma_f32_16x16x32_bf16 v[0:3], v[166:169], v[216:219], v[0:3]
	v_mfma_f32_16x16x32_bf16 v[60:63], v[170:173], v[186:189], v[60:63]
	v_mfma_f32_16x16x32_bf16 v[56:59], v[178:181], v[186:189], v[56:59]
	v_mfma_f32_16x16x32_bf16 v[44:47], v[170:173], v[196:199], v[44:47]
	v_mfma_f32_16x16x32_bf16 v[40:43], v[178:181], v[196:199], v[40:43]
	v_mfma_f32_16x16x32_bf16 v[28:31], v[170:173], v[204:207], v[28:31]
	v_mfma_f32_16x16x32_bf16 v[24:27], v[178:181], v[204:207], v[24:27]
	v_mfma_f32_16x16x32_bf16 v[12:15], v[170:173], v[212:215], v[12:15]
	v_mfma_f32_16x16x32_bf16 v[8:11], v[178:181], v[212:215], v[8:11]
	v_mfma_f32_16x16x32_bf16 v[60:63], v[174:177], v[190:193], v[60:63]
	v_mfma_f32_16x16x32_bf16 v[56:59], v[182:185], v[190:193], v[56:59]
	v_mfma_f32_16x16x32_bf16 v[44:47], v[174:177], v[200:203], v[44:47]
	v_mfma_f32_16x16x32_bf16 v[40:43], v[182:185], v[200:203], v[40:43]
	v_mfma_f32_16x16x32_bf16 v[28:31], v[174:177], v[208:211], v[28:31]
	v_mfma_f32_16x16x32_bf16 v[24:27], v[182:185], v[208:211], v[24:27]
	v_mfma_f32_16x16x32_bf16 v[12:15], v[174:177], v[216:219], v[12:15]
	v_mfma_f32_16x16x32_bf16 v[8:11], v[182:185], v[216:219], v[8:11]
	s_setprio 0
	s_barrier
	v_lshl_add_u64 v[222:223], v[222:223], 0, s[12:13]
	s_mov_b32 m0, s51
	s_nop 0
	global_load_lds_dwordx4 v[222:223], off
	v_lshl_add_u64 v[224:225], v[224:225], 0, s[12:13]
	s_mov_b32 m0, s52
	s_nop 0
	global_load_lds_dwordx4 v[224:225], off
	s_add_i32 s71, s71, 2
	s_add_u32 s28, s28, 0x100
	s_addc_u32 s29, s29, 0
	s_add_u32 s63, s63, 0x100
	s_addc_u32 s70, s70, 0
	s_cmp_gt_u32 s71, 13
	s_cbranch_scc0 .LBB0_410
	s_and_b64 vcc, exec, s[16:17]
	s_cbranch_vccz .LBB0_413
	s_barrier

.LBB0_532:
	ds_read_b128 v[146:149], v155
	ds_read_b128 v[160:163], v155 offset:1024
	ds_read_b128 v[164:167], v155 offset:2048
	ds_read_b128 v[168:171], v155 offset:3072
	ds_read_b128 v[172:175], v156
	ds_read_b128 v[176:179], v156 offset:1024
	ds_read_b128 v[180:183], v156 offset:2048
	ds_read_b128 v[184:187], v156 offset:3072
	s_add_u32 s30, s28, 0x100
	s_addc_u32 s31, s29, 0
	s_cmp_eq_u32 s77, 40
	s_cselect_b32 s37, s1, s31
	s_cselect_b32 s36, s0, s30
	s_cselect_b32 s35, s27, s73
	s_cselect_b32 s34, s26, s72
	v_lshl_add_u64 v[150:151], s[28:29], 0, v[138:139]
	s_add_i32 m0, s44, 0xc000
	ds_read_b128 v[188:191], v157
	ds_read_b128 v[196:199], v157 offset:1024
	ds_read_b128 v[200:203], v157 offset:2048
	ds_read_b128 v[204:207], v157 offset:3072
	ds_read_b128 v[208:211], v157 offset:4096
	ds_read_b128 v[212:215], v157 offset:5120
	ds_read_b128 v[216:219], v157 offset:6144
	ds_read_b128 v[220:223], v157 offset:7168
	global_load_lds_dwordx4 v[150:151], off
	v_lshl_add_u64 v[150:151], s[28:29], 0, v[140:141]
	s_add_i32 m0, s44, 0xe000
	s_nop 0
	global_load_lds_dwordx4 v[150:151], off
	s_waitcnt vmcnt(8)
	s_waitcnt lgkmcnt(0)
	s_barrier
	s_setprio 1
	s_waitcnt lgkmcnt(0)
	v_mfma_f32_16x16x32_bf16 v[124:127], v[146:149], v[188:191], v[124:127]
	v_mfma_f32_16x16x32_bf16 v[120:123], v[164:167], v[188:191], v[120:123]
	v_mfma_f32_16x16x32_bf16 v[108:111], v[146:149], v[200:203], v[108:111]
	v_mfma_f32_16x16x32_bf16 v[104:107], v[164:167], v[200:203], v[104:107]
	v_mfma_f32_16x16x32_bf16 v[92:95], v[146:149], v[208:211], v[92:95]
	v_mfma_f32_16x16x32_bf16 v[88:91], v[164:167], v[208:211], v[88:91]
	v_mfma_f32_16x16x32_bf16 v[76:79], v[146:149], v[216:219], v[76:79]
	v_mfma_f32_16x16x32_bf16 v[72:75], v[164:167], v[216:219], v[72:75]
	v_mfma_f32_16x16x32_bf16 v[124:127], v[160:163], v[196:199], v[124:127]
	v_mfma_f32_16x16x32_bf16 v[120:123], v[168:171], v[196:199], v[120:123]
	v_mfma_f32_16x16x32_bf16 v[108:111], v[160:163], v[204:207], v[108:111]
	v_mfma_f32_16x16x32_bf16 v[104:107], v[168:171], v[204:207], v[104:107]
	v_mfma_f32_16x16x32_bf16 v[92:95], v[160:163], v[212:215], v[92:95]
	v_mfma_f32_16x16x32_bf16 v[88:91], v[168:171], v[212:215], v[88:91]
	v_mfma_f32_16x16x32_bf16 v[76:79], v[160:163], v[220:223], v[76:79]
	v_mfma_f32_16x16x32_bf16 v[72:75], v[168:171], v[220:223], v[72:75]
	v_mfma_f32_16x16x32_bf16 v[116:119], v[172:175], v[188:191], v[116:119]
	v_mfma_f32_16x16x32_bf16 v[112:115], v[180:183], v[188:191], v[112:115]
	v_mfma_f32_16x16x32_bf16 v[100:103], v[172:175], v[200:203], v[100:103]
	v_mfma_f32_16x16x32_bf16 v[96:99], v[180:183], v[200:203], v[96:99]
	v_mfma_f32_16x16x32_bf16 v[84:87], v[172:175], v[208:211], v[84:87]
	v_mfma_f32_16x16x32_bf16 v[80:83], v[180:183], v[208:211], v[80:83]
	v_mfma_f32_16x16x32_bf16 v[68:71], v[172:175], v[216:219], v[68:71]
	v_mfma_f32_16x16x32_bf16 v[64:67], v[180:183], v[216:219], v[64:67]
	v_mfma_f32_16x16x32_bf16 v[116:119], v[176:179], v[196:199], v[116:119]
	v_mfma_f32_16x16x32_bf16 v[112:115], v[184:187], v[196:199], v[112:115]
	v_mfma_f32_16x16x32_bf16 v[100:103], v[176:179], v[204:207], v[100:103]
	v_mfma_f32_16x16x32_bf16 v[96:99], v[184:187], v[204:207], v[96:99]
	v_mfma_f32_16x16x32_bf16 v[84:87], v[176:179], v[212:215], v[84:87]
	v_mfma_f32_16x16x32_bf16 v[80:83], v[184:187], v[212:215], v[80:83]
	v_mfma_f32_16x16x32_bf16 v[68:71], v[176:179], v[220:223], v[68:71]
	v_mfma_f32_16x16x32_bf16 v[64:67], v[184:187], v[220:223], v[64:67]
	s_setprio 0
	s_barrier
	s_add_i32 s28, s60, s43
	v_lshl_add_u64 v[150:151], s[34:35], 0, v[132:133]
	s_mov_b32 m0, s28
	ds_read_b128 v[188:191], v157 offset:16384
	ds_read_b128 v[196:199], v157 offset:17408
	ds_read_b128 v[200:203], v157 offset:18432
	ds_read_b128 v[204:207], v157 offset:19456
	ds_read_b128 v[208:211], v157 offset:20480
	ds_read_b128 v[212:215], v157 offset:21504
	ds_read_b128 v[216:219], v157 offset:22528
	ds_read_b128 v[220:223], v157 offset:23552
	global_load_lds_dwordx4 v[150:151], off
	s_add_i32 m0, s28, 0x2000
	s_add_u32 s28, s34, 0xb0000
	v_lshl_add_u64 v[192:193], s[34:35], 0, v[136:137]
	s_addc_u32 s29, s35, 0
	s_add_i32 s78, s61, s43
	global_load_lds_dwordx4 v[192:193], off
	v_lshl_add_u64 v[224:225], s[28:29], 0, v[132:133]
	s_mov_b32 m0, s78
	v_lshl_add_u64 v[226:227], s[36:37], 0, v[134:135]
	global_load_lds_dwordx4 v[224:225], off
	v_lshl_add_u64 v[224:225], s[28:29], 0, v[136:137]
	s_add_i32 m0, s78, 0x2000
	s_nop 0
	global_load_lds_dwordx4 v[224:225], off
	v_lshl_add_u64 v[224:225], s[36:37], 0, v[130:131]
	s_waitcnt vmcnt(6)
	s_waitcnt lgkmcnt(0)
	s_barrier
	s_setprio 1
	s_waitcnt lgkmcnt(0)
	v_mfma_f32_16x16x32_bf16 v[60:63], v[146:149], v[188:191], v[60:63]
	v_mfma_f32_16x16x32_bf16 v[56:59], v[164:167], v[188:191], v[56:59]
	v_mfma_f32_16x16x32_bf16 v[44:47], v[146:149], v[200:203], v[44:47]
	v_mfma_f32_16x16x32_bf16 v[40:43], v[164:167], v[200:203], v[40:43]
	v_mfma_f32_16x16x32_bf16 v[28:31], v[146:149], v[208:211], v[28:31]
	v_mfma_f32_16x16x32_bf16 v[24:27], v[164:167], v[208:211], v[24:27]
	v_mfma_f32_16x16x32_bf16 v[12:15], v[146:149], v[216:219], v[12:15]
	v_mfma_f32_16x16x32_bf16 v[8:11], v[164:167], v[216:219], v[8:11]
	v_mfma_f32_16x16x32_bf16 v[60:63], v[160:163], v[196:199], v[60:63]
	v_mfma_f32_16x16x32_bf16 v[56:59], v[168:171], v[196:199], v[56:59]
	v_mfma_f32_16x16x32_bf16 v[44:47], v[160:163], v[204:207], v[44:47]
	v_mfma_f32_16x16x32_bf16 v[40:43], v[168:171], v[204:207], v[40:43]
	v_mfma_f32_16x16x32_bf16 v[28:31], v[160:163], v[212:215], v[28:31]
	v_mfma_f32_16x16x32_bf16 v[24:27], v[168:171], v[212:215], v[24:27]
	v_mfma_f32_16x16x32_bf16 v[12:15], v[160:163], v[220:223], v[12:15]
	v_mfma_f32_16x16x32_bf16 v[8:11], v[168:171], v[220:223], v[8:11]
	v_mfma_f32_16x16x32_bf16 v[52:55], v[172:175], v[188:191], v[52:55]
	v_mfma_f32_16x16x32_bf16 v[48:51], v[180:183], v[188:191], v[48:51]
	v_mfma_f32_16x16x32_bf16 v[36:39], v[172:175], v[200:203], v[36:39]
	v_mfma_f32_16x16x32_bf16 v[32:35], v[180:183], v[200:203], v[32:35]
	v_mfma_f32_16x16x32_bf16 v[20:23], v[172:175], v[208:211], v[20:23]
	v_mfma_f32_16x16x32_bf16 v[16:19], v[180:183], v[208:211], v[16:19]
	v_mfma_f32_16x16x32_bf16 v[4:7], v[172:175], v[216:219], v[4:7]
	v_mfma_f32_16x16x32_bf16 v[0:3], v[180:183], v[216:219], v[0:3]
	v_mfma_f32_16x16x32_bf16 v[52:55], v[176:179], v[196:199], v[52:55]
	v_mfma_f32_16x16x32_bf16 v[48:51], v[184:187], v[196:199], v[48:51]
	v_mfma_f32_16x16x32_bf16 v[36:39], v[176:179], v[204:207], v[36:39]
	v_mfma_f32_16x16x32_bf16 v[32:35], v[184:187], v[204:207], v[32:35]
	v_mfma_f32_16x16x32_bf16 v[20:23], v[176:179], v[212:215], v[20:23]
	v_mfma_f32_16x16x32_bf16 v[16:19], v[184:187], v[212:215], v[16:19]
	v_mfma_f32_16x16x32_bf16 v[4:7], v[176:179], v[220:223], v[4:7]
	v_mfma_f32_16x16x32_bf16 v[0:3], v[184:187], v[220:223], v[0:3]
	s_setprio 0
	s_barrier
	s_add_i32 s78, 0, 0x18000
	v_add_u32_e32 v159, s78, v153
	s_add_i32 s79, 0, 0x1c000
	ds_read_b128 v[146:149], v159
	ds_read_b128 v[160:163], v159 offset:1024
	ds_read_b128 v[164:167], v159 offset:2048
	ds_read_b128 v[168:171], v159 offset:3072
	v_add_u32_e32 v159, s79, v153
	ds_read_b128 v[172:175], v159
	ds_read_b128 v[176:179], v159 offset:1024
	ds_read_b128 v[180:183], v159 offset:2048
	ds_read_b128 v[184:187], v159 offset:3072
	s_add_u32 s28, s36, 0xb0000
	s_addc_u32 s29, s37, 0
	v_lshl_add_u64 v[228:229], s[28:29], 0, v[130:131]
	ds_read_b128 v[188:191], v157 offset:32768
	ds_read_b128 v[196:199], v157 offset:33792
	ds_read_b128 v[200:203], v157 offset:34816
	ds_read_b128 v[204:207], v157 offset:35840
	ds_read_b128 v[208:211], v157 offset:36864
	ds_read_b128 v[212:215], v157 offset:37888
	ds_read_b128 v[216:219], v157 offset:38912
	ds_read_b128 v[220:223], v157 offset:39936
	s_mov_b32 m0, s44
	s_nop 0
	global_load_lds_dwordx4 v[224:225], off
	s_mov_b32 m0, s45
	s_nop 0
	global_load_lds_dwordx4 v[226:227], off
	s_mov_b32 m0, s50
	s_nop 0
	global_load_lds_dwordx4 v[228:229], off
	v_lshl_add_u64 v[228:229], s[28:29], 0, v[134:135]
	s_mov_b32 m0, s51
	s_nop 0
	global_load_lds_dwordx4 v[228:229], off
	s_waitcnt vmcnt(8)
	s_waitcnt lgkmcnt(0)
	s_barrier
	s_setprio 1
	s_waitcnt lgkmcnt(0)
	v_mfma_f32_16x16x32_bf16 v[124:127], v[146:149], v[188:191], v[124:127]
	v_mfma_f32_16x16x32_bf16 v[120:123], v[164:167], v[188:191], v[120:123]
	v_mfma_f32_16x16x32_bf16 v[108:111], v[146:149], v[200:203], v[108:111]
	v_mfma_f32_16x16x32_bf16 v[104:107], v[164:167], v[200:203], v[104:107]
	v_mfma_f32_16x16x32_bf16 v[92:95], v[146:149], v[208:211], v[92:95]
	v_mfma_f32_16x16x32_bf16 v[88:91], v[164:167], v[208:211], v[88:91]
	v_mfma_f32_16x16x32_bf16 v[76:79], v[146:149], v[216:219], v[76:79]
	v_mfma_f32_16x16x32_bf16 v[72:75], v[164:167], v[216:219], v[72:75]
	v_mfma_f32_16x16x32_bf16 v[124:127], v[160:163], v[196:199], v[124:127]
	v_mfma_f32_16x16x32_bf16 v[120:123], v[168:171], v[196:199], v[120:123]
	v_mfma_f32_16x16x32_bf16 v[108:111], v[160:163], v[204:207], v[108:111]
	v_mfma_f32_16x16x32_bf16 v[104:107], v[168:171], v[204:207], v[104:107]
	v_mfma_f32_16x16x32_bf16 v[92:95], v[160:163], v[212:215], v[92:95]
	v_mfma_f32_16x16x32_bf16 v[88:91], v[168:171], v[212:215], v[88:91]
	v_mfma_f32_16x16x32_bf16 v[76:79], v[160:163], v[220:223], v[76:79]
	v_mfma_f32_16x16x32_bf16 v[72:75], v[168:171], v[220:223], v[72:75]
	v_mfma_f32_16x16x32_bf16 v[116:119], v[172:175], v[188:191], v[116:119]
	v_mfma_f32_16x16x32_bf16 v[112:115], v[180:183], v[188:191], v[112:115]
	v_mfma_f32_16x16x32_bf16 v[100:103], v[172:175], v[200:203], v[100:103]
	v_mfma_f32_16x16x32_bf16 v[96:99], v[180:183], v[200:203], v[96:99]
	v_mfma_f32_16x16x32_bf16 v[84:87], v[172:175], v[208:211], v[84:87]
	v_mfma_f32_16x16x32_bf16 v[80:83], v[180:183], v[208:211], v[80:83]
	v_mfma_f32_16x16x32_bf16 v[68:71], v[172:175], v[216:219], v[68:71]
	v_mfma_f32_16x16x32_bf16 v[64:67], v[180:183], v[216:219], v[64:67]
	v_mfma_f32_16x16x32_bf16 v[116:119], v[176:179], v[196:199], v[116:119]
	v_mfma_f32_16x16x32_bf16 v[112:115], v[184:187], v[196:199], v[112:115]
	v_mfma_f32_16x16x32_bf16 v[100:103], v[176:179], v[204:207], v[100:103]
	v_mfma_f32_16x16x32_bf16 v[96:99], v[184:187], v[204:207], v[96:99]
	v_mfma_f32_16x16x32_bf16 v[84:87], v[176:179], v[212:215], v[84:87]
	v_mfma_f32_16x16x32_bf16 v[80:83], v[184:187], v[212:215], v[80:83]
	v_mfma_f32_16x16x32_bf16 v[68:71], v[176:179], v[220:223], v[68:71]
	v_mfma_f32_16x16x32_bf16 v[64:67], v[184:187], v[220:223], v[64:67]
	s_setprio 0
	s_barrier
	s_add_i32 s28, s78, s43
	v_lshl_add_u64 v[150:151], v[150:151], 0, s[22:23]
	s_mov_b32 m0, s28
	ds_read_b128 v[188:191], v157 offset:49152
	ds_read_b128 v[196:199], v157 offset:50176
	ds_read_b128 v[200:203], v157 offset:51200
	ds_read_b128 v[204:207], v157 offset:52224
	ds_read_b128 v[208:211], v157 offset:53248
	ds_read_b128 v[212:215], v157 offset:54272
	ds_read_b128 v[216:219], v157 offset:55296
	ds_read_b128 v[220:223], v157 offset:56320
	global_load_lds_dwordx4 v[150:151], off
	s_add_i32 m0, s28, 0x2000
	s_add_u32 s28, s34, 0xb0080
	v_lshl_add_u64 v[150:151], v[192:193], 0, s[22:23]
	s_addc_u32 s29, s35, 0
	s_add_i32 s34, s79, s43
	global_load_lds_dwordx4 v[150:151], off
	v_lshl_add_u64 v[150:151], s[28:29], 0, v[132:133]
	s_mov_b32 m0, s34
	s_nop 0
	global_load_lds_dwordx4 v[150:151], off
	v_lshl_add_u64 v[150:151], s[28:29], 0, v[136:137]
	s_add_i32 m0, s34, 0x2000
	s_nop 0
	global_load_lds_dwordx4 v[150:151], off
	s_waitcnt vmcnt(6)
	s_waitcnt lgkmcnt(0)
	s_barrier
	s_setprio 1
	s_waitcnt lgkmcnt(0)
	v_mfma_f32_16x16x32_bf16 v[60:63], v[146:149], v[188:191], v[60:63]
	v_mfma_f32_16x16x32_bf16 v[56:59], v[164:167], v[188:191], v[56:59]
	v_mfma_f32_16x16x32_bf16 v[44:47], v[146:149], v[200:203], v[44:47]
	v_mfma_f32_16x16x32_bf16 v[40:43], v[164:167], v[200:203], v[40:43]
	v_mfma_f32_16x16x32_bf16 v[28:31], v[146:149], v[208:211], v[28:31]
	v_mfma_f32_16x16x32_bf16 v[24:27], v[164:167], v[208:211], v[24:27]
	v_mfma_f32_16x16x32_bf16 v[12:15], v[146:149], v[216:219], v[12:15]
	v_mfma_f32_16x16x32_bf16 v[8:11], v[164:167], v[216:219], v[8:11]
	v_mfma_f32_16x16x32_bf16 v[60:63], v[160:163], v[196:199], v[60:63]
	v_mfma_f32_16x16x32_bf16 v[56:59], v[168:171], v[196:199], v[56:59]
	v_mfma_f32_16x16x32_bf16 v[44:47], v[160:163], v[204:207], v[44:47]
	v_mfma_f32_16x16x32_bf16 v[40:43], v[168:171], v[204:207], v[40:43]
	v_mfma_f32_16x16x32_bf16 v[28:31], v[160:163], v[212:215], v[28:31]
	v_mfma_f32_16x16x32_bf16 v[24:27], v[168:171], v[212:215], v[24:27]
	v_mfma_f32_16x16x32_bf16 v[12:15], v[160:163], v[220:223], v[12:15]
	v_mfma_f32_16x16x32_bf16 v[8:11], v[168:171], v[220:223], v[8:11]
	v_mfma_f32_16x16x32_bf16 v[52:55], v[172:175], v[188:191], v[52:55]
	v_mfma_f32_16x16x32_bf16 v[48:51], v[180:183], v[188:191], v[48:51]
	v_mfma_f32_16x16x32_bf16 v[36:39], v[172:175], v[200:203], v[36:39]
	v_mfma_f32_16x16x32_bf16 v[32:35], v[180:183], v[200:203], v[32:35]
	v_mfma_f32_16x16x32_bf16 v[20:23], v[172:175], v[208:211], v[20:23]
	v_mfma_f32_16x16x32_bf16 v[16:19], v[180:183], v[208:211], v[16:19]
	v_mfma_f32_16x16x32_bf16 v[4:7], v[172:175], v[216:219], v[4:7]
	v_mfma_f32_16x16x32_bf16 v[0:3], v[180:183], v[216:219], v[0:3]
	v_mfma_f32_16x16x32_bf16 v[52:55], v[176:179], v[196:199], v[52:55]
	v_mfma_f32_16x16x32_bf16 v[48:51], v[184:187], v[196:199], v[48:51]
	v_mfma_f32_16x16x32_bf16 v[36:39], v[176:179], v[204:207], v[36:39]
	v_mfma_f32_16x16x32_bf16 v[32:35], v[184:187], v[204:207], v[32:35]
	v_mfma_f32_16x16x32_bf16 v[20:23], v[176:179], v[212:215], v[20:23]
	v_mfma_f32_16x16x32_bf16 v[16:19], v[184:187], v[212:215], v[16:19]
	v_mfma_f32_16x16x32_bf16 v[4:7], v[176:179], v[220:223], v[4:7]
	v_mfma_f32_16x16x32_bf16 v[0:3], v[184:187], v[220:223], v[0:3]
	s_setprio 0
	s_barrier
	v_lshl_add_u64 v[224:225], v[224:225], 0, s[22:23]
	s_mov_b32 m0, s55
	s_nop 0
	global_load_lds_dwordx4 v[224:225], off
	v_lshl_add_u64 v[226:227], v[226:227], 0, s[22:23]
	s_mov_b32 m0, s58
	s_nop 0
	global_load_lds_dwordx4 v[226:227], off
	s_add_i32 s77, s77, 2
	s_add_u32 s72, s72, 0x100
	s_addc_u32 s73, s73, 0
	s_cmp_gt_u32 s77, 41
	s_mov_b64 s[28:29], s[30:31]
	s_cbranch_scc0 .LBB0_532
	s_and_b64 vcc, exec, s[24:25]
	s_cbranch_vccz .LBB0_535
	s_barrier

.LBB0_626:
	ds_read_b128 v[152:155], v157
	ds_read_b128 v[162:165], v157 offset:1024
	ds_read_b128 v[166:169], v157 offset:2048
	ds_read_b128 v[170:173], v157 offset:3072
	ds_read_b128 v[174:177], v158
	ds_read_b128 v[178:181], v158 offset:1024
	ds_read_b128 v[182:185], v158 offset:2048
	ds_read_b128 v[186:189], v158 offset:3072
	s_add_u32 s40, s38, 0xfffc0080
	s_addc_u32 s41, s39, -1
	s_cmp_eq_u32 s86, 12
	s_cselect_b32 s43, s1, s41
	s_cselect_b32 s42, s11, s40
	s_cselect_b32 s41, s12, s85
	s_cselect_b32 s40, s29, s31
	v_lshl_add_u64 v[224:225], s[38:39], 0, v[144:145]
	s_add_i32 m0, s58, 0xc000
	ds_read_b128 v[190:193], v159
	ds_read_b128 v[196:199], v159 offset:1024
	ds_read_b128 v[200:203], v159 offset:2048
	ds_read_b128 v[204:207], v159 offset:3072
	ds_read_b128 v[208:211], v159 offset:4096
	ds_read_b128 v[212:215], v159 offset:5120
	ds_read_b128 v[216:219], v159 offset:6144
	ds_read_b128 v[220:223], v159 offset:7168
	global_load_lds_dwordx4 v[224:225], off
	v_lshl_add_u64 v[224:225], s[38:39], 0, v[146:147]
	s_add_i32 m0, s58, 0xe000
	s_nop 0
	global_load_lds_dwordx4 v[224:225], off
	s_waitcnt vmcnt(8)
	s_waitcnt lgkmcnt(0)
	s_barrier
	s_setprio 1
	s_waitcnt lgkmcnt(0)
	v_mfma_f32_16x16x32_bf16 v[124:127], v[152:155], v[190:193], v[124:127]
	v_mfma_f32_16x16x32_bf16 v[120:123], v[166:169], v[190:193], v[120:123]
	v_mfma_f32_16x16x32_bf16 v[108:111], v[152:155], v[200:203], v[108:111]
	v_mfma_f32_16x16x32_bf16 v[104:107], v[166:169], v[200:203], v[104:107]
	v_mfma_f32_16x16x32_bf16 v[92:95], v[152:155], v[208:211], v[92:95]
	v_mfma_f32_16x16x32_bf16 v[88:91], v[166:169], v[208:211], v[88:91]
	v_mfma_f32_16x16x32_bf16 v[76:79], v[152:155], v[216:219], v[76:79]
	v_mfma_f32_16x16x32_bf16 v[72:75], v[166:169], v[216:219], v[72:75]
	v_mfma_f32_16x16x32_bf16 v[124:127], v[162:165], v[196:199], v[124:127]
	v_mfma_f32_16x16x32_bf16 v[120:123], v[170:173], v[196:199], v[120:123]
	v_mfma_f32_16x16x32_bf16 v[108:111], v[162:165], v[204:207], v[108:111]
	v_mfma_f32_16x16x32_bf16 v[104:107], v[170:173], v[204:207], v[104:107]
	v_mfma_f32_16x16x32_bf16 v[92:95], v[162:165], v[212:215], v[92:95]
	v_mfma_f32_16x16x32_bf16 v[88:91], v[170:173], v[212:215], v[88:91]
	v_mfma_f32_16x16x32_bf16 v[76:79], v[162:165], v[220:223], v[76:79]
	v_mfma_f32_16x16x32_bf16 v[72:75], v[170:173], v[220:223], v[72:75]
	v_mfma_f32_16x16x32_bf16 v[116:119], v[174:177], v[190:193], v[116:119]
	v_mfma_f32_16x16x32_bf16 v[112:115], v[182:185], v[190:193], v[112:115]
	v_mfma_f32_16x16x32_bf16 v[100:103], v[174:177], v[200:203], v[100:103]
	v_mfma_f32_16x16x32_bf16 v[96:99], v[182:185], v[200:203], v[96:99]
	v_mfma_f32_16x16x32_bf16 v[84:87], v[174:177], v[208:211], v[84:87]
	v_mfma_f32_16x16x32_bf16 v[80:83], v[182:185], v[208:211], v[80:83]
	v_mfma_f32_16x16x32_bf16 v[68:71], v[174:177], v[216:219], v[68:71]
	v_mfma_f32_16x16x32_bf16 v[64:67], v[182:185], v[216:219], v[64:67]
	v_mfma_f32_16x16x32_bf16 v[116:119], v[178:181], v[196:199], v[116:119]
	v_mfma_f32_16x16x32_bf16 v[112:115], v[186:189], v[196:199], v[112:115]
	v_mfma_f32_16x16x32_bf16 v[100:103], v[178:181], v[204:207], v[100:103]
	v_mfma_f32_16x16x32_bf16 v[96:99], v[186:189], v[204:207], v[96:99]
	v_mfma_f32_16x16x32_bf16 v[84:87], v[178:181], v[212:215], v[84:87]
	v_mfma_f32_16x16x32_bf16 v[80:83], v[186:189], v[212:215], v[80:83]
	v_mfma_f32_16x16x32_bf16 v[68:71], v[178:181], v[220:223], v[68:71]
	v_mfma_f32_16x16x32_bf16 v[64:67], v[186:189], v[220:223], v[64:67]
	s_setprio 0
	s_barrier
	s_add_i32 s87, s73, s55
	v_lshl_add_u64 v[224:225], s[40:41], 0, v[130:131]
	s_mov_b32 m0, s87
	ds_read_b128 v[190:193], v159 offset:16384
	ds_read_b128 v[196:199], v159 offset:17408
	ds_read_b128 v[200:203], v159 offset:18432
	ds_read_b128 v[204:207], v159 offset:19456
	ds_read_b128 v[208:211], v159 offset:20480
	ds_read_b128 v[212:215], v159 offset:21504
	ds_read_b128 v[216:219], v159 offset:22528
	ds_read_b128 v[220:223], v159 offset:23552
	global_load_lds_dwordx4 v[224:225], off
	s_add_i32 m0, s87, 0x2000
	s_add_u32 s88, s40, 0x40000
	v_lshl_add_u64 v[226:227], s[40:41], 0, v[134:135]
	s_addc_u32 s89, s41, 0
	s_add_i32 s87, s77, s55
	global_load_lds_dwordx4 v[226:227], off
	v_lshl_add_u64 v[228:229], s[88:89], 0, v[130:131]
	s_mov_b32 m0, s87
	v_lshl_add_u64 v[230:231], s[42:43], 0, v[132:133]
	global_load_lds_dwordx4 v[228:229], off
	v_lshl_add_u64 v[228:229], s[88:89], 0, v[134:135]
	s_add_i32 m0, s87, 0x2000
	s_nop 0
	global_load_lds_dwordx4 v[228:229], off
	v_lshl_add_u64 v[228:229], s[42:43], 0, v[128:129]
	s_waitcnt vmcnt(6)
	s_waitcnt lgkmcnt(0)
	s_barrier
	s_setprio 1
	s_waitcnt lgkmcnt(0)
	v_mfma_f32_16x16x32_bf16 v[60:63], v[152:155], v[190:193], v[60:63]
	v_mfma_f32_16x16x32_bf16 v[56:59], v[166:169], v[190:193], v[56:59]
	v_mfma_f32_16x16x32_bf16 v[44:47], v[152:155], v[200:203], v[44:47]
	v_mfma_f32_16x16x32_bf16 v[40:43], v[166:169], v[200:203], v[40:43]
	v_mfma_f32_16x16x32_bf16 v[28:31], v[152:155], v[208:211], v[28:31]
	v_mfma_f32_16x16x32_bf16 v[24:27], v[166:169], v[208:211], v[24:27]
	v_mfma_f32_16x16x32_bf16 v[12:15], v[152:155], v[216:219], v[12:15]
	v_mfma_f32_16x16x32_bf16 v[8:11], v[166:169], v[216:219], v[8:11]
	v_mfma_f32_16x16x32_bf16 v[60:63], v[162:165], v[196:199], v[60:63]
	v_mfma_f32_16x16x32_bf16 v[56:59], v[170:173], v[196:199], v[56:59]
	v_mfma_f32_16x16x32_bf16 v[44:47], v[162:165], v[204:207], v[44:47]
	v_mfma_f32_16x16x32_bf16 v[40:43], v[170:173], v[204:207], v[40:43]
	v_mfma_f32_16x16x32_bf16 v[28:31], v[162:165], v[212:215], v[28:31]
	v_mfma_f32_16x16x32_bf16 v[24:27], v[170:173], v[212:215], v[24:27]
	v_mfma_f32_16x16x32_bf16 v[12:15], v[162:165], v[220:223], v[12:15]
	v_mfma_f32_16x16x32_bf16 v[8:11], v[170:173], v[220:223], v[8:11]
	v_mfma_f32_16x16x32_bf16 v[52:55], v[174:177], v[190:193], v[52:55]
	v_mfma_f32_16x16x32_bf16 v[48:51], v[182:185], v[190:193], v[48:51]
	v_mfma_f32_16x16x32_bf16 v[36:39], v[174:177], v[200:203], v[36:39]
	v_mfma_f32_16x16x32_bf16 v[32:35], v[182:185], v[200:203], v[32:35]
	v_mfma_f32_16x16x32_bf16 v[20:23], v[174:177], v[208:211], v[20:23]
	v_mfma_f32_16x16x32_bf16 v[16:19], v[182:185], v[208:211], v[16:19]
	v_mfma_f32_16x16x32_bf16 v[4:7], v[174:177], v[216:219], v[4:7]
	v_mfma_f32_16x16x32_bf16 v[0:3], v[182:185], v[216:219], v[0:3]
	v_mfma_f32_16x16x32_bf16 v[52:55], v[178:181], v[196:199], v[52:55]
	v_mfma_f32_16x16x32_bf16 v[48:51], v[186:189], v[196:199], v[48:51]
	v_mfma_f32_16x16x32_bf16 v[36:39], v[178:181], v[204:207], v[36:39]
	v_mfma_f32_16x16x32_bf16 v[32:35], v[186:189], v[204:207], v[32:35]
	v_mfma_f32_16x16x32_bf16 v[20:23], v[178:181], v[212:215], v[20:23]
	v_mfma_f32_16x16x32_bf16 v[16:19], v[186:189], v[212:215], v[16:19]
	v_mfma_f32_16x16x32_bf16 v[4:7], v[178:181], v[220:223], v[4:7]
	v_mfma_f32_16x16x32_bf16 v[0:3], v[186:189], v[220:223], v[0:3]
	s_setprio 0
	s_barrier
	s_add_i32 s87, 0, 0x18000
	v_add_u32_e32 v136, s87, v141
	s_add_i32 s88, 0, 0x1c000
	ds_read_b128 v[152:155], v136
	ds_read_b128 v[162:165], v136 offset:1024
	ds_read_b128 v[166:169], v136 offset:2048
	ds_read_b128 v[170:173], v136 offset:3072
	v_add_u32_e32 v136, s88, v141
	ds_read_b128 v[174:177], v136
	ds_read_b128 v[178:181], v136 offset:1024
	ds_read_b128 v[182:185], v136 offset:2048
	ds_read_b128 v[186:189], v136 offset:3072
	s_add_u32 s42, s42, 0x40000
	s_addc_u32 s43, s43, 0
	v_lshl_add_u64 v[232:233], s[42:43], 0, v[128:129]
	ds_read_b128 v[190:193], v159 offset:32768
	ds_read_b128 v[196:199], v159 offset:33792
	ds_read_b128 v[200:203], v159 offset:34816
	ds_read_b128 v[204:207], v159 offset:35840
	ds_read_b128 v[208:211], v159 offset:36864
	ds_read_b128 v[212:215], v159 offset:37888
	ds_read_b128 v[216:219], v159 offset:38912
	ds_read_b128 v[220:223], v159 offset:39936
	s_mov_b32 m0, s58
	s_nop 0
	global_load_lds_dwordx4 v[228:229], off
	s_mov_b32 m0, s59
	s_nop 0
	global_load_lds_dwordx4 v[230:231], off
	s_mov_b32 m0, s60
	s_nop 0
	global_load_lds_dwordx4 v[232:233], off
	v_lshl_add_u64 v[232:233], s[42:43], 0, v[132:133]
	s_mov_b32 m0, s61
	s_nop 0
	global_load_lds_dwordx4 v[232:233], off
	s_waitcnt vmcnt(8)
	s_waitcnt lgkmcnt(0)
	s_barrier
	s_setprio 1
	s_waitcnt lgkmcnt(0)
	v_mfma_f32_16x16x32_bf16 v[124:127], v[152:155], v[190:193], v[124:127]
	v_mfma_f32_16x16x32_bf16 v[120:123], v[166:169], v[190:193], v[120:123]
	v_mfma_f32_16x16x32_bf16 v[108:111], v[152:155], v[200:203], v[108:111]
	v_mfma_f32_16x16x32_bf16 v[104:107], v[166:169], v[200:203], v[104:107]
	v_mfma_f32_16x16x32_bf16 v[92:95], v[152:155], v[208:211], v[92:95]
	v_mfma_f32_16x16x32_bf16 v[88:91], v[166:169], v[208:211], v[88:91]
	v_mfma_f32_16x16x32_bf16 v[76:79], v[152:155], v[216:219], v[76:79]
	v_mfma_f32_16x16x32_bf16 v[72:75], v[166:169], v[216:219], v[72:75]
	v_mfma_f32_16x16x32_bf16 v[124:127], v[162:165], v[196:199], v[124:127]
	v_mfma_f32_16x16x32_bf16 v[120:123], v[170:173], v[196:199], v[120:123]
	v_mfma_f32_16x16x32_bf16 v[108:111], v[162:165], v[204:207], v[108:111]
	v_mfma_f32_16x16x32_bf16 v[104:107], v[170:173], v[204:207], v[104:107]
	v_mfma_f32_16x16x32_bf16 v[92:95], v[162:165], v[212:215], v[92:95]
	v_mfma_f32_16x16x32_bf16 v[88:91], v[170:173], v[212:215], v[88:91]
	v_mfma_f32_16x16x32_bf16 v[76:79], v[162:165], v[220:223], v[76:79]
	v_mfma_f32_16x16x32_bf16 v[72:75], v[170:173], v[220:223], v[72:75]
	v_mfma_f32_16x16x32_bf16 v[116:119], v[174:177], v[190:193], v[116:119]
	v_mfma_f32_16x16x32_bf16 v[112:115], v[182:185], v[190:193], v[112:115]
	v_mfma_f32_16x16x32_bf16 v[100:103], v[174:177], v[200:203], v[100:103]
	v_mfma_f32_16x16x32_bf16 v[96:99], v[182:185], v[200:203], v[96:99]
	v_mfma_f32_16x16x32_bf16 v[84:87], v[174:177], v[208:211], v[84:87]
	v_mfma_f32_16x16x32_bf16 v[80:83], v[182:185], v[208:211], v[80:83]
	v_mfma_f32_16x16x32_bf16 v[68:71], v[174:177], v[216:219], v[68:71]
	v_mfma_f32_16x16x32_bf16 v[64:67], v[182:185], v[216:219], v[64:67]
	v_mfma_f32_16x16x32_bf16 v[116:119], v[178:181], v[196:199], v[116:119]
	v_mfma_f32_16x16x32_bf16 v[112:115], v[186:189], v[196:199], v[112:115]
	v_mfma_f32_16x16x32_bf16 v[100:103], v[178:181], v[204:207], v[100:103]
	v_mfma_f32_16x16x32_bf16 v[96:99], v[186:189], v[204:207], v[96:99]
	v_mfma_f32_16x16x32_bf16 v[84:87], v[178:181], v[212:215], v[84:87]
	v_mfma_f32_16x16x32_bf16 v[80:83], v[186:189], v[212:215], v[80:83]
	v_mfma_f32_16x16x32_bf16 v[68:71], v[178:181], v[220:223], v[68:71]
	v_mfma_f32_16x16x32_bf16 v[64:67], v[186:189], v[220:223], v[64:67]
	s_setprio 0
	s_barrier
	s_add_i32 s42, s87, s55
	v_lshl_add_u64 v[224:225], v[224:225], 0, s[24:25]
	s_mov_b32 m0, s42
	ds_read_b128 v[190:193], v159 offset:49152
	ds_read_b128 v[196:199], v159 offset:50176
	ds_read_b128 v[200:203], v159 offset:51200
	ds_read_b128 v[204:207], v159 offset:52224
	ds_read_b128 v[208:211], v159 offset:53248
	ds_read_b128 v[212:215], v159 offset:54272
	ds_read_b128 v[216:219], v159 offset:55296
	ds_read_b128 v[220:223], v159 offset:56320
	global_load_lds_dwordx4 v[224:225], off
	s_add_i32 m0, s42, 0x2000
	s_add_u32 s40, s40, 0x40080
	v_lshl_add_u64 v[224:225], v[226:227], 0, s[24:25]
	s_addc_u32 s41, s41, 0
	s_add_i32 s42, s88, s55
	global_load_lds_dwordx4 v[224:225], off
	v_lshl_add_u64 v[224:225], s[40:41], 0, v[130:131]
	s_mov_b32 m0, s42
	s_nop 0
	global_load_lds_dwordx4 v[224:225], off
	v_lshl_add_u64 v[224:225], s[40:41], 0, v[134:135]
	s_add_i32 m0, s42, 0x2000
	s_nop 0
	global_load_lds_dwordx4 v[224:225], off
	s_waitcnt vmcnt(6)
	s_waitcnt lgkmcnt(0)
	s_barrier
	s_setprio 1
	s_waitcnt lgkmcnt(0)
	v_mfma_f32_16x16x32_bf16 v[60:63], v[152:155], v[190:193], v[60:63]
	v_mfma_f32_16x16x32_bf16 v[56:59], v[166:169], v[190:193], v[56:59]
	v_mfma_f32_16x16x32_bf16 v[44:47], v[152:155], v[200:203], v[44:47]
	v_mfma_f32_16x16x32_bf16 v[40:43], v[166:169], v[200:203], v[40:43]
	v_mfma_f32_16x16x32_bf16 v[28:31], v[152:155], v[208:211], v[28:31]
	v_mfma_f32_16x16x32_bf16 v[24:27], v[166:169], v[208:211], v[24:27]
	v_mfma_f32_16x16x32_bf16 v[12:15], v[152:155], v[216:219], v[12:15]
	v_mfma_f32_16x16x32_bf16 v[8:11], v[166:169], v[216:219], v[8:11]
	v_mfma_f32_16x16x32_bf16 v[60:63], v[162:165], v[196:199], v[60:63]
	v_mfma_f32_16x16x32_bf16 v[56:59], v[170:173], v[196:199], v[56:59]
	v_mfma_f32_16x16x32_bf16 v[44:47], v[162:165], v[204:207], v[44:47]
	v_mfma_f32_16x16x32_bf16 v[40:43], v[170:173], v[204:207], v[40:43]
	v_mfma_f32_16x16x32_bf16 v[28:31], v[162:165], v[212:215], v[28:31]
	v_mfma_f32_16x16x32_bf16 v[24:27], v[170:173], v[212:215], v[24:27]
	v_mfma_f32_16x16x32_bf16 v[12:15], v[162:165], v[220:223], v[12:15]
	v_mfma_f32_16x16x32_bf16 v[8:11], v[170:173], v[220:223], v[8:11]
	v_mfma_f32_16x16x32_bf16 v[52:55], v[174:177], v[190:193], v[52:55]
	v_mfma_f32_16x16x32_bf16 v[48:51], v[182:185], v[190:193], v[48:51]
	v_mfma_f32_16x16x32_bf16 v[36:39], v[174:177], v[200:203], v[36:39]
	v_mfma_f32_16x16x32_bf16 v[32:35], v[182:185], v[200:203], v[32:35]
	v_mfma_f32_16x16x32_bf16 v[20:23], v[174:177], v[208:211], v[20:23]
	v_mfma_f32_16x16x32_bf16 v[16:19], v[182:185], v[208:211], v[16:19]
	v_mfma_f32_16x16x32_bf16 v[4:7], v[174:177], v[216:219], v[4:7]
	v_mfma_f32_16x16x32_bf16 v[0:3], v[182:185], v[216:219], v[0:3]
	v_mfma_f32_16x16x32_bf16 v[52:55], v[178:181], v[196:199], v[52:55]
	v_mfma_f32_16x16x32_bf16 v[48:51], v[186:189], v[196:199], v[48:51]
	v_mfma_f32_16x16x32_bf16 v[36:39], v[178:181], v[204:207], v[36:39]
	v_mfma_f32_16x16x32_bf16 v[32:35], v[186:189], v[204:207], v[32:35]
	v_mfma_f32_16x16x32_bf16 v[20:23], v[178:181], v[212:215], v[20:23]
	v_mfma_f32_16x16x32_bf16 v[16:19], v[186:189], v[212:215], v[16:19]
	v_mfma_f32_16x16x32_bf16 v[4:7], v[178:181], v[220:223], v[4:7]
	v_mfma_f32_16x16x32_bf16 v[0:3], v[186:189], v[220:223], v[0:3]
	s_setprio 0
	s_barrier
	v_lshl_add_u64 v[228:229], v[228:229], 0, s[24:25]
	s_mov_b32 m0, s70
	s_nop 0
	global_load_lds_dwordx4 v[228:229], off
	v_lshl_add_u64 v[230:231], v[230:231], 0, s[24:25]
	s_mov_b32 m0, s71
	s_nop 0
	global_load_lds_dwordx4 v[230:231], off
	s_add_i32 s86, s86, 2
	s_add_u32 s38, s38, 0x100
	s_addc_u32 s39, s39, 0
	s_add_u32 s31, s31, 0x100
	s_addc_u32 s85, s85, 0
	s_cmp_gt_u32 s86, 13
	s_cbranch_scc0 .LBB0_626
	s_and_b64 vcc, exec, s[26:27]
	s_cbranch_vccz .LBB0_629
	s_barrier

.LBB0_760:
	ds_read_b128 v[148:151], v144
	ds_read_b128 v[152:155], v144 offset:1024
	ds_read_b128 v[156:159], v144 offset:2048
	ds_read_b128 v[160:163], v144 offset:3072
	ds_read_b128 v[164:167], v145
	ds_read_b128 v[168:171], v145 offset:1024
	ds_read_b128 v[172:175], v145 offset:2048
	ds_read_b128 v[176:179], v145 offset:3072
	s_add_u32 s36, s34, 0x100
	s_addc_u32 s37, s35, 0
	s_cmp_eq_u32 s83, 4
	s_cselect_b32 s41, s29, s37
	s_cselect_b32 s40, s28, s36
	s_cselect_b32 s39, s31, s25
	s_cselect_b32 s38, s30, s13
	v_lshl_add_u64 v[192:193], s[34:35], 0, v[138:139]
	s_add_i32 m0, s58, 0xc000
	ds_read_b128 v[180:183], v146
	ds_read_b128 v[184:187], v146 offset:1024
	ds_read_b128 v[188:191], v146 offset:2048
	ds_read_b128 v[196:199], v146 offset:3072
	ds_read_b128 v[200:203], v146 offset:4096
	ds_read_b128 v[204:207], v146 offset:5120
	ds_read_b128 v[208:211], v146 offset:6144
	ds_read_b128 v[212:215], v146 offset:7168
	global_load_lds_dwordx4 v[192:193], off
	v_lshl_add_u64 v[192:193], s[34:35], 0, v[140:141]
	s_add_i32 m0, s58, 0xe000
	s_nop 0
	global_load_lds_dwordx4 v[192:193], off
	s_waitcnt vmcnt(8)
	s_waitcnt lgkmcnt(0)
	s_barrier
	s_setprio 1
	s_waitcnt lgkmcnt(0)
	v_mfma_f32_16x16x32_bf16 v[124:127], v[148:151], v[180:183], v[124:127]
	v_mfma_f32_16x16x32_bf16 v[120:123], v[156:159], v[180:183], v[120:123]
	v_mfma_f32_16x16x32_bf16 v[116:119], v[148:151], v[188:191], v[116:119]
	v_mfma_f32_16x16x32_bf16 v[112:115], v[156:159], v[188:191], v[112:115]
	v_mfma_f32_16x16x32_bf16 v[104:107], v[148:151], v[200:203], v[104:107]
	v_mfma_f32_16x16x32_bf16 v[96:99], v[156:159], v[200:203], v[96:99]
	v_mfma_f32_16x16x32_bf16 v[88:91], v[148:151], v[208:211], v[88:91]
	v_mfma_f32_16x16x32_bf16 v[80:83], v[156:159], v[208:211], v[80:83]
	v_mfma_f32_16x16x32_bf16 v[124:127], v[152:155], v[184:187], v[124:127]
	v_mfma_f32_16x16x32_bf16 v[120:123], v[160:163], v[184:187], v[120:123]
	v_mfma_f32_16x16x32_bf16 v[116:119], v[152:155], v[196:199], v[116:119]
	v_mfma_f32_16x16x32_bf16 v[112:115], v[160:163], v[196:199], v[112:115]
	v_mfma_f32_16x16x32_bf16 v[104:107], v[152:155], v[204:207], v[104:107]
	v_mfma_f32_16x16x32_bf16 v[96:99], v[160:163], v[204:207], v[96:99]
	v_mfma_f32_16x16x32_bf16 v[88:91], v[152:155], v[212:215], v[88:91]
	v_mfma_f32_16x16x32_bf16 v[80:83], v[160:163], v[212:215], v[80:83]
	v_mfma_f32_16x16x32_bf16 v[108:111], v[164:167], v[180:183], v[108:111]
	v_mfma_f32_16x16x32_bf16 v[100:103], v[172:175], v[180:183], v[100:103]
	v_mfma_f32_16x16x32_bf16 v[92:95], v[164:167], v[188:191], v[92:95]
	v_mfma_f32_16x16x32_bf16 v[84:87], v[172:175], v[188:191], v[84:87]
	v_mfma_f32_16x16x32_bf16 v[76:79], v[164:167], v[200:203], v[76:79]
	v_mfma_f32_16x16x32_bf16 v[72:75], v[172:175], v[200:203], v[72:75]
	v_mfma_f32_16x16x32_bf16 v[68:71], v[164:167], v[208:211], v[68:71]
	v_mfma_f32_16x16x32_bf16 v[64:67], v[172:175], v[208:211], v[64:67]
	v_mfma_f32_16x16x32_bf16 v[108:111], v[168:171], v[184:187], v[108:111]
	v_mfma_f32_16x16x32_bf16 v[100:103], v[176:179], v[184:187], v[100:103]
	v_mfma_f32_16x16x32_bf16 v[92:95], v[168:171], v[196:199], v[92:95]
	v_mfma_f32_16x16x32_bf16 v[84:87], v[176:179], v[196:199], v[84:87]
	v_mfma_f32_16x16x32_bf16 v[76:79], v[168:171], v[204:207], v[76:79]
	v_mfma_f32_16x16x32_bf16 v[72:75], v[176:179], v[204:207], v[72:75]
	v_mfma_f32_16x16x32_bf16 v[68:71], v[168:171], v[212:215], v[68:71]
	v_mfma_f32_16x16x32_bf16 v[64:67], v[176:179], v[212:215], v[64:67]
	s_setprio 0
	s_barrier
	s_add_i32 s34, s77, s51
	v_lshl_add_u64 v[192:193], s[38:39], 0, v[132:133]
	s_mov_b32 m0, s34
	ds_read_b128 v[180:183], v146 offset:16384
	ds_read_b128 v[184:187], v146 offset:17408
	ds_read_b128 v[188:191], v146 offset:18432
	ds_read_b128 v[196:199], v146 offset:19456
	ds_read_b128 v[200:203], v146 offset:20480
	ds_read_b128 v[204:207], v146 offset:21504
	ds_read_b128 v[208:211], v146 offset:22528
	ds_read_b128 v[212:215], v146 offset:23552
	global_load_lds_dwordx4 v[192:193], off
	s_add_i32 m0, s34, 0x2000
	s_add_u32 s34, s38, 0x20000
	v_lshl_add_u64 v[216:217], s[38:39], 0, v[128:129]
	s_addc_u32 s35, s39, 0
	s_add_i32 s84, s78, s51
	global_load_lds_dwordx4 v[216:217], off
	v_lshl_add_u64 v[218:219], s[34:35], 0, v[132:133]
	s_mov_b32 m0, s84
	v_lshl_add_u64 v[220:221], s[40:41], 0, v[130:131]
	global_load_lds_dwordx4 v[218:219], off
	v_lshl_add_u64 v[218:219], s[34:35], 0, v[128:129]
	s_add_i32 m0, s84, 0x2000
	s_nop 0
	global_load_lds_dwordx4 v[218:219], off
	v_lshl_add_u64 v[218:219], s[40:41], 0, v[134:135]
	s_waitcnt vmcnt(6)
	s_waitcnt lgkmcnt(0)
	s_barrier
	s_setprio 1
	s_waitcnt lgkmcnt(0)
	v_mfma_f32_16x16x32_bf16 v[60:63], v[148:151], v[180:183], v[60:63]
	v_mfma_f32_16x16x32_bf16 v[56:59], v[156:159], v[180:183], v[56:59]
	v_mfma_f32_16x16x32_bf16 v[52:55], v[148:151], v[188:191], v[52:55]
	v_mfma_f32_16x16x32_bf16 v[48:51], v[156:159], v[188:191], v[48:51]
	v_mfma_f32_16x16x32_bf16 v[40:43], v[148:151], v[200:203], v[40:43]
	v_mfma_f32_16x16x32_bf16 v[32:35], v[156:159], v[200:203], v[32:35]
	v_mfma_f32_16x16x32_bf16 v[24:27], v[148:151], v[208:211], v[24:27]
	v_mfma_f32_16x16x32_bf16 v[16:19], v[156:159], v[208:211], v[16:19]
	v_mfma_f32_16x16x32_bf16 v[60:63], v[152:155], v[184:187], v[60:63]
	v_mfma_f32_16x16x32_bf16 v[56:59], v[160:163], v[184:187], v[56:59]
	v_mfma_f32_16x16x32_bf16 v[52:55], v[152:155], v[196:199], v[52:55]
	v_mfma_f32_16x16x32_bf16 v[48:51], v[160:163], v[196:199], v[48:51]
	v_mfma_f32_16x16x32_bf16 v[40:43], v[152:155], v[204:207], v[40:43]
	v_mfma_f32_16x16x32_bf16 v[32:35], v[160:163], v[204:207], v[32:35]
	v_mfma_f32_16x16x32_bf16 v[24:27], v[152:155], v[212:215], v[24:27]
	v_mfma_f32_16x16x32_bf16 v[16:19], v[160:163], v[212:215], v[16:19]
	v_mfma_f32_16x16x32_bf16 v[44:47], v[164:167], v[180:183], v[44:47]
	v_mfma_f32_16x16x32_bf16 v[36:39], v[172:175], v[180:183], v[36:39]
	v_mfma_f32_16x16x32_bf16 v[28:31], v[164:167], v[188:191], v[28:31]
	v_mfma_f32_16x16x32_bf16 v[20:23], v[172:175], v[188:191], v[20:23]
	v_mfma_f32_16x16x32_bf16 v[12:15], v[164:167], v[200:203], v[12:15]
	v_mfma_f32_16x16x32_bf16 v[8:11], v[172:175], v[200:203], v[8:11]
	v_mfma_f32_16x16x32_bf16 v[4:7], v[164:167], v[208:211], v[4:7]
	v_mfma_f32_16x16x32_bf16 v[0:3], v[172:175], v[208:211], v[0:3]
	v_mfma_f32_16x16x32_bf16 v[44:47], v[168:171], v[184:187], v[44:47]
	v_mfma_f32_16x16x32_bf16 v[36:39], v[176:179], v[184:187], v[36:39]
	v_mfma_f32_16x16x32_bf16 v[28:31], v[168:171], v[196:199], v[28:31]
	v_mfma_f32_16x16x32_bf16 v[20:23], v[176:179], v[196:199], v[20:23]
	v_mfma_f32_16x16x32_bf16 v[12:15], v[168:171], v[204:207], v[12:15]
	v_mfma_f32_16x16x32_bf16 v[8:11], v[176:179], v[204:207], v[8:11]
	v_mfma_f32_16x16x32_bf16 v[4:7], v[168:171], v[212:215], v[4:7]
	v_mfma_f32_16x16x32_bf16 v[0:3], v[176:179], v[212:215], v[0:3]
	s_setprio 0
	s_barrier
	s_add_i32 s84, 0, 0x18000
	v_add_u32_e32 v147, s84, v143
	s_add_i32 s85, 0, 0x1c000
	ds_read_b128 v[148:151], v147
	ds_read_b128 v[152:155], v147 offset:1024
	ds_read_b128 v[156:159], v147 offset:2048
	ds_read_b128 v[160:163], v147 offset:3072
	v_add_u32_e32 v147, s85, v143
	ds_read_b128 v[164:167], v147
	ds_read_b128 v[168:171], v147 offset:1024
	ds_read_b128 v[172:175], v147 offset:2048
	ds_read_b128 v[176:179], v147 offset:3072
	s_add_u32 s34, s40, 0x30000
	s_addc_u32 s35, s41, 0
	v_lshl_add_u64 v[222:223], s[34:35], 0, v[134:135]
	ds_read_b128 v[180:183], v146 offset:32768
	ds_read_b128 v[184:187], v146 offset:33792
	ds_read_b128 v[188:191], v146 offset:34816
	ds_read_b128 v[196:199], v146 offset:35840
	ds_read_b128 v[200:203], v146 offset:36864
	ds_read_b128 v[204:207], v146 offset:37888
	ds_read_b128 v[208:211], v146 offset:38912
	ds_read_b128 v[212:215], v146 offset:39936
	s_mov_b32 m0, s58
	s_nop 0
	global_load_lds_dwordx4 v[218:219], off
	s_mov_b32 m0, s59
	s_nop 0
	global_load_lds_dwordx4 v[220:221], off
	s_mov_b32 m0, s60
	s_nop 0
	global_load_lds_dwordx4 v[222:223], off
	v_lshl_add_u64 v[222:223], s[34:35], 0, v[130:131]
	s_mov_b32 m0, s61
	s_nop 0
	global_load_lds_dwordx4 v[222:223], off
	s_waitcnt vmcnt(8)
	s_waitcnt lgkmcnt(0)
	s_barrier
	s_setprio 1
	s_waitcnt lgkmcnt(0)
	v_mfma_f32_16x16x32_bf16 v[124:127], v[148:151], v[180:183], v[124:127]
	v_mfma_f32_16x16x32_bf16 v[120:123], v[156:159], v[180:183], v[120:123]
	v_mfma_f32_16x16x32_bf16 v[116:119], v[148:151], v[188:191], v[116:119]
	v_mfma_f32_16x16x32_bf16 v[112:115], v[156:159], v[188:191], v[112:115]
	v_mfma_f32_16x16x32_bf16 v[104:107], v[148:151], v[200:203], v[104:107]
	v_mfma_f32_16x16x32_bf16 v[96:99], v[156:159], v[200:203], v[96:99]
	v_mfma_f32_16x16x32_bf16 v[88:91], v[148:151], v[208:211], v[88:91]
	v_mfma_f32_16x16x32_bf16 v[80:83], v[156:159], v[208:211], v[80:83]
	v_mfma_f32_16x16x32_bf16 v[124:127], v[152:155], v[184:187], v[124:127]
	v_mfma_f32_16x16x32_bf16 v[120:123], v[160:163], v[184:187], v[120:123]
	v_mfma_f32_16x16x32_bf16 v[116:119], v[152:155], v[196:199], v[116:119]
	v_mfma_f32_16x16x32_bf16 v[112:115], v[160:163], v[196:199], v[112:115]
	v_mfma_f32_16x16x32_bf16 v[104:107], v[152:155], v[204:207], v[104:107]
	v_mfma_f32_16x16x32_bf16 v[96:99], v[160:163], v[204:207], v[96:99]
	v_mfma_f32_16x16x32_bf16 v[88:91], v[152:155], v[212:215], v[88:91]
	v_mfma_f32_16x16x32_bf16 v[80:83], v[160:163], v[212:215], v[80:83]
	v_mfma_f32_16x16x32_bf16 v[108:111], v[164:167], v[180:183], v[108:111]
	v_mfma_f32_16x16x32_bf16 v[100:103], v[172:175], v[180:183], v[100:103]
	v_mfma_f32_16x16x32_bf16 v[92:95], v[164:167], v[188:191], v[92:95]
	v_mfma_f32_16x16x32_bf16 v[84:87], v[172:175], v[188:191], v[84:87]
	v_mfma_f32_16x16x32_bf16 v[76:79], v[164:167], v[200:203], v[76:79]
	v_mfma_f32_16x16x32_bf16 v[72:75], v[172:175], v[200:203], v[72:75]
	v_mfma_f32_16x16x32_bf16 v[68:71], v[164:167], v[208:211], v[68:71]
	v_mfma_f32_16x16x32_bf16 v[64:67], v[172:175], v[208:211], v[64:67]
	v_mfma_f32_16x16x32_bf16 v[108:111], v[168:171], v[184:187], v[108:111]
	v_mfma_f32_16x16x32_bf16 v[100:103], v[176:179], v[184:187], v[100:103]
	v_mfma_f32_16x16x32_bf16 v[92:95], v[168:171], v[196:199], v[92:95]
	v_mfma_f32_16x16x32_bf16 v[84:87], v[176:179], v[196:199], v[84:87]
	v_mfma_f32_16x16x32_bf16 v[76:79], v[168:171], v[204:207], v[76:79]
	v_mfma_f32_16x16x32_bf16 v[72:75], v[176:179], v[204:207], v[72:75]
	v_mfma_f32_16x16x32_bf16 v[68:71], v[168:171], v[212:215], v[68:71]
	v_mfma_f32_16x16x32_bf16 v[64:67], v[176:179], v[212:215], v[64:67]
	s_setprio 0
	s_barrier
	s_add_i32 s34, s84, s51
	v_lshl_add_u64 v[192:193], v[192:193], 0, s[10:11]
	s_mov_b32 m0, s34
	ds_read_b128 v[180:183], v146 offset:49152
	ds_read_b128 v[184:187], v146 offset:50176
	ds_read_b128 v[188:191], v146 offset:51200
	ds_read_b128 v[196:199], v146 offset:52224
	ds_read_b128 v[200:203], v146 offset:53248
	ds_read_b128 v[204:207], v146 offset:54272
	ds_read_b128 v[208:211], v146 offset:55296
	ds_read_b128 v[212:215], v146 offset:56320
	global_load_lds_dwordx4 v[192:193], off
	s_add_i32 m0, s34, 0x2000
	s_add_u32 s34, s38, 0x20080
	v_lshl_add_u64 v[192:193], v[216:217], 0, s[10:11]
	s_addc_u32 s35, s39, 0
	s_add_i32 s38, s85, s51
	global_load_lds_dwordx4 v[192:193], off
	v_lshl_add_u64 v[192:193], s[34:35], 0, v[132:133]
	s_mov_b32 m0, s38
	s_nop 0
	global_load_lds_dwordx4 v[192:193], off
	v_lshl_add_u64 v[192:193], s[34:35], 0, v[128:129]
	s_add_i32 m0, s38, 0x2000
	s_nop 0
	global_load_lds_dwordx4 v[192:193], off
	s_waitcnt vmcnt(6)
	s_waitcnt lgkmcnt(0)
	s_barrier
	s_setprio 1
	s_waitcnt lgkmcnt(0)
	v_mfma_f32_16x16x32_bf16 v[60:63], v[148:151], v[180:183], v[60:63]
	v_mfma_f32_16x16x32_bf16 v[56:59], v[156:159], v[180:183], v[56:59]
	v_mfma_f32_16x16x32_bf16 v[52:55], v[148:151], v[188:191], v[52:55]
	v_mfma_f32_16x16x32_bf16 v[48:51], v[156:159], v[188:191], v[48:51]
	v_mfma_f32_16x16x32_bf16 v[40:43], v[148:151], v[200:203], v[40:43]
	v_mfma_f32_16x16x32_bf16 v[32:35], v[156:159], v[200:203], v[32:35]
	v_mfma_f32_16x16x32_bf16 v[24:27], v[148:151], v[208:211], v[24:27]
	v_mfma_f32_16x16x32_bf16 v[16:19], v[156:159], v[208:211], v[16:19]
	v_mfma_f32_16x16x32_bf16 v[60:63], v[152:155], v[184:187], v[60:63]
	v_mfma_f32_16x16x32_bf16 v[56:59], v[160:163], v[184:187], v[56:59]
	v_mfma_f32_16x16x32_bf16 v[52:55], v[152:155], v[196:199], v[52:55]
	v_mfma_f32_16x16x32_bf16 v[48:51], v[160:163], v[196:199], v[48:51]
	v_mfma_f32_16x16x32_bf16 v[40:43], v[152:155], v[204:207], v[40:43]
	v_mfma_f32_16x16x32_bf16 v[32:35], v[160:163], v[204:207], v[32:35]
	v_mfma_f32_16x16x32_bf16 v[24:27], v[152:155], v[212:215], v[24:27]
	v_mfma_f32_16x16x32_bf16 v[16:19], v[160:163], v[212:215], v[16:19]
	v_mfma_f32_16x16x32_bf16 v[44:47], v[164:167], v[180:183], v[44:47]
	v_mfma_f32_16x16x32_bf16 v[36:39], v[172:175], v[180:183], v[36:39]
	v_mfma_f32_16x16x32_bf16 v[28:31], v[164:167], v[188:191], v[28:31]
	v_mfma_f32_16x16x32_bf16 v[20:23], v[172:175], v[188:191], v[20:23]
	v_mfma_f32_16x16x32_bf16 v[12:15], v[164:167], v[200:203], v[12:15]
	v_mfma_f32_16x16x32_bf16 v[8:11], v[172:175], v[200:203], v[8:11]
	v_mfma_f32_16x16x32_bf16 v[4:7], v[164:167], v[208:211], v[4:7]
	v_mfma_f32_16x16x32_bf16 v[0:3], v[172:175], v[208:211], v[0:3]
	v_mfma_f32_16x16x32_bf16 v[44:47], v[168:171], v[184:187], v[44:47]
	v_mfma_f32_16x16x32_bf16 v[36:39], v[176:179], v[184:187], v[36:39]
	v_mfma_f32_16x16x32_bf16 v[28:31], v[168:171], v[196:199], v[28:31]
	v_mfma_f32_16x16x32_bf16 v[20:23], v[176:179], v[196:199], v[20:23]
	v_mfma_f32_16x16x32_bf16 v[12:15], v[168:171], v[204:207], v[12:15]
	v_mfma_f32_16x16x32_bf16 v[8:11], v[176:179], v[204:207], v[8:11]
	v_mfma_f32_16x16x32_bf16 v[4:7], v[168:171], v[212:215], v[4:7]
	v_mfma_f32_16x16x32_bf16 v[0:3], v[176:179], v[212:215], v[0:3]
	s_setprio 0
	s_barrier
	v_lshl_add_u64 v[218:219], v[218:219], 0, s[10:11]
	s_mov_b32 m0, s71
	s_nop 0
	global_load_lds_dwordx4 v[218:219], off
	v_lshl_add_u64 v[220:221], v[220:221], 0, s[10:11]
	s_mov_b32 m0, s72
	s_nop 0
	global_load_lds_dwordx4 v[220:221], off
	s_add_i32 s83, s83, 2
	s_add_u32 s13, s13, 0x100
	s_addc_u32 s25, s25, 0
	s_cmp_gt_u32 s83, 5
	s_mov_b64 s[34:35], s[36:37]
	s_cbranch_scc0 .LBB0_760
	s_and_b64 vcc, exec, s[16:17]
	s_cbranch_vccz .LBB0_763
	s_barrier

.LBB0_786:
	ds_read_b128 v[144:147], v153
	ds_read_b128 v[158:161], v153 offset:1024
	ds_read_b128 v[162:165], v153 offset:2048
	ds_read_b128 v[166:169], v153 offset:3072
	ds_read_b128 v[170:173], v154
	ds_read_b128 v[174:177], v154 offset:1024
	ds_read_b128 v[178:181], v154 offset:2048
	ds_read_b128 v[182:185], v154 offset:3072
	s_add_u32 s34, s30, 0xfffc0080
	s_addc_u32 s35, s31, -1
	s_cmp_eq_u32 s82, 12
	s_cselect_b32 s37, s25, s35
	s_cselect_b32 s36, s78, s34
	s_cselect_b32 s35, s23, s81
	s_cselect_b32 s34, s79, s80
	v_lshl_add_u64 v[148:149], s[30:31], 0, v[136:137]
	s_add_i32 m0, s50, 0xc000
	ds_read_b128 v[186:189], v155
	ds_read_b128 v[190:193], v155 offset:1024
	ds_read_b128 v[196:199], v155 offset:2048
	ds_read_b128 v[200:203], v155 offset:3072
	ds_read_b128 v[204:207], v155 offset:4096
	ds_read_b128 v[208:211], v155 offset:5120
	ds_read_b128 v[212:215], v155 offset:6144
	ds_read_b128 v[216:219], v155 offset:7168
	global_load_lds_dwordx4 v[148:149], off
	v_lshl_add_u64 v[148:149], s[30:31], 0, v[138:139]
	s_add_i32 m0, s50, 0xe000
	s_nop 0
	global_load_lds_dwordx4 v[148:149], off
	s_waitcnt vmcnt(8)
	s_waitcnt lgkmcnt(0)
	s_barrier
	s_setprio 1
	s_waitcnt lgkmcnt(0)
	v_mfma_f32_16x16x32_bf16 v[124:127], v[144:147], v[186:189], v[124:127]
	v_mfma_f32_16x16x32_bf16 v[120:123], v[162:165], v[186:189], v[120:123]
	v_mfma_f32_16x16x32_bf16 v[108:111], v[144:147], v[196:199], v[108:111]
	v_mfma_f32_16x16x32_bf16 v[104:107], v[162:165], v[196:199], v[104:107]
	v_mfma_f32_16x16x32_bf16 v[92:95], v[144:147], v[204:207], v[92:95]
	v_mfma_f32_16x16x32_bf16 v[88:91], v[162:165], v[204:207], v[88:91]
	v_mfma_f32_16x16x32_bf16 v[76:79], v[144:147], v[212:215], v[76:79]
	v_mfma_f32_16x16x32_bf16 v[72:75], v[162:165], v[212:215], v[72:75]
	v_mfma_f32_16x16x32_bf16 v[124:127], v[158:161], v[190:193], v[124:127]
	v_mfma_f32_16x16x32_bf16 v[120:123], v[166:169], v[190:193], v[120:123]
	v_mfma_f32_16x16x32_bf16 v[108:111], v[158:161], v[200:203], v[108:111]
	v_mfma_f32_16x16x32_bf16 v[104:107], v[166:169], v[200:203], v[104:107]
	v_mfma_f32_16x16x32_bf16 v[92:95], v[158:161], v[208:211], v[92:95]
	v_mfma_f32_16x16x32_bf16 v[88:91], v[166:169], v[208:211], v[88:91]
	v_mfma_f32_16x16x32_bf16 v[76:79], v[158:161], v[216:219], v[76:79]
	v_mfma_f32_16x16x32_bf16 v[72:75], v[166:169], v[216:219], v[72:75]
	v_mfma_f32_16x16x32_bf16 v[116:119], v[170:173], v[186:189], v[116:119]
	v_mfma_f32_16x16x32_bf16 v[112:115], v[178:181], v[186:189], v[112:115]
	v_mfma_f32_16x16x32_bf16 v[100:103], v[170:173], v[196:199], v[100:103]
	v_mfma_f32_16x16x32_bf16 v[96:99], v[178:181], v[196:199], v[96:99]
	v_mfma_f32_16x16x32_bf16 v[84:87], v[170:173], v[204:207], v[84:87]
	v_mfma_f32_16x16x32_bf16 v[80:83], v[178:181], v[204:207], v[80:83]
	v_mfma_f32_16x16x32_bf16 v[68:71], v[170:173], v[212:215], v[68:71]
	v_mfma_f32_16x16x32_bf16 v[64:67], v[178:181], v[212:215], v[64:67]
	v_mfma_f32_16x16x32_bf16 v[116:119], v[174:177], v[190:193], v[116:119]
	v_mfma_f32_16x16x32_bf16 v[112:115], v[182:185], v[190:193], v[112:115]
	v_mfma_f32_16x16x32_bf16 v[100:103], v[174:177], v[200:203], v[100:103]
	v_mfma_f32_16x16x32_bf16 v[96:99], v[182:185], v[200:203], v[96:99]
	v_mfma_f32_16x16x32_bf16 v[84:87], v[174:177], v[208:211], v[84:87]
	v_mfma_f32_16x16x32_bf16 v[80:83], v[182:185], v[208:211], v[80:83]
	v_mfma_f32_16x16x32_bf16 v[68:71], v[174:177], v[216:219], v[68:71]
	v_mfma_f32_16x16x32_bf16 v[64:67], v[182:185], v[216:219], v[64:67]
	s_setprio 0
	s_barrier
	s_add_i32 s83, s70, s45
	v_lshl_add_u64 v[148:149], s[34:35], 0, v[130:131]
	s_mov_b32 m0, s83
	ds_read_b128 v[186:189], v155 offset:16384
	ds_read_b128 v[190:193], v155 offset:17408
	ds_read_b128 v[196:199], v155 offset:18432
	ds_read_b128 v[200:203], v155 offset:19456
	ds_read_b128 v[204:207], v155 offset:20480
	ds_read_b128 v[208:211], v155 offset:21504
	ds_read_b128 v[212:215], v155 offset:22528
	ds_read_b128 v[216:219], v155 offset:23552
	global_load_lds_dwordx4 v[148:149], off
	s_add_i32 m0, s83, 0x2000
	s_add_u32 s84, s34, 0x40000
	v_lshl_add_u64 v[220:221], s[34:35], 0, v[134:135]
	s_addc_u32 s85, s35, 0
	s_add_i32 s83, s71, s45
	global_load_lds_dwordx4 v[220:221], off
	v_lshl_add_u64 v[222:223], s[84:85], 0, v[130:131]
	s_mov_b32 m0, s83
	v_lshl_add_u64 v[224:225], s[36:37], 0, v[132:133]
	global_load_lds_dwordx4 v[222:223], off
	v_lshl_add_u64 v[222:223], s[84:85], 0, v[134:135]
	s_add_i32 m0, s83, 0x2000
	s_nop 0
	global_load_lds_dwordx4 v[222:223], off
	v_lshl_add_u64 v[222:223], s[36:37], 0, v[128:129]
	s_waitcnt vmcnt(6)
	s_waitcnt lgkmcnt(0)
	s_barrier
	s_setprio 1
	s_waitcnt lgkmcnt(0)
	v_mfma_f32_16x16x32_bf16 v[60:63], v[144:147], v[186:189], v[60:63]
	v_mfma_f32_16x16x32_bf16 v[56:59], v[162:165], v[186:189], v[56:59]
	v_mfma_f32_16x16x32_bf16 v[44:47], v[144:147], v[196:199], v[44:47]
	v_mfma_f32_16x16x32_bf16 v[40:43], v[162:165], v[196:199], v[40:43]
	v_mfma_f32_16x16x32_bf16 v[28:31], v[144:147], v[204:207], v[28:31]
	v_mfma_f32_16x16x32_bf16 v[24:27], v[162:165], v[204:207], v[24:27]
	v_mfma_f32_16x16x32_bf16 v[12:15], v[144:147], v[212:215], v[12:15]
	v_mfma_f32_16x16x32_bf16 v[8:11], v[162:165], v[212:215], v[8:11]
	v_mfma_f32_16x16x32_bf16 v[60:63], v[158:161], v[190:193], v[60:63]
	v_mfma_f32_16x16x32_bf16 v[56:59], v[166:169], v[190:193], v[56:59]
	v_mfma_f32_16x16x32_bf16 v[44:47], v[158:161], v[200:203], v[44:47]
	v_mfma_f32_16x16x32_bf16 v[40:43], v[166:169], v[200:203], v[40:43]
	v_mfma_f32_16x16x32_bf16 v[28:31], v[158:161], v[208:211], v[28:31]
	v_mfma_f32_16x16x32_bf16 v[24:27], v[166:169], v[208:211], v[24:27]
	v_mfma_f32_16x16x32_bf16 v[12:15], v[158:161], v[216:219], v[12:15]
	v_mfma_f32_16x16x32_bf16 v[8:11], v[166:169], v[216:219], v[8:11]
	v_mfma_f32_16x16x32_bf16 v[52:55], v[170:173], v[186:189], v[52:55]
	v_mfma_f32_16x16x32_bf16 v[48:51], v[178:181], v[186:189], v[48:51]
	v_mfma_f32_16x16x32_bf16 v[36:39], v[170:173], v[196:199], v[36:39]
	v_mfma_f32_16x16x32_bf16 v[32:35], v[178:181], v[196:199], v[32:35]
	v_mfma_f32_16x16x32_bf16 v[20:23], v[170:173], v[204:207], v[20:23]
	v_mfma_f32_16x16x32_bf16 v[16:19], v[178:181], v[204:207], v[16:19]
	v_mfma_f32_16x16x32_bf16 v[4:7], v[170:173], v[212:215], v[4:7]
	v_mfma_f32_16x16x32_bf16 v[0:3], v[178:181], v[212:215], v[0:3]
	v_mfma_f32_16x16x32_bf16 v[52:55], v[174:177], v[190:193], v[52:55]
	v_mfma_f32_16x16x32_bf16 v[48:51], v[182:185], v[190:193], v[48:51]
	v_mfma_f32_16x16x32_bf16 v[36:39], v[174:177], v[200:203], v[36:39]
	v_mfma_f32_16x16x32_bf16 v[32:35], v[182:185], v[200:203], v[32:35]
	v_mfma_f32_16x16x32_bf16 v[20:23], v[174:177], v[208:211], v[20:23]
	v_mfma_f32_16x16x32_bf16 v[16:19], v[182:185], v[208:211], v[16:19]
	v_mfma_f32_16x16x32_bf16 v[4:7], v[174:177], v[216:219], v[4:7]
	v_mfma_f32_16x16x32_bf16 v[0:3], v[182:185], v[216:219], v[0:3]
	s_setprio 0
	s_barrier
	s_add_i32 s83, 0, 0x18000
	v_add_u32_e32 v157, s83, v151
	s_add_i32 s84, 0, 0x1c000
	ds_read_b128 v[144:147], v157
	ds_read_b128 v[158:161], v157 offset:1024
	ds_read_b128 v[162:165], v157 offset:2048
	ds_read_b128 v[166:169], v157 offset:3072
	v_add_u32_e32 v157, s84, v151
	ds_read_b128 v[170:173], v157
	ds_read_b128 v[174:177], v157 offset:1024
	ds_read_b128 v[178:181], v157 offset:2048
	ds_read_b128 v[182:185], v157 offset:3072
	s_add_u32 s36, s36, 0x40000
	s_addc_u32 s37, s37, 0
	v_lshl_add_u64 v[226:227], s[36:37], 0, v[128:129]
	ds_read_b128 v[186:189], v155 offset:32768
	ds_read_b128 v[190:193], v155 offset:33792
	ds_read_b128 v[196:199], v155 offset:34816
	ds_read_b128 v[200:203], v155 offset:35840
	ds_read_b128 v[204:207], v155 offset:36864
	ds_read_b128 v[208:211], v155 offset:37888
	ds_read_b128 v[212:215], v155 offset:38912
	ds_read_b128 v[216:219], v155 offset:39936
	s_mov_b32 m0, s50
	s_nop 0
	global_load_lds_dwordx4 v[222:223], off
	s_mov_b32 m0, s51
	s_nop 0
	global_load_lds_dwordx4 v[224:225], off
	s_mov_b32 m0, s58
	s_nop 0
	global_load_lds_dwordx4 v[226:227], off
	v_lshl_add_u64 v[226:227], s[36:37], 0, v[132:133]
	s_mov_b32 m0, s59
	s_nop 0
	global_load_lds_dwordx4 v[226:227], off
	s_waitcnt vmcnt(8)
	s_waitcnt lgkmcnt(0)
	s_barrier
	s_setprio 1
	s_waitcnt lgkmcnt(0)
	v_mfma_f32_16x16x32_bf16 v[124:127], v[144:147], v[186:189], v[124:127]
	v_mfma_f32_16x16x32_bf16 v[120:123], v[162:165], v[186:189], v[120:123]
	v_mfma_f32_16x16x32_bf16 v[108:111], v[144:147], v[196:199], v[108:111]
	v_mfma_f32_16x16x32_bf16 v[104:107], v[162:165], v[196:199], v[104:107]
	v_mfma_f32_16x16x32_bf16 v[92:95], v[144:147], v[204:207], v[92:95]
	v_mfma_f32_16x16x32_bf16 v[88:91], v[162:165], v[204:207], v[88:91]
	v_mfma_f32_16x16x32_bf16 v[76:79], v[144:147], v[212:215], v[76:79]
	v_mfma_f32_16x16x32_bf16 v[72:75], v[162:165], v[212:215], v[72:75]
	v_mfma_f32_16x16x32_bf16 v[124:127], v[158:161], v[190:193], v[124:127]
	v_mfma_f32_16x16x32_bf16 v[120:123], v[166:169], v[190:193], v[120:123]
	v_mfma_f32_16x16x32_bf16 v[108:111], v[158:161], v[200:203], v[108:111]
	v_mfma_f32_16x16x32_bf16 v[104:107], v[166:169], v[200:203], v[104:107]
	v_mfma_f32_16x16x32_bf16 v[92:95], v[158:161], v[208:211], v[92:95]
	v_mfma_f32_16x16x32_bf16 v[88:91], v[166:169], v[208:211], v[88:91]
	v_mfma_f32_16x16x32_bf16 v[76:79], v[158:161], v[216:219], v[76:79]
	v_mfma_f32_16x16x32_bf16 v[72:75], v[166:169], v[216:219], v[72:75]
	v_mfma_f32_16x16x32_bf16 v[116:119], v[170:173], v[186:189], v[116:119]
	v_mfma_f32_16x16x32_bf16 v[112:115], v[178:181], v[186:189], v[112:115]
	v_mfma_f32_16x16x32_bf16 v[100:103], v[170:173], v[196:199], v[100:103]
	v_mfma_f32_16x16x32_bf16 v[96:99], v[178:181], v[196:199], v[96:99]
	v_mfma_f32_16x16x32_bf16 v[84:87], v[170:173], v[204:207], v[84:87]
	v_mfma_f32_16x16x32_bf16 v[80:83], v[178:181], v[204:207], v[80:83]
	v_mfma_f32_16x16x32_bf16 v[68:71], v[170:173], v[212:215], v[68:71]
	v_mfma_f32_16x16x32_bf16 v[64:67], v[178:181], v[212:215], v[64:67]
	v_mfma_f32_16x16x32_bf16 v[116:119], v[174:177], v[190:193], v[116:119]
	v_mfma_f32_16x16x32_bf16 v[112:115], v[182:185], v[190:193], v[112:115]
	v_mfma_f32_16x16x32_bf16 v[100:103], v[174:177], v[200:203], v[100:103]
	v_mfma_f32_16x16x32_bf16 v[96:99], v[182:185], v[200:203], v[96:99]
	v_mfma_f32_16x16x32_bf16 v[84:87], v[174:177], v[208:211], v[84:87]
	v_mfma_f32_16x16x32_bf16 v[80:83], v[182:185], v[208:211], v[80:83]
	v_mfma_f32_16x16x32_bf16 v[68:71], v[174:177], v[216:219], v[68:71]
	v_mfma_f32_16x16x32_bf16 v[64:67], v[182:185], v[216:219], v[64:67]
	s_setprio 0
	s_barrier
	s_add_i32 s36, s83, s45
	v_lshl_add_u64 v[148:149], v[148:149], 0, s[18:19]
	s_mov_b32 m0, s36
	ds_read_b128 v[186:189], v155 offset:49152
	ds_read_b128 v[190:193], v155 offset:50176
	ds_read_b128 v[196:199], v155 offset:51200
	ds_read_b128 v[200:203], v155 offset:52224
	ds_read_b128 v[204:207], v155 offset:53248
	ds_read_b128 v[208:211], v155 offset:54272
	ds_read_b128 v[212:215], v155 offset:55296
	ds_read_b128 v[216:219], v155 offset:56320
	global_load_lds_dwordx4 v[148:149], off
	s_add_i32 m0, s36, 0x2000
	s_add_u32 s34, s34, 0x40080
	v_lshl_add_u64 v[148:149], v[220:221], 0, s[18:19]
	s_addc_u32 s35, s35, 0
	s_add_i32 s36, s84, s45
	global_load_lds_dwordx4 v[148:149], off
	v_lshl_add_u64 v[148:149], s[34:35], 0, v[130:131]
	s_mov_b32 m0, s36
	s_nop 0
	global_load_lds_dwordx4 v[148:149], off
	v_lshl_add_u64 v[148:149], s[34:35], 0, v[134:135]
	s_add_i32 m0, s36, 0x2000
	s_nop 0
	global_load_lds_dwordx4 v[148:149], off
	s_waitcnt vmcnt(6)
	s_waitcnt lgkmcnt(0)
	s_barrier
	s_setprio 1
	s_waitcnt lgkmcnt(0)
	v_mfma_f32_16x16x32_bf16 v[60:63], v[144:147], v[186:189], v[60:63]
	v_mfma_f32_16x16x32_bf16 v[56:59], v[162:165], v[186:189], v[56:59]
	v_mfma_f32_16x16x32_bf16 v[44:47], v[144:147], v[196:199], v[44:47]
	v_mfma_f32_16x16x32_bf16 v[40:43], v[162:165], v[196:199], v[40:43]
	v_mfma_f32_16x16x32_bf16 v[28:31], v[144:147], v[204:207], v[28:31]
	v_mfma_f32_16x16x32_bf16 v[24:27], v[162:165], v[204:207], v[24:27]
	v_mfma_f32_16x16x32_bf16 v[12:15], v[144:147], v[212:215], v[12:15]
	v_mfma_f32_16x16x32_bf16 v[8:11], v[162:165], v[212:215], v[8:11]
	v_mfma_f32_16x16x32_bf16 v[60:63], v[158:161], v[190:193], v[60:63]
	v_mfma_f32_16x16x32_bf16 v[56:59], v[166:169], v[190:193], v[56:59]
	v_mfma_f32_16x16x32_bf16 v[44:47], v[158:161], v[200:203], v[44:47]
	v_mfma_f32_16x16x32_bf16 v[40:43], v[166:169], v[200:203], v[40:43]
	v_mfma_f32_16x16x32_bf16 v[28:31], v[158:161], v[208:211], v[28:31]
	v_mfma_f32_16x16x32_bf16 v[24:27], v[166:169], v[208:211], v[24:27]
	v_mfma_f32_16x16x32_bf16 v[12:15], v[158:161], v[216:219], v[12:15]
	v_mfma_f32_16x16x32_bf16 v[8:11], v[166:169], v[216:219], v[8:11]
	v_mfma_f32_16x16x32_bf16 v[52:55], v[170:173], v[186:189], v[52:55]
	v_mfma_f32_16x16x32_bf16 v[48:51], v[178:181], v[186:189], v[48:51]
	v_mfma_f32_16x16x32_bf16 v[36:39], v[170:173], v[196:199], v[36:39]
	v_mfma_f32_16x16x32_bf16 v[32:35], v[178:181], v[196:199], v[32:35]
	v_mfma_f32_16x16x32_bf16 v[20:23], v[170:173], v[204:207], v[20:23]
	v_mfma_f32_16x16x32_bf16 v[16:19], v[178:181], v[204:207], v[16:19]
	v_mfma_f32_16x16x32_bf16 v[4:7], v[170:173], v[212:215], v[4:7]
	v_mfma_f32_16x16x32_bf16 v[0:3], v[178:181], v[212:215], v[0:3]
	v_mfma_f32_16x16x32_bf16 v[52:55], v[174:177], v[190:193], v[52:55]
	v_mfma_f32_16x16x32_bf16 v[48:51], v[182:185], v[190:193], v[48:51]
	v_mfma_f32_16x16x32_bf16 v[36:39], v[174:177], v[200:203], v[36:39]
	v_mfma_f32_16x16x32_bf16 v[32:35], v[182:185], v[200:203], v[32:35]
	v_mfma_f32_16x16x32_bf16 v[20:23], v[174:177], v[208:211], v[20:23]
	v_mfma_f32_16x16x32_bf16 v[16:19], v[182:185], v[208:211], v[16:19]
	v_mfma_f32_16x16x32_bf16 v[4:7], v[174:177], v[216:219], v[4:7]
	v_mfma_f32_16x16x32_bf16 v[0:3], v[182:185], v[216:219], v[0:3]
	s_setprio 0
	s_barrier
	v_lshl_add_u64 v[222:223], v[222:223], 0, s[18:19]
	s_mov_b32 m0, s61
	s_nop 0
	global_load_lds_dwordx4 v[222:223], off
	v_lshl_add_u64 v[224:225], v[224:225], 0, s[18:19]
	s_mov_b32 m0, s62
	s_nop 0
	global_load_lds_dwordx4 v[224:225], off
	s_add_i32 s82, s82, 2
	s_add_u32 s30, s30, 0x100
	s_addc_u32 s31, s31, 0
	s_add_u32 s80, s80, 0x100
	s_addc_u32 s81, s81, 0
	s_cmp_gt_u32 s82, 13
	s_cbranch_scc0 .LBB0_786
	s_and_b64 vcc, exec, s[20:21]
	s_cbranch_vccz .LBB0_789
	s_barrier

.LBB0_923:
	ds_read_b128 v[152:155], v148
	ds_read_b128 v[156:159], v148 offset:1024
	ds_read_b128 v[160:163], v148 offset:2048
	ds_read_b128 v[164:167], v148 offset:3072
	ds_read_b128 v[168:171], v149
	ds_read_b128 v[172:175], v149 offset:1024
	ds_read_b128 v[176:179], v149 offset:2048
	ds_read_b128 v[180:183], v149 offset:3072
	s_add_u32 s26, s24, 0x100
	s_addc_u32 s27, s25, 0
	s_cmp_eq_u32 s79, 8
	s_cselect_b32 s31, s21, s27
	s_cselect_b32 s30, s20, s26
	s_cselect_b32 s29, s23, s78
	s_cselect_b32 s28, s22, s73
	s_mov_b32 m0, s60
	v_lshl_add_u64 v[192:193], s[24:25], 0, v[138:139]
	ds_read_b128 v[184:187], v150
	ds_read_b128 v[188:191], v150 offset:1024
	ds_read_b128 v[196:199], v150 offset:2048
	ds_read_b128 v[200:203], v150 offset:3072
	ds_read_b128 v[204:207], v150 offset:4096
	ds_read_b128 v[208:211], v150 offset:5120
	ds_read_b128 v[212:215], v150 offset:6144
	ds_read_b128 v[216:219], v150 offset:7168
	global_load_lds_dwordx4 v[192:193], off
	v_lshl_add_u64 v[192:193], s[24:25], 0, v[140:141]
	s_add_i32 m0, s40, 0xe000
	s_nop 0
	global_load_lds_dwordx4 v[192:193], off
	s_waitcnt vmcnt(8)
	s_waitcnt lgkmcnt(0)
	s_barrier
	s_setprio 1
	s_waitcnt lgkmcnt(0)
	v_mfma_f32_16x16x32_bf16 v[124:127], v[152:155], v[184:187], v[124:127]
	v_mfma_f32_16x16x32_bf16 v[120:123], v[160:163], v[184:187], v[120:123]
	v_mfma_f32_16x16x32_bf16 v[108:111], v[152:155], v[196:199], v[108:111]
	v_mfma_f32_16x16x32_bf16 v[104:107], v[160:163], v[196:199], v[104:107]
	v_mfma_f32_16x16x32_bf16 v[92:95], v[152:155], v[204:207], v[92:95]
	v_mfma_f32_16x16x32_bf16 v[88:91], v[160:163], v[204:207], v[88:91]
	v_mfma_f32_16x16x32_bf16 v[76:79], v[152:155], v[212:215], v[76:79]
	v_mfma_f32_16x16x32_bf16 v[72:75], v[160:163], v[212:215], v[72:75]
	v_mfma_f32_16x16x32_bf16 v[124:127], v[156:159], v[188:191], v[124:127]
	v_mfma_f32_16x16x32_bf16 v[120:123], v[164:167], v[188:191], v[120:123]
	v_mfma_f32_16x16x32_bf16 v[108:111], v[156:159], v[200:203], v[108:111]
	v_mfma_f32_16x16x32_bf16 v[104:107], v[164:167], v[200:203], v[104:107]
	v_mfma_f32_16x16x32_bf16 v[92:95], v[156:159], v[208:211], v[92:95]
	v_mfma_f32_16x16x32_bf16 v[88:91], v[164:167], v[208:211], v[88:91]
	v_mfma_f32_16x16x32_bf16 v[76:79], v[156:159], v[216:219], v[76:79]
	v_mfma_f32_16x16x32_bf16 v[72:75], v[164:167], v[216:219], v[72:75]
	v_mfma_f32_16x16x32_bf16 v[116:119], v[168:171], v[184:187], v[116:119]
	v_mfma_f32_16x16x32_bf16 v[112:115], v[176:179], v[184:187], v[112:115]
	v_mfma_f32_16x16x32_bf16 v[100:103], v[168:171], v[196:199], v[100:103]
	v_mfma_f32_16x16x32_bf16 v[96:99], v[176:179], v[196:199], v[96:99]
	v_mfma_f32_16x16x32_bf16 v[84:87], v[168:171], v[204:207], v[84:87]
	v_mfma_f32_16x16x32_bf16 v[80:83], v[176:179], v[204:207], v[80:83]
	v_mfma_f32_16x16x32_bf16 v[68:71], v[168:171], v[212:215], v[68:71]
	v_mfma_f32_16x16x32_bf16 v[64:67], v[176:179], v[212:215], v[64:67]
	v_mfma_f32_16x16x32_bf16 v[116:119], v[172:175], v[188:191], v[116:119]
	v_mfma_f32_16x16x32_bf16 v[112:115], v[180:183], v[188:191], v[112:115]
	v_mfma_f32_16x16x32_bf16 v[100:103], v[172:175], v[200:203], v[100:103]
	v_mfma_f32_16x16x32_bf16 v[96:99], v[180:183], v[200:203], v[96:99]
	v_mfma_f32_16x16x32_bf16 v[84:87], v[172:175], v[208:211], v[84:87]
	v_mfma_f32_16x16x32_bf16 v[80:83], v[180:183], v[208:211], v[80:83]
	v_mfma_f32_16x16x32_bf16 v[68:71], v[172:175], v[216:219], v[68:71]
	v_mfma_f32_16x16x32_bf16 v[64:67], v[180:183], v[216:219], v[64:67]
	s_setprio 0
	s_barrier
	s_add_i32 s24, s58, s39
	v_lshl_add_u64 v[192:193], s[28:29], 0, v[132:133]
	s_mov_b32 m0, s24
	ds_read_b128 v[184:187], v150 offset:16384
	ds_read_b128 v[188:191], v150 offset:17408
	ds_read_b128 v[196:199], v150 offset:18432
	ds_read_b128 v[200:203], v150 offset:19456
	ds_read_b128 v[204:207], v150 offset:20480
	ds_read_b128 v[208:211], v150 offset:21504
	ds_read_b128 v[212:215], v150 offset:22528
	ds_read_b128 v[216:219], v150 offset:23552
	global_load_lds_dwordx4 v[192:193], off
	s_add_i32 m0, s24, 0x2000
	s_add_u32 s24, s28, 0x30000
	v_lshl_add_u64 v[220:221], s[28:29], 0, v[128:129]
	s_addc_u32 s25, s29, 0
	s_add_i32 s80, s59, s39
	global_load_lds_dwordx4 v[220:221], off
	v_lshl_add_u64 v[222:223], s[24:25], 0, v[132:133]
	s_mov_b32 m0, s80
	v_lshl_add_u64 v[224:225], s[30:31], 0, v[130:131]
	global_load_lds_dwordx4 v[222:223], off
	v_lshl_add_u64 v[222:223], s[24:25], 0, v[128:129]
	s_add_i32 m0, s80, 0x2000
	s_nop 0
	global_load_lds_dwordx4 v[222:223], off
	v_lshl_add_u64 v[222:223], s[30:31], 0, v[134:135]
	s_waitcnt vmcnt(6)
	s_waitcnt lgkmcnt(0)
	s_barrier
	s_setprio 1
	s_waitcnt lgkmcnt(0)
	v_mfma_f32_16x16x32_bf16 v[60:63], v[152:155], v[184:187], v[60:63]
	v_mfma_f32_16x16x32_bf16 v[56:59], v[160:163], v[184:187], v[56:59]
	v_mfma_f32_16x16x32_bf16 v[44:47], v[152:155], v[196:199], v[44:47]
	v_mfma_f32_16x16x32_bf16 v[40:43], v[160:163], v[196:199], v[40:43]
	v_mfma_f32_16x16x32_bf16 v[28:31], v[152:155], v[204:207], v[28:31]
	v_mfma_f32_16x16x32_bf16 v[24:27], v[160:163], v[204:207], v[24:27]
	v_mfma_f32_16x16x32_bf16 v[12:15], v[152:155], v[212:215], v[12:15]
	v_mfma_f32_16x16x32_bf16 v[8:11], v[160:163], v[212:215], v[8:11]
	v_mfma_f32_16x16x32_bf16 v[60:63], v[156:159], v[188:191], v[60:63]
	v_mfma_f32_16x16x32_bf16 v[56:59], v[164:167], v[188:191], v[56:59]
	v_mfma_f32_16x16x32_bf16 v[44:47], v[156:159], v[200:203], v[44:47]
	v_mfma_f32_16x16x32_bf16 v[40:43], v[164:167], v[200:203], v[40:43]
	v_mfma_f32_16x16x32_bf16 v[28:31], v[156:159], v[208:211], v[28:31]
	v_mfma_f32_16x16x32_bf16 v[24:27], v[164:167], v[208:211], v[24:27]
	v_mfma_f32_16x16x32_bf16 v[12:15], v[156:159], v[216:219], v[12:15]
	v_mfma_f32_16x16x32_bf16 v[8:11], v[164:167], v[216:219], v[8:11]
	v_mfma_f32_16x16x32_bf16 v[52:55], v[168:171], v[184:187], v[52:55]
	v_mfma_f32_16x16x32_bf16 v[48:51], v[176:179], v[184:187], v[48:51]
	v_mfma_f32_16x16x32_bf16 v[36:39], v[168:171], v[196:199], v[36:39]
	v_mfma_f32_16x16x32_bf16 v[32:35], v[176:179], v[196:199], v[32:35]
	v_mfma_f32_16x16x32_bf16 v[20:23], v[168:171], v[204:207], v[20:23]
	v_mfma_f32_16x16x32_bf16 v[16:19], v[176:179], v[204:207], v[16:19]
	v_mfma_f32_16x16x32_bf16 v[4:7], v[168:171], v[212:215], v[4:7]
	v_mfma_f32_16x16x32_bf16 v[0:3], v[176:179], v[212:215], v[0:3]
	v_mfma_f32_16x16x32_bf16 v[52:55], v[172:175], v[188:191], v[52:55]
	v_mfma_f32_16x16x32_bf16 v[48:51], v[180:183], v[188:191], v[48:51]
	v_mfma_f32_16x16x32_bf16 v[36:39], v[172:175], v[200:203], v[36:39]
	v_mfma_f32_16x16x32_bf16 v[32:35], v[180:183], v[200:203], v[32:35]
	v_mfma_f32_16x16x32_bf16 v[20:23], v[172:175], v[208:211], v[20:23]
	v_mfma_f32_16x16x32_bf16 v[16:19], v[180:183], v[208:211], v[16:19]
	v_mfma_f32_16x16x32_bf16 v[4:7], v[172:175], v[216:219], v[4:7]
	v_mfma_f32_16x16x32_bf16 v[0:3], v[180:183], v[216:219], v[0:3]
	s_setprio 0
	s_barrier
	s_add_i32 s80, 0, 0x18000
	v_add_u32_e32 v151, s80, v142
	s_add_i32 s81, 0, 0x1c000
	ds_read_b128 v[152:155], v151
	ds_read_b128 v[156:159], v151 offset:1024
	ds_read_b128 v[160:163], v151 offset:2048
	ds_read_b128 v[164:167], v151 offset:3072
	v_add_u32_e32 v151, s81, v142
	ds_read_b128 v[168:171], v151
	ds_read_b128 v[172:175], v151 offset:1024
	ds_read_b128 v[176:179], v151 offset:2048
	ds_read_b128 v[180:183], v151 offset:3072
	s_add_u32 s24, s30, 0x30000
	s_addc_u32 s25, s31, 0
	v_lshl_add_u64 v[226:227], s[24:25], 0, v[134:135]
	ds_read_b128 v[184:187], v150 offset:32768
	ds_read_b128 v[188:191], v150 offset:33792
	ds_read_b128 v[196:199], v150 offset:34816
	ds_read_b128 v[200:203], v150 offset:35840
	ds_read_b128 v[204:207], v150 offset:36864
	ds_read_b128 v[208:211], v150 offset:37888
	ds_read_b128 v[212:215], v150 offset:38912
	ds_read_b128 v[216:219], v150 offset:39936
	s_mov_b32 m0, s40
	s_nop 0
	global_load_lds_dwordx4 v[222:223], off
	s_mov_b32 m0, s41
	s_nop 0
	global_load_lds_dwordx4 v[224:225], off
	s_mov_b32 m0, s42
	s_nop 0
	global_load_lds_dwordx4 v[226:227], off
	v_lshl_add_u64 v[226:227], s[24:25], 0, v[130:131]
	s_mov_b32 m0, s43
	s_nop 0
	global_load_lds_dwordx4 v[226:227], off
	s_waitcnt vmcnt(8)
	s_waitcnt lgkmcnt(0)
	s_barrier
	s_setprio 1
	s_waitcnt lgkmcnt(0)
	v_mfma_f32_16x16x32_bf16 v[124:127], v[152:155], v[184:187], v[124:127]
	v_mfma_f32_16x16x32_bf16 v[120:123], v[160:163], v[184:187], v[120:123]
	v_mfma_f32_16x16x32_bf16 v[108:111], v[152:155], v[196:199], v[108:111]
	v_mfma_f32_16x16x32_bf16 v[104:107], v[160:163], v[196:199], v[104:107]
	v_mfma_f32_16x16x32_bf16 v[92:95], v[152:155], v[204:207], v[92:95]
	v_mfma_f32_16x16x32_bf16 v[88:91], v[160:163], v[204:207], v[88:91]
	v_mfma_f32_16x16x32_bf16 v[76:79], v[152:155], v[212:215], v[76:79]
	v_mfma_f32_16x16x32_bf16 v[72:75], v[160:163], v[212:215], v[72:75]
	v_mfma_f32_16x16x32_bf16 v[124:127], v[156:159], v[188:191], v[124:127]
	v_mfma_f32_16x16x32_bf16 v[120:123], v[164:167], v[188:191], v[120:123]
	v_mfma_f32_16x16x32_bf16 v[108:111], v[156:159], v[200:203], v[108:111]
	v_mfma_f32_16x16x32_bf16 v[104:107], v[164:167], v[200:203], v[104:107]
	v_mfma_f32_16x16x32_bf16 v[92:95], v[156:159], v[208:211], v[92:95]
	v_mfma_f32_16x16x32_bf16 v[88:91], v[164:167], v[208:211], v[88:91]
	v_mfma_f32_16x16x32_bf16 v[76:79], v[156:159], v[216:219], v[76:79]
	v_mfma_f32_16x16x32_bf16 v[72:75], v[164:167], v[216:219], v[72:75]
	v_mfma_f32_16x16x32_bf16 v[116:119], v[168:171], v[184:187], v[116:119]
	v_mfma_f32_16x16x32_bf16 v[112:115], v[176:179], v[184:187], v[112:115]
	v_mfma_f32_16x16x32_bf16 v[100:103], v[168:171], v[196:199], v[100:103]
	v_mfma_f32_16x16x32_bf16 v[96:99], v[176:179], v[196:199], v[96:99]
	v_mfma_f32_16x16x32_bf16 v[84:87], v[168:171], v[204:207], v[84:87]
	v_mfma_f32_16x16x32_bf16 v[80:83], v[176:179], v[204:207], v[80:83]
	v_mfma_f32_16x16x32_bf16 v[68:71], v[168:171], v[212:215], v[68:71]
	v_mfma_f32_16x16x32_bf16 v[64:67], v[176:179], v[212:215], v[64:67]
	v_mfma_f32_16x16x32_bf16 v[116:119], v[172:175], v[188:191], v[116:119]
	v_mfma_f32_16x16x32_bf16 v[112:115], v[180:183], v[188:191], v[112:115]
	v_mfma_f32_16x16x32_bf16 v[100:103], v[172:175], v[200:203], v[100:103]
	v_mfma_f32_16x16x32_bf16 v[96:99], v[180:183], v[200:203], v[96:99]
	v_mfma_f32_16x16x32_bf16 v[84:87], v[172:175], v[208:211], v[84:87]
	v_mfma_f32_16x16x32_bf16 v[80:83], v[180:183], v[208:211], v[80:83]
	v_mfma_f32_16x16x32_bf16 v[68:71], v[172:175], v[216:219], v[68:71]
	v_mfma_f32_16x16x32_bf16 v[64:67], v[180:183], v[216:219], v[64:67]
	s_setprio 0
	s_barrier
	s_add_i32 s24, s80, s39
	v_lshl_add_u64 v[192:193], v[192:193], 0, s[16:17]
	s_mov_b32 m0, s24
	ds_read_b128 v[184:187], v150 offset:49152
	ds_read_b128 v[188:191], v150 offset:50176
	ds_read_b128 v[196:199], v150 offset:51200
	ds_read_b128 v[200:203], v150 offset:52224
	ds_read_b128 v[204:207], v150 offset:53248
	ds_read_b128 v[208:211], v150 offset:54272
	ds_read_b128 v[212:215], v150 offset:55296
	ds_read_b128 v[216:219], v150 offset:56320
	global_load_lds_dwordx4 v[192:193], off
	s_add_i32 m0, s24, 0x2000
	s_add_u32 s24, s28, 0x30080
	v_lshl_add_u64 v[192:193], v[220:221], 0, s[16:17]
	s_addc_u32 s25, s29, 0
	s_add_i32 s28, s81, s39
	global_load_lds_dwordx4 v[192:193], off
	v_lshl_add_u64 v[192:193], s[24:25], 0, v[132:133]
	s_mov_b32 m0, s28
	s_nop 0
	global_load_lds_dwordx4 v[192:193], off
	v_lshl_add_u64 v[192:193], s[24:25], 0, v[128:129]
	s_add_i32 m0, s28, 0x2000
	s_nop 0
	global_load_lds_dwordx4 v[192:193], off
	s_waitcnt vmcnt(6)
	s_waitcnt lgkmcnt(0)
	s_barrier
	s_setprio 1
	s_waitcnt lgkmcnt(0)
	v_mfma_f32_16x16x32_bf16 v[60:63], v[152:155], v[184:187], v[60:63]
	v_mfma_f32_16x16x32_bf16 v[56:59], v[160:163], v[184:187], v[56:59]
	v_mfma_f32_16x16x32_bf16 v[44:47], v[152:155], v[196:199], v[44:47]
	v_mfma_f32_16x16x32_bf16 v[40:43], v[160:163], v[196:199], v[40:43]
	v_mfma_f32_16x16x32_bf16 v[28:31], v[152:155], v[204:207], v[28:31]
	v_mfma_f32_16x16x32_bf16 v[24:27], v[160:163], v[204:207], v[24:27]
	v_mfma_f32_16x16x32_bf16 v[12:15], v[152:155], v[212:215], v[12:15]
	v_mfma_f32_16x16x32_bf16 v[8:11], v[160:163], v[212:215], v[8:11]
	v_mfma_f32_16x16x32_bf16 v[60:63], v[156:159], v[188:191], v[60:63]
	v_mfma_f32_16x16x32_bf16 v[56:59], v[164:167], v[188:191], v[56:59]
	v_mfma_f32_16x16x32_bf16 v[44:47], v[156:159], v[200:203], v[44:47]
	v_mfma_f32_16x16x32_bf16 v[40:43], v[164:167], v[200:203], v[40:43]
	v_mfma_f32_16x16x32_bf16 v[28:31], v[156:159], v[208:211], v[28:31]
	v_mfma_f32_16x16x32_bf16 v[24:27], v[164:167], v[208:211], v[24:27]
	v_mfma_f32_16x16x32_bf16 v[12:15], v[156:159], v[216:219], v[12:15]
	v_mfma_f32_16x16x32_bf16 v[8:11], v[164:167], v[216:219], v[8:11]
	v_mfma_f32_16x16x32_bf16 v[52:55], v[168:171], v[184:187], v[52:55]
	v_mfma_f32_16x16x32_bf16 v[48:51], v[176:179], v[184:187], v[48:51]
	v_mfma_f32_16x16x32_bf16 v[36:39], v[168:171], v[196:199], v[36:39]
	v_mfma_f32_16x16x32_bf16 v[32:35], v[176:179], v[196:199], v[32:35]
	v_mfma_f32_16x16x32_bf16 v[20:23], v[168:171], v[204:207], v[20:23]
	v_mfma_f32_16x16x32_bf16 v[16:19], v[176:179], v[204:207], v[16:19]
	v_mfma_f32_16x16x32_bf16 v[4:7], v[168:171], v[212:215], v[4:7]
	v_mfma_f32_16x16x32_bf16 v[0:3], v[176:179], v[212:215], v[0:3]
	v_mfma_f32_16x16x32_bf16 v[52:55], v[172:175], v[188:191], v[52:55]
	v_mfma_f32_16x16x32_bf16 v[48:51], v[180:183], v[188:191], v[48:51]
	v_mfma_f32_16x16x32_bf16 v[36:39], v[172:175], v[200:203], v[36:39]
	v_mfma_f32_16x16x32_bf16 v[32:35], v[180:183], v[200:203], v[32:35]
	v_mfma_f32_16x16x32_bf16 v[20:23], v[172:175], v[208:211], v[20:23]
	v_mfma_f32_16x16x32_bf16 v[16:19], v[180:183], v[208:211], v[16:19]
	v_mfma_f32_16x16x32_bf16 v[4:7], v[172:175], v[216:219], v[4:7]
	v_mfma_f32_16x16x32_bf16 v[0:3], v[180:183], v[216:219], v[0:3]
	s_setprio 0
	s_barrier
	v_lshl_add_u64 v[222:223], v[222:223], 0, s[16:17]
	s_mov_b32 m0, s45
	s_nop 0
	global_load_lds_dwordx4 v[222:223], off
	v_lshl_add_u64 v[224:225], v[224:225], 0, s[16:17]
	s_mov_b32 m0, s50
	s_nop 0
	global_load_lds_dwordx4 v[224:225], off
	s_add_i32 s79, s79, 2
	s_add_u32 s73, s73, 0x100
	s_addc_u32 s78, s78, 0
	s_cmp_gt_u32 s79, 9
	s_mov_b64 s[24:25], s[26:27]
	s_cbranch_scc0 .LBB0_923
	s_and_b64 vcc, exec, s[18:19]
	s_cbranch_vccz .LBB0_926
	s_barrier

.LBB0_947:
	ds_read_b128 v[144:147], v153
	ds_read_b128 v[158:161], v153 offset:1024
	ds_read_b128 v[162:165], v153 offset:2048
	ds_read_b128 v[166:169], v153 offset:3072
	ds_read_b128 v[170:173], v154
	ds_read_b128 v[174:177], v154 offset:1024
	ds_read_b128 v[178:181], v154 offset:2048
	ds_read_b128 v[182:185], v154 offset:3072
	s_add_u32 s36, s34, 0xfffc0080
	s_addc_u32 s37, s35, -1
	s_cmp_eq_u32 s85, 12
	s_cselect_b32 s39, s27, s37
	s_cselect_b32 s38, s81, s36
	s_cselect_b32 s37, s25, s84
	s_cselect_b32 s36, s82, s83
	v_lshl_add_u64 v[148:149], s[34:35], 0, v[136:137]
	s_add_i32 m0, s59, 0xc000
	ds_read_b128 v[186:189], v155
	ds_read_b128 v[190:193], v155 offset:1024
	ds_read_b128 v[196:199], v155 offset:2048
	ds_read_b128 v[200:203], v155 offset:3072
	ds_read_b128 v[204:207], v155 offset:4096
	ds_read_b128 v[208:211], v155 offset:5120
	ds_read_b128 v[212:215], v155 offset:6144
	ds_read_b128 v[216:219], v155 offset:7168
	global_load_lds_dwordx4 v[148:149], off
	v_lshl_add_u64 v[148:149], s[34:35], 0, v[138:139]
	s_add_i32 m0, s59, 0xe000
	s_nop 0
	global_load_lds_dwordx4 v[148:149], off
	s_waitcnt vmcnt(8)
	s_waitcnt lgkmcnt(0)
	s_barrier
	s_setprio 1
	s_waitcnt lgkmcnt(0)
	v_mfma_f32_16x16x32_bf16 v[124:127], v[144:147], v[186:189], v[124:127]
	v_mfma_f32_16x16x32_bf16 v[120:123], v[162:165], v[186:189], v[120:123]
	v_mfma_f32_16x16x32_bf16 v[108:111], v[144:147], v[196:199], v[108:111]
	v_mfma_f32_16x16x32_bf16 v[104:107], v[162:165], v[196:199], v[104:107]
	v_mfma_f32_16x16x32_bf16 v[92:95], v[144:147], v[204:207], v[92:95]
	v_mfma_f32_16x16x32_bf16 v[88:91], v[162:165], v[204:207], v[88:91]
	v_mfma_f32_16x16x32_bf16 v[76:79], v[144:147], v[212:215], v[76:79]
	v_mfma_f32_16x16x32_bf16 v[72:75], v[162:165], v[212:215], v[72:75]
	v_mfma_f32_16x16x32_bf16 v[124:127], v[158:161], v[190:193], v[124:127]
	v_mfma_f32_16x16x32_bf16 v[120:123], v[166:169], v[190:193], v[120:123]
	v_mfma_f32_16x16x32_bf16 v[108:111], v[158:161], v[200:203], v[108:111]
	v_mfma_f32_16x16x32_bf16 v[104:107], v[166:169], v[200:203], v[104:107]
	v_mfma_f32_16x16x32_bf16 v[92:95], v[158:161], v[208:211], v[92:95]
	v_mfma_f32_16x16x32_bf16 v[88:91], v[166:169], v[208:211], v[88:91]
	v_mfma_f32_16x16x32_bf16 v[76:79], v[158:161], v[216:219], v[76:79]
	v_mfma_f32_16x16x32_bf16 v[72:75], v[166:169], v[216:219], v[72:75]
	v_mfma_f32_16x16x32_bf16 v[116:119], v[170:173], v[186:189], v[116:119]
	v_mfma_f32_16x16x32_bf16 v[112:115], v[178:181], v[186:189], v[112:115]
	v_mfma_f32_16x16x32_bf16 v[100:103], v[170:173], v[196:199], v[100:103]
	v_mfma_f32_16x16x32_bf16 v[96:99], v[178:181], v[196:199], v[96:99]
	v_mfma_f32_16x16x32_bf16 v[84:87], v[170:173], v[204:207], v[84:87]
	v_mfma_f32_16x16x32_bf16 v[80:83], v[178:181], v[204:207], v[80:83]
	v_mfma_f32_16x16x32_bf16 v[68:71], v[170:173], v[212:215], v[68:71]
	v_mfma_f32_16x16x32_bf16 v[64:67], v[178:181], v[212:215], v[64:67]
	v_mfma_f32_16x16x32_bf16 v[116:119], v[174:177], v[190:193], v[116:119]
	v_mfma_f32_16x16x32_bf16 v[112:115], v[182:185], v[190:193], v[112:115]
	v_mfma_f32_16x16x32_bf16 v[100:103], v[174:177], v[200:203], v[100:103]
	v_mfma_f32_16x16x32_bf16 v[96:99], v[182:185], v[200:203], v[96:99]
	v_mfma_f32_16x16x32_bf16 v[84:87], v[174:177], v[208:211], v[84:87]
	v_mfma_f32_16x16x32_bf16 v[80:83], v[182:185], v[208:211], v[80:83]
	v_mfma_f32_16x16x32_bf16 v[68:71], v[174:177], v[216:219], v[68:71]
	v_mfma_f32_16x16x32_bf16 v[64:67], v[182:185], v[216:219], v[64:67]
	s_setprio 0
	s_barrier
	s_add_i32 s86, s73, s58
	v_lshl_add_u64 v[148:149], s[36:37], 0, v[130:131]
	s_mov_b32 m0, s86
	ds_read_b128 v[186:189], v155 offset:16384
	ds_read_b128 v[190:193], v155 offset:17408
	ds_read_b128 v[196:199], v155 offset:18432
	ds_read_b128 v[200:203], v155 offset:19456
	ds_read_b128 v[204:207], v155 offset:20480
	ds_read_b128 v[208:211], v155 offset:21504
	ds_read_b128 v[212:215], v155 offset:22528
	ds_read_b128 v[216:219], v155 offset:23552
	global_load_lds_dwordx4 v[148:149], off
	s_add_i32 m0, s86, 0x2000
	s_add_u32 s86, s36, 0x40000
	v_lshl_add_u64 v[220:221], s[36:37], 0, v[134:135]
	s_addc_u32 s87, s37, 0
	s_add_i32 s88, s78, s58
	global_load_lds_dwordx4 v[220:221], off
	v_lshl_add_u64 v[222:223], s[86:87], 0, v[130:131]
	s_mov_b32 m0, s88
	v_lshl_add_u64 v[224:225], s[38:39], 0, v[132:133]
	global_load_lds_dwordx4 v[222:223], off
	v_lshl_add_u64 v[222:223], s[86:87], 0, v[134:135]
	s_add_i32 m0, s88, 0x2000
	s_nop 0
	global_load_lds_dwordx4 v[222:223], off
	v_lshl_add_u64 v[222:223], s[38:39], 0, v[128:129]
	s_waitcnt vmcnt(6)
	s_waitcnt lgkmcnt(0)
	s_barrier
	s_setprio 1
	s_waitcnt lgkmcnt(0)
	v_mfma_f32_16x16x32_bf16 v[60:63], v[144:147], v[186:189], v[60:63]
	v_mfma_f32_16x16x32_bf16 v[56:59], v[162:165], v[186:189], v[56:59]
	v_mfma_f32_16x16x32_bf16 v[44:47], v[144:147], v[196:199], v[44:47]
	v_mfma_f32_16x16x32_bf16 v[40:43], v[162:165], v[196:199], v[40:43]
	v_mfma_f32_16x16x32_bf16 v[28:31], v[144:147], v[204:207], v[28:31]
	v_mfma_f32_16x16x32_bf16 v[24:27], v[162:165], v[204:207], v[24:27]
	v_mfma_f32_16x16x32_bf16 v[12:15], v[144:147], v[212:215], v[12:15]
	v_mfma_f32_16x16x32_bf16 v[8:11], v[162:165], v[212:215], v[8:11]
	v_mfma_f32_16x16x32_bf16 v[60:63], v[158:161], v[190:193], v[60:63]
	v_mfma_f32_16x16x32_bf16 v[56:59], v[166:169], v[190:193], v[56:59]
	v_mfma_f32_16x16x32_bf16 v[44:47], v[158:161], v[200:203], v[44:47]
	v_mfma_f32_16x16x32_bf16 v[40:43], v[166:169], v[200:203], v[40:43]
	v_mfma_f32_16x16x32_bf16 v[28:31], v[158:161], v[208:211], v[28:31]
	v_mfma_f32_16x16x32_bf16 v[24:27], v[166:169], v[208:211], v[24:27]
	v_mfma_f32_16x16x32_bf16 v[12:15], v[158:161], v[216:219], v[12:15]
	v_mfma_f32_16x16x32_bf16 v[8:11], v[166:169], v[216:219], v[8:11]
	v_mfma_f32_16x16x32_bf16 v[52:55], v[170:173], v[186:189], v[52:55]
	v_mfma_f32_16x16x32_bf16 v[48:51], v[178:181], v[186:189], v[48:51]
	v_mfma_f32_16x16x32_bf16 v[36:39], v[170:173], v[196:199], v[36:39]
	v_mfma_f32_16x16x32_bf16 v[32:35], v[178:181], v[196:199], v[32:35]
	v_mfma_f32_16x16x32_bf16 v[20:23], v[170:173], v[204:207], v[20:23]
	v_mfma_f32_16x16x32_bf16 v[16:19], v[178:181], v[204:207], v[16:19]
	v_mfma_f32_16x16x32_bf16 v[4:7], v[170:173], v[212:215], v[4:7]
	v_mfma_f32_16x16x32_bf16 v[0:3], v[178:181], v[212:215], v[0:3]
	v_mfma_f32_16x16x32_bf16 v[52:55], v[174:177], v[190:193], v[52:55]
	v_mfma_f32_16x16x32_bf16 v[48:51], v[182:185], v[190:193], v[48:51]
	v_mfma_f32_16x16x32_bf16 v[36:39], v[174:177], v[200:203], v[36:39]
	v_mfma_f32_16x16x32_bf16 v[32:35], v[182:185], v[200:203], v[32:35]
	v_mfma_f32_16x16x32_bf16 v[20:23], v[174:177], v[208:211], v[20:23]
	v_mfma_f32_16x16x32_bf16 v[16:19], v[182:185], v[208:211], v[16:19]
	v_mfma_f32_16x16x32_bf16 v[4:7], v[174:177], v[216:219], v[4:7]
	v_mfma_f32_16x16x32_bf16 v[0:3], v[182:185], v[216:219], v[0:3]
	s_setprio 0
	s_barrier
	s_add_i32 s86, 0, 0x18000
	v_add_u32_e32 v157, s86, v151
	s_add_i32 s87, 0, 0x1c000
	ds_read_b128 v[144:147], v157
	ds_read_b128 v[158:161], v157 offset:1024
	ds_read_b128 v[162:165], v157 offset:2048
	ds_read_b128 v[166:169], v157 offset:3072
	v_add_u32_e32 v157, s87, v151
	ds_read_b128 v[170:173], v157
	ds_read_b128 v[174:177], v157 offset:1024
	ds_read_b128 v[178:181], v157 offset:2048
	ds_read_b128 v[182:185], v157 offset:3072
	s_add_u32 s38, s38, 0x40000
	s_addc_u32 s39, s39, 0
	v_lshl_add_u64 v[226:227], s[38:39], 0, v[128:129]
	ds_read_b128 v[186:189], v155 offset:32768
	ds_read_b128 v[190:193], v155 offset:33792
	ds_read_b128 v[196:199], v155 offset:34816
	ds_read_b128 v[200:203], v155 offset:35840
	ds_read_b128 v[204:207], v155 offset:36864
	ds_read_b128 v[208:211], v155 offset:37888
	ds_read_b128 v[212:215], v155 offset:38912
	ds_read_b128 v[216:219], v155 offset:39936
	s_mov_b32 m0, s59
	s_nop 0
	global_load_lds_dwordx4 v[222:223], off
	s_mov_b32 m0, s60
	s_nop 0
	global_load_lds_dwordx4 v[224:225], off
	s_mov_b32 m0, s61
	s_nop 0
	global_load_lds_dwordx4 v[226:227], off
	v_lshl_add_u64 v[226:227], s[38:39], 0, v[132:133]
	s_mov_b32 m0, s62
	s_nop 0
	global_load_lds_dwordx4 v[226:227], off
	s_waitcnt vmcnt(8)
	s_waitcnt lgkmcnt(0)
	s_barrier
	s_setprio 1
	s_waitcnt lgkmcnt(0)
	v_mfma_f32_16x16x32_bf16 v[124:127], v[144:147], v[186:189], v[124:127]
	v_mfma_f32_16x16x32_bf16 v[120:123], v[162:165], v[186:189], v[120:123]
	v_mfma_f32_16x16x32_bf16 v[108:111], v[144:147], v[196:199], v[108:111]
	v_mfma_f32_16x16x32_bf16 v[104:107], v[162:165], v[196:199], v[104:107]
	v_mfma_f32_16x16x32_bf16 v[92:95], v[144:147], v[204:207], v[92:95]
	v_mfma_f32_16x16x32_bf16 v[88:91], v[162:165], v[204:207], v[88:91]
	v_mfma_f32_16x16x32_bf16 v[76:79], v[144:147], v[212:215], v[76:79]
	v_mfma_f32_16x16x32_bf16 v[72:75], v[162:165], v[212:215], v[72:75]
	v_mfma_f32_16x16x32_bf16 v[124:127], v[158:161], v[190:193], v[124:127]
	v_mfma_f32_16x16x32_bf16 v[120:123], v[166:169], v[190:193], v[120:123]
	v_mfma_f32_16x16x32_bf16 v[108:111], v[158:161], v[200:203], v[108:111]
	v_mfma_f32_16x16x32_bf16 v[104:107], v[166:169], v[200:203], v[104:107]
	v_mfma_f32_16x16x32_bf16 v[92:95], v[158:161], v[208:211], v[92:95]
	v_mfma_f32_16x16x32_bf16 v[88:91], v[166:169], v[208:211], v[88:91]
	v_mfma_f32_16x16x32_bf16 v[76:79], v[158:161], v[216:219], v[76:79]
	v_mfma_f32_16x16x32_bf16 v[72:75], v[166:169], v[216:219], v[72:75]
	v_mfma_f32_16x16x32_bf16 v[116:119], v[170:173], v[186:189], v[116:119]
	v_mfma_f32_16x16x32_bf16 v[112:115], v[178:181], v[186:189], v[112:115]
	v_mfma_f32_16x16x32_bf16 v[100:103], v[170:173], v[196:199], v[100:103]
	v_mfma_f32_16x16x32_bf16 v[96:99], v[178:181], v[196:199], v[96:99]
	v_mfma_f32_16x16x32_bf16 v[84:87], v[170:173], v[204:207], v[84:87]
	v_mfma_f32_16x16x32_bf16 v[80:83], v[178:181], v[204:207], v[80:83]
	v_mfma_f32_16x16x32_bf16 v[68:71], v[170:173], v[212:215], v[68:71]
	v_mfma_f32_16x16x32_bf16 v[64:67], v[178:181], v[212:215], v[64:67]
	v_mfma_f32_16x16x32_bf16 v[116:119], v[174:177], v[190:193], v[116:119]
	v_mfma_f32_16x16x32_bf16 v[112:115], v[182:185], v[190:193], v[112:115]
	v_mfma_f32_16x16x32_bf16 v[100:103], v[174:177], v[200:203], v[100:103]
	v_mfma_f32_16x16x32_bf16 v[96:99], v[182:185], v[200:203], v[96:99]
	v_mfma_f32_16x16x32_bf16 v[84:87], v[174:177], v[208:211], v[84:87]
	v_mfma_f32_16x16x32_bf16 v[80:83], v[182:185], v[208:211], v[80:83]
	v_mfma_f32_16x16x32_bf16 v[68:71], v[174:177], v[216:219], v[68:71]
	v_mfma_f32_16x16x32_bf16 v[64:67], v[182:185], v[216:219], v[64:67]
	s_setprio 0
	s_barrier
	s_add_i32 s38, s86, s58
	v_lshl_add_u64 v[148:149], v[148:149], 0, s[20:21]
	s_mov_b32 m0, s38
	ds_read_b128 v[186:189], v155 offset:49152
	ds_read_b128 v[190:193], v155 offset:50176
	ds_read_b128 v[196:199], v155 offset:51200
	ds_read_b128 v[200:203], v155 offset:52224
	ds_read_b128 v[204:207], v155 offset:53248
	ds_read_b128 v[208:211], v155 offset:54272
	ds_read_b128 v[212:215], v155 offset:55296
	ds_read_b128 v[216:219], v155 offset:56320
	global_load_lds_dwordx4 v[148:149], off
	s_add_i32 m0, s38, 0x2000
	s_add_u32 s36, s36, 0x40080
	v_lshl_add_u64 v[148:149], v[220:221], 0, s[20:21]
	s_addc_u32 s37, s37, 0
	s_add_i32 s38, s87, s58
	global_load_lds_dwordx4 v[148:149], off
	v_lshl_add_u64 v[148:149], s[36:37], 0, v[130:131]
	s_mov_b32 m0, s38
	s_nop 0
	global_load_lds_dwordx4 v[148:149], off
	v_lshl_add_u64 v[148:149], s[36:37], 0, v[134:135]
	s_add_i32 m0, s38, 0x2000
	s_nop 0
	global_load_lds_dwordx4 v[148:149], off
	s_waitcnt vmcnt(6)
	s_waitcnt lgkmcnt(0)
	s_barrier
	s_setprio 1
	s_waitcnt lgkmcnt(0)
	v_mfma_f32_16x16x32_bf16 v[60:63], v[144:147], v[186:189], v[60:63]
	v_mfma_f32_16x16x32_bf16 v[56:59], v[162:165], v[186:189], v[56:59]
	v_mfma_f32_16x16x32_bf16 v[44:47], v[144:147], v[196:199], v[44:47]
	v_mfma_f32_16x16x32_bf16 v[40:43], v[162:165], v[196:199], v[40:43]
	v_mfma_f32_16x16x32_bf16 v[28:31], v[144:147], v[204:207], v[28:31]
	v_mfma_f32_16x16x32_bf16 v[24:27], v[162:165], v[204:207], v[24:27]
	v_mfma_f32_16x16x32_bf16 v[12:15], v[144:147], v[212:215], v[12:15]
	v_mfma_f32_16x16x32_bf16 v[8:11], v[162:165], v[212:215], v[8:11]
	v_mfma_f32_16x16x32_bf16 v[60:63], v[158:161], v[190:193], v[60:63]
	v_mfma_f32_16x16x32_bf16 v[56:59], v[166:169], v[190:193], v[56:59]
	v_mfma_f32_16x16x32_bf16 v[44:47], v[158:161], v[200:203], v[44:47]
	v_mfma_f32_16x16x32_bf16 v[40:43], v[166:169], v[200:203], v[40:43]
	v_mfma_f32_16x16x32_bf16 v[28:31], v[158:161], v[208:211], v[28:31]
	v_mfma_f32_16x16x32_bf16 v[24:27], v[166:169], v[208:211], v[24:27]
	v_mfma_f32_16x16x32_bf16 v[12:15], v[158:161], v[216:219], v[12:15]
	v_mfma_f32_16x16x32_bf16 v[8:11], v[166:169], v[216:219], v[8:11]
	v_mfma_f32_16x16x32_bf16 v[52:55], v[170:173], v[186:189], v[52:55]
	v_mfma_f32_16x16x32_bf16 v[48:51], v[178:181], v[186:189], v[48:51]
	v_mfma_f32_16x16x32_bf16 v[36:39], v[170:173], v[196:199], v[36:39]
	v_mfma_f32_16x16x32_bf16 v[32:35], v[178:181], v[196:199], v[32:35]
	v_mfma_f32_16x16x32_bf16 v[20:23], v[170:173], v[204:207], v[20:23]
	v_mfma_f32_16x16x32_bf16 v[16:19], v[178:181], v[204:207], v[16:19]
	v_mfma_f32_16x16x32_bf16 v[4:7], v[170:173], v[212:215], v[4:7]
	v_mfma_f32_16x16x32_bf16 v[0:3], v[178:181], v[212:215], v[0:3]
	v_mfma_f32_16x16x32_bf16 v[52:55], v[174:177], v[190:193], v[52:55]
	v_mfma_f32_16x16x32_bf16 v[48:51], v[182:185], v[190:193], v[48:51]
	v_mfma_f32_16x16x32_bf16 v[36:39], v[174:177], v[200:203], v[36:39]
	v_mfma_f32_16x16x32_bf16 v[32:35], v[182:185], v[200:203], v[32:35]
	v_mfma_f32_16x16x32_bf16 v[20:23], v[174:177], v[208:211], v[20:23]
	v_mfma_f32_16x16x32_bf16 v[16:19], v[182:185], v[208:211], v[16:19]
	v_mfma_f32_16x16x32_bf16 v[4:7], v[174:177], v[216:219], v[4:7]
	v_mfma_f32_16x16x32_bf16 v[0:3], v[182:185], v[216:219], v[0:3]
	s_setprio 0
	s_barrier
	v_lshl_add_u64 v[222:223], v[222:223], 0, s[20:21]
	s_mov_b32 m0, s70
	s_nop 0
	global_load_lds_dwordx4 v[222:223], off
	v_lshl_add_u64 v[224:225], v[224:225], 0, s[20:21]
	s_mov_b32 m0, s71
	s_nop 0
	global_load_lds_dwordx4 v[224:225], off
	s_add_i32 s85, s85, 2
	s_add_u32 s34, s34, 0x100
	s_addc_u32 s35, s35, 0
	s_add_u32 s83, s83, 0x100
	s_addc_u32 s84, s84, 0
	s_cmp_gt_u32 s85, 13
	s_cbranch_scc0 .LBB0_947
	s_and_b64 vcc, exec, s[22:23]
	s_cbranch_vccz .LBB0_950
	s_barrier

.LBB0_1023:
	ds_read_b128 v[144:147], v153
	ds_read_b128 v[156:159], v153 offset:1024
	ds_read_b128 v[160:163], v153 offset:2048
	ds_read_b128 v[164:167], v153 offset:3072
	ds_read_b128 v[168:171], v154
	ds_read_b128 v[172:175], v154 offset:1024
	ds_read_b128 v[176:179], v154 offset:2048
	ds_read_b128 v[180:183], v154 offset:3072
	s_add_u32 s44, s42, 0xfffe0080
	s_addc_u32 s45, s43, -1
	s_cmp_eq_u32 s87, 4
	s_cselect_b32 s59, s35, s45
	s_cselect_b32 s58, s83, s44
	s_cselect_b32 s45, s31, s86
	s_cselect_b32 s44, s84, s85
	v_lshl_add_u64 v[148:149], s[42:43], 0, v[136:137]
	s_add_i32 m0, s41, 0xc000
	ds_read_b128 v[184:187], v155
	ds_read_b128 v[188:191], v155 offset:1024
	ds_read_b128 v[196:199], v155 offset:2048
	ds_read_b128 v[200:203], v155 offset:3072
	ds_read_b128 v[204:207], v155 offset:4096
	ds_read_b128 v[208:211], v155 offset:5120
	ds_read_b128 v[212:215], v155 offset:6144
	ds_read_b128 v[216:219], v155 offset:7168
	global_load_lds_dwordx4 v[148:149], off
	v_lshl_add_u64 v[148:149], s[42:43], 0, v[138:139]
	s_add_i32 m0, s41, 0xe000
	s_nop 0
	global_load_lds_dwordx4 v[148:149], off
	s_waitcnt vmcnt(8)
	s_waitcnt lgkmcnt(0)
	s_barrier
	s_setprio 1
	s_waitcnt lgkmcnt(0)
	v_mfma_f32_16x16x32_bf16 v[124:127], v[144:147], v[184:187], v[124:127]
	v_mfma_f32_16x16x32_bf16 v[120:123], v[160:163], v[184:187], v[120:123]
	v_mfma_f32_16x16x32_bf16 v[108:111], v[144:147], v[196:199], v[108:111]
	v_mfma_f32_16x16x32_bf16 v[104:107], v[160:163], v[196:199], v[104:107]
	v_mfma_f32_16x16x32_bf16 v[92:95], v[144:147], v[204:207], v[92:95]
	v_mfma_f32_16x16x32_bf16 v[88:91], v[160:163], v[204:207], v[88:91]
	v_mfma_f32_16x16x32_bf16 v[76:79], v[144:147], v[212:215], v[76:79]
	v_mfma_f32_16x16x32_bf16 v[72:75], v[160:163], v[212:215], v[72:75]
	v_mfma_f32_16x16x32_bf16 v[124:127], v[156:159], v[188:191], v[124:127]
	v_mfma_f32_16x16x32_bf16 v[120:123], v[164:167], v[188:191], v[120:123]
	v_mfma_f32_16x16x32_bf16 v[108:111], v[156:159], v[200:203], v[108:111]
	v_mfma_f32_16x16x32_bf16 v[104:107], v[164:167], v[200:203], v[104:107]
	v_mfma_f32_16x16x32_bf16 v[92:95], v[156:159], v[208:211], v[92:95]
	v_mfma_f32_16x16x32_bf16 v[88:91], v[164:167], v[208:211], v[88:91]
	v_mfma_f32_16x16x32_bf16 v[76:79], v[156:159], v[216:219], v[76:79]
	v_mfma_f32_16x16x32_bf16 v[72:75], v[164:167], v[216:219], v[72:75]
	v_mfma_f32_16x16x32_bf16 v[116:119], v[168:171], v[184:187], v[116:119]
	v_mfma_f32_16x16x32_bf16 v[112:115], v[176:179], v[184:187], v[112:115]
	v_mfma_f32_16x16x32_bf16 v[100:103], v[168:171], v[196:199], v[100:103]
	v_mfma_f32_16x16x32_bf16 v[96:99], v[176:179], v[196:199], v[96:99]
	v_mfma_f32_16x16x32_bf16 v[84:87], v[168:171], v[204:207], v[84:87]
	v_mfma_f32_16x16x32_bf16 v[80:83], v[176:179], v[204:207], v[80:83]
	v_mfma_f32_16x16x32_bf16 v[68:71], v[168:171], v[212:215], v[68:71]
	v_mfma_f32_16x16x32_bf16 v[64:67], v[176:179], v[212:215], v[64:67]
	v_mfma_f32_16x16x32_bf16 v[116:119], v[172:175], v[188:191], v[116:119]
	v_mfma_f32_16x16x32_bf16 v[112:115], v[180:183], v[188:191], v[112:115]
	v_mfma_f32_16x16x32_bf16 v[100:103], v[172:175], v[200:203], v[100:103]
	v_mfma_f32_16x16x32_bf16 v[96:99], v[180:183], v[200:203], v[96:99]
	v_mfma_f32_16x16x32_bf16 v[84:87], v[172:175], v[208:211], v[84:87]
	v_mfma_f32_16x16x32_bf16 v[80:83], v[180:183], v[208:211], v[80:83]
	v_mfma_f32_16x16x32_bf16 v[68:71], v[172:175], v[216:219], v[68:71]
	v_mfma_f32_16x16x32_bf16 v[64:67], v[180:183], v[216:219], v[64:67]
	s_setprio 0
	s_barrier
	s_add_i32 s88, s80, s62
	v_lshl_add_u64 v[148:149], s[44:45], 0, v[130:131]
	s_mov_b32 m0, s88
	ds_read_b128 v[184:187], v155 offset:16384
	ds_read_b128 v[188:191], v155 offset:17408
	ds_read_b128 v[196:199], v155 offset:18432
	ds_read_b128 v[200:203], v155 offset:19456
	ds_read_b128 v[204:207], v155 offset:20480
	ds_read_b128 v[208:211], v155 offset:21504
	ds_read_b128 v[212:215], v155 offset:22528
	ds_read_b128 v[216:219], v155 offset:23552
	global_load_lds_dwordx4 v[148:149], off
	s_add_i32 m0, s88, 0x2000
	s_add_u32 s88, s44, 0x20000
	v_lshl_add_u64 v[192:193], s[44:45], 0, v[134:135]
	s_addc_u32 s89, s45, 0
	s_add_i32 s90, s81, s62
	global_load_lds_dwordx4 v[192:193], off
	v_lshl_add_u64 v[220:221], s[88:89], 0, v[130:131]
	s_mov_b32 m0, s90
	v_lshl_add_u64 v[222:223], s[58:59], 0, v[132:133]
	global_load_lds_dwordx4 v[220:221], off
	v_lshl_add_u64 v[220:221], s[88:89], 0, v[134:135]
	s_add_i32 m0, s90, 0x2000
	s_nop 0
	global_load_lds_dwordx4 v[220:221], off
	v_lshl_add_u64 v[220:221], s[58:59], 0, v[128:129]
	s_waitcnt vmcnt(6)
	s_waitcnt lgkmcnt(0)
	s_barrier
	s_setprio 1
	s_waitcnt lgkmcnt(0)
	v_mfma_f32_16x16x32_bf16 v[60:63], v[144:147], v[184:187], v[60:63]
	v_mfma_f32_16x16x32_bf16 v[56:59], v[160:163], v[184:187], v[56:59]
	v_mfma_f32_16x16x32_bf16 v[44:47], v[144:147], v[196:199], v[44:47]
	v_mfma_f32_16x16x32_bf16 v[40:43], v[160:163], v[196:199], v[40:43]
	v_mfma_f32_16x16x32_bf16 v[28:31], v[144:147], v[204:207], v[28:31]
	v_mfma_f32_16x16x32_bf16 v[24:27], v[160:163], v[204:207], v[24:27]
	v_mfma_f32_16x16x32_bf16 v[12:15], v[144:147], v[212:215], v[12:15]
	v_mfma_f32_16x16x32_bf16 v[8:11], v[160:163], v[212:215], v[8:11]
	v_mfma_f32_16x16x32_bf16 v[60:63], v[156:159], v[188:191], v[60:63]
	v_mfma_f32_16x16x32_bf16 v[56:59], v[164:167], v[188:191], v[56:59]
	v_mfma_f32_16x16x32_bf16 v[44:47], v[156:159], v[200:203], v[44:47]
	v_mfma_f32_16x16x32_bf16 v[40:43], v[164:167], v[200:203], v[40:43]
	v_mfma_f32_16x16x32_bf16 v[28:31], v[156:159], v[208:211], v[28:31]
	v_mfma_f32_16x16x32_bf16 v[24:27], v[164:167], v[208:211], v[24:27]
	v_mfma_f32_16x16x32_bf16 v[12:15], v[156:159], v[216:219], v[12:15]
	v_mfma_f32_16x16x32_bf16 v[8:11], v[164:167], v[216:219], v[8:11]
	v_mfma_f32_16x16x32_bf16 v[52:55], v[168:171], v[184:187], v[52:55]
	v_mfma_f32_16x16x32_bf16 v[48:51], v[176:179], v[184:187], v[48:51]
	v_mfma_f32_16x16x32_bf16 v[36:39], v[168:171], v[196:199], v[36:39]
	v_mfma_f32_16x16x32_bf16 v[32:35], v[176:179], v[196:199], v[32:35]
	v_mfma_f32_16x16x32_bf16 v[20:23], v[168:171], v[204:207], v[20:23]
	v_mfma_f32_16x16x32_bf16 v[16:19], v[176:179], v[204:207], v[16:19]
	v_mfma_f32_16x16x32_bf16 v[4:7], v[168:171], v[212:215], v[4:7]
	v_mfma_f32_16x16x32_bf16 v[0:3], v[176:179], v[212:215], v[0:3]
	v_mfma_f32_16x16x32_bf16 v[52:55], v[172:175], v[188:191], v[52:55]
	v_mfma_f32_16x16x32_bf16 v[48:51], v[180:183], v[188:191], v[48:51]
	v_mfma_f32_16x16x32_bf16 v[36:39], v[172:175], v[200:203], v[36:39]
	v_mfma_f32_16x16x32_bf16 v[32:35], v[180:183], v[200:203], v[32:35]
	v_mfma_f32_16x16x32_bf16 v[20:23], v[172:175], v[208:211], v[20:23]
	v_mfma_f32_16x16x32_bf16 v[16:19], v[180:183], v[208:211], v[16:19]
	v_mfma_f32_16x16x32_bf16 v[4:7], v[172:175], v[216:219], v[4:7]
	v_mfma_f32_16x16x32_bf16 v[0:3], v[180:183], v[216:219], v[0:3]
	s_setprio 0
	s_barrier
	s_add_i32 s88, 0, 0x18000
	s_add_i32 s89, 0, 0x1c000
	v_add_u32_e32 v164, s88, v151
	v_add_u32_e32 v180, s89, v151
	ds_read_b128 v[144:147], v164
	ds_read_b128 v[156:159], v164 offset:1024
	ds_read_b128 v[160:163], v164 offset:2048
	ds_read_b128 v[164:167], v164 offset:3072
	ds_read_b128 v[168:171], v180
	ds_read_b128 v[172:175], v180 offset:1024
	ds_read_b128 v[176:179], v180 offset:2048
	ds_read_b128 v[180:183], v180 offset:3072
	s_add_u32 s58, s58, 0x20000
	s_addc_u32 s59, s59, 0
	v_lshl_add_u64 v[224:225], s[58:59], 0, v[128:129]
	ds_read_b128 v[184:187], v155 offset:32768
	ds_read_b128 v[188:191], v155 offset:33792
	ds_read_b128 v[196:199], v155 offset:34816
	ds_read_b128 v[200:203], v155 offset:35840
	ds_read_b128 v[204:207], v155 offset:36864
	ds_read_b128 v[208:211], v155 offset:37888
	ds_read_b128 v[212:215], v155 offset:38912
	ds_read_b128 v[216:219], v155 offset:39936
	s_mov_b32 m0, s41
	s_nop 0
	global_load_lds_dwordx4 v[220:221], off
	s_mov_b32 m0, s63
	s_nop 0
	global_load_lds_dwordx4 v[222:223], off
	s_mov_b32 m0, s70
	s_nop 0
	global_load_lds_dwordx4 v[224:225], off
	v_lshl_add_u64 v[224:225], s[58:59], 0, v[132:133]
	s_mov_b32 m0, s71
	s_nop 0
	global_load_lds_dwordx4 v[224:225], off
	s_waitcnt vmcnt(8)
	s_waitcnt lgkmcnt(0)
	s_barrier
	s_setprio 1
	s_waitcnt lgkmcnt(0)
	v_mfma_f32_16x16x32_bf16 v[124:127], v[144:147], v[184:187], v[124:127]
	v_mfma_f32_16x16x32_bf16 v[120:123], v[160:163], v[184:187], v[120:123]
	v_mfma_f32_16x16x32_bf16 v[108:111], v[144:147], v[196:199], v[108:111]
	v_mfma_f32_16x16x32_bf16 v[104:107], v[160:163], v[196:199], v[104:107]
	v_mfma_f32_16x16x32_bf16 v[92:95], v[144:147], v[204:207], v[92:95]
	v_mfma_f32_16x16x32_bf16 v[88:91], v[160:163], v[204:207], v[88:91]
	v_mfma_f32_16x16x32_bf16 v[76:79], v[144:147], v[212:215], v[76:79]
	v_mfma_f32_16x16x32_bf16 v[72:75], v[160:163], v[212:215], v[72:75]
	v_mfma_f32_16x16x32_bf16 v[124:127], v[156:159], v[188:191], v[124:127]
	v_mfma_f32_16x16x32_bf16 v[120:123], v[164:167], v[188:191], v[120:123]
	v_mfma_f32_16x16x32_bf16 v[108:111], v[156:159], v[200:203], v[108:111]
	v_mfma_f32_16x16x32_bf16 v[104:107], v[164:167], v[200:203], v[104:107]
	v_mfma_f32_16x16x32_bf16 v[92:95], v[156:159], v[208:211], v[92:95]
	v_mfma_f32_16x16x32_bf16 v[88:91], v[164:167], v[208:211], v[88:91]
	v_mfma_f32_16x16x32_bf16 v[76:79], v[156:159], v[216:219], v[76:79]
	v_mfma_f32_16x16x32_bf16 v[72:75], v[164:167], v[216:219], v[72:75]
	v_mfma_f32_16x16x32_bf16 v[116:119], v[168:171], v[184:187], v[116:119]
	v_mfma_f32_16x16x32_bf16 v[112:115], v[176:179], v[184:187], v[112:115]
	v_mfma_f32_16x16x32_bf16 v[100:103], v[168:171], v[196:199], v[100:103]
	v_mfma_f32_16x16x32_bf16 v[96:99], v[176:179], v[196:199], v[96:99]
	v_mfma_f32_16x16x32_bf16 v[84:87], v[168:171], v[204:207], v[84:87]
	v_mfma_f32_16x16x32_bf16 v[80:83], v[176:179], v[204:207], v[80:83]
	v_mfma_f32_16x16x32_bf16 v[68:71], v[168:171], v[212:215], v[68:71]
	v_mfma_f32_16x16x32_bf16 v[64:67], v[176:179], v[212:215], v[64:67]
	v_mfma_f32_16x16x32_bf16 v[116:119], v[172:175], v[188:191], v[116:119]
	v_mfma_f32_16x16x32_bf16 v[112:115], v[180:183], v[188:191], v[112:115]
	v_mfma_f32_16x16x32_bf16 v[100:103], v[172:175], v[200:203], v[100:103]
	v_mfma_f32_16x16x32_bf16 v[96:99], v[180:183], v[200:203], v[96:99]
	v_mfma_f32_16x16x32_bf16 v[84:87], v[172:175], v[208:211], v[84:87]
	v_mfma_f32_16x16x32_bf16 v[80:83], v[180:183], v[208:211], v[80:83]
	v_mfma_f32_16x16x32_bf16 v[68:71], v[172:175], v[216:219], v[68:71]
	v_mfma_f32_16x16x32_bf16 v[64:67], v[180:183], v[216:219], v[64:67]
	s_setprio 0
	s_barrier
	s_add_i32 s58, s88, s62
	v_lshl_add_u64 v[148:149], v[148:149], 0, s[20:21]
	s_mov_b32 m0, s58
	ds_read_b128 v[184:187], v155 offset:49152
	ds_read_b128 v[188:191], v155 offset:50176
	ds_read_b128 v[196:199], v155 offset:51200
	ds_read_b128 v[200:203], v155 offset:52224
	ds_read_b128 v[204:207], v155 offset:53248
	ds_read_b128 v[208:211], v155 offset:54272
	ds_read_b128 v[212:215], v155 offset:55296
	ds_read_b128 v[216:219], v155 offset:56320
	global_load_lds_dwordx4 v[148:149], off
	s_add_i32 m0, s58, 0x2000
	s_add_u32 s44, s44, 0x20080
	v_lshl_add_u64 v[148:149], v[192:193], 0, s[20:21]
	s_addc_u32 s45, s45, 0
	s_add_i32 s58, s89, s62
	global_load_lds_dwordx4 v[148:149], off
	v_lshl_add_u64 v[148:149], s[44:45], 0, v[130:131]
	s_mov_b32 m0, s58
	s_nop 0
	global_load_lds_dwordx4 v[148:149], off
	v_lshl_add_u64 v[148:149], s[44:45], 0, v[134:135]
	s_add_i32 m0, s58, 0x2000
	s_nop 0
	global_load_lds_dwordx4 v[148:149], off
	s_waitcnt vmcnt(6)
	s_waitcnt lgkmcnt(0)
	s_barrier
	s_setprio 1
	s_waitcnt lgkmcnt(0)
	v_mfma_f32_16x16x32_bf16 v[60:63], v[144:147], v[184:187], v[60:63]
	v_mfma_f32_16x16x32_bf16 v[56:59], v[160:163], v[184:187], v[56:59]
	v_mfma_f32_16x16x32_bf16 v[44:47], v[144:147], v[196:199], v[44:47]
	v_mfma_f32_16x16x32_bf16 v[40:43], v[160:163], v[196:199], v[40:43]
	v_mfma_f32_16x16x32_bf16 v[28:31], v[144:147], v[204:207], v[28:31]
	v_mfma_f32_16x16x32_bf16 v[24:27], v[160:163], v[204:207], v[24:27]
	v_mfma_f32_16x16x32_bf16 v[12:15], v[144:147], v[212:215], v[12:15]
	v_mfma_f32_16x16x32_bf16 v[8:11], v[160:163], v[212:215], v[8:11]
	v_mfma_f32_16x16x32_bf16 v[60:63], v[156:159], v[188:191], v[60:63]
	v_mfma_f32_16x16x32_bf16 v[56:59], v[164:167], v[188:191], v[56:59]
	v_mfma_f32_16x16x32_bf16 v[44:47], v[156:159], v[200:203], v[44:47]
	v_mfma_f32_16x16x32_bf16 v[40:43], v[164:167], v[200:203], v[40:43]
	v_mfma_f32_16x16x32_bf16 v[28:31], v[156:159], v[208:211], v[28:31]
	v_mfma_f32_16x16x32_bf16 v[24:27], v[164:167], v[208:211], v[24:27]
	v_mfma_f32_16x16x32_bf16 v[12:15], v[156:159], v[216:219], v[12:15]
	v_mfma_f32_16x16x32_bf16 v[8:11], v[164:167], v[216:219], v[8:11]
	v_mfma_f32_16x16x32_bf16 v[52:55], v[168:171], v[184:187], v[52:55]
	v_mfma_f32_16x16x32_bf16 v[48:51], v[176:179], v[184:187], v[48:51]
	v_mfma_f32_16x16x32_bf16 v[36:39], v[168:171], v[196:199], v[36:39]
	v_mfma_f32_16x16x32_bf16 v[32:35], v[176:179], v[196:199], v[32:35]
	v_mfma_f32_16x16x32_bf16 v[20:23], v[168:171], v[204:207], v[20:23]
	v_mfma_f32_16x16x32_bf16 v[16:19], v[176:179], v[204:207], v[16:19]
	v_mfma_f32_16x16x32_bf16 v[4:7], v[168:171], v[212:215], v[4:7]
	v_mfma_f32_16x16x32_bf16 v[0:3], v[176:179], v[212:215], v[0:3]
	v_mfma_f32_16x16x32_bf16 v[52:55], v[172:175], v[188:191], v[52:55]
	v_mfma_f32_16x16x32_bf16 v[48:51], v[180:183], v[188:191], v[48:51]
	v_mfma_f32_16x16x32_bf16 v[36:39], v[172:175], v[200:203], v[36:39]
	v_mfma_f32_16x16x32_bf16 v[32:35], v[180:183], v[200:203], v[32:35]
	v_mfma_f32_16x16x32_bf16 v[20:23], v[172:175], v[208:211], v[20:23]
	v_mfma_f32_16x16x32_bf16 v[16:19], v[180:183], v[208:211], v[16:19]
	v_mfma_f32_16x16x32_bf16 v[4:7], v[172:175], v[216:219], v[4:7]
	v_mfma_f32_16x16x32_bf16 v[0:3], v[180:183], v[216:219], v[0:3]
	s_setprio 0
	s_barrier
	v_lshl_add_u64 v[220:221], v[220:221], 0, s[20:21]
	s_mov_b32 m0, s73
	s_nop 0
	global_load_lds_dwordx4 v[220:221], off
	v_lshl_add_u64 v[222:223], v[222:223], 0, s[20:21]
	s_mov_b32 m0, s78
	s_nop 0
	global_load_lds_dwordx4 v[222:223], off
	s_add_i32 s87, s87, 2
	s_add_u32 s42, s42, 0x100
	s_addc_u32 s43, s43, 0
	s_add_u32 s85, s85, 0x100
	s_addc_u32 s86, s86, 0
	s_cmp_gt_u32 s87, 5
	s_cbranch_scc0 .LBB0_1023
	s_and_b64 vcc, exec, s[22:23]
	s_cbranch_vccz .LBB0_1026
	s_barrier

.LBB0_1421:
	ds_read_b128 v[146:149], v155
	ds_read_b128 v[160:163], v155 offset:1024
	ds_read_b128 v[164:167], v155 offset:2048
	ds_read_b128 v[168:171], v155 offset:3072
	ds_read_b128 v[172:175], v156
	ds_read_b128 v[176:179], v156 offset:1024
	ds_read_b128 v[180:183], v156 offset:2048
	ds_read_b128 v[184:187], v156 offset:3072
	s_add_u32 s40, s0, 0xfffc0080
	s_addc_u32 s41, s1, -1
	s_cmp_eq_u32 s83, 12
	s_cselect_b32 s43, s25, s41
	s_cselect_b32 s42, s27, s40
	s_cselect_b32 s41, s31, s82
	s_cselect_b32 s40, s30, s29
	v_lshl_add_u64 v[150:151], s[0:1], 0, v[138:139]
	s_add_i32 m0, s39, 0xc000
	ds_read_b128 v[188:191], v157
	ds_read_b128 v[196:199], v157 offset:1024
	ds_read_b128 v[200:203], v157 offset:2048
	ds_read_b128 v[204:207], v157 offset:3072
	ds_read_b128 v[208:211], v157 offset:4096
	ds_read_b128 v[212:215], v157 offset:5120
	ds_read_b128 v[216:219], v157 offset:6144
	ds_read_b128 v[220:223], v157 offset:7168
	global_load_lds_dwordx4 v[150:151], off
	v_lshl_add_u64 v[150:151], s[0:1], 0, v[140:141]
	s_add_i32 m0, s39, 0xe000
	s_nop 0
	global_load_lds_dwordx4 v[150:151], off
	s_waitcnt vmcnt(8)
	s_waitcnt lgkmcnt(0)
	s_barrier
	s_setprio 1
	s_waitcnt lgkmcnt(0)
	v_mfma_f32_16x16x32_bf16 v[124:127], v[146:149], v[188:191], v[124:127]
	v_mfma_f32_16x16x32_bf16 v[120:123], v[164:167], v[188:191], v[120:123]
	v_mfma_f32_16x16x32_bf16 v[108:111], v[146:149], v[200:203], v[108:111]
	v_mfma_f32_16x16x32_bf16 v[104:107], v[164:167], v[200:203], v[104:107]
	v_mfma_f32_16x16x32_bf16 v[92:95], v[146:149], v[208:211], v[92:95]
	v_mfma_f32_16x16x32_bf16 v[88:91], v[164:167], v[208:211], v[88:91]
	v_mfma_f32_16x16x32_bf16 v[76:79], v[146:149], v[216:219], v[76:79]
	v_mfma_f32_16x16x32_bf16 v[72:75], v[164:167], v[216:219], v[72:75]
	v_mfma_f32_16x16x32_bf16 v[124:127], v[160:163], v[196:199], v[124:127]
	v_mfma_f32_16x16x32_bf16 v[120:123], v[168:171], v[196:199], v[120:123]
	v_mfma_f32_16x16x32_bf16 v[108:111], v[160:163], v[204:207], v[108:111]
	v_mfma_f32_16x16x32_bf16 v[104:107], v[168:171], v[204:207], v[104:107]
	v_mfma_f32_16x16x32_bf16 v[92:95], v[160:163], v[212:215], v[92:95]
	v_mfma_f32_16x16x32_bf16 v[88:91], v[168:171], v[212:215], v[88:91]
	v_mfma_f32_16x16x32_bf16 v[76:79], v[160:163], v[220:223], v[76:79]
	v_mfma_f32_16x16x32_bf16 v[72:75], v[168:171], v[220:223], v[72:75]
	v_mfma_f32_16x16x32_bf16 v[116:119], v[172:175], v[188:191], v[116:119]
	v_mfma_f32_16x16x32_bf16 v[112:115], v[180:183], v[188:191], v[112:115]
	v_mfma_f32_16x16x32_bf16 v[100:103], v[172:175], v[200:203], v[100:103]
	v_mfma_f32_16x16x32_bf16 v[96:99], v[180:183], v[200:203], v[96:99]
	v_mfma_f32_16x16x32_bf16 v[84:87], v[172:175], v[208:211], v[84:87]
	v_mfma_f32_16x16x32_bf16 v[80:83], v[180:183], v[208:211], v[80:83]
	v_mfma_f32_16x16x32_bf16 v[68:71], v[172:175], v[216:219], v[68:71]
	v_mfma_f32_16x16x32_bf16 v[64:67], v[180:183], v[216:219], v[64:67]
	v_mfma_f32_16x16x32_bf16 v[116:119], v[176:179], v[196:199], v[116:119]
	v_mfma_f32_16x16x32_bf16 v[112:115], v[184:187], v[196:199], v[112:115]
	v_mfma_f32_16x16x32_bf16 v[100:103], v[176:179], v[204:207], v[100:103]
	v_mfma_f32_16x16x32_bf16 v[96:99], v[184:187], v[204:207], v[96:99]
	v_mfma_f32_16x16x32_bf16 v[84:87], v[176:179], v[212:215], v[84:87]
	v_mfma_f32_16x16x32_bf16 v[80:83], v[184:187], v[212:215], v[80:83]
	v_mfma_f32_16x16x32_bf16 v[68:71], v[176:179], v[220:223], v[68:71]
	v_mfma_f32_16x16x32_bf16 v[64:67], v[184:187], v[220:223], v[64:67]
	s_setprio 0
	s_barrier
	s_add_i32 s84, s78, s60
	v_lshl_add_u64 v[150:151], s[40:41], 0, v[132:133]
	s_mov_b32 m0, s84
	ds_read_b128 v[188:191], v157 offset:16384
	ds_read_b128 v[196:199], v157 offset:17408
	ds_read_b128 v[200:203], v157 offset:18432
	ds_read_b128 v[204:207], v157 offset:19456
	ds_read_b128 v[208:211], v157 offset:20480
	ds_read_b128 v[212:215], v157 offset:21504
	ds_read_b128 v[216:219], v157 offset:22528
	ds_read_b128 v[220:223], v157 offset:23552
	global_load_lds_dwordx4 v[150:151], off
	s_add_i32 m0, s84, 0x2000
	s_add_u32 s84, s40, 0x40000
	v_lshl_add_u64 v[192:193], s[40:41], 0, v[136:137]
	s_addc_u32 s85, s41, 0
	s_add_i32 s86, s79, s60
	global_load_lds_dwordx4 v[192:193], off
	v_lshl_add_u64 v[224:225], s[84:85], 0, v[132:133]
	s_mov_b32 m0, s86
	v_lshl_add_u64 v[226:227], s[42:43], 0, v[134:135]
	global_load_lds_dwordx4 v[224:225], off
	v_lshl_add_u64 v[224:225], s[84:85], 0, v[136:137]
	s_add_i32 m0, s86, 0x2000
	s_nop 0
	global_load_lds_dwordx4 v[224:225], off
	v_lshl_add_u64 v[224:225], s[42:43], 0, v[130:131]
	s_waitcnt vmcnt(6)
	s_waitcnt lgkmcnt(0)
	s_barrier
	s_setprio 1
	s_waitcnt lgkmcnt(0)
	v_mfma_f32_16x16x32_bf16 v[60:63], v[146:149], v[188:191], v[60:63]
	v_mfma_f32_16x16x32_bf16 v[56:59], v[164:167], v[188:191], v[56:59]
	v_mfma_f32_16x16x32_bf16 v[44:47], v[146:149], v[200:203], v[44:47]
	v_mfma_f32_16x16x32_bf16 v[40:43], v[164:167], v[200:203], v[40:43]
	v_mfma_f32_16x16x32_bf16 v[28:31], v[146:149], v[208:211], v[28:31]
	v_mfma_f32_16x16x32_bf16 v[24:27], v[164:167], v[208:211], v[24:27]
	v_mfma_f32_16x16x32_bf16 v[12:15], v[146:149], v[216:219], v[12:15]
	v_mfma_f32_16x16x32_bf16 v[8:11], v[164:167], v[216:219], v[8:11]
	v_mfma_f32_16x16x32_bf16 v[60:63], v[160:163], v[196:199], v[60:63]
	v_mfma_f32_16x16x32_bf16 v[56:59], v[168:171], v[196:199], v[56:59]
	v_mfma_f32_16x16x32_bf16 v[44:47], v[160:163], v[204:207], v[44:47]
	v_mfma_f32_16x16x32_bf16 v[40:43], v[168:171], v[204:207], v[40:43]
	v_mfma_f32_16x16x32_bf16 v[28:31], v[160:163], v[212:215], v[28:31]
	v_mfma_f32_16x16x32_bf16 v[24:27], v[168:171], v[212:215], v[24:27]
	v_mfma_f32_16x16x32_bf16 v[12:15], v[160:163], v[220:223], v[12:15]
	v_mfma_f32_16x16x32_bf16 v[8:11], v[168:171], v[220:223], v[8:11]
	v_mfma_f32_16x16x32_bf16 v[52:55], v[172:175], v[188:191], v[52:55]
	v_mfma_f32_16x16x32_bf16 v[48:51], v[180:183], v[188:191], v[48:51]
	v_mfma_f32_16x16x32_bf16 v[36:39], v[172:175], v[200:203], v[36:39]
	v_mfma_f32_16x16x32_bf16 v[32:35], v[180:183], v[200:203], v[32:35]
	v_mfma_f32_16x16x32_bf16 v[20:23], v[172:175], v[208:211], v[20:23]
	v_mfma_f32_16x16x32_bf16 v[16:19], v[180:183], v[208:211], v[16:19]
	v_mfma_f32_16x16x32_bf16 v[4:7], v[172:175], v[216:219], v[4:7]
	v_mfma_f32_16x16x32_bf16 v[0:3], v[180:183], v[216:219], v[0:3]
	v_mfma_f32_16x16x32_bf16 v[52:55], v[176:179], v[196:199], v[52:55]
	v_mfma_f32_16x16x32_bf16 v[48:51], v[184:187], v[196:199], v[48:51]
	v_mfma_f32_16x16x32_bf16 v[36:39], v[176:179], v[204:207], v[36:39]
	v_mfma_f32_16x16x32_bf16 v[32:35], v[184:187], v[204:207], v[32:35]
	v_mfma_f32_16x16x32_bf16 v[20:23], v[176:179], v[212:215], v[20:23]
	v_mfma_f32_16x16x32_bf16 v[16:19], v[184:187], v[212:215], v[16:19]
	v_mfma_f32_16x16x32_bf16 v[4:7], v[176:179], v[220:223], v[4:7]
	v_mfma_f32_16x16x32_bf16 v[0:3], v[184:187], v[220:223], v[0:3]
	s_setprio 0
	s_barrier
	s_add_i32 s84, 0, 0x18000
	v_add_u32_e32 v159, s84, v153
	s_add_i32 s85, 0, 0x1c000
	ds_read_b128 v[146:149], v159
	ds_read_b128 v[160:163], v159 offset:1024
	ds_read_b128 v[164:167], v159 offset:2048
	ds_read_b128 v[168:171], v159 offset:3072
	v_add_u32_e32 v159, s85, v153
	ds_read_b128 v[172:175], v159
	ds_read_b128 v[176:179], v159 offset:1024
	ds_read_b128 v[180:183], v159 offset:2048
	ds_read_b128 v[184:187], v159 offset:3072
	s_add_u32 s42, s42, 0x40000
	s_addc_u32 s43, s43, 0
	v_lshl_add_u64 v[228:229], s[42:43], 0, v[130:131]
	ds_read_b128 v[188:191], v157 offset:32768
	ds_read_b128 v[196:199], v157 offset:33792
	ds_read_b128 v[200:203], v157 offset:34816
	ds_read_b128 v[204:207], v157 offset:35840
	ds_read_b128 v[208:211], v157 offset:36864
	ds_read_b128 v[212:215], v157 offset:37888
	ds_read_b128 v[216:219], v157 offset:38912
	ds_read_b128 v[220:223], v157 offset:39936
	s_mov_b32 m0, s39
	s_nop 0
	global_load_lds_dwordx4 v[224:225], off
	s_mov_b32 m0, s61
	s_nop 0
	global_load_lds_dwordx4 v[226:227], off
	s_mov_b32 m0, s62
	s_nop 0
	global_load_lds_dwordx4 v[228:229], off
	v_lshl_add_u64 v[228:229], s[42:43], 0, v[134:135]
	s_mov_b32 m0, s63
	s_nop 0
	global_load_lds_dwordx4 v[228:229], off
	s_waitcnt vmcnt(8)
	s_waitcnt lgkmcnt(0)
	s_barrier
	s_setprio 1
	s_waitcnt lgkmcnt(0)
	v_mfma_f32_16x16x32_bf16 v[124:127], v[146:149], v[188:191], v[124:127]
	v_mfma_f32_16x16x32_bf16 v[120:123], v[164:167], v[188:191], v[120:123]
	v_mfma_f32_16x16x32_bf16 v[108:111], v[146:149], v[200:203], v[108:111]
	v_mfma_f32_16x16x32_bf16 v[104:107], v[164:167], v[200:203], v[104:107]
	v_mfma_f32_16x16x32_bf16 v[92:95], v[146:149], v[208:211], v[92:95]
	v_mfma_f32_16x16x32_bf16 v[88:91], v[164:167], v[208:211], v[88:91]
	v_mfma_f32_16x16x32_bf16 v[76:79], v[146:149], v[216:219], v[76:79]
	v_mfma_f32_16x16x32_bf16 v[72:75], v[164:167], v[216:219], v[72:75]
	v_mfma_f32_16x16x32_bf16 v[124:127], v[160:163], v[196:199], v[124:127]
	v_mfma_f32_16x16x32_bf16 v[120:123], v[168:171], v[196:199], v[120:123]
	v_mfma_f32_16x16x32_bf16 v[108:111], v[160:163], v[204:207], v[108:111]
	v_mfma_f32_16x16x32_bf16 v[104:107], v[168:171], v[204:207], v[104:107]
	v_mfma_f32_16x16x32_bf16 v[92:95], v[160:163], v[212:215], v[92:95]
	v_mfma_f32_16x16x32_bf16 v[88:91], v[168:171], v[212:215], v[88:91]
	v_mfma_f32_16x16x32_bf16 v[76:79], v[160:163], v[220:223], v[76:79]
	v_mfma_f32_16x16x32_bf16 v[72:75], v[168:171], v[220:223], v[72:75]
	v_mfma_f32_16x16x32_bf16 v[116:119], v[172:175], v[188:191], v[116:119]
	v_mfma_f32_16x16x32_bf16 v[112:115], v[180:183], v[188:191], v[112:115]
	v_mfma_f32_16x16x32_bf16 v[100:103], v[172:175], v[200:203], v[100:103]
	v_mfma_f32_16x16x32_bf16 v[96:99], v[180:183], v[200:203], v[96:99]
	v_mfma_f32_16x16x32_bf16 v[84:87], v[172:175], v[208:211], v[84:87]
	v_mfma_f32_16x16x32_bf16 v[80:83], v[180:183], v[208:211], v[80:83]
	v_mfma_f32_16x16x32_bf16 v[68:71], v[172:175], v[216:219], v[68:71]
	v_mfma_f32_16x16x32_bf16 v[64:67], v[180:183], v[216:219], v[64:67]
	v_mfma_f32_16x16x32_bf16 v[116:119], v[176:179], v[196:199], v[116:119]
	v_mfma_f32_16x16x32_bf16 v[112:115], v[184:187], v[196:199], v[112:115]
	v_mfma_f32_16x16x32_bf16 v[100:103], v[176:179], v[204:207], v[100:103]
	v_mfma_f32_16x16x32_bf16 v[96:99], v[184:187], v[204:207], v[96:99]
	v_mfma_f32_16x16x32_bf16 v[84:87], v[176:179], v[212:215], v[84:87]
	v_mfma_f32_16x16x32_bf16 v[80:83], v[184:187], v[212:215], v[80:83]
	v_mfma_f32_16x16x32_bf16 v[68:71], v[176:179], v[220:223], v[68:71]
	v_mfma_f32_16x16x32_bf16 v[64:67], v[184:187], v[220:223], v[64:67]
	s_setprio 0
	s_barrier
	s_add_i32 s42, s84, s60
	v_lshl_add_u64 v[150:151], v[150:151], 0, s[20:21]
	s_mov_b32 m0, s42
	ds_read_b128 v[188:191], v157 offset:49152
	ds_read_b128 v[196:199], v157 offset:50176
	ds_read_b128 v[200:203], v157 offset:51200
	ds_read_b128 v[204:207], v157 offset:52224
	ds_read_b128 v[208:211], v157 offset:53248
	ds_read_b128 v[212:215], v157 offset:54272
	ds_read_b128 v[216:219], v157 offset:55296
	ds_read_b128 v[220:223], v157 offset:56320
	global_load_lds_dwordx4 v[150:151], off
	s_add_i32 m0, s42, 0x2000
	s_add_u32 s40, s40, 0x40080
	v_lshl_add_u64 v[150:151], v[192:193], 0, s[20:21]
	s_addc_u32 s41, s41, 0
	s_add_i32 s42, s85, s60
	global_load_lds_dwordx4 v[150:151], off
	v_lshl_add_u64 v[150:151], s[40:41], 0, v[132:133]
	s_mov_b32 m0, s42
	s_nop 0
	global_load_lds_dwordx4 v[150:151], off
	v_lshl_add_u64 v[150:151], s[40:41], 0, v[136:137]
	s_add_i32 m0, s42, 0x2000
	s_nop 0
	global_load_lds_dwordx4 v[150:151], off
	s_waitcnt vmcnt(6)
	s_waitcnt lgkmcnt(0)
	s_barrier
	s_setprio 1
	s_waitcnt lgkmcnt(0)
	v_mfma_f32_16x16x32_bf16 v[60:63], v[146:149], v[188:191], v[60:63]
	v_mfma_f32_16x16x32_bf16 v[56:59], v[164:167], v[188:191], v[56:59]
	v_mfma_f32_16x16x32_bf16 v[44:47], v[146:149], v[200:203], v[44:47]
	v_mfma_f32_16x16x32_bf16 v[40:43], v[164:167], v[200:203], v[40:43]
	v_mfma_f32_16x16x32_bf16 v[28:31], v[146:149], v[208:211], v[28:31]
	v_mfma_f32_16x16x32_bf16 v[24:27], v[164:167], v[208:211], v[24:27]
	v_mfma_f32_16x16x32_bf16 v[12:15], v[146:149], v[216:219], v[12:15]
	v_mfma_f32_16x16x32_bf16 v[8:11], v[164:167], v[216:219], v[8:11]
	v_mfma_f32_16x16x32_bf16 v[60:63], v[160:163], v[196:199], v[60:63]
	v_mfma_f32_16x16x32_bf16 v[56:59], v[168:171], v[196:199], v[56:59]
	v_mfma_f32_16x16x32_bf16 v[44:47], v[160:163], v[204:207], v[44:47]
	v_mfma_f32_16x16x32_bf16 v[40:43], v[168:171], v[204:207], v[40:43]
	v_mfma_f32_16x16x32_bf16 v[28:31], v[160:163], v[212:215], v[28:31]
	v_mfma_f32_16x16x32_bf16 v[24:27], v[168:171], v[212:215], v[24:27]
	v_mfma_f32_16x16x32_bf16 v[12:15], v[160:163], v[220:223], v[12:15]
	v_mfma_f32_16x16x32_bf16 v[8:11], v[168:171], v[220:223], v[8:11]
	v_mfma_f32_16x16x32_bf16 v[52:55], v[172:175], v[188:191], v[52:55]
	v_mfma_f32_16x16x32_bf16 v[48:51], v[180:183], v[188:191], v[48:51]
	v_mfma_f32_16x16x32_bf16 v[36:39], v[172:175], v[200:203], v[36:39]
	v_mfma_f32_16x16x32_bf16 v[32:35], v[180:183], v[200:203], v[32:35]
	v_mfma_f32_16x16x32_bf16 v[20:23], v[172:175], v[208:211], v[20:23]
	v_mfma_f32_16x16x32_bf16 v[16:19], v[180:183], v[208:211], v[16:19]
	v_mfma_f32_16x16x32_bf16 v[4:7], v[172:175], v[216:219], v[4:7]
	v_mfma_f32_16x16x32_bf16 v[0:3], v[180:183], v[216:219], v[0:3]
	v_mfma_f32_16x16x32_bf16 v[52:55], v[176:179], v[196:199], v[52:55]
	v_mfma_f32_16x16x32_bf16 v[48:51], v[184:187], v[196:199], v[48:51]
	v_mfma_f32_16x16x32_bf16 v[36:39], v[176:179], v[204:207], v[36:39]
	v_mfma_f32_16x16x32_bf16 v[32:35], v[184:187], v[204:207], v[32:35]
	v_mfma_f32_16x16x32_bf16 v[20:23], v[176:179], v[212:215], v[20:23]
	v_mfma_f32_16x16x32_bf16 v[16:19], v[184:187], v[212:215], v[16:19]
	v_mfma_f32_16x16x32_bf16 v[4:7], v[176:179], v[220:223], v[4:7]
	v_mfma_f32_16x16x32_bf16 v[0:3], v[184:187], v[220:223], v[0:3]
	s_setprio 0
	s_barrier
	v_lshl_add_u64 v[224:225], v[224:225], 0, s[20:21]
	s_mov_b32 m0, s70
	s_nop 0
	global_load_lds_dwordx4 v[224:225], off
	v_lshl_add_u64 v[226:227], v[226:227], 0, s[20:21]
	s_mov_b32 m0, s71
	s_nop 0
	global_load_lds_dwordx4 v[226:227], off
	s_add_i32 s83, s83, 2
	s_add_u32 s0, s0, 0x100
	s_addc_u32 s1, s1, 0
	s_add_u32 s29, s29, 0x100
	s_addc_u32 s82, s82, 0
	s_cmp_gt_u32 s83, 13
	s_cbranch_scc0 .LBB0_1421
	s_and_b64 vcc, exec, s[22:23]
	s_cbranch_vccz .LBB0_1424
	s_barrier

.LBB0_1451:
	ds_read_b128 v[144:147], v159
	ds_read_b128 v[148:151], v159 offset:1024
	ds_read_b128 v[152:155], v159 offset:2048
	ds_read_b128 v[162:165], v159 offset:3072
	ds_read_b128 v[166:169], v160
	ds_read_b128 v[170:173], v160 offset:1024
	ds_read_b128 v[174:177], v160 offset:2048
	ds_read_b128 v[178:181], v160 offset:3072
	s_add_u32 s41, s58, 0xfffe0080
	s_addc_u32 s43, s59, -1
	s_cmp_eq_u32 s39, 4
	s_cselect_b32 s71, s1, s43
	s_cselect_b32 s70, s0, s41
	s_cselect_b32 s63, s45, s17
	s_cselect_b32 s62, s44, s15
	v_lshl_add_u64 v[216:217], s[58:59], 0, v[136:137]
	s_add_i32 m0, s83, 0xc000
	ds_read_b128 v[182:185], v161
	ds_read_b128 v[186:189], v161 offset:1024
	ds_read_b128 v[190:193], v161 offset:2048
	ds_read_b128 v[196:199], v161 offset:3072
	ds_read_b128 v[200:203], v161 offset:4096
	ds_read_b128 v[204:207], v161 offset:5120
	ds_read_b128 v[208:211], v161 offset:6144
	ds_read_b128 v[212:215], v161 offset:7168
	global_load_lds_dwordx4 v[216:217], off
	v_lshl_add_u64 v[216:217], s[58:59], 0, v[138:139]
	s_add_i32 m0, s83, 0xe000
	s_nop 0
	global_load_lds_dwordx4 v[216:217], off
	s_waitcnt vmcnt(8)
	s_waitcnt lgkmcnt(0)
	s_barrier
	s_setprio 1
	s_waitcnt lgkmcnt(0)
	v_mfma_f32_16x16x32_bf16 v[124:127], v[144:147], v[182:185], v[124:127]
	v_mfma_f32_16x16x32_bf16 v[120:123], v[152:155], v[182:185], v[120:123]
	v_mfma_f32_16x16x32_bf16 v[108:111], v[144:147], v[190:193], v[108:111]
	v_mfma_f32_16x16x32_bf16 v[104:107], v[152:155], v[190:193], v[104:107]
	v_mfma_f32_16x16x32_bf16 v[92:95], v[144:147], v[200:203], v[92:95]
	v_mfma_f32_16x16x32_bf16 v[88:91], v[152:155], v[200:203], v[88:91]
	v_mfma_f32_16x16x32_bf16 v[76:79], v[144:147], v[208:211], v[76:79]
	v_mfma_f32_16x16x32_bf16 v[72:75], v[152:155], v[208:211], v[72:75]
	v_mfma_f32_16x16x32_bf16 v[124:127], v[148:151], v[186:189], v[124:127]
	v_mfma_f32_16x16x32_bf16 v[120:123], v[162:165], v[186:189], v[120:123]
	v_mfma_f32_16x16x32_bf16 v[108:111], v[148:151], v[196:199], v[108:111]
	v_mfma_f32_16x16x32_bf16 v[104:107], v[162:165], v[196:199], v[104:107]
	v_mfma_f32_16x16x32_bf16 v[92:95], v[148:151], v[204:207], v[92:95]
	v_mfma_f32_16x16x32_bf16 v[88:91], v[162:165], v[204:207], v[88:91]
	v_mfma_f32_16x16x32_bf16 v[76:79], v[148:151], v[212:215], v[76:79]
	v_mfma_f32_16x16x32_bf16 v[72:75], v[162:165], v[212:215], v[72:75]
	v_mfma_f32_16x16x32_bf16 v[116:119], v[166:169], v[182:185], v[116:119]
	v_mfma_f32_16x16x32_bf16 v[112:115], v[174:177], v[182:185], v[112:115]
	v_mfma_f32_16x16x32_bf16 v[100:103], v[166:169], v[190:193], v[100:103]
	v_mfma_f32_16x16x32_bf16 v[96:99], v[174:177], v[190:193], v[96:99]
	v_mfma_f32_16x16x32_bf16 v[84:87], v[166:169], v[200:203], v[84:87]
	v_mfma_f32_16x16x32_bf16 v[80:83], v[174:177], v[200:203], v[80:83]
	v_mfma_f32_16x16x32_bf16 v[68:71], v[166:169], v[208:211], v[68:71]
	v_mfma_f32_16x16x32_bf16 v[64:67], v[174:177], v[208:211], v[64:67]
	v_mfma_f32_16x16x32_bf16 v[116:119], v[170:173], v[186:189], v[116:119]
	v_mfma_f32_16x16x32_bf16 v[112:115], v[178:181], v[186:189], v[112:115]
	v_mfma_f32_16x16x32_bf16 v[100:103], v[170:173], v[196:199], v[100:103]
	v_mfma_f32_16x16x32_bf16 v[96:99], v[178:181], v[196:199], v[96:99]
	v_mfma_f32_16x16x32_bf16 v[84:87], v[170:173], v[204:207], v[84:87]
	v_mfma_f32_16x16x32_bf16 v[80:83], v[178:181], v[204:207], v[80:83]
	v_mfma_f32_16x16x32_bf16 v[68:71], v[170:173], v[212:215], v[68:71]
	v_mfma_f32_16x16x32_bf16 v[64:67], v[178:181], v[212:215], v[64:67]
	s_setprio 0
	s_barrier
	s_add_i32 s41, s90, s80
	v_lshl_add_u64 v[216:217], s[62:63], 0, v[130:131]
	s_mov_b32 m0, s41
	ds_read_b128 v[182:185], v161 offset:16384
	ds_read_b128 v[186:189], v161 offset:17408
	ds_read_b128 v[190:193], v161 offset:18432
	ds_read_b128 v[196:199], v161 offset:19456
	ds_read_b128 v[200:203], v161 offset:20480
	ds_read_b128 v[204:207], v161 offset:21504
	ds_read_b128 v[208:211], v161 offset:22528
	ds_read_b128 v[212:215], v161 offset:23552
	global_load_lds_dwordx4 v[216:217], off
	s_add_i32 m0, s41, 0x2000
	s_add_u32 s94, s62, 0x20000
	v_lshl_add_u64 v[218:219], s[62:63], 0, v[134:135]
	s_addc_u32 s95, s63, 0
	s_add_i32 s41, s91, s80
	global_load_lds_dwordx4 v[218:219], off
	v_lshl_add_u64 v[220:221], s[94:95], 0, v[130:131]
	s_mov_b32 m0, s41
	v_lshl_add_u64 v[222:223], s[70:71], 0, v[132:133]
	global_load_lds_dwordx4 v[220:221], off
	v_lshl_add_u64 v[220:221], s[94:95], 0, v[134:135]
	s_add_i32 m0, s41, 0x2000
	s_nop 0
	global_load_lds_dwordx4 v[220:221], off
	v_lshl_add_u64 v[220:221], s[70:71], 0, v[128:129]
	s_waitcnt vmcnt(6)
	s_waitcnt lgkmcnt(0)
	s_barrier
	s_setprio 1
	s_waitcnt lgkmcnt(0)
	v_mfma_f32_16x16x32_bf16 v[60:63], v[144:147], v[182:185], v[60:63]
	v_mfma_f32_16x16x32_bf16 v[56:59], v[152:155], v[182:185], v[56:59]
	v_mfma_f32_16x16x32_bf16 v[44:47], v[144:147], v[190:193], v[44:47]
	v_mfma_f32_16x16x32_bf16 v[40:43], v[152:155], v[190:193], v[40:43]
	v_mfma_f32_16x16x32_bf16 v[28:31], v[144:147], v[200:203], v[28:31]
	v_mfma_f32_16x16x32_bf16 v[24:27], v[152:155], v[200:203], v[24:27]
	v_mfma_f32_16x16x32_bf16 v[12:15], v[144:147], v[208:211], v[12:15]
	v_mfma_f32_16x16x32_bf16 v[8:11], v[152:155], v[208:211], v[8:11]
	v_mfma_f32_16x16x32_bf16 v[60:63], v[148:151], v[186:189], v[60:63]
	v_mfma_f32_16x16x32_bf16 v[56:59], v[162:165], v[186:189], v[56:59]
	v_mfma_f32_16x16x32_bf16 v[44:47], v[148:151], v[196:199], v[44:47]
	v_mfma_f32_16x16x32_bf16 v[40:43], v[162:165], v[196:199], v[40:43]
	v_mfma_f32_16x16x32_bf16 v[28:31], v[148:151], v[204:207], v[28:31]
	v_mfma_f32_16x16x32_bf16 v[24:27], v[162:165], v[204:207], v[24:27]
	v_mfma_f32_16x16x32_bf16 v[12:15], v[148:151], v[212:215], v[12:15]
	v_mfma_f32_16x16x32_bf16 v[8:11], v[162:165], v[212:215], v[8:11]
	v_mfma_f32_16x16x32_bf16 v[52:55], v[166:169], v[182:185], v[52:55]
	v_mfma_f32_16x16x32_bf16 v[48:51], v[174:177], v[182:185], v[48:51]
	v_mfma_f32_16x16x32_bf16 v[36:39], v[166:169], v[190:193], v[36:39]
	v_mfma_f32_16x16x32_bf16 v[32:35], v[174:177], v[190:193], v[32:35]
	v_mfma_f32_16x16x32_bf16 v[20:23], v[166:169], v[200:203], v[20:23]
	v_mfma_f32_16x16x32_bf16 v[16:19], v[174:177], v[200:203], v[16:19]
	v_mfma_f32_16x16x32_bf16 v[4:7], v[166:169], v[208:211], v[4:7]
	v_mfma_f32_16x16x32_bf16 v[0:3], v[174:177], v[208:211], v[0:3]
	v_mfma_f32_16x16x32_bf16 v[52:55], v[170:173], v[186:189], v[52:55]
	v_mfma_f32_16x16x32_bf16 v[48:51], v[178:181], v[186:189], v[48:51]
	v_mfma_f32_16x16x32_bf16 v[36:39], v[170:173], v[196:199], v[36:39]
	v_mfma_f32_16x16x32_bf16 v[32:35], v[178:181], v[196:199], v[32:35]
	v_mfma_f32_16x16x32_bf16 v[20:23], v[170:173], v[204:207], v[20:23]
	v_mfma_f32_16x16x32_bf16 v[16:19], v[178:181], v[204:207], v[16:19]
	v_mfma_f32_16x16x32_bf16 v[4:7], v[170:173], v[212:215], v[4:7]
	v_mfma_f32_16x16x32_bf16 v[0:3], v[178:181], v[212:215], v[0:3]
	s_setprio 0
	s_barrier
	s_add_i32 s41, 0, 0x18000
	s_add_i32 s43, 0, 0x1c000
	v_add_u32_e32 v162, s41, v157
	v_add_u32_e32 v178, s43, v157
	ds_read_b128 v[144:147], v162
	ds_read_b128 v[148:151], v162 offset:1024
	ds_read_b128 v[152:155], v162 offset:2048
	ds_read_b128 v[162:165], v162 offset:3072
	ds_read_b128 v[166:169], v178
	ds_read_b128 v[170:173], v178 offset:1024
	ds_read_b128 v[174:177], v178 offset:2048
	ds_read_b128 v[178:181], v178 offset:3072
	s_add_u32 s70, s70, 0x20000
	s_addc_u32 s71, s71, 0
	v_lshl_add_u64 v[224:225], s[70:71], 0, v[128:129]
	ds_read_b128 v[182:185], v161 offset:32768
	ds_read_b128 v[186:189], v161 offset:33792
	ds_read_b128 v[190:193], v161 offset:34816
	ds_read_b128 v[196:199], v161 offset:35840
	ds_read_b128 v[200:203], v161 offset:36864
	ds_read_b128 v[204:207], v161 offset:37888
	ds_read_b128 v[208:211], v161 offset:38912
	ds_read_b128 v[212:215], v161 offset:39936
	s_mov_b32 m0, s83
	s_nop 0
	global_load_lds_dwordx4 v[220:221], off
	s_mov_b32 m0, s84
	s_nop 0
	global_load_lds_dwordx4 v[222:223], off
	s_mov_b32 m0, s85
	s_nop 0
	global_load_lds_dwordx4 v[224:225], off
	v_lshl_add_u64 v[224:225], s[70:71], 0, v[132:133]
	s_mov_b32 m0, s86
	s_nop 0
	global_load_lds_dwordx4 v[224:225], off
	s_waitcnt vmcnt(8)
	s_waitcnt lgkmcnt(0)
	s_barrier
	s_setprio 1
	s_waitcnt lgkmcnt(0)
	v_mfma_f32_16x16x32_bf16 v[124:127], v[144:147], v[182:185], v[124:127]
	v_mfma_f32_16x16x32_bf16 v[120:123], v[152:155], v[182:185], v[120:123]
	v_mfma_f32_16x16x32_bf16 v[108:111], v[144:147], v[190:193], v[108:111]
	v_mfma_f32_16x16x32_bf16 v[104:107], v[152:155], v[190:193], v[104:107]
	v_mfma_f32_16x16x32_bf16 v[92:95], v[144:147], v[200:203], v[92:95]
	v_mfma_f32_16x16x32_bf16 v[88:91], v[152:155], v[200:203], v[88:91]
	v_mfma_f32_16x16x32_bf16 v[76:79], v[144:147], v[208:211], v[76:79]
	v_mfma_f32_16x16x32_bf16 v[72:75], v[152:155], v[208:211], v[72:75]
	v_mfma_f32_16x16x32_bf16 v[124:127], v[148:151], v[186:189], v[124:127]
	v_mfma_f32_16x16x32_bf16 v[120:123], v[162:165], v[186:189], v[120:123]
	v_mfma_f32_16x16x32_bf16 v[108:111], v[148:151], v[196:199], v[108:111]
	v_mfma_f32_16x16x32_bf16 v[104:107], v[162:165], v[196:199], v[104:107]
	v_mfma_f32_16x16x32_bf16 v[92:95], v[148:151], v[204:207], v[92:95]
	v_mfma_f32_16x16x32_bf16 v[88:91], v[162:165], v[204:207], v[88:91]
	v_mfma_f32_16x16x32_bf16 v[76:79], v[148:151], v[212:215], v[76:79]
	v_mfma_f32_16x16x32_bf16 v[72:75], v[162:165], v[212:215], v[72:75]
	v_mfma_f32_16x16x32_bf16 v[116:119], v[166:169], v[182:185], v[116:119]
	v_mfma_f32_16x16x32_bf16 v[112:115], v[174:177], v[182:185], v[112:115]
	v_mfma_f32_16x16x32_bf16 v[100:103], v[166:169], v[190:193], v[100:103]
	v_mfma_f32_16x16x32_bf16 v[96:99], v[174:177], v[190:193], v[96:99]
	v_mfma_f32_16x16x32_bf16 v[84:87], v[166:169], v[200:203], v[84:87]
	v_mfma_f32_16x16x32_bf16 v[80:83], v[174:177], v[200:203], v[80:83]
	v_mfma_f32_16x16x32_bf16 v[68:71], v[166:169], v[208:211], v[68:71]
	v_mfma_f32_16x16x32_bf16 v[64:67], v[174:177], v[208:211], v[64:67]
	v_mfma_f32_16x16x32_bf16 v[116:119], v[170:173], v[186:189], v[116:119]
	v_mfma_f32_16x16x32_bf16 v[112:115], v[178:181], v[186:189], v[112:115]
	v_mfma_f32_16x16x32_bf16 v[100:103], v[170:173], v[196:199], v[100:103]
	v_mfma_f32_16x16x32_bf16 v[96:99], v[178:181], v[196:199], v[96:99]
	v_mfma_f32_16x16x32_bf16 v[84:87], v[170:173], v[204:207], v[84:87]
	v_mfma_f32_16x16x32_bf16 v[80:83], v[178:181], v[204:207], v[80:83]
	v_mfma_f32_16x16x32_bf16 v[68:71], v[170:173], v[212:215], v[68:71]
	v_mfma_f32_16x16x32_bf16 v[64:67], v[178:181], v[212:215], v[64:67]
	s_setprio 0
	s_barrier
	s_add_i32 s41, s41, s80
	v_lshl_add_u64 v[216:217], v[216:217], 0, s[26:27]
	s_mov_b32 m0, s41
	ds_read_b128 v[182:185], v161 offset:49152
	ds_read_b128 v[186:189], v161 offset:50176
	ds_read_b128 v[190:193], v161 offset:51200
	ds_read_b128 v[196:199], v161 offset:52224
	ds_read_b128 v[200:203], v161 offset:53248
	ds_read_b128 v[204:207], v161 offset:54272
	ds_read_b128 v[208:211], v161 offset:55296
	ds_read_b128 v[212:215], v161 offset:56320
	global_load_lds_dwordx4 v[216:217], off
	s_add_i32 m0, s41, 0x2000
	s_add_u32 s62, s62, 0x20080
	v_lshl_add_u64 v[216:217], v[218:219], 0, s[26:27]
	s_addc_u32 s63, s63, 0
	s_add_i32 s41, s43, s80
	global_load_lds_dwordx4 v[216:217], off
	v_lshl_add_u64 v[216:217], s[62:63], 0, v[130:131]
	s_mov_b32 m0, s41
	s_nop 0
	global_load_lds_dwordx4 v[216:217], off
	v_lshl_add_u64 v[216:217], s[62:63], 0, v[134:135]
	s_add_i32 m0, s41, 0x2000
	s_nop 0
	global_load_lds_dwordx4 v[216:217], off
	s_waitcnt vmcnt(6)
	s_waitcnt lgkmcnt(0)
	s_barrier
	s_setprio 1
	s_waitcnt lgkmcnt(0)
	v_mfma_f32_16x16x32_bf16 v[60:63], v[144:147], v[182:185], v[60:63]
	v_mfma_f32_16x16x32_bf16 v[56:59], v[152:155], v[182:185], v[56:59]
	v_mfma_f32_16x16x32_bf16 v[44:47], v[144:147], v[190:193], v[44:47]
	v_mfma_f32_16x16x32_bf16 v[40:43], v[152:155], v[190:193], v[40:43]
	v_mfma_f32_16x16x32_bf16 v[28:31], v[144:147], v[200:203], v[28:31]
	v_mfma_f32_16x16x32_bf16 v[24:27], v[152:155], v[200:203], v[24:27]
	v_mfma_f32_16x16x32_bf16 v[12:15], v[144:147], v[208:211], v[12:15]
	v_mfma_f32_16x16x32_bf16 v[8:11], v[152:155], v[208:211], v[8:11]
	v_mfma_f32_16x16x32_bf16 v[60:63], v[148:151], v[186:189], v[60:63]
	v_mfma_f32_16x16x32_bf16 v[56:59], v[162:165], v[186:189], v[56:59]
	v_mfma_f32_16x16x32_bf16 v[44:47], v[148:151], v[196:199], v[44:47]
	v_mfma_f32_16x16x32_bf16 v[40:43], v[162:165], v[196:199], v[40:43]
	v_mfma_f32_16x16x32_bf16 v[28:31], v[148:151], v[204:207], v[28:31]
	v_mfma_f32_16x16x32_bf16 v[24:27], v[162:165], v[204:207], v[24:27]
	v_mfma_f32_16x16x32_bf16 v[12:15], v[148:151], v[212:215], v[12:15]
	v_mfma_f32_16x16x32_bf16 v[8:11], v[162:165], v[212:215], v[8:11]
	v_mfma_f32_16x16x32_bf16 v[52:55], v[166:169], v[182:185], v[52:55]
	v_mfma_f32_16x16x32_bf16 v[48:51], v[174:177], v[182:185], v[48:51]
	v_mfma_f32_16x16x32_bf16 v[36:39], v[166:169], v[190:193], v[36:39]
	v_mfma_f32_16x16x32_bf16 v[32:35], v[174:177], v[190:193], v[32:35]
	v_mfma_f32_16x16x32_bf16 v[20:23], v[166:169], v[200:203], v[20:23]
	v_mfma_f32_16x16x32_bf16 v[16:19], v[174:177], v[200:203], v[16:19]
	v_mfma_f32_16x16x32_bf16 v[4:7], v[166:169], v[208:211], v[4:7]
	v_mfma_f32_16x16x32_bf16 v[0:3], v[174:177], v[208:211], v[0:3]
	v_mfma_f32_16x16x32_bf16 v[52:55], v[170:173], v[186:189], v[52:55]
	v_mfma_f32_16x16x32_bf16 v[48:51], v[178:181], v[186:189], v[48:51]
	v_mfma_f32_16x16x32_bf16 v[36:39], v[170:173], v[196:199], v[36:39]
	v_mfma_f32_16x16x32_bf16 v[32:35], v[178:181], v[196:199], v[32:35]
	v_mfma_f32_16x16x32_bf16 v[20:23], v[170:173], v[204:207], v[20:23]
	v_mfma_f32_16x16x32_bf16 v[16:19], v[178:181], v[204:207], v[16:19]
	v_mfma_f32_16x16x32_bf16 v[4:7], v[170:173], v[212:215], v[4:7]
	v_mfma_f32_16x16x32_bf16 v[0:3], v[178:181], v[212:215], v[0:3]
	s_setprio 0
	s_barrier
	v_lshl_add_u64 v[220:221], v[220:221], 0, s[26:27]
	s_mov_b32 m0, s87
	s_nop 0
	global_load_lds_dwordx4 v[220:221], off
	v_lshl_add_u64 v[222:223], v[222:223], 0, s[26:27]
	s_mov_b32 m0, s88
	s_nop 0
	global_load_lds_dwordx4 v[222:223], off
	s_add_i32 s39, s39, 2
	s_add_u32 s58, s58, 0x100
	s_addc_u32 s59, s59, 0
	s_add_u32 s15, s15, 0x100
	s_addc_u32 s17, s17, 0
	s_cmp_gt_u32 s39, 5
	s_cbranch_scc0 .LBB0_1451
	s_and_b64 vcc, exec, s[28:29]
	s_cbranch_vccz .LBB0_1454
	s_barrier

.LBB0_1625:
	ds_read_b128 v[144:147], v151
	ds_read_b128 v[156:159], v151 offset:1024
	ds_read_b128 v[160:163], v151 offset:2048
	ds_read_b128 v[164:167], v151 offset:3072
	ds_read_b128 v[168:171], v152
	ds_read_b128 v[172:175], v152 offset:1024
	ds_read_b128 v[176:179], v152 offset:2048
	ds_read_b128 v[180:183], v152 offset:3072
	s_add_u32 s42, s40, 0xfffc0080
	s_addc_u32 s43, s41, -1
	s_cmp_eq_u32 s87, 12
	s_cselect_b32 s45, s31, s43
	s_cselect_b32 s44, s39, s42
	s_cselect_b32 s43, s29, s86
	s_cselect_b32 s42, s84, s85
	v_lshl_add_u64 v[192:193], s[40:41], 0, v[136:137]
	s_add_i32 m0, s63, 0xc000
	ds_read_b128 v[184:187], v153
	ds_read_b128 v[188:191], v153 offset:1024
	ds_read_b128 v[196:199], v153 offset:2048
	ds_read_b128 v[200:203], v153 offset:3072
	ds_read_b128 v[204:207], v153 offset:4096
	ds_read_b128 v[208:211], v153 offset:5120
	ds_read_b128 v[212:215], v153 offset:6144
	ds_read_b128 v[216:219], v153 offset:7168
	global_load_lds_dwordx4 v[192:193], off
	v_lshl_add_u64 v[192:193], s[40:41], 0, v[138:139]
	s_add_i32 m0, s63, 0xe000
	s_nop 0
	global_load_lds_dwordx4 v[192:193], off
	s_waitcnt vmcnt(8)
	s_waitcnt lgkmcnt(0)
	s_barrier
	s_setprio 1
	s_waitcnt lgkmcnt(0)
	v_mfma_f32_16x16x32_bf16 v[124:127], v[144:147], v[184:187], v[124:127]
	v_mfma_f32_16x16x32_bf16 v[120:123], v[160:163], v[184:187], v[120:123]
	v_mfma_f32_16x16x32_bf16 v[108:111], v[144:147], v[196:199], v[108:111]
	v_mfma_f32_16x16x32_bf16 v[104:107], v[160:163], v[196:199], v[104:107]
	v_mfma_f32_16x16x32_bf16 v[92:95], v[144:147], v[204:207], v[92:95]
	v_mfma_f32_16x16x32_bf16 v[88:91], v[160:163], v[204:207], v[88:91]
	v_mfma_f32_16x16x32_bf16 v[76:79], v[144:147], v[212:215], v[76:79]
	v_mfma_f32_16x16x32_bf16 v[72:75], v[160:163], v[212:215], v[72:75]
	v_mfma_f32_16x16x32_bf16 v[124:127], v[156:159], v[188:191], v[124:127]
	v_mfma_f32_16x16x32_bf16 v[120:123], v[164:167], v[188:191], v[120:123]
	v_mfma_f32_16x16x32_bf16 v[108:111], v[156:159], v[200:203], v[108:111]
	v_mfma_f32_16x16x32_bf16 v[104:107], v[164:167], v[200:203], v[104:107]
	v_mfma_f32_16x16x32_bf16 v[92:95], v[156:159], v[208:211], v[92:95]
	v_mfma_f32_16x16x32_bf16 v[88:91], v[164:167], v[208:211], v[88:91]
	v_mfma_f32_16x16x32_bf16 v[76:79], v[156:159], v[216:219], v[76:79]
	v_mfma_f32_16x16x32_bf16 v[72:75], v[164:167], v[216:219], v[72:75]
	v_mfma_f32_16x16x32_bf16 v[116:119], v[168:171], v[184:187], v[116:119]
	v_mfma_f32_16x16x32_bf16 v[112:115], v[176:179], v[184:187], v[112:115]
	v_mfma_f32_16x16x32_bf16 v[100:103], v[168:171], v[196:199], v[100:103]
	v_mfma_f32_16x16x32_bf16 v[96:99], v[176:179], v[196:199], v[96:99]
	v_mfma_f32_16x16x32_bf16 v[84:87], v[168:171], v[204:207], v[84:87]
	v_mfma_f32_16x16x32_bf16 v[80:83], v[176:179], v[204:207], v[80:83]
	v_mfma_f32_16x16x32_bf16 v[68:71], v[168:171], v[212:215], v[68:71]
	v_mfma_f32_16x16x32_bf16 v[64:67], v[176:179], v[212:215], v[64:67]
	v_mfma_f32_16x16x32_bf16 v[116:119], v[172:175], v[188:191], v[116:119]
	v_mfma_f32_16x16x32_bf16 v[112:115], v[180:183], v[188:191], v[112:115]
	v_mfma_f32_16x16x32_bf16 v[100:103], v[172:175], v[200:203], v[100:103]
	v_mfma_f32_16x16x32_bf16 v[96:99], v[180:183], v[200:203], v[96:99]
	v_mfma_f32_16x16x32_bf16 v[84:87], v[172:175], v[208:211], v[84:87]
	v_mfma_f32_16x16x32_bf16 v[80:83], v[180:183], v[208:211], v[80:83]
	v_mfma_f32_16x16x32_bf16 v[68:71], v[172:175], v[216:219], v[68:71]
	v_mfma_f32_16x16x32_bf16 v[64:67], v[180:183], v[216:219], v[64:67]
	s_setprio 0
	s_barrier
	s_add_i32 s88, s81, s62
	v_lshl_add_u64 v[192:193], s[42:43], 0, v[130:131]
	s_mov_b32 m0, s88
	ds_read_b128 v[184:187], v153 offset:16384
	ds_read_b128 v[188:191], v153 offset:17408
	ds_read_b128 v[196:199], v153 offset:18432
	ds_read_b128 v[200:203], v153 offset:19456
	ds_read_b128 v[204:207], v153 offset:20480
	ds_read_b128 v[208:211], v153 offset:21504
	ds_read_b128 v[212:215], v153 offset:22528
	ds_read_b128 v[216:219], v153 offset:23552
	global_load_lds_dwordx4 v[192:193], off
	s_add_i32 m0, s88, 0x2000
	s_add_u32 s88, s42, 0x40000
	v_lshl_add_u64 v[220:221], s[42:43], 0, v[134:135]
	s_addc_u32 s89, s43, 0
	s_add_i32 s90, s82, s62
	global_load_lds_dwordx4 v[220:221], off
	v_lshl_add_u64 v[222:223], s[88:89], 0, v[130:131]
	s_mov_b32 m0, s90
	v_lshl_add_u64 v[224:225], s[44:45], 0, v[132:133]
	global_load_lds_dwordx4 v[222:223], off
	v_lshl_add_u64 v[222:223], s[88:89], 0, v[134:135]
	s_add_i32 m0, s90, 0x2000
	s_nop 0
	global_load_lds_dwordx4 v[222:223], off
	v_lshl_add_u64 v[222:223], s[44:45], 0, v[128:129]
	s_waitcnt vmcnt(6)
	s_waitcnt lgkmcnt(0)
	s_barrier
	s_setprio 1
	s_waitcnt lgkmcnt(0)
	v_mfma_f32_16x16x32_bf16 v[60:63], v[144:147], v[184:187], v[60:63]
	v_mfma_f32_16x16x32_bf16 v[56:59], v[160:163], v[184:187], v[56:59]
	v_mfma_f32_16x16x32_bf16 v[44:47], v[144:147], v[196:199], v[44:47]
	v_mfma_f32_16x16x32_bf16 v[40:43], v[160:163], v[196:199], v[40:43]
	v_mfma_f32_16x16x32_bf16 v[28:31], v[144:147], v[204:207], v[28:31]
	v_mfma_f32_16x16x32_bf16 v[24:27], v[160:163], v[204:207], v[24:27]
	v_mfma_f32_16x16x32_bf16 v[12:15], v[144:147], v[212:215], v[12:15]
	v_mfma_f32_16x16x32_bf16 v[8:11], v[160:163], v[212:215], v[8:11]
	v_mfma_f32_16x16x32_bf16 v[60:63], v[156:159], v[188:191], v[60:63]
	v_mfma_f32_16x16x32_bf16 v[56:59], v[164:167], v[188:191], v[56:59]
	v_mfma_f32_16x16x32_bf16 v[44:47], v[156:159], v[200:203], v[44:47]
	v_mfma_f32_16x16x32_bf16 v[40:43], v[164:167], v[200:203], v[40:43]
	v_mfma_f32_16x16x32_bf16 v[28:31], v[156:159], v[208:211], v[28:31]
	v_mfma_f32_16x16x32_bf16 v[24:27], v[164:167], v[208:211], v[24:27]
	v_mfma_f32_16x16x32_bf16 v[12:15], v[156:159], v[216:219], v[12:15]
	v_mfma_f32_16x16x32_bf16 v[8:11], v[164:167], v[216:219], v[8:11]
	v_mfma_f32_16x16x32_bf16 v[52:55], v[168:171], v[184:187], v[52:55]
	v_mfma_f32_16x16x32_bf16 v[48:51], v[176:179], v[184:187], v[48:51]
	v_mfma_f32_16x16x32_bf16 v[36:39], v[168:171], v[196:199], v[36:39]
	v_mfma_f32_16x16x32_bf16 v[32:35], v[176:179], v[196:199], v[32:35]
	v_mfma_f32_16x16x32_bf16 v[20:23], v[168:171], v[204:207], v[20:23]
	v_mfma_f32_16x16x32_bf16 v[16:19], v[176:179], v[204:207], v[16:19]
	v_mfma_f32_16x16x32_bf16 v[4:7], v[168:171], v[212:215], v[4:7]
	v_mfma_f32_16x16x32_bf16 v[0:3], v[176:179], v[212:215], v[0:3]
	v_mfma_f32_16x16x32_bf16 v[52:55], v[172:175], v[188:191], v[52:55]
	v_mfma_f32_16x16x32_bf16 v[48:51], v[180:183], v[188:191], v[48:51]
	v_mfma_f32_16x16x32_bf16 v[36:39], v[172:175], v[200:203], v[36:39]
	v_mfma_f32_16x16x32_bf16 v[32:35], v[180:183], v[200:203], v[32:35]
	v_mfma_f32_16x16x32_bf16 v[20:23], v[172:175], v[208:211], v[20:23]
	v_mfma_f32_16x16x32_bf16 v[16:19], v[180:183], v[208:211], v[16:19]
	v_mfma_f32_16x16x32_bf16 v[4:7], v[172:175], v[216:219], v[4:7]
	v_mfma_f32_16x16x32_bf16 v[0:3], v[180:183], v[216:219], v[0:3]
	s_setprio 0
	s_barrier
	s_add_i32 s88, 0, 0x18000
	v_add_u32_e32 v155, s88, v149
	s_add_i32 s89, 0, 0x1c000
	ds_read_b128 v[144:147], v155
	ds_read_b128 v[156:159], v155 offset:1024
	ds_read_b128 v[160:163], v155 offset:2048
	ds_read_b128 v[164:167], v155 offset:3072
	v_add_u32_e32 v155, s89, v149
	ds_read_b128 v[168:171], v155
	ds_read_b128 v[172:175], v155 offset:1024
	ds_read_b128 v[176:179], v155 offset:2048
	ds_read_b128 v[180:183], v155 offset:3072
	s_add_u32 s44, s44, 0x40000
	s_addc_u32 s45, s45, 0
	v_lshl_add_u64 v[226:227], s[44:45], 0, v[128:129]
	ds_read_b128 v[184:187], v153 offset:32768
	ds_read_b128 v[188:191], v153 offset:33792
	ds_read_b128 v[196:199], v153 offset:34816
	ds_read_b128 v[200:203], v153 offset:35840
	ds_read_b128 v[204:207], v153 offset:36864
	ds_read_b128 v[208:211], v153 offset:37888
	ds_read_b128 v[212:215], v153 offset:38912
	ds_read_b128 v[216:219], v153 offset:39936
	s_mov_b32 m0, s63
	s_nop 0
	global_load_lds_dwordx4 v[222:223], off
	s_mov_b32 m0, s70
	s_nop 0
	global_load_lds_dwordx4 v[224:225], off
	s_mov_b32 m0, s71
	s_nop 0
	global_load_lds_dwordx4 v[226:227], off
	v_lshl_add_u64 v[226:227], s[44:45], 0, v[132:133]
	s_mov_b32 m0, s72
	s_nop 0
	global_load_lds_dwordx4 v[226:227], off
	s_waitcnt vmcnt(8)
	s_waitcnt lgkmcnt(0)
	s_barrier
	s_setprio 1
	s_waitcnt lgkmcnt(0)
	v_mfma_f32_16x16x32_bf16 v[124:127], v[144:147], v[184:187], v[124:127]
	v_mfma_f32_16x16x32_bf16 v[120:123], v[160:163], v[184:187], v[120:123]
	v_mfma_f32_16x16x32_bf16 v[108:111], v[144:147], v[196:199], v[108:111]
	v_mfma_f32_16x16x32_bf16 v[104:107], v[160:163], v[196:199], v[104:107]
	v_mfma_f32_16x16x32_bf16 v[92:95], v[144:147], v[204:207], v[92:95]
	v_mfma_f32_16x16x32_bf16 v[88:91], v[160:163], v[204:207], v[88:91]
	v_mfma_f32_16x16x32_bf16 v[76:79], v[144:147], v[212:215], v[76:79]
	v_mfma_f32_16x16x32_bf16 v[72:75], v[160:163], v[212:215], v[72:75]
	v_mfma_f32_16x16x32_bf16 v[124:127], v[156:159], v[188:191], v[124:127]
	v_mfma_f32_16x16x32_bf16 v[120:123], v[164:167], v[188:191], v[120:123]
	v_mfma_f32_16x16x32_bf16 v[108:111], v[156:159], v[200:203], v[108:111]
	v_mfma_f32_16x16x32_bf16 v[104:107], v[164:167], v[200:203], v[104:107]
	v_mfma_f32_16x16x32_bf16 v[92:95], v[156:159], v[208:211], v[92:95]
	v_mfma_f32_16x16x32_bf16 v[88:91], v[164:167], v[208:211], v[88:91]
	v_mfma_f32_16x16x32_bf16 v[76:79], v[156:159], v[216:219], v[76:79]
	v_mfma_f32_16x16x32_bf16 v[72:75], v[164:167], v[216:219], v[72:75]
	v_mfma_f32_16x16x32_bf16 v[116:119], v[168:171], v[184:187], v[116:119]
	v_mfma_f32_16x16x32_bf16 v[112:115], v[176:179], v[184:187], v[112:115]
	v_mfma_f32_16x16x32_bf16 v[100:103], v[168:171], v[196:199], v[100:103]
	v_mfma_f32_16x16x32_bf16 v[96:99], v[176:179], v[196:199], v[96:99]
	v_mfma_f32_16x16x32_bf16 v[84:87], v[168:171], v[204:207], v[84:87]
	v_mfma_f32_16x16x32_bf16 v[80:83], v[176:179], v[204:207], v[80:83]
	v_mfma_f32_16x16x32_bf16 v[68:71], v[168:171], v[212:215], v[68:71]
	v_mfma_f32_16x16x32_bf16 v[64:67], v[176:179], v[212:215], v[64:67]
	v_mfma_f32_16x16x32_bf16 v[116:119], v[172:175], v[188:191], v[116:119]
	v_mfma_f32_16x16x32_bf16 v[112:115], v[180:183], v[188:191], v[112:115]
	v_mfma_f32_16x16x32_bf16 v[100:103], v[172:175], v[200:203], v[100:103]
	v_mfma_f32_16x16x32_bf16 v[96:99], v[180:183], v[200:203], v[96:99]
	v_mfma_f32_16x16x32_bf16 v[84:87], v[172:175], v[208:211], v[84:87]
	v_mfma_f32_16x16x32_bf16 v[80:83], v[180:183], v[208:211], v[80:83]
	v_mfma_f32_16x16x32_bf16 v[68:71], v[172:175], v[216:219], v[68:71]
	v_mfma_f32_16x16x32_bf16 v[64:67], v[180:183], v[216:219], v[64:67]
	s_setprio 0
	s_barrier
	s_add_i32 s44, s88, s62
	v_lshl_add_u64 v[192:193], v[192:193], 0, s[24:25]
	s_mov_b32 m0, s44
	ds_read_b128 v[184:187], v153 offset:49152
	ds_read_b128 v[188:191], v153 offset:50176
	ds_read_b128 v[196:199], v153 offset:51200
	ds_read_b128 v[200:203], v153 offset:52224
	ds_read_b128 v[204:207], v153 offset:53248
	ds_read_b128 v[208:211], v153 offset:54272
	ds_read_b128 v[212:215], v153 offset:55296
	ds_read_b128 v[216:219], v153 offset:56320
	global_load_lds_dwordx4 v[192:193], off
	s_add_i32 m0, s44, 0x2000
	s_add_u32 s42, s42, 0x40080
	v_lshl_add_u64 v[192:193], v[220:221], 0, s[24:25]
	s_addc_u32 s43, s43, 0
	s_add_i32 s44, s89, s62
	global_load_lds_dwordx4 v[192:193], off
	v_lshl_add_u64 v[192:193], s[42:43], 0, v[130:131]
	s_mov_b32 m0, s44
	s_nop 0
	global_load_lds_dwordx4 v[192:193], off
	v_lshl_add_u64 v[192:193], s[42:43], 0, v[134:135]
	s_add_i32 m0, s44, 0x2000
	s_nop 0
	global_load_lds_dwordx4 v[192:193], off
	s_waitcnt vmcnt(6)
	s_waitcnt lgkmcnt(0)
	s_barrier
	s_setprio 1
	s_waitcnt lgkmcnt(0)
	v_mfma_f32_16x16x32_bf16 v[60:63], v[144:147], v[184:187], v[60:63]
	v_mfma_f32_16x16x32_bf16 v[56:59], v[160:163], v[184:187], v[56:59]
	v_mfma_f32_16x16x32_bf16 v[44:47], v[144:147], v[196:199], v[44:47]
	v_mfma_f32_16x16x32_bf16 v[40:43], v[160:163], v[196:199], v[40:43]
	v_mfma_f32_16x16x32_bf16 v[28:31], v[144:147], v[204:207], v[28:31]
	v_mfma_f32_16x16x32_bf16 v[24:27], v[160:163], v[204:207], v[24:27]
	v_mfma_f32_16x16x32_bf16 v[12:15], v[144:147], v[212:215], v[12:15]
	v_mfma_f32_16x16x32_bf16 v[8:11], v[160:163], v[212:215], v[8:11]
	v_mfma_f32_16x16x32_bf16 v[60:63], v[156:159], v[188:191], v[60:63]
	v_mfma_f32_16x16x32_bf16 v[56:59], v[164:167], v[188:191], v[56:59]
	v_mfma_f32_16x16x32_bf16 v[44:47], v[156:159], v[200:203], v[44:47]
	v_mfma_f32_16x16x32_bf16 v[40:43], v[164:167], v[200:203], v[40:43]
	v_mfma_f32_16x16x32_bf16 v[28:31], v[156:159], v[208:211], v[28:31]
	v_mfma_f32_16x16x32_bf16 v[24:27], v[164:167], v[208:211], v[24:27]
	v_mfma_f32_16x16x32_bf16 v[12:15], v[156:159], v[216:219], v[12:15]
	v_mfma_f32_16x16x32_bf16 v[8:11], v[164:167], v[216:219], v[8:11]
	v_mfma_f32_16x16x32_bf16 v[52:55], v[168:171], v[184:187], v[52:55]
	v_mfma_f32_16x16x32_bf16 v[48:51], v[176:179], v[184:187], v[48:51]
	v_mfma_f32_16x16x32_bf16 v[36:39], v[168:171], v[196:199], v[36:39]
	v_mfma_f32_16x16x32_bf16 v[32:35], v[176:179], v[196:199], v[32:35]
	v_mfma_f32_16x16x32_bf16 v[20:23], v[168:171], v[204:207], v[20:23]
	v_mfma_f32_16x16x32_bf16 v[16:19], v[176:179], v[204:207], v[16:19]
	v_mfma_f32_16x16x32_bf16 v[4:7], v[168:171], v[212:215], v[4:7]
	v_mfma_f32_16x16x32_bf16 v[0:3], v[176:179], v[212:215], v[0:3]
	v_mfma_f32_16x16x32_bf16 v[52:55], v[172:175], v[188:191], v[52:55]
	v_mfma_f32_16x16x32_bf16 v[48:51], v[180:183], v[188:191], v[48:51]
	v_mfma_f32_16x16x32_bf16 v[36:39], v[172:175], v[200:203], v[36:39]
	v_mfma_f32_16x16x32_bf16 v[32:35], v[180:183], v[200:203], v[32:35]
	v_mfma_f32_16x16x32_bf16 v[20:23], v[172:175], v[208:211], v[20:23]
	v_mfma_f32_16x16x32_bf16 v[16:19], v[180:183], v[208:211], v[16:19]
	v_mfma_f32_16x16x32_bf16 v[4:7], v[172:175], v[216:219], v[4:7]
	v_mfma_f32_16x16x32_bf16 v[0:3], v[180:183], v[216:219], v[0:3]
	s_setprio 0
	s_barrier
	v_lshl_add_u64 v[222:223], v[222:223], 0, s[24:25]
	s_mov_b32 m0, s78
	s_nop 0
	global_load_lds_dwordx4 v[222:223], off
	v_lshl_add_u64 v[224:225], v[224:225], 0, s[24:25]
	s_mov_b32 m0, s79
	s_nop 0
	global_load_lds_dwordx4 v[224:225], off
	s_add_i32 s87, s87, 2
	s_add_u32 s40, s40, 0x100
	s_addc_u32 s41, s41, 0
	s_add_u32 s85, s85, 0x100
	s_addc_u32 s86, s86, 0
	s_cmp_gt_u32 s87, 13
	s_cbranch_scc0 .LBB0_1625
	s_and_b64 vcc, exec, s[26:27]
	s_cbranch_vccz .LBB0_1628
	s_barrier

.LBB0_1709:
	ds_read_b128 v[154:157], v149
	ds_read_b128 v[158:161], v149 offset:1024
	ds_read_b128 v[162:165], v149 offset:2048
	ds_read_b128 v[166:169], v149 offset:3072
	ds_read_b128 v[170:173], v150
	ds_read_b128 v[174:177], v150 offset:1024
	ds_read_b128 v[178:181], v150 offset:2048
	ds_read_b128 v[182:185], v150 offset:3072
	s_add_u32 s38, s36, 0xfffc0080
	s_addc_u32 s39, s37, -1
	s_cmp_eq_u32 s84, 12
	s_cselect_b32 s41, s27, s39
	s_cselect_b32 s40, s80, s38
	s_cselect_b32 s39, s25, s83
	s_cselect_b32 s38, s81, s82
	v_lshl_add_u64 v[144:145], s[36:37], 0, v[136:137]
	s_add_i32 m0, s35, 0xc000
	ds_read_b128 v[186:189], v151
	ds_read_b128 v[190:193], v151 offset:1024
	ds_read_b128 v[196:199], v151 offset:2048
	ds_read_b128 v[200:203], v151 offset:3072
	ds_read_b128 v[204:207], v151 offset:4096
	ds_read_b128 v[208:211], v151 offset:5120
	ds_read_b128 v[212:215], v151 offset:6144
	ds_read_b128 v[216:219], v151 offset:7168
	global_load_lds_dwordx4 v[144:145], off
	v_lshl_add_u64 v[144:145], s[36:37], 0, v[138:139]
	s_add_i32 m0, s35, 0xe000
	s_nop 0
	global_load_lds_dwordx4 v[144:145], off
	s_waitcnt vmcnt(8)
	s_waitcnt lgkmcnt(0)
	s_barrier
	s_setprio 1
	s_waitcnt lgkmcnt(0)
	v_mfma_f32_16x16x32_bf16 v[116:119], v[154:157], v[186:189], v[116:119]
	v_mfma_f32_16x16x32_bf16 v[112:115], v[162:165], v[186:189], v[112:115]
	v_mfma_f32_16x16x32_bf16 v[100:103], v[154:157], v[196:199], v[100:103]
	v_mfma_f32_16x16x32_bf16 v[96:99], v[162:165], v[196:199], v[96:99]
	v_mfma_f32_16x16x32_bf16 v[84:87], v[154:157], v[204:207], v[84:87]
	v_mfma_f32_16x16x32_bf16 v[80:83], v[162:165], v[204:207], v[80:83]
	v_mfma_f32_16x16x32_bf16 v[68:71], v[154:157], v[212:215], v[68:71]
	v_mfma_f32_16x16x32_bf16 v[64:67], v[162:165], v[212:215], v[64:67]
	v_mfma_f32_16x16x32_bf16 v[116:119], v[158:161], v[190:193], v[116:119]
	v_mfma_f32_16x16x32_bf16 v[112:115], v[166:169], v[190:193], v[112:115]
	v_mfma_f32_16x16x32_bf16 v[100:103], v[158:161], v[200:203], v[100:103]
	v_mfma_f32_16x16x32_bf16 v[96:99], v[166:169], v[200:203], v[96:99]
	v_mfma_f32_16x16x32_bf16 v[84:87], v[158:161], v[208:211], v[84:87]
	v_mfma_f32_16x16x32_bf16 v[80:83], v[166:169], v[208:211], v[80:83]
	v_mfma_f32_16x16x32_bf16 v[68:71], v[158:161], v[216:219], v[68:71]
	v_mfma_f32_16x16x32_bf16 v[64:67], v[166:169], v[216:219], v[64:67]
	v_mfma_f32_16x16x32_bf16 v[124:127], v[170:173], v[186:189], v[124:127]
	v_mfma_f32_16x16x32_bf16 v[120:123], v[178:181], v[186:189], v[120:123]
	v_mfma_f32_16x16x32_bf16 v[108:111], v[170:173], v[196:199], v[108:111]
	v_mfma_f32_16x16x32_bf16 v[104:107], v[178:181], v[196:199], v[104:107]
	v_mfma_f32_16x16x32_bf16 v[92:95], v[170:173], v[204:207], v[92:95]
	v_mfma_f32_16x16x32_bf16 v[88:91], v[178:181], v[204:207], v[88:91]
	v_mfma_f32_16x16x32_bf16 v[76:79], v[170:173], v[212:215], v[76:79]
	v_mfma_f32_16x16x32_bf16 v[72:75], v[178:181], v[212:215], v[72:75]
	v_mfma_f32_16x16x32_bf16 v[124:127], v[174:177], v[190:193], v[124:127]
	v_mfma_f32_16x16x32_bf16 v[120:123], v[182:185], v[190:193], v[120:123]
	v_mfma_f32_16x16x32_bf16 v[108:111], v[174:177], v[200:203], v[108:111]
	v_mfma_f32_16x16x32_bf16 v[104:107], v[182:185], v[200:203], v[104:107]
	v_mfma_f32_16x16x32_bf16 v[92:95], v[174:177], v[208:211], v[92:95]
	v_mfma_f32_16x16x32_bf16 v[88:91], v[182:185], v[208:211], v[88:91]
	v_mfma_f32_16x16x32_bf16 v[76:79], v[174:177], v[216:219], v[76:79]
	v_mfma_f32_16x16x32_bf16 v[72:75], v[182:185], v[216:219], v[72:75]
	s_setprio 0
	s_barrier
	s_add_i32 s85, s71, s56
	v_lshl_add_u64 v[144:145], s[38:39], 0, v[132:133]
	s_mov_b32 m0, s85
	ds_read_b128 v[186:189], v151 offset:16384
	ds_read_b128 v[190:193], v151 offset:17408
	ds_read_b128 v[196:199], v151 offset:18432
	ds_read_b128 v[200:203], v151 offset:19456
	ds_read_b128 v[204:207], v151 offset:20480
	ds_read_b128 v[208:211], v151 offset:21504
	ds_read_b128 v[212:215], v151 offset:22528
	ds_read_b128 v[216:219], v151 offset:23552
	global_load_lds_dwordx4 v[144:145], off
	s_add_i32 m0, s85, 0x2000
	s_add_u32 s86, s38, 0x40000
	v_lshl_add_u64 v[220:221], s[38:39], 0, v[128:129]
	s_addc_u32 s87, s39, 0
	s_add_i32 s85, s72, s56
	global_load_lds_dwordx4 v[220:221], off
	v_lshl_add_u64 v[222:223], s[86:87], 0, v[132:133]
	s_mov_b32 m0, s85
	v_lshl_add_u64 v[224:225], s[40:41], 0, v[130:131]
	global_load_lds_dwordx4 v[222:223], off
	v_lshl_add_u64 v[222:223], s[86:87], 0, v[128:129]
	s_add_i32 m0, s85, 0x2000
	s_nop 0
	global_load_lds_dwordx4 v[222:223], off
	v_lshl_add_u64 v[222:223], s[40:41], 0, v[134:135]
	s_waitcnt vmcnt(6)
	s_waitcnt lgkmcnt(0)
	s_barrier
	s_setprio 1
	s_waitcnt lgkmcnt(0)
	v_mfma_f32_16x16x32_bf16 v[52:55], v[154:157], v[186:189], v[52:55]
	v_mfma_f32_16x16x32_bf16 v[48:51], v[162:165], v[186:189], v[48:51]
	v_mfma_f32_16x16x32_bf16 v[36:39], v[154:157], v[196:199], v[36:39]
	v_mfma_f32_16x16x32_bf16 v[32:35], v[162:165], v[196:199], v[32:35]
	v_mfma_f32_16x16x32_bf16 v[20:23], v[154:157], v[204:207], v[20:23]
	v_mfma_f32_16x16x32_bf16 v[16:19], v[162:165], v[204:207], v[16:19]
	v_mfma_f32_16x16x32_bf16 v[4:7], v[154:157], v[212:215], v[4:7]
	v_mfma_f32_16x16x32_bf16 v[0:3], v[162:165], v[212:215], v[0:3]
	v_mfma_f32_16x16x32_bf16 v[52:55], v[158:161], v[190:193], v[52:55]
	v_mfma_f32_16x16x32_bf16 v[48:51], v[166:169], v[190:193], v[48:51]
	v_mfma_f32_16x16x32_bf16 v[36:39], v[158:161], v[200:203], v[36:39]
	v_mfma_f32_16x16x32_bf16 v[32:35], v[166:169], v[200:203], v[32:35]
	v_mfma_f32_16x16x32_bf16 v[20:23], v[158:161], v[208:211], v[20:23]
	v_mfma_f32_16x16x32_bf16 v[16:19], v[166:169], v[208:211], v[16:19]
	v_mfma_f32_16x16x32_bf16 v[4:7], v[158:161], v[216:219], v[4:7]
	v_mfma_f32_16x16x32_bf16 v[0:3], v[166:169], v[216:219], v[0:3]
	v_mfma_f32_16x16x32_bf16 v[60:63], v[170:173], v[186:189], v[60:63]
	v_mfma_f32_16x16x32_bf16 v[56:59], v[178:181], v[186:189], v[56:59]
	v_mfma_f32_16x16x32_bf16 v[44:47], v[170:173], v[196:199], v[44:47]
	v_mfma_f32_16x16x32_bf16 v[40:43], v[178:181], v[196:199], v[40:43]
	v_mfma_f32_16x16x32_bf16 v[28:31], v[170:173], v[204:207], v[28:31]
	v_mfma_f32_16x16x32_bf16 v[24:27], v[178:181], v[204:207], v[24:27]
	v_mfma_f32_16x16x32_bf16 v[12:15], v[170:173], v[212:215], v[12:15]
	v_mfma_f32_16x16x32_bf16 v[8:11], v[178:181], v[212:215], v[8:11]
	v_mfma_f32_16x16x32_bf16 v[60:63], v[174:177], v[190:193], v[60:63]
	v_mfma_f32_16x16x32_bf16 v[56:59], v[182:185], v[190:193], v[56:59]
	v_mfma_f32_16x16x32_bf16 v[44:47], v[174:177], v[200:203], v[44:47]
	v_mfma_f32_16x16x32_bf16 v[40:43], v[182:185], v[200:203], v[40:43]
	v_mfma_f32_16x16x32_bf16 v[28:31], v[174:177], v[208:211], v[28:31]
	v_mfma_f32_16x16x32_bf16 v[24:27], v[182:185], v[208:211], v[24:27]
	v_mfma_f32_16x16x32_bf16 v[12:15], v[174:177], v[216:219], v[12:15]
	v_mfma_f32_16x16x32_bf16 v[8:11], v[182:185], v[216:219], v[8:11]
	s_setprio 0
	s_barrier
	s_add_i32 s85, 0, 0x18000
	v_add_u32_e32 v153, s85, v147
	s_add_i32 s86, 0, 0x1c000
	ds_read_b128 v[154:157], v153
	ds_read_b128 v[158:161], v153 offset:1024
	ds_read_b128 v[162:165], v153 offset:2048
	ds_read_b128 v[166:169], v153 offset:3072
	v_add_u32_e32 v153, s86, v147
	ds_read_b128 v[170:173], v153
	ds_read_b128 v[174:177], v153 offset:1024
	ds_read_b128 v[178:181], v153 offset:2048
	ds_read_b128 v[182:185], v153 offset:3072
	s_add_u32 s40, s40, 0x40000
	s_addc_u32 s41, s41, 0
	v_lshl_add_u64 v[226:227], s[40:41], 0, v[134:135]
	ds_read_b128 v[186:189], v151 offset:32768
	ds_read_b128 v[190:193], v151 offset:33792
	ds_read_b128 v[196:199], v151 offset:34816
	ds_read_b128 v[200:203], v151 offset:35840
	ds_read_b128 v[204:207], v151 offset:36864
	ds_read_b128 v[208:211], v151 offset:37888
	ds_read_b128 v[212:215], v151 offset:38912
	ds_read_b128 v[216:219], v151 offset:39936
	s_mov_b32 m0, s35
	s_nop 0
	global_load_lds_dwordx4 v[222:223], off
	s_mov_b32 m0, s58
	s_nop 0
	global_load_lds_dwordx4 v[224:225], off
	s_mov_b32 m0, s59
	s_nop 0
	global_load_lds_dwordx4 v[226:227], off
	v_lshl_add_u64 v[226:227], s[40:41], 0, v[130:131]
	s_mov_b32 m0, s60
	s_nop 0
	global_load_lds_dwordx4 v[226:227], off
	s_waitcnt vmcnt(8)
	s_waitcnt lgkmcnt(0)
	s_barrier
	s_setprio 1
	s_waitcnt lgkmcnt(0)
	v_mfma_f32_16x16x32_bf16 v[116:119], v[154:157], v[186:189], v[116:119]
	v_mfma_f32_16x16x32_bf16 v[112:115], v[162:165], v[186:189], v[112:115]
	v_mfma_f32_16x16x32_bf16 v[100:103], v[154:157], v[196:199], v[100:103]
	v_mfma_f32_16x16x32_bf16 v[96:99], v[162:165], v[196:199], v[96:99]
	v_mfma_f32_16x16x32_bf16 v[84:87], v[154:157], v[204:207], v[84:87]
	v_mfma_f32_16x16x32_bf16 v[80:83], v[162:165], v[204:207], v[80:83]
	v_mfma_f32_16x16x32_bf16 v[68:71], v[154:157], v[212:215], v[68:71]
	v_mfma_f32_16x16x32_bf16 v[64:67], v[162:165], v[212:215], v[64:67]
	v_mfma_f32_16x16x32_bf16 v[116:119], v[158:161], v[190:193], v[116:119]
	v_mfma_f32_16x16x32_bf16 v[112:115], v[166:169], v[190:193], v[112:115]
	v_mfma_f32_16x16x32_bf16 v[100:103], v[158:161], v[200:203], v[100:103]
	v_mfma_f32_16x16x32_bf16 v[96:99], v[166:169], v[200:203], v[96:99]
	v_mfma_f32_16x16x32_bf16 v[84:87], v[158:161], v[208:211], v[84:87]
	v_mfma_f32_16x16x32_bf16 v[80:83], v[166:169], v[208:211], v[80:83]
	v_mfma_f32_16x16x32_bf16 v[68:71], v[158:161], v[216:219], v[68:71]
	v_mfma_f32_16x16x32_bf16 v[64:67], v[166:169], v[216:219], v[64:67]
	v_mfma_f32_16x16x32_bf16 v[124:127], v[170:173], v[186:189], v[124:127]
	v_mfma_f32_16x16x32_bf16 v[120:123], v[178:181], v[186:189], v[120:123]
	v_mfma_f32_16x16x32_bf16 v[108:111], v[170:173], v[196:199], v[108:111]
	v_mfma_f32_16x16x32_bf16 v[104:107], v[178:181], v[196:199], v[104:107]
	v_mfma_f32_16x16x32_bf16 v[92:95], v[170:173], v[204:207], v[92:95]
	v_mfma_f32_16x16x32_bf16 v[88:91], v[178:181], v[204:207], v[88:91]
	v_mfma_f32_16x16x32_bf16 v[76:79], v[170:173], v[212:215], v[76:79]
	v_mfma_f32_16x16x32_bf16 v[72:75], v[178:181], v[212:215], v[72:75]
	v_mfma_f32_16x16x32_bf16 v[124:127], v[174:177], v[190:193], v[124:127]
	v_mfma_f32_16x16x32_bf16 v[120:123], v[182:185], v[190:193], v[120:123]
	v_mfma_f32_16x16x32_bf16 v[108:111], v[174:177], v[200:203], v[108:111]
	v_mfma_f32_16x16x32_bf16 v[104:107], v[182:185], v[200:203], v[104:107]
	v_mfma_f32_16x16x32_bf16 v[92:95], v[174:177], v[208:211], v[92:95]
	v_mfma_f32_16x16x32_bf16 v[88:91], v[182:185], v[208:211], v[88:91]
	v_mfma_f32_16x16x32_bf16 v[76:79], v[174:177], v[216:219], v[76:79]
	v_mfma_f32_16x16x32_bf16 v[72:75], v[182:185], v[216:219], v[72:75]
	s_setprio 0
	s_barrier
	s_add_i32 s40, s85, s56
	v_lshl_add_u64 v[144:145], v[144:145], 0, s[20:21]
	s_mov_b32 m0, s40
	ds_read_b128 v[186:189], v151 offset:49152
	ds_read_b128 v[190:193], v151 offset:50176
	ds_read_b128 v[196:199], v151 offset:51200
	ds_read_b128 v[200:203], v151 offset:52224
	ds_read_b128 v[204:207], v151 offset:53248
	ds_read_b128 v[208:211], v151 offset:54272
	ds_read_b128 v[212:215], v151 offset:55296
	ds_read_b128 v[216:219], v151 offset:56320
	global_load_lds_dwordx4 v[144:145], off
	s_add_i32 m0, s40, 0x2000
	s_add_u32 s38, s38, 0x40080
	v_lshl_add_u64 v[144:145], v[220:221], 0, s[20:21]
	s_addc_u32 s39, s39, 0
	s_add_i32 s40, s86, s56
	global_load_lds_dwordx4 v[144:145], off
	v_lshl_add_u64 v[144:145], s[38:39], 0, v[132:133]
	s_mov_b32 m0, s40
	s_nop 0
	global_load_lds_dwordx4 v[144:145], off
	v_lshl_add_u64 v[144:145], s[38:39], 0, v[128:129]
	s_add_i32 m0, s40, 0x2000
	s_nop 0
	global_load_lds_dwordx4 v[144:145], off
	s_waitcnt vmcnt(6)
	s_waitcnt lgkmcnt(0)
	s_barrier
	s_setprio 1
	s_waitcnt lgkmcnt(0)
	v_mfma_f32_16x16x32_bf16 v[52:55], v[154:157], v[186:189], v[52:55]
	v_mfma_f32_16x16x32_bf16 v[48:51], v[162:165], v[186:189], v[48:51]
	v_mfma_f32_16x16x32_bf16 v[36:39], v[154:157], v[196:199], v[36:39]
	v_mfma_f32_16x16x32_bf16 v[32:35], v[162:165], v[196:199], v[32:35]
	v_mfma_f32_16x16x32_bf16 v[20:23], v[154:157], v[204:207], v[20:23]
	v_mfma_f32_16x16x32_bf16 v[16:19], v[162:165], v[204:207], v[16:19]
	v_mfma_f32_16x16x32_bf16 v[4:7], v[154:157], v[212:215], v[4:7]
	v_mfma_f32_16x16x32_bf16 v[0:3], v[162:165], v[212:215], v[0:3]
	v_mfma_f32_16x16x32_bf16 v[52:55], v[158:161], v[190:193], v[52:55]
	v_mfma_f32_16x16x32_bf16 v[48:51], v[166:169], v[190:193], v[48:51]
	v_mfma_f32_16x16x32_bf16 v[36:39], v[158:161], v[200:203], v[36:39]
	v_mfma_f32_16x16x32_bf16 v[32:35], v[166:169], v[200:203], v[32:35]
	v_mfma_f32_16x16x32_bf16 v[20:23], v[158:161], v[208:211], v[20:23]
	v_mfma_f32_16x16x32_bf16 v[16:19], v[166:169], v[208:211], v[16:19]
	v_mfma_f32_16x16x32_bf16 v[4:7], v[158:161], v[216:219], v[4:7]
	v_mfma_f32_16x16x32_bf16 v[0:3], v[166:169], v[216:219], v[0:3]
	v_mfma_f32_16x16x32_bf16 v[60:63], v[170:173], v[186:189], v[60:63]
	v_mfma_f32_16x16x32_bf16 v[56:59], v[178:181], v[186:189], v[56:59]
	v_mfma_f32_16x16x32_bf16 v[44:47], v[170:173], v[196:199], v[44:47]
	v_mfma_f32_16x16x32_bf16 v[40:43], v[178:181], v[196:199], v[40:43]
	v_mfma_f32_16x16x32_bf16 v[28:31], v[170:173], v[204:207], v[28:31]
	v_mfma_f32_16x16x32_bf16 v[24:27], v[178:181], v[204:207], v[24:27]
	v_mfma_f32_16x16x32_bf16 v[12:15], v[170:173], v[212:215], v[12:15]
	v_mfma_f32_16x16x32_bf16 v[8:11], v[178:181], v[212:215], v[8:11]
	v_mfma_f32_16x16x32_bf16 v[60:63], v[174:177], v[190:193], v[60:63]
	v_mfma_f32_16x16x32_bf16 v[56:59], v[182:185], v[190:193], v[56:59]
	v_mfma_f32_16x16x32_bf16 v[44:47], v[174:177], v[200:203], v[44:47]
	v_mfma_f32_16x16x32_bf16 v[40:43], v[182:185], v[200:203], v[40:43]
	v_mfma_f32_16x16x32_bf16 v[28:31], v[174:177], v[208:211], v[28:31]
	v_mfma_f32_16x16x32_bf16 v[24:27], v[182:185], v[208:211], v[24:27]
	v_mfma_f32_16x16x32_bf16 v[12:15], v[174:177], v[216:219], v[12:15]
	v_mfma_f32_16x16x32_bf16 v[8:11], v[182:185], v[216:219], v[8:11]
	s_setprio 0
	s_barrier
	v_lshl_add_u64 v[222:223], v[222:223], 0, s[20:21]
	s_mov_b32 m0, s62
	s_nop 0
	global_load_lds_dwordx4 v[222:223], off
	v_lshl_add_u64 v[224:225], v[224:225], 0, s[20:21]
	s_mov_b32 m0, s63
	s_nop 0
	global_load_lds_dwordx4 v[224:225], off
	s_add_i32 s84, s84, 2
	s_add_u32 s36, s36, 0x100
	s_addc_u32 s37, s37, 0
	s_add_u32 s82, s82, 0x100
	s_addc_u32 s83, s83, 0
	s_cmp_gt_u32 s84, 13
	s_cbranch_scc0 .LBB0_1709
	s_and_b64 vcc, exec, s[22:23]
	s_cbranch_vccz .LBB0_1712
	s_barrier

.LBB0_1791:
	ds_read_b128 v[144:147], v151
	ds_read_b128 v[156:159], v151 offset:1024
	ds_read_b128 v[160:163], v151 offset:2048
	ds_read_b128 v[164:167], v151 offset:3072
	ds_read_b128 v[168:171], v152
	ds_read_b128 v[172:175], v152 offset:1024
	ds_read_b128 v[176:179], v152 offset:2048
	ds_read_b128 v[180:183], v152 offset:3072
	s_add_u32 s38, s36, 0x100
	s_addc_u32 s39, s37, 0
	s_cmp_eq_u32 s85, 40
	s_cselect_b32 s43, s1, s39
	s_cselect_b32 s42, s0, s38
	s_cselect_b32 s41, s35, s84
	s_cselect_b32 s40, s34, s83
	v_lshl_add_u64 v[192:193], s[36:37], 0, v[136:137]
	s_add_i32 m0, s59, 0xc000
	ds_read_b128 v[184:187], v153
	ds_read_b128 v[188:191], v153 offset:1024
	ds_read_b128 v[196:199], v153 offset:2048
	ds_read_b128 v[200:203], v153 offset:3072
	ds_read_b128 v[204:207], v153 offset:4096
	ds_read_b128 v[208:211], v153 offset:5120
	ds_read_b128 v[212:215], v153 offset:6144
	ds_read_b128 v[216:219], v153 offset:7168
	global_load_lds_dwordx4 v[192:193], off
	v_lshl_add_u64 v[192:193], s[36:37], 0, v[138:139]
	s_add_i32 m0, s59, 0xe000
	s_nop 0
	global_load_lds_dwordx4 v[192:193], off
	s_waitcnt vmcnt(8)
	s_waitcnt lgkmcnt(0)
	s_barrier
	s_setprio 1
	s_waitcnt lgkmcnt(0)
	v_mfma_f32_16x16x32_bf16 v[124:127], v[144:147], v[184:187], v[124:127]
	v_mfma_f32_16x16x32_bf16 v[120:123], v[160:163], v[184:187], v[120:123]
	v_mfma_f32_16x16x32_bf16 v[108:111], v[144:147], v[196:199], v[108:111]
	v_mfma_f32_16x16x32_bf16 v[104:107], v[160:163], v[196:199], v[104:107]
	v_mfma_f32_16x16x32_bf16 v[92:95], v[144:147], v[204:207], v[92:95]
	v_mfma_f32_16x16x32_bf16 v[88:91], v[160:163], v[204:207], v[88:91]
	v_mfma_f32_16x16x32_bf16 v[76:79], v[144:147], v[212:215], v[76:79]
	v_mfma_f32_16x16x32_bf16 v[72:75], v[160:163], v[212:215], v[72:75]
	v_mfma_f32_16x16x32_bf16 v[124:127], v[156:159], v[188:191], v[124:127]
	v_mfma_f32_16x16x32_bf16 v[120:123], v[164:167], v[188:191], v[120:123]
	v_mfma_f32_16x16x32_bf16 v[108:111], v[156:159], v[200:203], v[108:111]
	v_mfma_f32_16x16x32_bf16 v[104:107], v[164:167], v[200:203], v[104:107]
	v_mfma_f32_16x16x32_bf16 v[92:95], v[156:159], v[208:211], v[92:95]
	v_mfma_f32_16x16x32_bf16 v[88:91], v[164:167], v[208:211], v[88:91]
	v_mfma_f32_16x16x32_bf16 v[76:79], v[156:159], v[216:219], v[76:79]
	v_mfma_f32_16x16x32_bf16 v[72:75], v[164:167], v[216:219], v[72:75]
	v_mfma_f32_16x16x32_bf16 v[116:119], v[168:171], v[184:187], v[116:119]
	v_mfma_f32_16x16x32_bf16 v[112:115], v[176:179], v[184:187], v[112:115]
	v_mfma_f32_16x16x32_bf16 v[100:103], v[168:171], v[196:199], v[100:103]
	v_mfma_f32_16x16x32_bf16 v[96:99], v[176:179], v[196:199], v[96:99]
	v_mfma_f32_16x16x32_bf16 v[84:87], v[168:171], v[204:207], v[84:87]
	v_mfma_f32_16x16x32_bf16 v[80:83], v[176:179], v[204:207], v[80:83]
	v_mfma_f32_16x16x32_bf16 v[68:71], v[168:171], v[212:215], v[68:71]
	v_mfma_f32_16x16x32_bf16 v[64:67], v[176:179], v[212:215], v[64:67]
	v_mfma_f32_16x16x32_bf16 v[116:119], v[172:175], v[188:191], v[116:119]
	v_mfma_f32_16x16x32_bf16 v[112:115], v[180:183], v[188:191], v[112:115]
	v_mfma_f32_16x16x32_bf16 v[100:103], v[172:175], v[200:203], v[100:103]
	v_mfma_f32_16x16x32_bf16 v[96:99], v[180:183], v[200:203], v[96:99]
	v_mfma_f32_16x16x32_bf16 v[84:87], v[172:175], v[208:211], v[84:87]
	v_mfma_f32_16x16x32_bf16 v[80:83], v[180:183], v[208:211], v[80:83]
	v_mfma_f32_16x16x32_bf16 v[68:71], v[172:175], v[216:219], v[68:71]
	v_mfma_f32_16x16x32_bf16 v[64:67], v[180:183], v[216:219], v[64:67]
	s_setprio 0
	s_barrier
	s_add_i32 s36, s73, s58
	v_lshl_add_u64 v[192:193], s[40:41], 0, v[130:131]
	s_mov_b32 m0, s36
	ds_read_b128 v[184:187], v153 offset:16384
	ds_read_b128 v[188:191], v153 offset:17408
	ds_read_b128 v[196:199], v153 offset:18432
	ds_read_b128 v[200:203], v153 offset:19456
	ds_read_b128 v[204:207], v153 offset:20480
	ds_read_b128 v[208:211], v153 offset:21504
	ds_read_b128 v[212:215], v153 offset:22528
	ds_read_b128 v[216:219], v153 offset:23552
	global_load_lds_dwordx4 v[192:193], off
	s_add_i32 m0, s36, 0x2000
	s_add_u32 s36, s40, 0xb0000
	v_lshl_add_u64 v[220:221], s[40:41], 0, v[134:135]
	s_addc_u32 s37, s41, 0
	s_add_i32 s86, s78, s58
	global_load_lds_dwordx4 v[220:221], off
	v_lshl_add_u64 v[222:223], s[36:37], 0, v[130:131]
	s_mov_b32 m0, s86
	v_lshl_add_u64 v[224:225], s[42:43], 0, v[132:133]
	global_load_lds_dwordx4 v[222:223], off
	v_lshl_add_u64 v[222:223], s[36:37], 0, v[134:135]
	s_add_i32 m0, s86, 0x2000
	s_nop 0
	global_load_lds_dwordx4 v[222:223], off
	v_lshl_add_u64 v[222:223], s[42:43], 0, v[128:129]
	s_waitcnt vmcnt(6)
	s_waitcnt lgkmcnt(0)
	s_barrier
	s_setprio 1
	s_waitcnt lgkmcnt(0)
	v_mfma_f32_16x16x32_bf16 v[60:63], v[144:147], v[184:187], v[60:63]
	v_mfma_f32_16x16x32_bf16 v[56:59], v[160:163], v[184:187], v[56:59]
	v_mfma_f32_16x16x32_bf16 v[44:47], v[144:147], v[196:199], v[44:47]
	v_mfma_f32_16x16x32_bf16 v[40:43], v[160:163], v[196:199], v[40:43]
	v_mfma_f32_16x16x32_bf16 v[28:31], v[144:147], v[204:207], v[28:31]
	v_mfma_f32_16x16x32_bf16 v[24:27], v[160:163], v[204:207], v[24:27]
	v_mfma_f32_16x16x32_bf16 v[12:15], v[144:147], v[212:215], v[12:15]
	v_mfma_f32_16x16x32_bf16 v[8:11], v[160:163], v[212:215], v[8:11]
	v_mfma_f32_16x16x32_bf16 v[60:63], v[156:159], v[188:191], v[60:63]
	v_mfma_f32_16x16x32_bf16 v[56:59], v[164:167], v[188:191], v[56:59]
	v_mfma_f32_16x16x32_bf16 v[44:47], v[156:159], v[200:203], v[44:47]
	v_mfma_f32_16x16x32_bf16 v[40:43], v[164:167], v[200:203], v[40:43]
	v_mfma_f32_16x16x32_bf16 v[28:31], v[156:159], v[208:211], v[28:31]
	v_mfma_f32_16x16x32_bf16 v[24:27], v[164:167], v[208:211], v[24:27]
	v_mfma_f32_16x16x32_bf16 v[12:15], v[156:159], v[216:219], v[12:15]
	v_mfma_f32_16x16x32_bf16 v[8:11], v[164:167], v[216:219], v[8:11]
	v_mfma_f32_16x16x32_bf16 v[52:55], v[168:171], v[184:187], v[52:55]
	v_mfma_f32_16x16x32_bf16 v[48:51], v[176:179], v[184:187], v[48:51]
	v_mfma_f32_16x16x32_bf16 v[36:39], v[168:171], v[196:199], v[36:39]
	v_mfma_f32_16x16x32_bf16 v[32:35], v[176:179], v[196:199], v[32:35]
	v_mfma_f32_16x16x32_bf16 v[20:23], v[168:171], v[204:207], v[20:23]
	v_mfma_f32_16x16x32_bf16 v[16:19], v[176:179], v[204:207], v[16:19]
	v_mfma_f32_16x16x32_bf16 v[4:7], v[168:171], v[212:215], v[4:7]
	v_mfma_f32_16x16x32_bf16 v[0:3], v[176:179], v[212:215], v[0:3]
	v_mfma_f32_16x16x32_bf16 v[52:55], v[172:175], v[188:191], v[52:55]
	v_mfma_f32_16x16x32_bf16 v[48:51], v[180:183], v[188:191], v[48:51]
	v_mfma_f32_16x16x32_bf16 v[36:39], v[172:175], v[200:203], v[36:39]
	v_mfma_f32_16x16x32_bf16 v[32:35], v[180:183], v[200:203], v[32:35]
	v_mfma_f32_16x16x32_bf16 v[20:23], v[172:175], v[208:211], v[20:23]
	v_mfma_f32_16x16x32_bf16 v[16:19], v[180:183], v[208:211], v[16:19]
	v_mfma_f32_16x16x32_bf16 v[4:7], v[172:175], v[216:219], v[4:7]
	v_mfma_f32_16x16x32_bf16 v[0:3], v[180:183], v[216:219], v[0:3]
	s_setprio 0
	s_barrier
	s_add_i32 s86, 0, 0x18000
	v_add_u32_e32 v155, s86, v149
	s_add_i32 s87, 0, 0x1c000
	ds_read_b128 v[144:147], v155
	ds_read_b128 v[156:159], v155 offset:1024
	ds_read_b128 v[160:163], v155 offset:2048
	ds_read_b128 v[164:167], v155 offset:3072
	v_add_u32_e32 v155, s87, v149
	ds_read_b128 v[168:171], v155
	ds_read_b128 v[172:175], v155 offset:1024
	ds_read_b128 v[176:179], v155 offset:2048
	ds_read_b128 v[180:183], v155 offset:3072
	s_add_u32 s36, s42, 0xb0000
	s_addc_u32 s37, s43, 0
	v_lshl_add_u64 v[226:227], s[36:37], 0, v[128:129]
	ds_read_b128 v[184:187], v153 offset:32768
	ds_read_b128 v[188:191], v153 offset:33792
	ds_read_b128 v[196:199], v153 offset:34816
	ds_read_b128 v[200:203], v153 offset:35840
	ds_read_b128 v[204:207], v153 offset:36864
	ds_read_b128 v[208:211], v153 offset:37888
	ds_read_b128 v[212:215], v153 offset:38912
	ds_read_b128 v[216:219], v153 offset:39936
	s_mov_b32 m0, s59
	s_nop 0
	global_load_lds_dwordx4 v[222:223], off
	s_mov_b32 m0, s60
	s_nop 0
	global_load_lds_dwordx4 v[224:225], off
	s_mov_b32 m0, s61
	s_nop 0
	global_load_lds_dwordx4 v[226:227], off
	v_lshl_add_u64 v[226:227], s[36:37], 0, v[132:133]
	s_mov_b32 m0, s62
	s_nop 0
	global_load_lds_dwordx4 v[226:227], off
	s_waitcnt vmcnt(8)
	s_waitcnt lgkmcnt(0)
	s_barrier
	s_setprio 1
	s_waitcnt lgkmcnt(0)
	v_mfma_f32_16x16x32_bf16 v[124:127], v[144:147], v[184:187], v[124:127]
	v_mfma_f32_16x16x32_bf16 v[120:123], v[160:163], v[184:187], v[120:123]
	v_mfma_f32_16x16x32_bf16 v[108:111], v[144:147], v[196:199], v[108:111]
	v_mfma_f32_16x16x32_bf16 v[104:107], v[160:163], v[196:199], v[104:107]
	v_mfma_f32_16x16x32_bf16 v[92:95], v[144:147], v[204:207], v[92:95]
	v_mfma_f32_16x16x32_bf16 v[88:91], v[160:163], v[204:207], v[88:91]
	v_mfma_f32_16x16x32_bf16 v[76:79], v[144:147], v[212:215], v[76:79]
	v_mfma_f32_16x16x32_bf16 v[72:75], v[160:163], v[212:215], v[72:75]
	v_mfma_f32_16x16x32_bf16 v[124:127], v[156:159], v[188:191], v[124:127]
	v_mfma_f32_16x16x32_bf16 v[120:123], v[164:167], v[188:191], v[120:123]
	v_mfma_f32_16x16x32_bf16 v[108:111], v[156:159], v[200:203], v[108:111]
	v_mfma_f32_16x16x32_bf16 v[104:107], v[164:167], v[200:203], v[104:107]
	v_mfma_f32_16x16x32_bf16 v[92:95], v[156:159], v[208:211], v[92:95]
	v_mfma_f32_16x16x32_bf16 v[88:91], v[164:167], v[208:211], v[88:91]
	v_mfma_f32_16x16x32_bf16 v[76:79], v[156:159], v[216:219], v[76:79]
	v_mfma_f32_16x16x32_bf16 v[72:75], v[164:167], v[216:219], v[72:75]
	v_mfma_f32_16x16x32_bf16 v[116:119], v[168:171], v[184:187], v[116:119]
	v_mfma_f32_16x16x32_bf16 v[112:115], v[176:179], v[184:187], v[112:115]
	v_mfma_f32_16x16x32_bf16 v[100:103], v[168:171], v[196:199], v[100:103]
	v_mfma_f32_16x16x32_bf16 v[96:99], v[176:179], v[196:199], v[96:99]
	v_mfma_f32_16x16x32_bf16 v[84:87], v[168:171], v[204:207], v[84:87]
	v_mfma_f32_16x16x32_bf16 v[80:83], v[176:179], v[204:207], v[80:83]
	v_mfma_f32_16x16x32_bf16 v[68:71], v[168:171], v[212:215], v[68:71]
	v_mfma_f32_16x16x32_bf16 v[64:67], v[176:179], v[212:215], v[64:67]
	v_mfma_f32_16x16x32_bf16 v[116:119], v[172:175], v[188:191], v[116:119]
	v_mfma_f32_16x16x32_bf16 v[112:115], v[180:183], v[188:191], v[112:115]
	v_mfma_f32_16x16x32_bf16 v[100:103], v[172:175], v[200:203], v[100:103]
	v_mfma_f32_16x16x32_bf16 v[96:99], v[180:183], v[200:203], v[96:99]
	v_mfma_f32_16x16x32_bf16 v[84:87], v[172:175], v[208:211], v[84:87]
	v_mfma_f32_16x16x32_bf16 v[80:83], v[180:183], v[208:211], v[80:83]
	v_mfma_f32_16x16x32_bf16 v[68:71], v[172:175], v[216:219], v[68:71]
	v_mfma_f32_16x16x32_bf16 v[64:67], v[180:183], v[216:219], v[64:67]
	s_setprio 0
	s_barrier
	s_add_i32 s36, s86, s58
	v_lshl_add_u64 v[192:193], v[192:193], 0, s[28:29]
	s_mov_b32 m0, s36
	ds_read_b128 v[184:187], v153 offset:49152
	ds_read_b128 v[188:191], v153 offset:50176
	ds_read_b128 v[196:199], v153 offset:51200
	ds_read_b128 v[200:203], v153 offset:52224
	ds_read_b128 v[204:207], v153 offset:53248
	ds_read_b128 v[208:211], v153 offset:54272
	ds_read_b128 v[212:215], v153 offset:55296
	ds_read_b128 v[216:219], v153 offset:56320
	global_load_lds_dwordx4 v[192:193], off
	s_add_i32 m0, s36, 0x2000
	s_add_u32 s36, s40, 0xb0080
	v_lshl_add_u64 v[192:193], v[220:221], 0, s[28:29]
	s_addc_u32 s37, s41, 0
	s_add_i32 s40, s87, s58
	global_load_lds_dwordx4 v[192:193], off
	v_lshl_add_u64 v[192:193], s[36:37], 0, v[130:131]
	s_mov_b32 m0, s40
	s_nop 0
	global_load_lds_dwordx4 v[192:193], off
	v_lshl_add_u64 v[192:193], s[36:37], 0, v[134:135]
	s_add_i32 m0, s40, 0x2000
	s_nop 0
	global_load_lds_dwordx4 v[192:193], off
	s_waitcnt vmcnt(6)
	s_waitcnt lgkmcnt(0)
	s_barrier
	s_setprio 1
	s_waitcnt lgkmcnt(0)
	v_mfma_f32_16x16x32_bf16 v[60:63], v[144:147], v[184:187], v[60:63]
	v_mfma_f32_16x16x32_bf16 v[56:59], v[160:163], v[184:187], v[56:59]
	v_mfma_f32_16x16x32_bf16 v[44:47], v[144:147], v[196:199], v[44:47]
	v_mfma_f32_16x16x32_bf16 v[40:43], v[160:163], v[196:199], v[40:43]
	v_mfma_f32_16x16x32_bf16 v[28:31], v[144:147], v[204:207], v[28:31]
	v_mfma_f32_16x16x32_bf16 v[24:27], v[160:163], v[204:207], v[24:27]
	v_mfma_f32_16x16x32_bf16 v[12:15], v[144:147], v[212:215], v[12:15]
	v_mfma_f32_16x16x32_bf16 v[8:11], v[160:163], v[212:215], v[8:11]
	v_mfma_f32_16x16x32_bf16 v[60:63], v[156:159], v[188:191], v[60:63]
	v_mfma_f32_16x16x32_bf16 v[56:59], v[164:167], v[188:191], v[56:59]
	v_mfma_f32_16x16x32_bf16 v[44:47], v[156:159], v[200:203], v[44:47]
	v_mfma_f32_16x16x32_bf16 v[40:43], v[164:167], v[200:203], v[40:43]
	v_mfma_f32_16x16x32_bf16 v[28:31], v[156:159], v[208:211], v[28:31]
	v_mfma_f32_16x16x32_bf16 v[24:27], v[164:167], v[208:211], v[24:27]
	v_mfma_f32_16x16x32_bf16 v[12:15], v[156:159], v[216:219], v[12:15]
	v_mfma_f32_16x16x32_bf16 v[8:11], v[164:167], v[216:219], v[8:11]
	v_mfma_f32_16x16x32_bf16 v[52:55], v[168:171], v[184:187], v[52:55]
	v_mfma_f32_16x16x32_bf16 v[48:51], v[176:179], v[184:187], v[48:51]
	v_mfma_f32_16x16x32_bf16 v[36:39], v[168:171], v[196:199], v[36:39]
	v_mfma_f32_16x16x32_bf16 v[32:35], v[176:179], v[196:199], v[32:35]
	v_mfma_f32_16x16x32_bf16 v[20:23], v[168:171], v[204:207], v[20:23]
	v_mfma_f32_16x16x32_bf16 v[16:19], v[176:179], v[204:207], v[16:19]
	v_mfma_f32_16x16x32_bf16 v[4:7], v[168:171], v[212:215], v[4:7]
	v_mfma_f32_16x16x32_bf16 v[0:3], v[176:179], v[212:215], v[0:3]
	v_mfma_f32_16x16x32_bf16 v[52:55], v[172:175], v[188:191], v[52:55]
	v_mfma_f32_16x16x32_bf16 v[48:51], v[180:183], v[188:191], v[48:51]
	v_mfma_f32_16x16x32_bf16 v[36:39], v[172:175], v[200:203], v[36:39]
	v_mfma_f32_16x16x32_bf16 v[32:35], v[180:183], v[200:203], v[32:35]
	v_mfma_f32_16x16x32_bf16 v[20:23], v[172:175], v[208:211], v[20:23]
	v_mfma_f32_16x16x32_bf16 v[16:19], v[180:183], v[208:211], v[16:19]
	v_mfma_f32_16x16x32_bf16 v[4:7], v[172:175], v[216:219], v[4:7]
	v_mfma_f32_16x16x32_bf16 v[0:3], v[180:183], v[216:219], v[0:3]
	s_setprio 0
	s_barrier
	v_lshl_add_u64 v[222:223], v[222:223], 0, s[28:29]
	s_mov_b32 m0, s70
	s_nop 0
	global_load_lds_dwordx4 v[222:223], off
	v_lshl_add_u64 v[224:225], v[224:225], 0, s[28:29]
	s_mov_b32 m0, s71
	s_nop 0
	global_load_lds_dwordx4 v[224:225], off
	s_add_i32 s85, s85, 2
	s_add_u32 s83, s83, 0x100
	s_addc_u32 s84, s84, 0
	s_cmp_gt_u32 s85, 41
	s_mov_b64 s[36:37], s[38:39]
	s_cbranch_scc0 .LBB0_1791
	s_and_b64 vcc, exec, s[30:31]
	s_cbranch_vccz .LBB0_1794
	s_barrier

.LBB0_2142:
	ds_read_b128 v[144:147], v151
	ds_read_b128 v[156:159], v151 offset:1024
	ds_read_b128 v[160:163], v151 offset:2048
	ds_read_b128 v[164:167], v151 offset:3072
	ds_read_b128 v[168:171], v152
	ds_read_b128 v[172:175], v152 offset:1024
	ds_read_b128 v[176:179], v152 offset:2048
	ds_read_b128 v[180:183], v152 offset:3072
	s_add_u32 s38, s36, 0x100
	s_addc_u32 s39, s37, 0
	s_cmp_eq_u32 s83, 40
	s_cselect_b32 s43, s1, s39
	s_cselect_b32 s42, s0, s38
	s_cselect_b32 s41, s35, s82
	s_cselect_b32 s40, s34, s81
	v_lshl_add_u64 v[192:193], s[36:37], 0, v[136:137]
	s_add_i32 m0, s57, 0xc000
	ds_read_b128 v[184:187], v153
	ds_read_b128 v[188:191], v153 offset:1024
	ds_read_b128 v[196:199], v153 offset:2048
	ds_read_b128 v[200:203], v153 offset:3072
	ds_read_b128 v[204:207], v153 offset:4096
	ds_read_b128 v[208:211], v153 offset:5120
	ds_read_b128 v[212:215], v153 offset:6144
	ds_read_b128 v[216:219], v153 offset:7168
	global_load_lds_dwordx4 v[192:193], off
	v_lshl_add_u64 v[192:193], s[36:37], 0, v[138:139]
	s_add_i32 m0, s57, 0xe000
	s_nop 0
	global_load_lds_dwordx4 v[192:193], off
	s_waitcnt vmcnt(8)
	s_waitcnt lgkmcnt(0)
	s_barrier
	s_setprio 1
	s_waitcnt lgkmcnt(0)
	v_mfma_f32_16x16x32_bf16 v[124:127], v[144:147], v[184:187], v[124:127]
	v_mfma_f32_16x16x32_bf16 v[120:123], v[160:163], v[184:187], v[120:123]
	v_mfma_f32_16x16x32_bf16 v[108:111], v[144:147], v[196:199], v[108:111]
	v_mfma_f32_16x16x32_bf16 v[104:107], v[160:163], v[196:199], v[104:107]
	v_mfma_f32_16x16x32_bf16 v[92:95], v[144:147], v[204:207], v[92:95]
	v_mfma_f32_16x16x32_bf16 v[88:91], v[160:163], v[204:207], v[88:91]
	v_mfma_f32_16x16x32_bf16 v[76:79], v[144:147], v[212:215], v[76:79]
	v_mfma_f32_16x16x32_bf16 v[72:75], v[160:163], v[212:215], v[72:75]
	v_mfma_f32_16x16x32_bf16 v[124:127], v[156:159], v[188:191], v[124:127]
	v_mfma_f32_16x16x32_bf16 v[120:123], v[164:167], v[188:191], v[120:123]
	v_mfma_f32_16x16x32_bf16 v[108:111], v[156:159], v[200:203], v[108:111]
	v_mfma_f32_16x16x32_bf16 v[104:107], v[164:167], v[200:203], v[104:107]
	v_mfma_f32_16x16x32_bf16 v[92:95], v[156:159], v[208:211], v[92:95]
	v_mfma_f32_16x16x32_bf16 v[88:91], v[164:167], v[208:211], v[88:91]
	v_mfma_f32_16x16x32_bf16 v[76:79], v[156:159], v[216:219], v[76:79]
	v_mfma_f32_16x16x32_bf16 v[72:75], v[164:167], v[216:219], v[72:75]
	v_mfma_f32_16x16x32_bf16 v[116:119], v[168:171], v[184:187], v[116:119]
	v_mfma_f32_16x16x32_bf16 v[112:115], v[176:179], v[184:187], v[112:115]
	v_mfma_f32_16x16x32_bf16 v[100:103], v[168:171], v[196:199], v[100:103]
	v_mfma_f32_16x16x32_bf16 v[96:99], v[176:179], v[196:199], v[96:99]
	v_mfma_f32_16x16x32_bf16 v[84:87], v[168:171], v[204:207], v[84:87]
	v_mfma_f32_16x16x32_bf16 v[80:83], v[176:179], v[204:207], v[80:83]
	v_mfma_f32_16x16x32_bf16 v[68:71], v[168:171], v[212:215], v[68:71]
	v_mfma_f32_16x16x32_bf16 v[64:67], v[176:179], v[212:215], v[64:67]
	v_mfma_f32_16x16x32_bf16 v[116:119], v[172:175], v[188:191], v[116:119]
	v_mfma_f32_16x16x32_bf16 v[112:115], v[180:183], v[188:191], v[112:115]
	v_mfma_f32_16x16x32_bf16 v[100:103], v[172:175], v[200:203], v[100:103]
	v_mfma_f32_16x16x32_bf16 v[96:99], v[180:183], v[200:203], v[96:99]
	v_mfma_f32_16x16x32_bf16 v[84:87], v[172:175], v[208:211], v[84:87]
	v_mfma_f32_16x16x32_bf16 v[80:83], v[180:183], v[208:211], v[80:83]
	v_mfma_f32_16x16x32_bf16 v[68:71], v[172:175], v[216:219], v[68:71]
	v_mfma_f32_16x16x32_bf16 v[64:67], v[180:183], v[216:219], v[64:67]
	s_setprio 0
	s_barrier
	s_add_i32 s36, s71, s56
	v_lshl_add_u64 v[192:193], s[40:41], 0, v[130:131]
	s_mov_b32 m0, s36
	ds_read_b128 v[184:187], v153 offset:16384
	ds_read_b128 v[188:191], v153 offset:17408
	ds_read_b128 v[196:199], v153 offset:18432
	ds_read_b128 v[200:203], v153 offset:19456
	ds_read_b128 v[204:207], v153 offset:20480
	ds_read_b128 v[208:211], v153 offset:21504
	ds_read_b128 v[212:215], v153 offset:22528
	ds_read_b128 v[216:219], v153 offset:23552
	global_load_lds_dwordx4 v[192:193], off
	s_add_i32 m0, s36, 0x2000
	s_add_u32 s36, s40, 0xb0000
	v_lshl_add_u64 v[220:221], s[40:41], 0, v[134:135]
	s_addc_u32 s37, s41, 0
	s_add_i32 s84, s72, s56
	global_load_lds_dwordx4 v[220:221], off
	v_lshl_add_u64 v[222:223], s[36:37], 0, v[130:131]
	s_mov_b32 m0, s84
	v_lshl_add_u64 v[224:225], s[42:43], 0, v[132:133]
	global_load_lds_dwordx4 v[222:223], off
	v_lshl_add_u64 v[222:223], s[36:37], 0, v[134:135]
	s_add_i32 m0, s84, 0x2000
	s_nop 0
	global_load_lds_dwordx4 v[222:223], off
	v_lshl_add_u64 v[222:223], s[42:43], 0, v[128:129]
	s_waitcnt vmcnt(6)
	s_waitcnt lgkmcnt(0)
	s_barrier
	s_setprio 1
	s_waitcnt lgkmcnt(0)
	v_mfma_f32_16x16x32_bf16 v[60:63], v[144:147], v[184:187], v[60:63]
	v_mfma_f32_16x16x32_bf16 v[56:59], v[160:163], v[184:187], v[56:59]
	v_mfma_f32_16x16x32_bf16 v[44:47], v[144:147], v[196:199], v[44:47]
	v_mfma_f32_16x16x32_bf16 v[40:43], v[160:163], v[196:199], v[40:43]
	v_mfma_f32_16x16x32_bf16 v[28:31], v[144:147], v[204:207], v[28:31]
	v_mfma_f32_16x16x32_bf16 v[24:27], v[160:163], v[204:207], v[24:27]
	v_mfma_f32_16x16x32_bf16 v[12:15], v[144:147], v[212:215], v[12:15]
	v_mfma_f32_16x16x32_bf16 v[8:11], v[160:163], v[212:215], v[8:11]
	v_mfma_f32_16x16x32_bf16 v[60:63], v[156:159], v[188:191], v[60:63]
	v_mfma_f32_16x16x32_bf16 v[56:59], v[164:167], v[188:191], v[56:59]
	v_mfma_f32_16x16x32_bf16 v[44:47], v[156:159], v[200:203], v[44:47]
	v_mfma_f32_16x16x32_bf16 v[40:43], v[164:167], v[200:203], v[40:43]
	v_mfma_f32_16x16x32_bf16 v[28:31], v[156:159], v[208:211], v[28:31]
	v_mfma_f32_16x16x32_bf16 v[24:27], v[164:167], v[208:211], v[24:27]
	v_mfma_f32_16x16x32_bf16 v[12:15], v[156:159], v[216:219], v[12:15]
	v_mfma_f32_16x16x32_bf16 v[8:11], v[164:167], v[216:219], v[8:11]
	v_mfma_f32_16x16x32_bf16 v[52:55], v[168:171], v[184:187], v[52:55]
	v_mfma_f32_16x16x32_bf16 v[48:51], v[176:179], v[184:187], v[48:51]
	v_mfma_f32_16x16x32_bf16 v[36:39], v[168:171], v[196:199], v[36:39]
	v_mfma_f32_16x16x32_bf16 v[32:35], v[176:179], v[196:199], v[32:35]
	v_mfma_f32_16x16x32_bf16 v[20:23], v[168:171], v[204:207], v[20:23]
	v_mfma_f32_16x16x32_bf16 v[16:19], v[176:179], v[204:207], v[16:19]
	v_mfma_f32_16x16x32_bf16 v[4:7], v[168:171], v[212:215], v[4:7]
	v_mfma_f32_16x16x32_bf16 v[0:3], v[176:179], v[212:215], v[0:3]
	v_mfma_f32_16x16x32_bf16 v[52:55], v[172:175], v[188:191], v[52:55]
	v_mfma_f32_16x16x32_bf16 v[48:51], v[180:183], v[188:191], v[48:51]
	v_mfma_f32_16x16x32_bf16 v[36:39], v[172:175], v[200:203], v[36:39]
	v_mfma_f32_16x16x32_bf16 v[32:35], v[180:183], v[200:203], v[32:35]
	v_mfma_f32_16x16x32_bf16 v[20:23], v[172:175], v[208:211], v[20:23]
	v_mfma_f32_16x16x32_bf16 v[16:19], v[180:183], v[208:211], v[16:19]
	v_mfma_f32_16x16x32_bf16 v[4:7], v[172:175], v[216:219], v[4:7]
	v_mfma_f32_16x16x32_bf16 v[0:3], v[180:183], v[216:219], v[0:3]
	s_setprio 0
	s_barrier
	s_add_i32 s84, 0, 0x18000
	v_add_u32_e32 v155, s84, v149
	s_add_i32 s85, 0, 0x1c000
	ds_read_b128 v[144:147], v155
	ds_read_b128 v[156:159], v155 offset:1024
	ds_read_b128 v[160:163], v155 offset:2048
	ds_read_b128 v[164:167], v155 offset:3072
	v_add_u32_e32 v155, s85, v149
	ds_read_b128 v[168:171], v155
	ds_read_b128 v[172:175], v155 offset:1024
	ds_read_b128 v[176:179], v155 offset:2048
	ds_read_b128 v[180:183], v155 offset:3072
	s_add_u32 s36, s42, 0xb0000
	s_addc_u32 s37, s43, 0
	v_lshl_add_u64 v[226:227], s[36:37], 0, v[128:129]
	ds_read_b128 v[184:187], v153 offset:32768
	ds_read_b128 v[188:191], v153 offset:33792
	ds_read_b128 v[196:199], v153 offset:34816
	ds_read_b128 v[200:203], v153 offset:35840
	ds_read_b128 v[204:207], v153 offset:36864
	ds_read_b128 v[208:211], v153 offset:37888
	ds_read_b128 v[212:215], v153 offset:38912
	ds_read_b128 v[216:219], v153 offset:39936
	s_mov_b32 m0, s57
	s_nop 0
	global_load_lds_dwordx4 v[222:223], off
	s_mov_b32 m0, s58
	s_nop 0
	global_load_lds_dwordx4 v[224:225], off
	s_mov_b32 m0, s59
	s_nop 0
	global_load_lds_dwordx4 v[226:227], off
	v_lshl_add_u64 v[226:227], s[36:37], 0, v[132:133]
	s_mov_b32 m0, s60
	s_nop 0
	global_load_lds_dwordx4 v[226:227], off
	s_waitcnt vmcnt(8)
	s_waitcnt lgkmcnt(0)
	s_barrier
	s_setprio 1
	s_waitcnt lgkmcnt(0)
	v_mfma_f32_16x16x32_bf16 v[124:127], v[144:147], v[184:187], v[124:127]
	v_mfma_f32_16x16x32_bf16 v[120:123], v[160:163], v[184:187], v[120:123]
	v_mfma_f32_16x16x32_bf16 v[108:111], v[144:147], v[196:199], v[108:111]
	v_mfma_f32_16x16x32_bf16 v[104:107], v[160:163], v[196:199], v[104:107]
	v_mfma_f32_16x16x32_bf16 v[92:95], v[144:147], v[204:207], v[92:95]
	v_mfma_f32_16x16x32_bf16 v[88:91], v[160:163], v[204:207], v[88:91]
	v_mfma_f32_16x16x32_bf16 v[76:79], v[144:147], v[212:215], v[76:79]
	v_mfma_f32_16x16x32_bf16 v[72:75], v[160:163], v[212:215], v[72:75]
	v_mfma_f32_16x16x32_bf16 v[124:127], v[156:159], v[188:191], v[124:127]
	v_mfma_f32_16x16x32_bf16 v[120:123], v[164:167], v[188:191], v[120:123]
	v_mfma_f32_16x16x32_bf16 v[108:111], v[156:159], v[200:203], v[108:111]
	v_mfma_f32_16x16x32_bf16 v[104:107], v[164:167], v[200:203], v[104:107]
	v_mfma_f32_16x16x32_bf16 v[92:95], v[156:159], v[208:211], v[92:95]
	v_mfma_f32_16x16x32_bf16 v[88:91], v[164:167], v[208:211], v[88:91]
	v_mfma_f32_16x16x32_bf16 v[76:79], v[156:159], v[216:219], v[76:79]
	v_mfma_f32_16x16x32_bf16 v[72:75], v[164:167], v[216:219], v[72:75]
	v_mfma_f32_16x16x32_bf16 v[116:119], v[168:171], v[184:187], v[116:119]
	v_mfma_f32_16x16x32_bf16 v[112:115], v[176:179], v[184:187], v[112:115]
	v_mfma_f32_16x16x32_bf16 v[100:103], v[168:171], v[196:199], v[100:103]
	v_mfma_f32_16x16x32_bf16 v[96:99], v[176:179], v[196:199], v[96:99]
	v_mfma_f32_16x16x32_bf16 v[84:87], v[168:171], v[204:207], v[84:87]
	v_mfma_f32_16x16x32_bf16 v[80:83], v[176:179], v[204:207], v[80:83]
	v_mfma_f32_16x16x32_bf16 v[68:71], v[168:171], v[212:215], v[68:71]
	v_mfma_f32_16x16x32_bf16 v[64:67], v[176:179], v[212:215], v[64:67]
	v_mfma_f32_16x16x32_bf16 v[116:119], v[172:175], v[188:191], v[116:119]
	v_mfma_f32_16x16x32_bf16 v[112:115], v[180:183], v[188:191], v[112:115]
	v_mfma_f32_16x16x32_bf16 v[100:103], v[172:175], v[200:203], v[100:103]
	v_mfma_f32_16x16x32_bf16 v[96:99], v[180:183], v[200:203], v[96:99]
	v_mfma_f32_16x16x32_bf16 v[84:87], v[172:175], v[208:211], v[84:87]
	v_mfma_f32_16x16x32_bf16 v[80:83], v[180:183], v[208:211], v[80:83]
	v_mfma_f32_16x16x32_bf16 v[68:71], v[172:175], v[216:219], v[68:71]
	v_mfma_f32_16x16x32_bf16 v[64:67], v[180:183], v[216:219], v[64:67]
	s_setprio 0
	s_barrier
	s_add_i32 s36, s84, s56
	v_lshl_add_u64 v[192:193], v[192:193], 0, s[28:29]
	s_mov_b32 m0, s36
	ds_read_b128 v[184:187], v153 offset:49152
	ds_read_b128 v[188:191], v153 offset:50176
	ds_read_b128 v[196:199], v153 offset:51200
	ds_read_b128 v[200:203], v153 offset:52224
	ds_read_b128 v[204:207], v153 offset:53248
	ds_read_b128 v[208:211], v153 offset:54272
	ds_read_b128 v[212:215], v153 offset:55296
	ds_read_b128 v[216:219], v153 offset:56320
	global_load_lds_dwordx4 v[192:193], off
	s_add_i32 m0, s36, 0x2000
	s_add_u32 s36, s40, 0xb0080
	v_lshl_add_u64 v[192:193], v[220:221], 0, s[28:29]
	s_addc_u32 s37, s41, 0
	s_add_i32 s40, s85, s56
	global_load_lds_dwordx4 v[192:193], off
	v_lshl_add_u64 v[192:193], s[36:37], 0, v[130:131]
	s_mov_b32 m0, s40
	s_nop 0
	global_load_lds_dwordx4 v[192:193], off
	v_lshl_add_u64 v[192:193], s[36:37], 0, v[134:135]
	s_add_i32 m0, s40, 0x2000
	s_nop 0
	global_load_lds_dwordx4 v[192:193], off
	s_waitcnt vmcnt(6)
	s_waitcnt lgkmcnt(0)
	s_barrier
	s_setprio 1
	s_waitcnt lgkmcnt(0)
	v_mfma_f32_16x16x32_bf16 v[60:63], v[144:147], v[184:187], v[60:63]
	v_mfma_f32_16x16x32_bf16 v[56:59], v[160:163], v[184:187], v[56:59]
	v_mfma_f32_16x16x32_bf16 v[44:47], v[144:147], v[196:199], v[44:47]
	v_mfma_f32_16x16x32_bf16 v[40:43], v[160:163], v[196:199], v[40:43]
	v_mfma_f32_16x16x32_bf16 v[28:31], v[144:147], v[204:207], v[28:31]
	v_mfma_f32_16x16x32_bf16 v[24:27], v[160:163], v[204:207], v[24:27]
	v_mfma_f32_16x16x32_bf16 v[12:15], v[144:147], v[212:215], v[12:15]
	v_mfma_f32_16x16x32_bf16 v[8:11], v[160:163], v[212:215], v[8:11]
	v_mfma_f32_16x16x32_bf16 v[60:63], v[156:159], v[188:191], v[60:63]
	v_mfma_f32_16x16x32_bf16 v[56:59], v[164:167], v[188:191], v[56:59]
	v_mfma_f32_16x16x32_bf16 v[44:47], v[156:159], v[200:203], v[44:47]
	v_mfma_f32_16x16x32_bf16 v[40:43], v[164:167], v[200:203], v[40:43]
	v_mfma_f32_16x16x32_bf16 v[28:31], v[156:159], v[208:211], v[28:31]
	v_mfma_f32_16x16x32_bf16 v[24:27], v[164:167], v[208:211], v[24:27]
	v_mfma_f32_16x16x32_bf16 v[12:15], v[156:159], v[216:219], v[12:15]
	v_mfma_f32_16x16x32_bf16 v[8:11], v[164:167], v[216:219], v[8:11]
	v_mfma_f32_16x16x32_bf16 v[52:55], v[168:171], v[184:187], v[52:55]
	v_mfma_f32_16x16x32_bf16 v[48:51], v[176:179], v[184:187], v[48:51]
	v_mfma_f32_16x16x32_bf16 v[36:39], v[168:171], v[196:199], v[36:39]
	v_mfma_f32_16x16x32_bf16 v[32:35], v[176:179], v[196:199], v[32:35]
	v_mfma_f32_16x16x32_bf16 v[20:23], v[168:171], v[204:207], v[20:23]
	v_mfma_f32_16x16x32_bf16 v[16:19], v[176:179], v[204:207], v[16:19]
	v_mfma_f32_16x16x32_bf16 v[4:7], v[168:171], v[212:215], v[4:7]
	v_mfma_f32_16x16x32_bf16 v[0:3], v[176:179], v[212:215], v[0:3]
	v_mfma_f32_16x16x32_bf16 v[52:55], v[172:175], v[188:191], v[52:55]
	v_mfma_f32_16x16x32_bf16 v[48:51], v[180:183], v[188:191], v[48:51]
	v_mfma_f32_16x16x32_bf16 v[36:39], v[172:175], v[200:203], v[36:39]
	v_mfma_f32_16x16x32_bf16 v[32:35], v[180:183], v[200:203], v[32:35]
	v_mfma_f32_16x16x32_bf16 v[20:23], v[172:175], v[208:211], v[20:23]
	v_mfma_f32_16x16x32_bf16 v[16:19], v[180:183], v[208:211], v[16:19]
	v_mfma_f32_16x16x32_bf16 v[4:7], v[172:175], v[216:219], v[4:7]
	v_mfma_f32_16x16x32_bf16 v[0:3], v[180:183], v[216:219], v[0:3]
	s_setprio 0
	s_barrier
	v_lshl_add_u64 v[222:223], v[222:223], 0, s[28:29]
	s_mov_b32 m0, s62
	s_nop 0
	global_load_lds_dwordx4 v[222:223], off
	v_lshl_add_u64 v[224:225], v[224:225], 0, s[28:29]
	s_mov_b32 m0, s63
	s_nop 0
	global_load_lds_dwordx4 v[224:225], off
	s_add_i32 s83, s83, 2
	s_add_u32 s81, s81, 0x100
	s_addc_u32 s82, s82, 0
	s_cmp_gt_u32 s83, 41
	s_mov_b64 s[36:37], s[38:39]
	s_cbranch_scc0 .LBB0_2142
	s_and_b64 vcc, exec, s[30:31]
	s_cbranch_vccz .LBB0_2145
	s_barrier

.LBB0_2236:
	ds_read_b128 v[152:155], v157
	ds_read_b128 v[162:165], v157 offset:1024
	ds_read_b128 v[166:169], v157 offset:2048
	ds_read_b128 v[170:173], v157 offset:3072
	ds_read_b128 v[174:177], v158
	ds_read_b128 v[178:181], v158 offset:1024
	ds_read_b128 v[182:185], v158 offset:2048
	ds_read_b128 v[186:189], v158 offset:3072
	s_add_u32 s42, s40, 0xfffc0080
	s_addc_u32 s43, s41, -1
	s_cmp_eq_u32 s88, 12
	s_cselect_b32 s45, s1, s43
	s_cselect_b32 s44, s15, s42
	s_cselect_b32 s43, s16, s87
	s_cselect_b32 s42, s31, s35
	v_lshl_add_u64 v[224:225], s[40:41], 0, v[144:145]
	s_add_i32 m0, s59, 0xc000
	ds_read_b128 v[190:193], v159
	ds_read_b128 v[196:199], v159 offset:1024
	ds_read_b128 v[200:203], v159 offset:2048
	ds_read_b128 v[204:207], v159 offset:3072
	ds_read_b128 v[208:211], v159 offset:4096
	ds_read_b128 v[212:215], v159 offset:5120
	ds_read_b128 v[216:219], v159 offset:6144
	ds_read_b128 v[220:223], v159 offset:7168
	global_load_lds_dwordx4 v[224:225], off
	v_lshl_add_u64 v[224:225], s[40:41], 0, v[146:147]
	s_add_i32 m0, s59, 0xe000
	s_nop 0
	global_load_lds_dwordx4 v[224:225], off
	s_waitcnt vmcnt(8)
	s_waitcnt lgkmcnt(0)
	s_barrier
	s_setprio 1
	s_waitcnt lgkmcnt(0)
	v_mfma_f32_16x16x32_bf16 v[124:127], v[152:155], v[190:193], v[124:127]
	v_mfma_f32_16x16x32_bf16 v[120:123], v[166:169], v[190:193], v[120:123]
	v_mfma_f32_16x16x32_bf16 v[108:111], v[152:155], v[200:203], v[108:111]
	v_mfma_f32_16x16x32_bf16 v[104:107], v[166:169], v[200:203], v[104:107]
	v_mfma_f32_16x16x32_bf16 v[92:95], v[152:155], v[208:211], v[92:95]
	v_mfma_f32_16x16x32_bf16 v[88:91], v[166:169], v[208:211], v[88:91]
	v_mfma_f32_16x16x32_bf16 v[76:79], v[152:155], v[216:219], v[76:79]
	v_mfma_f32_16x16x32_bf16 v[72:75], v[166:169], v[216:219], v[72:75]
	v_mfma_f32_16x16x32_bf16 v[124:127], v[162:165], v[196:199], v[124:127]
	v_mfma_f32_16x16x32_bf16 v[120:123], v[170:173], v[196:199], v[120:123]
	v_mfma_f32_16x16x32_bf16 v[108:111], v[162:165], v[204:207], v[108:111]
	v_mfma_f32_16x16x32_bf16 v[104:107], v[170:173], v[204:207], v[104:107]
	v_mfma_f32_16x16x32_bf16 v[92:95], v[162:165], v[212:215], v[92:95]
	v_mfma_f32_16x16x32_bf16 v[88:91], v[170:173], v[212:215], v[88:91]
	v_mfma_f32_16x16x32_bf16 v[76:79], v[162:165], v[220:223], v[76:79]
	v_mfma_f32_16x16x32_bf16 v[72:75], v[170:173], v[220:223], v[72:75]
	v_mfma_f32_16x16x32_bf16 v[116:119], v[174:177], v[190:193], v[116:119]
	v_mfma_f32_16x16x32_bf16 v[112:115], v[182:185], v[190:193], v[112:115]
	v_mfma_f32_16x16x32_bf16 v[100:103], v[174:177], v[200:203], v[100:103]
	v_mfma_f32_16x16x32_bf16 v[96:99], v[182:185], v[200:203], v[96:99]
	v_mfma_f32_16x16x32_bf16 v[84:87], v[174:177], v[208:211], v[84:87]
	v_mfma_f32_16x16x32_bf16 v[80:83], v[182:185], v[208:211], v[80:83]
	v_mfma_f32_16x16x32_bf16 v[68:71], v[174:177], v[216:219], v[68:71]
	v_mfma_f32_16x16x32_bf16 v[64:67], v[182:185], v[216:219], v[64:67]
	v_mfma_f32_16x16x32_bf16 v[116:119], v[178:181], v[196:199], v[116:119]
	v_mfma_f32_16x16x32_bf16 v[112:115], v[186:189], v[196:199], v[112:115]
	v_mfma_f32_16x16x32_bf16 v[100:103], v[178:181], v[204:207], v[100:103]
	v_mfma_f32_16x16x32_bf16 v[96:99], v[186:189], v[204:207], v[96:99]
	v_mfma_f32_16x16x32_bf16 v[84:87], v[178:181], v[212:215], v[84:87]
	v_mfma_f32_16x16x32_bf16 v[80:83], v[186:189], v[212:215], v[80:83]
	v_mfma_f32_16x16x32_bf16 v[68:71], v[178:181], v[220:223], v[68:71]
	v_mfma_f32_16x16x32_bf16 v[64:67], v[186:189], v[220:223], v[64:67]
	s_setprio 0
	s_barrier
	s_add_i32 s89, s78, s58
	v_lshl_add_u64 v[224:225], s[42:43], 0, v[130:131]
	s_mov_b32 m0, s89
	ds_read_b128 v[190:193], v159 offset:16384
	ds_read_b128 v[196:199], v159 offset:17408
	ds_read_b128 v[200:203], v159 offset:18432
	ds_read_b128 v[204:207], v159 offset:19456
	ds_read_b128 v[208:211], v159 offset:20480
	ds_read_b128 v[212:215], v159 offset:21504
	ds_read_b128 v[216:219], v159 offset:22528
	ds_read_b128 v[220:223], v159 offset:23552
	global_load_lds_dwordx4 v[224:225], off
	s_add_i32 m0, s89, 0x2000
	s_add_u32 s90, s42, 0x40000
	v_lshl_add_u64 v[226:227], s[42:43], 0, v[134:135]
	s_addc_u32 s91, s43, 0
	s_add_i32 s89, s79, s58
	global_load_lds_dwordx4 v[226:227], off
	v_lshl_add_u64 v[228:229], s[90:91], 0, v[130:131]
	s_mov_b32 m0, s89
	v_lshl_add_u64 v[230:231], s[44:45], 0, v[132:133]
	global_load_lds_dwordx4 v[228:229], off
	v_lshl_add_u64 v[228:229], s[90:91], 0, v[134:135]
	s_add_i32 m0, s89, 0x2000
	s_nop 0
	global_load_lds_dwordx4 v[228:229], off
	v_lshl_add_u64 v[228:229], s[44:45], 0, v[128:129]
	s_waitcnt vmcnt(6)
	s_waitcnt lgkmcnt(0)
	s_barrier
	s_setprio 1
	s_waitcnt lgkmcnt(0)
	v_mfma_f32_16x16x32_bf16 v[60:63], v[152:155], v[190:193], v[60:63]
	v_mfma_f32_16x16x32_bf16 v[56:59], v[166:169], v[190:193], v[56:59]
	v_mfma_f32_16x16x32_bf16 v[44:47], v[152:155], v[200:203], v[44:47]
	v_mfma_f32_16x16x32_bf16 v[40:43], v[166:169], v[200:203], v[40:43]
	v_mfma_f32_16x16x32_bf16 v[28:31], v[152:155], v[208:211], v[28:31]
	v_mfma_f32_16x16x32_bf16 v[24:27], v[166:169], v[208:211], v[24:27]
	v_mfma_f32_16x16x32_bf16 v[12:15], v[152:155], v[216:219], v[12:15]
	v_mfma_f32_16x16x32_bf16 v[8:11], v[166:169], v[216:219], v[8:11]
	v_mfma_f32_16x16x32_bf16 v[60:63], v[162:165], v[196:199], v[60:63]
	v_mfma_f32_16x16x32_bf16 v[56:59], v[170:173], v[196:199], v[56:59]
	v_mfma_f32_16x16x32_bf16 v[44:47], v[162:165], v[204:207], v[44:47]
	v_mfma_f32_16x16x32_bf16 v[40:43], v[170:173], v[204:207], v[40:43]
	v_mfma_f32_16x16x32_bf16 v[28:31], v[162:165], v[212:215], v[28:31]
	v_mfma_f32_16x16x32_bf16 v[24:27], v[170:173], v[212:215], v[24:27]
	v_mfma_f32_16x16x32_bf16 v[12:15], v[162:165], v[220:223], v[12:15]
	v_mfma_f32_16x16x32_bf16 v[8:11], v[170:173], v[220:223], v[8:11]
	v_mfma_f32_16x16x32_bf16 v[52:55], v[174:177], v[190:193], v[52:55]
	v_mfma_f32_16x16x32_bf16 v[48:51], v[182:185], v[190:193], v[48:51]
	v_mfma_f32_16x16x32_bf16 v[36:39], v[174:177], v[200:203], v[36:39]
	v_mfma_f32_16x16x32_bf16 v[32:35], v[182:185], v[200:203], v[32:35]
	v_mfma_f32_16x16x32_bf16 v[20:23], v[174:177], v[208:211], v[20:23]
	v_mfma_f32_16x16x32_bf16 v[16:19], v[182:185], v[208:211], v[16:19]
	v_mfma_f32_16x16x32_bf16 v[4:7], v[174:177], v[216:219], v[4:7]
	v_mfma_f32_16x16x32_bf16 v[0:3], v[182:185], v[216:219], v[0:3]
	v_mfma_f32_16x16x32_bf16 v[52:55], v[178:181], v[196:199], v[52:55]
	v_mfma_f32_16x16x32_bf16 v[48:51], v[186:189], v[196:199], v[48:51]
	v_mfma_f32_16x16x32_bf16 v[36:39], v[178:181], v[204:207], v[36:39]
	v_mfma_f32_16x16x32_bf16 v[32:35], v[186:189], v[204:207], v[32:35]
	v_mfma_f32_16x16x32_bf16 v[20:23], v[178:181], v[212:215], v[20:23]
	v_mfma_f32_16x16x32_bf16 v[16:19], v[186:189], v[212:215], v[16:19]
	v_mfma_f32_16x16x32_bf16 v[4:7], v[178:181], v[220:223], v[4:7]
	v_mfma_f32_16x16x32_bf16 v[0:3], v[186:189], v[220:223], v[0:3]
	s_setprio 0
	s_barrier
	s_add_i32 s89, 0, 0x18000
	v_add_u32_e32 v136, s89, v141
	s_add_i32 s90, 0, 0x1c000
	ds_read_b128 v[152:155], v136
	ds_read_b128 v[162:165], v136 offset:1024
	ds_read_b128 v[166:169], v136 offset:2048
	ds_read_b128 v[170:173], v136 offset:3072
	v_add_u32_e32 v136, s90, v141
	ds_read_b128 v[174:177], v136
	ds_read_b128 v[178:181], v136 offset:1024
	ds_read_b128 v[182:185], v136 offset:2048
	ds_read_b128 v[186:189], v136 offset:3072
	s_add_u32 s44, s44, 0x40000
	s_addc_u32 s45, s45, 0
	v_lshl_add_u64 v[232:233], s[44:45], 0, v[128:129]
	ds_read_b128 v[190:193], v159 offset:32768
	ds_read_b128 v[196:199], v159 offset:33792
	ds_read_b128 v[200:203], v159 offset:34816
	ds_read_b128 v[204:207], v159 offset:35840
	ds_read_b128 v[208:211], v159 offset:36864
	ds_read_b128 v[212:215], v159 offset:37888
	ds_read_b128 v[216:219], v159 offset:38912
	ds_read_b128 v[220:223], v159 offset:39936
	s_mov_b32 m0, s59
	s_nop 0
	global_load_lds_dwordx4 v[228:229], off
	s_mov_b32 m0, s60
	s_nop 0
	global_load_lds_dwordx4 v[230:231], off
	s_mov_b32 m0, s61
	s_nop 0
	global_load_lds_dwordx4 v[232:233], off
	v_lshl_add_u64 v[232:233], s[44:45], 0, v[132:133]
	s_mov_b32 m0, s62
	s_nop 0
	global_load_lds_dwordx4 v[232:233], off
	s_waitcnt vmcnt(8)
	s_waitcnt lgkmcnt(0)
	s_barrier
	s_setprio 1
	s_waitcnt lgkmcnt(0)
	v_mfma_f32_16x16x32_bf16 v[124:127], v[152:155], v[190:193], v[124:127]
	v_mfma_f32_16x16x32_bf16 v[120:123], v[166:169], v[190:193], v[120:123]
	v_mfma_f32_16x16x32_bf16 v[108:111], v[152:155], v[200:203], v[108:111]
	v_mfma_f32_16x16x32_bf16 v[104:107], v[166:169], v[200:203], v[104:107]
	v_mfma_f32_16x16x32_bf16 v[92:95], v[152:155], v[208:211], v[92:95]
	v_mfma_f32_16x16x32_bf16 v[88:91], v[166:169], v[208:211], v[88:91]
	v_mfma_f32_16x16x32_bf16 v[76:79], v[152:155], v[216:219], v[76:79]
	v_mfma_f32_16x16x32_bf16 v[72:75], v[166:169], v[216:219], v[72:75]
	v_mfma_f32_16x16x32_bf16 v[124:127], v[162:165], v[196:199], v[124:127]
	v_mfma_f32_16x16x32_bf16 v[120:123], v[170:173], v[196:199], v[120:123]
	v_mfma_f32_16x16x32_bf16 v[108:111], v[162:165], v[204:207], v[108:111]
	v_mfma_f32_16x16x32_bf16 v[104:107], v[170:173], v[204:207], v[104:107]
	v_mfma_f32_16x16x32_bf16 v[92:95], v[162:165], v[212:215], v[92:95]
	v_mfma_f32_16x16x32_bf16 v[88:91], v[170:173], v[212:215], v[88:91]
	v_mfma_f32_16x16x32_bf16 v[76:79], v[162:165], v[220:223], v[76:79]
	v_mfma_f32_16x16x32_bf16 v[72:75], v[170:173], v[220:223], v[72:75]
	v_mfma_f32_16x16x32_bf16 v[116:119], v[174:177], v[190:193], v[116:119]
	v_mfma_f32_16x16x32_bf16 v[112:115], v[182:185], v[190:193], v[112:115]
	v_mfma_f32_16x16x32_bf16 v[100:103], v[174:177], v[200:203], v[100:103]
	v_mfma_f32_16x16x32_bf16 v[96:99], v[182:185], v[200:203], v[96:99]
	v_mfma_f32_16x16x32_bf16 v[84:87], v[174:177], v[208:211], v[84:87]
	v_mfma_f32_16x16x32_bf16 v[80:83], v[182:185], v[208:211], v[80:83]
	v_mfma_f32_16x16x32_bf16 v[68:71], v[174:177], v[216:219], v[68:71]
	v_mfma_f32_16x16x32_bf16 v[64:67], v[182:185], v[216:219], v[64:67]
	v_mfma_f32_16x16x32_bf16 v[116:119], v[178:181], v[196:199], v[116:119]
	v_mfma_f32_16x16x32_bf16 v[112:115], v[186:189], v[196:199], v[112:115]
	v_mfma_f32_16x16x32_bf16 v[100:103], v[178:181], v[204:207], v[100:103]
	v_mfma_f32_16x16x32_bf16 v[96:99], v[186:189], v[204:207], v[96:99]
	v_mfma_f32_16x16x32_bf16 v[84:87], v[178:181], v[212:215], v[84:87]
	v_mfma_f32_16x16x32_bf16 v[80:83], v[186:189], v[212:215], v[80:83]
	v_mfma_f32_16x16x32_bf16 v[68:71], v[178:181], v[220:223], v[68:71]
	v_mfma_f32_16x16x32_bf16 v[64:67], v[186:189], v[220:223], v[64:67]
	s_setprio 0
	s_barrier
	s_add_i32 s44, s89, s58
	v_lshl_add_u64 v[224:225], v[224:225], 0, s[26:27]
	s_mov_b32 m0, s44
	ds_read_b128 v[190:193], v159 offset:49152
	ds_read_b128 v[196:199], v159 offset:50176
	ds_read_b128 v[200:203], v159 offset:51200
	ds_read_b128 v[204:207], v159 offset:52224
	ds_read_b128 v[208:211], v159 offset:53248
	ds_read_b128 v[212:215], v159 offset:54272
	ds_read_b128 v[216:219], v159 offset:55296
	ds_read_b128 v[220:223], v159 offset:56320
	global_load_lds_dwordx4 v[224:225], off
	s_add_i32 m0, s44, 0x2000
	s_add_u32 s42, s42, 0x40080
	v_lshl_add_u64 v[224:225], v[226:227], 0, s[26:27]
	s_addc_u32 s43, s43, 0
	s_add_i32 s44, s90, s58
	global_load_lds_dwordx4 v[224:225], off
	v_lshl_add_u64 v[224:225], s[42:43], 0, v[130:131]
	s_mov_b32 m0, s44
	s_nop 0
	global_load_lds_dwordx4 v[224:225], off
	v_lshl_add_u64 v[224:225], s[42:43], 0, v[134:135]
	s_add_i32 m0, s44, 0x2000
	s_nop 0
	global_load_lds_dwordx4 v[224:225], off
	s_waitcnt vmcnt(6)
	s_waitcnt lgkmcnt(0)
	s_barrier
	s_setprio 1
	s_waitcnt lgkmcnt(0)
	v_mfma_f32_16x16x32_bf16 v[60:63], v[152:155], v[190:193], v[60:63]
	v_mfma_f32_16x16x32_bf16 v[56:59], v[166:169], v[190:193], v[56:59]
	v_mfma_f32_16x16x32_bf16 v[44:47], v[152:155], v[200:203], v[44:47]
	v_mfma_f32_16x16x32_bf16 v[40:43], v[166:169], v[200:203], v[40:43]
	v_mfma_f32_16x16x32_bf16 v[28:31], v[152:155], v[208:211], v[28:31]
	v_mfma_f32_16x16x32_bf16 v[24:27], v[166:169], v[208:211], v[24:27]
	v_mfma_f32_16x16x32_bf16 v[12:15], v[152:155], v[216:219], v[12:15]
	v_mfma_f32_16x16x32_bf16 v[8:11], v[166:169], v[216:219], v[8:11]
	v_mfma_f32_16x16x32_bf16 v[60:63], v[162:165], v[196:199], v[60:63]
	v_mfma_f32_16x16x32_bf16 v[56:59], v[170:173], v[196:199], v[56:59]
	v_mfma_f32_16x16x32_bf16 v[44:47], v[162:165], v[204:207], v[44:47]
	v_mfma_f32_16x16x32_bf16 v[40:43], v[170:173], v[204:207], v[40:43]
	v_mfma_f32_16x16x32_bf16 v[28:31], v[162:165], v[212:215], v[28:31]
	v_mfma_f32_16x16x32_bf16 v[24:27], v[170:173], v[212:215], v[24:27]
	v_mfma_f32_16x16x32_bf16 v[12:15], v[162:165], v[220:223], v[12:15]
	v_mfma_f32_16x16x32_bf16 v[8:11], v[170:173], v[220:223], v[8:11]
	v_mfma_f32_16x16x32_bf16 v[52:55], v[174:177], v[190:193], v[52:55]
	v_mfma_f32_16x16x32_bf16 v[48:51], v[182:185], v[190:193], v[48:51]
	v_mfma_f32_16x16x32_bf16 v[36:39], v[174:177], v[200:203], v[36:39]
	v_mfma_f32_16x16x32_bf16 v[32:35], v[182:185], v[200:203], v[32:35]
	v_mfma_f32_16x16x32_bf16 v[20:23], v[174:177], v[208:211], v[20:23]
	v_mfma_f32_16x16x32_bf16 v[16:19], v[182:185], v[208:211], v[16:19]
	v_mfma_f32_16x16x32_bf16 v[4:7], v[174:177], v[216:219], v[4:7]
	v_mfma_f32_16x16x32_bf16 v[0:3], v[182:185], v[216:219], v[0:3]
	v_mfma_f32_16x16x32_bf16 v[52:55], v[178:181], v[196:199], v[52:55]
	v_mfma_f32_16x16x32_bf16 v[48:51], v[186:189], v[196:199], v[48:51]
	v_mfma_f32_16x16x32_bf16 v[36:39], v[178:181], v[204:207], v[36:39]
	v_mfma_f32_16x16x32_bf16 v[32:35], v[186:189], v[204:207], v[32:35]
	v_mfma_f32_16x16x32_bf16 v[20:23], v[178:181], v[212:215], v[20:23]
	v_mfma_f32_16x16x32_bf16 v[16:19], v[186:189], v[212:215], v[16:19]
	v_mfma_f32_16x16x32_bf16 v[4:7], v[178:181], v[220:223], v[4:7]
	v_mfma_f32_16x16x32_bf16 v[0:3], v[186:189], v[220:223], v[0:3]
	s_setprio 0
	s_barrier
	v_lshl_add_u64 v[228:229], v[228:229], 0, s[26:27]
	s_mov_b32 m0, s71
	s_nop 0
	global_load_lds_dwordx4 v[228:229], off
	v_lshl_add_u64 v[230:231], v[230:231], 0, s[26:27]
	s_mov_b32 m0, s72
	s_nop 0
	global_load_lds_dwordx4 v[230:231], off
	s_add_i32 s88, s88, 2
	s_add_u32 s40, s40, 0x100
	s_addc_u32 s41, s41, 0
	s_add_u32 s35, s35, 0x100
	s_addc_u32 s87, s87, 0
	s_cmp_gt_u32 s88, 13
	s_cbranch_scc0 .LBB0_2236
	s_and_b64 vcc, exec, s[28:29]
	s_cbranch_vccz .LBB0_2239
	s_barrier

.LBB0_2370:
	ds_read_b128 v[148:151], v144
	ds_read_b128 v[152:155], v144 offset:1024
	ds_read_b128 v[156:159], v144 offset:2048
	ds_read_b128 v[160:163], v144 offset:3072
	ds_read_b128 v[164:167], v145
	ds_read_b128 v[168:171], v145 offset:1024
	ds_read_b128 v[172:175], v145 offset:2048
	ds_read_b128 v[176:179], v145 offset:3072
	s_add_u32 s38, s36, 0x100
	s_addc_u32 s39, s37, 0
	s_cmp_eq_u32 s81, 4
	s_cselect_b32 s43, s31, s39
	s_cselect_b32 s42, s30, s38
	s_cselect_b32 s41, s35, s27
	s_cselect_b32 s40, s34, s17
	v_lshl_add_u64 v[192:193], s[36:37], 0, v[138:139]
	s_add_i32 m0, s55, 0xc000
	ds_read_b128 v[180:183], v146
	ds_read_b128 v[184:187], v146 offset:1024
	ds_read_b128 v[188:191], v146 offset:2048
	ds_read_b128 v[196:199], v146 offset:3072
	ds_read_b128 v[200:203], v146 offset:4096
	ds_read_b128 v[204:207], v146 offset:5120
	ds_read_b128 v[208:211], v146 offset:6144
	ds_read_b128 v[212:215], v146 offset:7168
	global_load_lds_dwordx4 v[192:193], off
	v_lshl_add_u64 v[192:193], s[36:37], 0, v[140:141]
	s_add_i32 m0, s55, 0xe000
	s_nop 0
	global_load_lds_dwordx4 v[192:193], off
	s_waitcnt vmcnt(8)
	s_waitcnt lgkmcnt(0)
	s_barrier
	s_setprio 1
	s_waitcnt lgkmcnt(0)
	v_mfma_f32_16x16x32_bf16 v[124:127], v[148:151], v[180:183], v[124:127]
	v_mfma_f32_16x16x32_bf16 v[120:123], v[156:159], v[180:183], v[120:123]
	v_mfma_f32_16x16x32_bf16 v[116:119], v[148:151], v[188:191], v[116:119]
	v_mfma_f32_16x16x32_bf16 v[112:115], v[156:159], v[188:191], v[112:115]
	v_mfma_f32_16x16x32_bf16 v[104:107], v[148:151], v[200:203], v[104:107]
	v_mfma_f32_16x16x32_bf16 v[96:99], v[156:159], v[200:203], v[96:99]
	v_mfma_f32_16x16x32_bf16 v[88:91], v[148:151], v[208:211], v[88:91]
	v_mfma_f32_16x16x32_bf16 v[80:83], v[156:159], v[208:211], v[80:83]
	v_mfma_f32_16x16x32_bf16 v[124:127], v[152:155], v[184:187], v[124:127]
	v_mfma_f32_16x16x32_bf16 v[120:123], v[160:163], v[184:187], v[120:123]
	v_mfma_f32_16x16x32_bf16 v[116:119], v[152:155], v[196:199], v[116:119]
	v_mfma_f32_16x16x32_bf16 v[112:115], v[160:163], v[196:199], v[112:115]
	v_mfma_f32_16x16x32_bf16 v[104:107], v[152:155], v[204:207], v[104:107]
	v_mfma_f32_16x16x32_bf16 v[96:99], v[160:163], v[204:207], v[96:99]
	v_mfma_f32_16x16x32_bf16 v[88:91], v[152:155], v[212:215], v[88:91]
	v_mfma_f32_16x16x32_bf16 v[80:83], v[160:163], v[212:215], v[80:83]
	v_mfma_f32_16x16x32_bf16 v[108:111], v[164:167], v[180:183], v[108:111]
	v_mfma_f32_16x16x32_bf16 v[100:103], v[172:175], v[180:183], v[100:103]
	v_mfma_f32_16x16x32_bf16 v[92:95], v[164:167], v[188:191], v[92:95]
	v_mfma_f32_16x16x32_bf16 v[84:87], v[172:175], v[188:191], v[84:87]
	v_mfma_f32_16x16x32_bf16 v[76:79], v[164:167], v[200:203], v[76:79]
	v_mfma_f32_16x16x32_bf16 v[72:75], v[172:175], v[200:203], v[72:75]
	v_mfma_f32_16x16x32_bf16 v[68:71], v[164:167], v[208:211], v[68:71]
	v_mfma_f32_16x16x32_bf16 v[64:67], v[172:175], v[208:211], v[64:67]
	v_mfma_f32_16x16x32_bf16 v[108:111], v[168:171], v[184:187], v[108:111]
	v_mfma_f32_16x16x32_bf16 v[100:103], v[176:179], v[184:187], v[100:103]
	v_mfma_f32_16x16x32_bf16 v[92:95], v[168:171], v[196:199], v[92:95]
	v_mfma_f32_16x16x32_bf16 v[84:87], v[176:179], v[196:199], v[84:87]
	v_mfma_f32_16x16x32_bf16 v[76:79], v[168:171], v[204:207], v[76:79]
	v_mfma_f32_16x16x32_bf16 v[72:75], v[176:179], v[204:207], v[72:75]
	v_mfma_f32_16x16x32_bf16 v[68:71], v[168:171], v[212:215], v[68:71]
	v_mfma_f32_16x16x32_bf16 v[64:67], v[176:179], v[212:215], v[64:67]
	s_setprio 0
	s_barrier
	s_add_i32 s36, s71, s54
	v_lshl_add_u64 v[192:193], s[40:41], 0, v[132:133]
	s_mov_b32 m0, s36
	ds_read_b128 v[180:183], v146 offset:16384
	ds_read_b128 v[184:187], v146 offset:17408
	ds_read_b128 v[188:191], v146 offset:18432
	ds_read_b128 v[196:199], v146 offset:19456
	ds_read_b128 v[200:203], v146 offset:20480
	ds_read_b128 v[204:207], v146 offset:21504
	ds_read_b128 v[208:211], v146 offset:22528
	ds_read_b128 v[212:215], v146 offset:23552
	global_load_lds_dwordx4 v[192:193], off
	s_add_i32 m0, s36, 0x2000
	s_add_u32 s36, s40, 0x20000
	v_lshl_add_u64 v[216:217], s[40:41], 0, v[128:129]
	s_addc_u32 s37, s41, 0
	s_add_i32 s82, s72, s54
	global_load_lds_dwordx4 v[216:217], off
	v_lshl_add_u64 v[218:219], s[36:37], 0, v[132:133]
	s_mov_b32 m0, s82
	v_lshl_add_u64 v[220:221], s[42:43], 0, v[130:131]
	global_load_lds_dwordx4 v[218:219], off
	v_lshl_add_u64 v[218:219], s[36:37], 0, v[128:129]
	s_add_i32 m0, s82, 0x2000
	s_nop 0
	global_load_lds_dwordx4 v[218:219], off
	v_lshl_add_u64 v[218:219], s[42:43], 0, v[134:135]
	s_waitcnt vmcnt(6)
	s_waitcnt lgkmcnt(0)
	s_barrier
	s_setprio 1
	s_waitcnt lgkmcnt(0)
	v_mfma_f32_16x16x32_bf16 v[60:63], v[148:151], v[180:183], v[60:63]
	v_mfma_f32_16x16x32_bf16 v[56:59], v[156:159], v[180:183], v[56:59]
	v_mfma_f32_16x16x32_bf16 v[52:55], v[148:151], v[188:191], v[52:55]
	v_mfma_f32_16x16x32_bf16 v[48:51], v[156:159], v[188:191], v[48:51]
	v_mfma_f32_16x16x32_bf16 v[40:43], v[148:151], v[200:203], v[40:43]
	v_mfma_f32_16x16x32_bf16 v[32:35], v[156:159], v[200:203], v[32:35]
	v_mfma_f32_16x16x32_bf16 v[24:27], v[148:151], v[208:211], v[24:27]
	v_mfma_f32_16x16x32_bf16 v[16:19], v[156:159], v[208:211], v[16:19]
	v_mfma_f32_16x16x32_bf16 v[60:63], v[152:155], v[184:187], v[60:63]
	v_mfma_f32_16x16x32_bf16 v[56:59], v[160:163], v[184:187], v[56:59]
	v_mfma_f32_16x16x32_bf16 v[52:55], v[152:155], v[196:199], v[52:55]
	v_mfma_f32_16x16x32_bf16 v[48:51], v[160:163], v[196:199], v[48:51]
	v_mfma_f32_16x16x32_bf16 v[40:43], v[152:155], v[204:207], v[40:43]
	v_mfma_f32_16x16x32_bf16 v[32:35], v[160:163], v[204:207], v[32:35]
	v_mfma_f32_16x16x32_bf16 v[24:27], v[152:155], v[212:215], v[24:27]
	v_mfma_f32_16x16x32_bf16 v[16:19], v[160:163], v[212:215], v[16:19]
	v_mfma_f32_16x16x32_bf16 v[44:47], v[164:167], v[180:183], v[44:47]
	v_mfma_f32_16x16x32_bf16 v[36:39], v[172:175], v[180:183], v[36:39]
	v_mfma_f32_16x16x32_bf16 v[28:31], v[164:167], v[188:191], v[28:31]
	v_mfma_f32_16x16x32_bf16 v[20:23], v[172:175], v[188:191], v[20:23]
	v_mfma_f32_16x16x32_bf16 v[12:15], v[164:167], v[200:203], v[12:15]
	v_mfma_f32_16x16x32_bf16 v[8:11], v[172:175], v[200:203], v[8:11]
	v_mfma_f32_16x16x32_bf16 v[4:7], v[164:167], v[208:211], v[4:7]
	v_mfma_f32_16x16x32_bf16 v[0:3], v[172:175], v[208:211], v[0:3]
	v_mfma_f32_16x16x32_bf16 v[44:47], v[168:171], v[184:187], v[44:47]
	v_mfma_f32_16x16x32_bf16 v[36:39], v[176:179], v[184:187], v[36:39]
	v_mfma_f32_16x16x32_bf16 v[28:31], v[168:171], v[196:199], v[28:31]
	v_mfma_f32_16x16x32_bf16 v[20:23], v[176:179], v[196:199], v[20:23]
	v_mfma_f32_16x16x32_bf16 v[12:15], v[168:171], v[204:207], v[12:15]
	v_mfma_f32_16x16x32_bf16 v[8:11], v[176:179], v[204:207], v[8:11]
	v_mfma_f32_16x16x32_bf16 v[4:7], v[168:171], v[212:215], v[4:7]
	v_mfma_f32_16x16x32_bf16 v[0:3], v[176:179], v[212:215], v[0:3]
	s_setprio 0
	s_barrier
	s_add_i32 s82, 0, 0x18000
	v_add_u32_e32 v147, s82, v143
	s_add_i32 s83, 0, 0x1c000
	ds_read_b128 v[148:151], v147
	ds_read_b128 v[152:155], v147 offset:1024
	ds_read_b128 v[156:159], v147 offset:2048
	ds_read_b128 v[160:163], v147 offset:3072
	v_add_u32_e32 v147, s83, v143
	ds_read_b128 v[164:167], v147
	ds_read_b128 v[168:171], v147 offset:1024
	ds_read_b128 v[172:175], v147 offset:2048
	ds_read_b128 v[176:179], v147 offset:3072
	s_add_u32 s36, s42, 0x30000
	s_addc_u32 s37, s43, 0
	v_lshl_add_u64 v[222:223], s[36:37], 0, v[134:135]
	ds_read_b128 v[180:183], v146 offset:32768
	ds_read_b128 v[184:187], v146 offset:33792
	ds_read_b128 v[188:191], v146 offset:34816
	ds_read_b128 v[196:199], v146 offset:35840
	ds_read_b128 v[200:203], v146 offset:36864
	ds_read_b128 v[204:207], v146 offset:37888
	ds_read_b128 v[208:211], v146 offset:38912
	ds_read_b128 v[212:215], v146 offset:39936
	s_mov_b32 m0, s55
	s_nop 0
	global_load_lds_dwordx4 v[218:219], off
	s_mov_b32 m0, s56
	s_nop 0
	global_load_lds_dwordx4 v[220:221], off
	s_mov_b32 m0, s57
	s_nop 0
	global_load_lds_dwordx4 v[222:223], off
	v_lshl_add_u64 v[222:223], s[36:37], 0, v[130:131]
	s_mov_b32 m0, s58
	s_nop 0
	global_load_lds_dwordx4 v[222:223], off
	s_waitcnt vmcnt(8)
	s_waitcnt lgkmcnt(0)
	s_barrier
	s_setprio 1
	s_waitcnt lgkmcnt(0)
	v_mfma_f32_16x16x32_bf16 v[124:127], v[148:151], v[180:183], v[124:127]
	v_mfma_f32_16x16x32_bf16 v[120:123], v[156:159], v[180:183], v[120:123]
	v_mfma_f32_16x16x32_bf16 v[116:119], v[148:151], v[188:191], v[116:119]
	v_mfma_f32_16x16x32_bf16 v[112:115], v[156:159], v[188:191], v[112:115]
	v_mfma_f32_16x16x32_bf16 v[104:107], v[148:151], v[200:203], v[104:107]
	v_mfma_f32_16x16x32_bf16 v[96:99], v[156:159], v[200:203], v[96:99]
	v_mfma_f32_16x16x32_bf16 v[88:91], v[148:151], v[208:211], v[88:91]
	v_mfma_f32_16x16x32_bf16 v[80:83], v[156:159], v[208:211], v[80:83]
	v_mfma_f32_16x16x32_bf16 v[124:127], v[152:155], v[184:187], v[124:127]
	v_mfma_f32_16x16x32_bf16 v[120:123], v[160:163], v[184:187], v[120:123]
	v_mfma_f32_16x16x32_bf16 v[116:119], v[152:155], v[196:199], v[116:119]
	v_mfma_f32_16x16x32_bf16 v[112:115], v[160:163], v[196:199], v[112:115]
	v_mfma_f32_16x16x32_bf16 v[104:107], v[152:155], v[204:207], v[104:107]
	v_mfma_f32_16x16x32_bf16 v[96:99], v[160:163], v[204:207], v[96:99]
	v_mfma_f32_16x16x32_bf16 v[88:91], v[152:155], v[212:215], v[88:91]
	v_mfma_f32_16x16x32_bf16 v[80:83], v[160:163], v[212:215], v[80:83]
	v_mfma_f32_16x16x32_bf16 v[108:111], v[164:167], v[180:183], v[108:111]
	v_mfma_f32_16x16x32_bf16 v[100:103], v[172:175], v[180:183], v[100:103]
	v_mfma_f32_16x16x32_bf16 v[92:95], v[164:167], v[188:191], v[92:95]
	v_mfma_f32_16x16x32_bf16 v[84:87], v[172:175], v[188:191], v[84:87]
	v_mfma_f32_16x16x32_bf16 v[76:79], v[164:167], v[200:203], v[76:79]
	v_mfma_f32_16x16x32_bf16 v[72:75], v[172:175], v[200:203], v[72:75]
	v_mfma_f32_16x16x32_bf16 v[68:71], v[164:167], v[208:211], v[68:71]
	v_mfma_f32_16x16x32_bf16 v[64:67], v[172:175], v[208:211], v[64:67]
	v_mfma_f32_16x16x32_bf16 v[108:111], v[168:171], v[184:187], v[108:111]
	v_mfma_f32_16x16x32_bf16 v[100:103], v[176:179], v[184:187], v[100:103]
	v_mfma_f32_16x16x32_bf16 v[92:95], v[168:171], v[196:199], v[92:95]
	v_mfma_f32_16x16x32_bf16 v[84:87], v[176:179], v[196:199], v[84:87]
	v_mfma_f32_16x16x32_bf16 v[76:79], v[168:171], v[204:207], v[76:79]
	v_mfma_f32_16x16x32_bf16 v[72:75], v[176:179], v[204:207], v[72:75]
	v_mfma_f32_16x16x32_bf16 v[68:71], v[168:171], v[212:215], v[68:71]
	v_mfma_f32_16x16x32_bf16 v[64:67], v[176:179], v[212:215], v[64:67]
	s_setprio 0
	s_barrier
	s_add_i32 s36, s82, s54
	v_lshl_add_u64 v[192:193], v[192:193], 0, s[14:15]
	s_mov_b32 m0, s36
	ds_read_b128 v[180:183], v146 offset:49152
	ds_read_b128 v[184:187], v146 offset:50176
	ds_read_b128 v[188:191], v146 offset:51200
	ds_read_b128 v[196:199], v146 offset:52224
	ds_read_b128 v[200:203], v146 offset:53248
	ds_read_b128 v[204:207], v146 offset:54272
	ds_read_b128 v[208:211], v146 offset:55296
	ds_read_b128 v[212:215], v146 offset:56320
	global_load_lds_dwordx4 v[192:193], off
	s_add_i32 m0, s36, 0x2000
	s_add_u32 s36, s40, 0x20080
	v_lshl_add_u64 v[192:193], v[216:217], 0, s[14:15]
	s_addc_u32 s37, s41, 0
	s_add_i32 s40, s83, s54
	global_load_lds_dwordx4 v[192:193], off
	v_lshl_add_u64 v[192:193], s[36:37], 0, v[132:133]
	s_mov_b32 m0, s40
	s_nop 0
	global_load_lds_dwordx4 v[192:193], off
	v_lshl_add_u64 v[192:193], s[36:37], 0, v[128:129]
	s_add_i32 m0, s40, 0x2000
	s_nop 0
	global_load_lds_dwordx4 v[192:193], off
	s_waitcnt vmcnt(6)
	s_waitcnt lgkmcnt(0)
	s_barrier
	s_setprio 1
	s_waitcnt lgkmcnt(0)
	v_mfma_f32_16x16x32_bf16 v[60:63], v[148:151], v[180:183], v[60:63]
	v_mfma_f32_16x16x32_bf16 v[56:59], v[156:159], v[180:183], v[56:59]
	v_mfma_f32_16x16x32_bf16 v[52:55], v[148:151], v[188:191], v[52:55]
	v_mfma_f32_16x16x32_bf16 v[48:51], v[156:159], v[188:191], v[48:51]
	v_mfma_f32_16x16x32_bf16 v[40:43], v[148:151], v[200:203], v[40:43]
	v_mfma_f32_16x16x32_bf16 v[32:35], v[156:159], v[200:203], v[32:35]
	v_mfma_f32_16x16x32_bf16 v[24:27], v[148:151], v[208:211], v[24:27]
	v_mfma_f32_16x16x32_bf16 v[16:19], v[156:159], v[208:211], v[16:19]
	v_mfma_f32_16x16x32_bf16 v[60:63], v[152:155], v[184:187], v[60:63]
	v_mfma_f32_16x16x32_bf16 v[56:59], v[160:163], v[184:187], v[56:59]
	v_mfma_f32_16x16x32_bf16 v[52:55], v[152:155], v[196:199], v[52:55]
	v_mfma_f32_16x16x32_bf16 v[48:51], v[160:163], v[196:199], v[48:51]
	v_mfma_f32_16x16x32_bf16 v[40:43], v[152:155], v[204:207], v[40:43]
	v_mfma_f32_16x16x32_bf16 v[32:35], v[160:163], v[204:207], v[32:35]
	v_mfma_f32_16x16x32_bf16 v[24:27], v[152:155], v[212:215], v[24:27]
	v_mfma_f32_16x16x32_bf16 v[16:19], v[160:163], v[212:215], v[16:19]
	v_mfma_f32_16x16x32_bf16 v[44:47], v[164:167], v[180:183], v[44:47]
	v_mfma_f32_16x16x32_bf16 v[36:39], v[172:175], v[180:183], v[36:39]
	v_mfma_f32_16x16x32_bf16 v[28:31], v[164:167], v[188:191], v[28:31]
	v_mfma_f32_16x16x32_bf16 v[20:23], v[172:175], v[188:191], v[20:23]
	v_mfma_f32_16x16x32_bf16 v[12:15], v[164:167], v[200:203], v[12:15]
	v_mfma_f32_16x16x32_bf16 v[8:11], v[172:175], v[200:203], v[8:11]
	v_mfma_f32_16x16x32_bf16 v[4:7], v[164:167], v[208:211], v[4:7]
	v_mfma_f32_16x16x32_bf16 v[0:3], v[172:175], v[208:211], v[0:3]
	v_mfma_f32_16x16x32_bf16 v[44:47], v[168:171], v[184:187], v[44:47]
	v_mfma_f32_16x16x32_bf16 v[36:39], v[176:179], v[184:187], v[36:39]
	v_mfma_f32_16x16x32_bf16 v[28:31], v[168:171], v[196:199], v[28:31]
	v_mfma_f32_16x16x32_bf16 v[20:23], v[176:179], v[196:199], v[20:23]
	v_mfma_f32_16x16x32_bf16 v[12:15], v[168:171], v[204:207], v[12:15]
	v_mfma_f32_16x16x32_bf16 v[8:11], v[176:179], v[204:207], v[8:11]
	v_mfma_f32_16x16x32_bf16 v[4:7], v[168:171], v[212:215], v[4:7]
	v_mfma_f32_16x16x32_bf16 v[0:3], v[176:179], v[212:215], v[0:3]
	s_setprio 0
	s_barrier
	v_lshl_add_u64 v[218:219], v[218:219], 0, s[14:15]
	s_mov_b32 m0, s62
	s_nop 0
	global_load_lds_dwordx4 v[218:219], off
	v_lshl_add_u64 v[220:221], v[220:221], 0, s[14:15]
	s_mov_b32 m0, s63
	s_nop 0
	global_load_lds_dwordx4 v[220:221], off
	s_add_i32 s81, s81, 2
	s_add_u32 s17, s17, 0x100
	s_addc_u32 s27, s27, 0
	s_cmp_gt_u32 s81, 5
	s_mov_b64 s[36:37], s[38:39]
	s_cbranch_scc0 .LBB0_2370
	s_and_b64 vcc, exec, s[18:19]
	s_cbranch_vccz .LBB0_2373
	s_barrier

.LBB0_2396:
	ds_read_b128 v[144:147], v153
	ds_read_b128 v[158:161], v153 offset:1024
	ds_read_b128 v[162:165], v153 offset:2048
	ds_read_b128 v[166:169], v153 offset:3072
	ds_read_b128 v[170:173], v154
	ds_read_b128 v[174:177], v154 offset:1024
	ds_read_b128 v[178:181], v154 offset:2048
	ds_read_b128 v[182:185], v154 offset:3072
	s_add_u32 s36, s34, 0xfffc0080
	s_addc_u32 s37, s35, -1
	s_cmp_eq_u32 s78, 12
	s_cselect_b32 s39, s27, s37
	s_cselect_b32 s38, s71, s36
	s_cselect_b32 s37, s25, s77
	s_cselect_b32 s36, s72, s73
	v_lshl_add_u64 v[148:149], s[34:35], 0, v[136:137]
	s_add_i32 m0, s53, 0xc000
	ds_read_b128 v[186:189], v155
	ds_read_b128 v[190:193], v155 offset:1024
	ds_read_b128 v[196:199], v155 offset:2048
	ds_read_b128 v[200:203], v155 offset:3072
	ds_read_b128 v[204:207], v155 offset:4096
	ds_read_b128 v[208:211], v155 offset:5120
	ds_read_b128 v[212:215], v155 offset:6144
	ds_read_b128 v[216:219], v155 offset:7168
	global_load_lds_dwordx4 v[148:149], off
	v_lshl_add_u64 v[148:149], s[34:35], 0, v[138:139]
	s_add_i32 m0, s53, 0xe000
	s_nop 0
	global_load_lds_dwordx4 v[148:149], off
	s_waitcnt vmcnt(8)
	s_waitcnt lgkmcnt(0)
	s_barrier
	s_setprio 1
	s_waitcnt lgkmcnt(0)
	v_mfma_f32_16x16x32_bf16 v[124:127], v[144:147], v[186:189], v[124:127]
	v_mfma_f32_16x16x32_bf16 v[120:123], v[162:165], v[186:189], v[120:123]
	v_mfma_f32_16x16x32_bf16 v[108:111], v[144:147], v[196:199], v[108:111]
	v_mfma_f32_16x16x32_bf16 v[104:107], v[162:165], v[196:199], v[104:107]
	v_mfma_f32_16x16x32_bf16 v[92:95], v[144:147], v[204:207], v[92:95]
	v_mfma_f32_16x16x32_bf16 v[88:91], v[162:165], v[204:207], v[88:91]
	v_mfma_f32_16x16x32_bf16 v[76:79], v[144:147], v[212:215], v[76:79]
	v_mfma_f32_16x16x32_bf16 v[72:75], v[162:165], v[212:215], v[72:75]
	v_mfma_f32_16x16x32_bf16 v[124:127], v[158:161], v[190:193], v[124:127]
	v_mfma_f32_16x16x32_bf16 v[120:123], v[166:169], v[190:193], v[120:123]
	v_mfma_f32_16x16x32_bf16 v[108:111], v[158:161], v[200:203], v[108:111]
	v_mfma_f32_16x16x32_bf16 v[104:107], v[166:169], v[200:203], v[104:107]
	v_mfma_f32_16x16x32_bf16 v[92:95], v[158:161], v[208:211], v[92:95]
	v_mfma_f32_16x16x32_bf16 v[88:91], v[166:169], v[208:211], v[88:91]
	v_mfma_f32_16x16x32_bf16 v[76:79], v[158:161], v[216:219], v[76:79]
	v_mfma_f32_16x16x32_bf16 v[72:75], v[166:169], v[216:219], v[72:75]
	v_mfma_f32_16x16x32_bf16 v[116:119], v[170:173], v[186:189], v[116:119]
	v_mfma_f32_16x16x32_bf16 v[112:115], v[178:181], v[186:189], v[112:115]
	v_mfma_f32_16x16x32_bf16 v[100:103], v[170:173], v[196:199], v[100:103]
	v_mfma_f32_16x16x32_bf16 v[96:99], v[178:181], v[196:199], v[96:99]
	v_mfma_f32_16x16x32_bf16 v[84:87], v[170:173], v[204:207], v[84:87]
	v_mfma_f32_16x16x32_bf16 v[80:83], v[178:181], v[204:207], v[80:83]
	v_mfma_f32_16x16x32_bf16 v[68:71], v[170:173], v[212:215], v[68:71]
	v_mfma_f32_16x16x32_bf16 v[64:67], v[178:181], v[212:215], v[64:67]
	v_mfma_f32_16x16x32_bf16 v[116:119], v[174:177], v[190:193], v[116:119]
	v_mfma_f32_16x16x32_bf16 v[112:115], v[182:185], v[190:193], v[112:115]
	v_mfma_f32_16x16x32_bf16 v[100:103], v[174:177], v[200:203], v[100:103]
	v_mfma_f32_16x16x32_bf16 v[96:99], v[182:185], v[200:203], v[96:99]
	v_mfma_f32_16x16x32_bf16 v[84:87], v[174:177], v[208:211], v[84:87]
	v_mfma_f32_16x16x32_bf16 v[80:83], v[182:185], v[208:211], v[80:83]
	v_mfma_f32_16x16x32_bf16 v[68:71], v[174:177], v[216:219], v[68:71]
	v_mfma_f32_16x16x32_bf16 v[64:67], v[182:185], v[216:219], v[64:67]
	s_setprio 0
	s_barrier
	s_add_i32 s79, s61, s52
	v_lshl_add_u64 v[148:149], s[36:37], 0, v[130:131]
	s_mov_b32 m0, s79
	ds_read_b128 v[186:189], v155 offset:16384
	ds_read_b128 v[190:193], v155 offset:17408
	ds_read_b128 v[196:199], v155 offset:18432
	ds_read_b128 v[200:203], v155 offset:19456
	ds_read_b128 v[204:207], v155 offset:20480
	ds_read_b128 v[208:211], v155 offset:21504
	ds_read_b128 v[212:215], v155 offset:22528
	ds_read_b128 v[216:219], v155 offset:23552
	global_load_lds_dwordx4 v[148:149], off
	s_add_i32 m0, s79, 0x2000
	s_add_u32 s80, s36, 0x40000
	v_lshl_add_u64 v[220:221], s[36:37], 0, v[134:135]
	s_addc_u32 s81, s37, 0
	s_add_i32 s79, s62, s52
	global_load_lds_dwordx4 v[220:221], off
	v_lshl_add_u64 v[222:223], s[80:81], 0, v[130:131]
	s_mov_b32 m0, s79
	v_lshl_add_u64 v[224:225], s[38:39], 0, v[132:133]
	global_load_lds_dwordx4 v[222:223], off
	v_lshl_add_u64 v[222:223], s[80:81], 0, v[134:135]
	s_add_i32 m0, s79, 0x2000
	s_nop 0
	global_load_lds_dwordx4 v[222:223], off
	v_lshl_add_u64 v[222:223], s[38:39], 0, v[128:129]
	s_waitcnt vmcnt(6)
	s_waitcnt lgkmcnt(0)
	s_barrier
	s_setprio 1
	s_waitcnt lgkmcnt(0)
	v_mfma_f32_16x16x32_bf16 v[60:63], v[144:147], v[186:189], v[60:63]
	v_mfma_f32_16x16x32_bf16 v[56:59], v[162:165], v[186:189], v[56:59]
	v_mfma_f32_16x16x32_bf16 v[44:47], v[144:147], v[196:199], v[44:47]
	v_mfma_f32_16x16x32_bf16 v[40:43], v[162:165], v[196:199], v[40:43]
	v_mfma_f32_16x16x32_bf16 v[28:31], v[144:147], v[204:207], v[28:31]
	v_mfma_f32_16x16x32_bf16 v[24:27], v[162:165], v[204:207], v[24:27]
	v_mfma_f32_16x16x32_bf16 v[12:15], v[144:147], v[212:215], v[12:15]
	v_mfma_f32_16x16x32_bf16 v[8:11], v[162:165], v[212:215], v[8:11]
	v_mfma_f32_16x16x32_bf16 v[60:63], v[158:161], v[190:193], v[60:63]
	v_mfma_f32_16x16x32_bf16 v[56:59], v[166:169], v[190:193], v[56:59]
	v_mfma_f32_16x16x32_bf16 v[44:47], v[158:161], v[200:203], v[44:47]
	v_mfma_f32_16x16x32_bf16 v[40:43], v[166:169], v[200:203], v[40:43]
	v_mfma_f32_16x16x32_bf16 v[28:31], v[158:161], v[208:211], v[28:31]
	v_mfma_f32_16x16x32_bf16 v[24:27], v[166:169], v[208:211], v[24:27]
	v_mfma_f32_16x16x32_bf16 v[12:15], v[158:161], v[216:219], v[12:15]
	v_mfma_f32_16x16x32_bf16 v[8:11], v[166:169], v[216:219], v[8:11]
	v_mfma_f32_16x16x32_bf16 v[52:55], v[170:173], v[186:189], v[52:55]
	v_mfma_f32_16x16x32_bf16 v[48:51], v[178:181], v[186:189], v[48:51]
	v_mfma_f32_16x16x32_bf16 v[36:39], v[170:173], v[196:199], v[36:39]
	v_mfma_f32_16x16x32_bf16 v[32:35], v[178:181], v[196:199], v[32:35]
	v_mfma_f32_16x16x32_bf16 v[20:23], v[170:173], v[204:207], v[20:23]
	v_mfma_f32_16x16x32_bf16 v[16:19], v[178:181], v[204:207], v[16:19]
	v_mfma_f32_16x16x32_bf16 v[4:7], v[170:173], v[212:215], v[4:7]
	v_mfma_f32_16x16x32_bf16 v[0:3], v[178:181], v[212:215], v[0:3]
	v_mfma_f32_16x16x32_bf16 v[52:55], v[174:177], v[190:193], v[52:55]
	v_mfma_f32_16x16x32_bf16 v[48:51], v[182:185], v[190:193], v[48:51]
	v_mfma_f32_16x16x32_bf16 v[36:39], v[174:177], v[200:203], v[36:39]
	v_mfma_f32_16x16x32_bf16 v[32:35], v[182:185], v[200:203], v[32:35]
	v_mfma_f32_16x16x32_bf16 v[20:23], v[174:177], v[208:211], v[20:23]
	v_mfma_f32_16x16x32_bf16 v[16:19], v[182:185], v[208:211], v[16:19]
	v_mfma_f32_16x16x32_bf16 v[4:7], v[174:177], v[216:219], v[4:7]
	v_mfma_f32_16x16x32_bf16 v[0:3], v[182:185], v[216:219], v[0:3]
	s_setprio 0
	s_barrier
	s_add_i32 s79, 0, 0x18000
	v_add_u32_e32 v157, s79, v151
	s_add_i32 s80, 0, 0x1c000
	ds_read_b128 v[144:147], v157
	ds_read_b128 v[158:161], v157 offset:1024
	ds_read_b128 v[162:165], v157 offset:2048
	ds_read_b128 v[166:169], v157 offset:3072
	v_add_u32_e32 v157, s80, v151
	ds_read_b128 v[170:173], v157
	ds_read_b128 v[174:177], v157 offset:1024
	ds_read_b128 v[178:181], v157 offset:2048
	ds_read_b128 v[182:185], v157 offset:3072
	s_add_u32 s38, s38, 0x40000
	s_addc_u32 s39, s39, 0
	v_lshl_add_u64 v[226:227], s[38:39], 0, v[128:129]
	ds_read_b128 v[186:189], v155 offset:32768
	ds_read_b128 v[190:193], v155 offset:33792
	ds_read_b128 v[196:199], v155 offset:34816
	ds_read_b128 v[200:203], v155 offset:35840
	ds_read_b128 v[204:207], v155 offset:36864
	ds_read_b128 v[208:211], v155 offset:37888
	ds_read_b128 v[212:215], v155 offset:38912
	ds_read_b128 v[216:219], v155 offset:39936
	s_mov_b32 m0, s53
	s_nop 0
	global_load_lds_dwordx4 v[222:223], off
	s_mov_b32 m0, s54
	s_nop 0
	global_load_lds_dwordx4 v[224:225], off
	s_mov_b32 m0, s55
	s_nop 0
	global_load_lds_dwordx4 v[226:227], off
	v_lshl_add_u64 v[226:227], s[38:39], 0, v[132:133]
	s_mov_b32 m0, s56
	s_nop 0
	global_load_lds_dwordx4 v[226:227], off
	s_waitcnt vmcnt(8)
	s_waitcnt lgkmcnt(0)
	s_barrier
	s_setprio 1
	s_waitcnt lgkmcnt(0)
	v_mfma_f32_16x16x32_bf16 v[124:127], v[144:147], v[186:189], v[124:127]
	v_mfma_f32_16x16x32_bf16 v[120:123], v[162:165], v[186:189], v[120:123]
	v_mfma_f32_16x16x32_bf16 v[108:111], v[144:147], v[196:199], v[108:111]
	v_mfma_f32_16x16x32_bf16 v[104:107], v[162:165], v[196:199], v[104:107]
	v_mfma_f32_16x16x32_bf16 v[92:95], v[144:147], v[204:207], v[92:95]
	v_mfma_f32_16x16x32_bf16 v[88:91], v[162:165], v[204:207], v[88:91]
	v_mfma_f32_16x16x32_bf16 v[76:79], v[144:147], v[212:215], v[76:79]
	v_mfma_f32_16x16x32_bf16 v[72:75], v[162:165], v[212:215], v[72:75]
	v_mfma_f32_16x16x32_bf16 v[124:127], v[158:161], v[190:193], v[124:127]
	v_mfma_f32_16x16x32_bf16 v[120:123], v[166:169], v[190:193], v[120:123]
	v_mfma_f32_16x16x32_bf16 v[108:111], v[158:161], v[200:203], v[108:111]
	v_mfma_f32_16x16x32_bf16 v[104:107], v[166:169], v[200:203], v[104:107]
	v_mfma_f32_16x16x32_bf16 v[92:95], v[158:161], v[208:211], v[92:95]
	v_mfma_f32_16x16x32_bf16 v[88:91], v[166:169], v[208:211], v[88:91]
	v_mfma_f32_16x16x32_bf16 v[76:79], v[158:161], v[216:219], v[76:79]
	v_mfma_f32_16x16x32_bf16 v[72:75], v[166:169], v[216:219], v[72:75]
	v_mfma_f32_16x16x32_bf16 v[116:119], v[170:173], v[186:189], v[116:119]
	v_mfma_f32_16x16x32_bf16 v[112:115], v[178:181], v[186:189], v[112:115]
	v_mfma_f32_16x16x32_bf16 v[100:103], v[170:173], v[196:199], v[100:103]
	v_mfma_f32_16x16x32_bf16 v[96:99], v[178:181], v[196:199], v[96:99]
	v_mfma_f32_16x16x32_bf16 v[84:87], v[170:173], v[204:207], v[84:87]
	v_mfma_f32_16x16x32_bf16 v[80:83], v[178:181], v[204:207], v[80:83]
	v_mfma_f32_16x16x32_bf16 v[68:71], v[170:173], v[212:215], v[68:71]
	v_mfma_f32_16x16x32_bf16 v[64:67], v[178:181], v[212:215], v[64:67]
	v_mfma_f32_16x16x32_bf16 v[116:119], v[174:177], v[190:193], v[116:119]
	v_mfma_f32_16x16x32_bf16 v[112:115], v[182:185], v[190:193], v[112:115]
	v_mfma_f32_16x16x32_bf16 v[100:103], v[174:177], v[200:203], v[100:103]
	v_mfma_f32_16x16x32_bf16 v[96:99], v[182:185], v[200:203], v[96:99]
	v_mfma_f32_16x16x32_bf16 v[84:87], v[174:177], v[208:211], v[84:87]
	v_mfma_f32_16x16x32_bf16 v[80:83], v[182:185], v[208:211], v[80:83]
	v_mfma_f32_16x16x32_bf16 v[68:71], v[174:177], v[216:219], v[68:71]
	v_mfma_f32_16x16x32_bf16 v[64:67], v[182:185], v[216:219], v[64:67]
	s_setprio 0
	s_barrier
	s_add_i32 s38, s79, s52
	v_lshl_add_u64 v[148:149], v[148:149], 0, s[20:21]
	s_mov_b32 m0, s38
	ds_read_b128 v[186:189], v155 offset:49152
	ds_read_b128 v[190:193], v155 offset:50176
	ds_read_b128 v[196:199], v155 offset:51200
	ds_read_b128 v[200:203], v155 offset:52224
	ds_read_b128 v[204:207], v155 offset:53248
	ds_read_b128 v[208:211], v155 offset:54272
	ds_read_b128 v[212:215], v155 offset:55296
	ds_read_b128 v[216:219], v155 offset:56320
	global_load_lds_dwordx4 v[148:149], off
	s_add_i32 m0, s38, 0x2000
	s_add_u32 s36, s36, 0x40080
	v_lshl_add_u64 v[148:149], v[220:221], 0, s[20:21]
	s_addc_u32 s37, s37, 0
	s_add_i32 s38, s80, s52
	global_load_lds_dwordx4 v[148:149], off
	v_lshl_add_u64 v[148:149], s[36:37], 0, v[130:131]
	s_mov_b32 m0, s38
	s_nop 0
	global_load_lds_dwordx4 v[148:149], off
	v_lshl_add_u64 v[148:149], s[36:37], 0, v[134:135]
	s_add_i32 m0, s38, 0x2000
	s_nop 0
	global_load_lds_dwordx4 v[148:149], off
	s_waitcnt vmcnt(6)
	s_waitcnt lgkmcnt(0)
	s_barrier
	s_setprio 1
	s_waitcnt lgkmcnt(0)
	v_mfma_f32_16x16x32_bf16 v[60:63], v[144:147], v[186:189], v[60:63]
	v_mfma_f32_16x16x32_bf16 v[56:59], v[162:165], v[186:189], v[56:59]
	v_mfma_f32_16x16x32_bf16 v[44:47], v[144:147], v[196:199], v[44:47]
	v_mfma_f32_16x16x32_bf16 v[40:43], v[162:165], v[196:199], v[40:43]
	v_mfma_f32_16x16x32_bf16 v[28:31], v[144:147], v[204:207], v[28:31]
	v_mfma_f32_16x16x32_bf16 v[24:27], v[162:165], v[204:207], v[24:27]
	v_mfma_f32_16x16x32_bf16 v[12:15], v[144:147], v[212:215], v[12:15]
	v_mfma_f32_16x16x32_bf16 v[8:11], v[162:165], v[212:215], v[8:11]
	v_mfma_f32_16x16x32_bf16 v[60:63], v[158:161], v[190:193], v[60:63]
	v_mfma_f32_16x16x32_bf16 v[56:59], v[166:169], v[190:193], v[56:59]
	v_mfma_f32_16x16x32_bf16 v[44:47], v[158:161], v[200:203], v[44:47]
	v_mfma_f32_16x16x32_bf16 v[40:43], v[166:169], v[200:203], v[40:43]
	v_mfma_f32_16x16x32_bf16 v[28:31], v[158:161], v[208:211], v[28:31]
	v_mfma_f32_16x16x32_bf16 v[24:27], v[166:169], v[208:211], v[24:27]
	v_mfma_f32_16x16x32_bf16 v[12:15], v[158:161], v[216:219], v[12:15]
	v_mfma_f32_16x16x32_bf16 v[8:11], v[166:169], v[216:219], v[8:11]
	v_mfma_f32_16x16x32_bf16 v[52:55], v[170:173], v[186:189], v[52:55]
	v_mfma_f32_16x16x32_bf16 v[48:51], v[178:181], v[186:189], v[48:51]
	v_mfma_f32_16x16x32_bf16 v[36:39], v[170:173], v[196:199], v[36:39]
	v_mfma_f32_16x16x32_bf16 v[32:35], v[178:181], v[196:199], v[32:35]
	v_mfma_f32_16x16x32_bf16 v[20:23], v[170:173], v[204:207], v[20:23]
	v_mfma_f32_16x16x32_bf16 v[16:19], v[178:181], v[204:207], v[16:19]
	v_mfma_f32_16x16x32_bf16 v[4:7], v[170:173], v[212:215], v[4:7]
	v_mfma_f32_16x16x32_bf16 v[0:3], v[178:181], v[212:215], v[0:3]
	v_mfma_f32_16x16x32_bf16 v[52:55], v[174:177], v[190:193], v[52:55]
	v_mfma_f32_16x16x32_bf16 v[48:51], v[182:185], v[190:193], v[48:51]
	v_mfma_f32_16x16x32_bf16 v[36:39], v[174:177], v[200:203], v[36:39]
	v_mfma_f32_16x16x32_bf16 v[32:35], v[182:185], v[200:203], v[32:35]
	v_mfma_f32_16x16x32_bf16 v[20:23], v[174:177], v[208:211], v[20:23]
	v_mfma_f32_16x16x32_bf16 v[16:19], v[182:185], v[208:211], v[16:19]
	v_mfma_f32_16x16x32_bf16 v[4:7], v[174:177], v[216:219], v[4:7]
	v_mfma_f32_16x16x32_bf16 v[0:3], v[182:185], v[216:219], v[0:3]
	s_setprio 0
	s_barrier
	v_lshl_add_u64 v[222:223], v[222:223], 0, s[20:21]
	s_mov_b32 m0, s58
	s_nop 0
	global_load_lds_dwordx4 v[222:223], off
	v_lshl_add_u64 v[224:225], v[224:225], 0, s[20:21]
	s_mov_b32 m0, s59
	s_nop 0
	global_load_lds_dwordx4 v[224:225], off
	s_add_i32 s78, s78, 2
	s_add_u32 s34, s34, 0x100
	s_addc_u32 s35, s35, 0
	s_add_u32 s73, s73, 0x100
	s_addc_u32 s77, s77, 0
	s_cmp_gt_u32 s78, 13
	s_cbranch_scc0 .LBB0_2396
	s_and_b64 vcc, exec, s[22:23]
	s_cbranch_vccz .LBB0_2399
	s_barrier

.LBB0_2533:
	ds_read_b128 v[152:155], v148
	ds_read_b128 v[156:159], v148 offset:1024
	ds_read_b128 v[160:163], v148 offset:2048
	ds_read_b128 v[164:167], v148 offset:3072
	ds_read_b128 v[168:171], v149
	ds_read_b128 v[172:175], v149 offset:1024
	ds_read_b128 v[176:179], v149 offset:2048
	ds_read_b128 v[180:183], v149 offset:3072
	s_add_u32 s26, s24, 0x100
	s_addc_u32 s27, s25, 0
	s_cmp_eq_u32 s62, 8
	s_cselect_b32 s31, s21, s27
	s_cselect_b32 s30, s20, s26
	s_cselect_b32 s29, s23, s61
	s_cselect_b32 s28, s22, s60
	s_mov_b32 m0, s53
	v_lshl_add_u64 v[192:193], s[24:25], 0, v[138:139]
	ds_read_b128 v[184:187], v150
	ds_read_b128 v[188:191], v150 offset:1024
	ds_read_b128 v[196:199], v150 offset:2048
	ds_read_b128 v[200:203], v150 offset:3072
	ds_read_b128 v[204:207], v150 offset:4096
	ds_read_b128 v[208:211], v150 offset:5120
	ds_read_b128 v[212:215], v150 offset:6144
	ds_read_b128 v[216:219], v150 offset:7168
	global_load_lds_dwordx4 v[192:193], off
	v_lshl_add_u64 v[192:193], s[24:25], 0, v[140:141]
	s_add_i32 m0, s40, 0xe000
	s_nop 0
	global_load_lds_dwordx4 v[192:193], off
	s_waitcnt vmcnt(8)
	s_waitcnt lgkmcnt(0)
	s_barrier
	s_setprio 1
	s_waitcnt lgkmcnt(0)
	v_mfma_f32_16x16x32_bf16 v[124:127], v[152:155], v[184:187], v[124:127]
	v_mfma_f32_16x16x32_bf16 v[120:123], v[160:163], v[184:187], v[120:123]
	v_mfma_f32_16x16x32_bf16 v[108:111], v[152:155], v[196:199], v[108:111]
	v_mfma_f32_16x16x32_bf16 v[104:107], v[160:163], v[196:199], v[104:107]
	v_mfma_f32_16x16x32_bf16 v[92:95], v[152:155], v[204:207], v[92:95]
	v_mfma_f32_16x16x32_bf16 v[88:91], v[160:163], v[204:207], v[88:91]
	v_mfma_f32_16x16x32_bf16 v[76:79], v[152:155], v[212:215], v[76:79]
	v_mfma_f32_16x16x32_bf16 v[72:75], v[160:163], v[212:215], v[72:75]
	v_mfma_f32_16x16x32_bf16 v[124:127], v[156:159], v[188:191], v[124:127]
	v_mfma_f32_16x16x32_bf16 v[120:123], v[164:167], v[188:191], v[120:123]
	v_mfma_f32_16x16x32_bf16 v[108:111], v[156:159], v[200:203], v[108:111]
	v_mfma_f32_16x16x32_bf16 v[104:107], v[164:167], v[200:203], v[104:107]
	v_mfma_f32_16x16x32_bf16 v[92:95], v[156:159], v[208:211], v[92:95]
	v_mfma_f32_16x16x32_bf16 v[88:91], v[164:167], v[208:211], v[88:91]
	v_mfma_f32_16x16x32_bf16 v[76:79], v[156:159], v[216:219], v[76:79]
	v_mfma_f32_16x16x32_bf16 v[72:75], v[164:167], v[216:219], v[72:75]
	v_mfma_f32_16x16x32_bf16 v[116:119], v[168:171], v[184:187], v[116:119]
	v_mfma_f32_16x16x32_bf16 v[112:115], v[176:179], v[184:187], v[112:115]
	v_mfma_f32_16x16x32_bf16 v[100:103], v[168:171], v[196:199], v[100:103]
	v_mfma_f32_16x16x32_bf16 v[96:99], v[176:179], v[196:199], v[96:99]
	v_mfma_f32_16x16x32_bf16 v[84:87], v[168:171], v[204:207], v[84:87]
	v_mfma_f32_16x16x32_bf16 v[80:83], v[176:179], v[204:207], v[80:83]
	v_mfma_f32_16x16x32_bf16 v[68:71], v[168:171], v[212:215], v[68:71]
	v_mfma_f32_16x16x32_bf16 v[64:67], v[176:179], v[212:215], v[64:67]
	v_mfma_f32_16x16x32_bf16 v[116:119], v[172:175], v[188:191], v[116:119]
	v_mfma_f32_16x16x32_bf16 v[112:115], v[180:183], v[188:191], v[112:115]
	v_mfma_f32_16x16x32_bf16 v[100:103], v[172:175], v[200:203], v[100:103]
	v_mfma_f32_16x16x32_bf16 v[96:99], v[180:183], v[200:203], v[96:99]
	v_mfma_f32_16x16x32_bf16 v[84:87], v[172:175], v[208:211], v[84:87]
	v_mfma_f32_16x16x32_bf16 v[80:83], v[180:183], v[208:211], v[80:83]
	v_mfma_f32_16x16x32_bf16 v[68:71], v[172:175], v[216:219], v[68:71]
	v_mfma_f32_16x16x32_bf16 v[64:67], v[180:183], v[216:219], v[64:67]
	s_setprio 0
	s_barrier
	s_add_i32 s24, s51, s39
	v_lshl_add_u64 v[192:193], s[28:29], 0, v[132:133]
	s_mov_b32 m0, s24
	ds_read_b128 v[184:187], v150 offset:16384
	ds_read_b128 v[188:191], v150 offset:17408
	ds_read_b128 v[196:199], v150 offset:18432
	ds_read_b128 v[200:203], v150 offset:19456
	ds_read_b128 v[204:207], v150 offset:20480
	ds_read_b128 v[208:211], v150 offset:21504
	ds_read_b128 v[212:215], v150 offset:22528
	ds_read_b128 v[216:219], v150 offset:23552
	global_load_lds_dwordx4 v[192:193], off
	s_add_i32 m0, s24, 0x2000
	s_add_u32 s24, s28, 0x30000
	v_lshl_add_u64 v[220:221], s[28:29], 0, v[128:129]
	s_addc_u32 s25, s29, 0
	s_add_i32 s63, s52, s39
	global_load_lds_dwordx4 v[220:221], off
	v_lshl_add_u64 v[222:223], s[24:25], 0, v[132:133]
	s_mov_b32 m0, s63
	v_lshl_add_u64 v[224:225], s[30:31], 0, v[130:131]
	global_load_lds_dwordx4 v[222:223], off
	v_lshl_add_u64 v[222:223], s[24:25], 0, v[128:129]
	s_add_i32 m0, s63, 0x2000
	s_nop 0
	global_load_lds_dwordx4 v[222:223], off
	v_lshl_add_u64 v[222:223], s[30:31], 0, v[134:135]
	s_waitcnt vmcnt(6)
	s_waitcnt lgkmcnt(0)
	s_barrier
	s_setprio 1
	s_waitcnt lgkmcnt(0)
	v_mfma_f32_16x16x32_bf16 v[60:63], v[152:155], v[184:187], v[60:63]
	v_mfma_f32_16x16x32_bf16 v[56:59], v[160:163], v[184:187], v[56:59]
	v_mfma_f32_16x16x32_bf16 v[44:47], v[152:155], v[196:199], v[44:47]
	v_mfma_f32_16x16x32_bf16 v[40:43], v[160:163], v[196:199], v[40:43]
	v_mfma_f32_16x16x32_bf16 v[28:31], v[152:155], v[204:207], v[28:31]
	v_mfma_f32_16x16x32_bf16 v[24:27], v[160:163], v[204:207], v[24:27]
	v_mfma_f32_16x16x32_bf16 v[12:15], v[152:155], v[212:215], v[12:15]
	v_mfma_f32_16x16x32_bf16 v[8:11], v[160:163], v[212:215], v[8:11]
	v_mfma_f32_16x16x32_bf16 v[60:63], v[156:159], v[188:191], v[60:63]
	v_mfma_f32_16x16x32_bf16 v[56:59], v[164:167], v[188:191], v[56:59]
	v_mfma_f32_16x16x32_bf16 v[44:47], v[156:159], v[200:203], v[44:47]
	v_mfma_f32_16x16x32_bf16 v[40:43], v[164:167], v[200:203], v[40:43]
	v_mfma_f32_16x16x32_bf16 v[28:31], v[156:159], v[208:211], v[28:31]
	v_mfma_f32_16x16x32_bf16 v[24:27], v[164:167], v[208:211], v[24:27]
	v_mfma_f32_16x16x32_bf16 v[12:15], v[156:159], v[216:219], v[12:15]
	v_mfma_f32_16x16x32_bf16 v[8:11], v[164:167], v[216:219], v[8:11]
	v_mfma_f32_16x16x32_bf16 v[52:55], v[168:171], v[184:187], v[52:55]
	v_mfma_f32_16x16x32_bf16 v[48:51], v[176:179], v[184:187], v[48:51]
	v_mfma_f32_16x16x32_bf16 v[36:39], v[168:171], v[196:199], v[36:39]
	v_mfma_f32_16x16x32_bf16 v[32:35], v[176:179], v[196:199], v[32:35]
	v_mfma_f32_16x16x32_bf16 v[20:23], v[168:171], v[204:207], v[20:23]
	v_mfma_f32_16x16x32_bf16 v[16:19], v[176:179], v[204:207], v[16:19]
	v_mfma_f32_16x16x32_bf16 v[4:7], v[168:171], v[212:215], v[4:7]
	v_mfma_f32_16x16x32_bf16 v[0:3], v[176:179], v[212:215], v[0:3]
	v_mfma_f32_16x16x32_bf16 v[52:55], v[172:175], v[188:191], v[52:55]
	v_mfma_f32_16x16x32_bf16 v[48:51], v[180:183], v[188:191], v[48:51]
	v_mfma_f32_16x16x32_bf16 v[36:39], v[172:175], v[200:203], v[36:39]
	v_mfma_f32_16x16x32_bf16 v[32:35], v[180:183], v[200:203], v[32:35]
	v_mfma_f32_16x16x32_bf16 v[20:23], v[172:175], v[208:211], v[20:23]
	v_mfma_f32_16x16x32_bf16 v[16:19], v[180:183], v[208:211], v[16:19]
	v_mfma_f32_16x16x32_bf16 v[4:7], v[172:175], v[216:219], v[4:7]
	v_mfma_f32_16x16x32_bf16 v[0:3], v[180:183], v[216:219], v[0:3]
	s_setprio 0
	s_barrier
	s_add_i32 s63, 0, 0x18000
	v_add_u32_e32 v151, s63, v142
	s_add_i32 s70, 0, 0x1c000
	ds_read_b128 v[152:155], v151
	ds_read_b128 v[156:159], v151 offset:1024
	ds_read_b128 v[160:163], v151 offset:2048
	ds_read_b128 v[164:167], v151 offset:3072
	v_add_u32_e32 v151, s70, v142
	ds_read_b128 v[168:171], v151
	ds_read_b128 v[172:175], v151 offset:1024
	ds_read_b128 v[176:179], v151 offset:2048
	ds_read_b128 v[180:183], v151 offset:3072
	s_add_u32 s24, s30, 0x30000
	s_addc_u32 s25, s31, 0
	v_lshl_add_u64 v[226:227], s[24:25], 0, v[134:135]
	ds_read_b128 v[184:187], v150 offset:32768
	ds_read_b128 v[188:191], v150 offset:33792
	ds_read_b128 v[196:199], v150 offset:34816
	ds_read_b128 v[200:203], v150 offset:35840
	ds_read_b128 v[204:207], v150 offset:36864
	ds_read_b128 v[208:211], v150 offset:37888
	ds_read_b128 v[212:215], v150 offset:38912
	ds_read_b128 v[216:219], v150 offset:39936
	s_mov_b32 m0, s40
	s_nop 0
	global_load_lds_dwordx4 v[222:223], off
	s_mov_b32 m0, s41
	s_nop 0
	global_load_lds_dwordx4 v[224:225], off
	s_mov_b32 m0, s42
	s_nop 0
	global_load_lds_dwordx4 v[226:227], off
	v_lshl_add_u64 v[226:227], s[24:25], 0, v[130:131]
	s_mov_b32 m0, s43
	s_nop 0
	global_load_lds_dwordx4 v[226:227], off
	s_waitcnt vmcnt(8)
	s_waitcnt lgkmcnt(0)
	s_barrier
	s_setprio 1
	s_waitcnt lgkmcnt(0)
	v_mfma_f32_16x16x32_bf16 v[124:127], v[152:155], v[184:187], v[124:127]
	v_mfma_f32_16x16x32_bf16 v[120:123], v[160:163], v[184:187], v[120:123]
	v_mfma_f32_16x16x32_bf16 v[108:111], v[152:155], v[196:199], v[108:111]
	v_mfma_f32_16x16x32_bf16 v[104:107], v[160:163], v[196:199], v[104:107]
	v_mfma_f32_16x16x32_bf16 v[92:95], v[152:155], v[204:207], v[92:95]
	v_mfma_f32_16x16x32_bf16 v[88:91], v[160:163], v[204:207], v[88:91]
	v_mfma_f32_16x16x32_bf16 v[76:79], v[152:155], v[212:215], v[76:79]
	v_mfma_f32_16x16x32_bf16 v[72:75], v[160:163], v[212:215], v[72:75]
	v_mfma_f32_16x16x32_bf16 v[124:127], v[156:159], v[188:191], v[124:127]
	v_mfma_f32_16x16x32_bf16 v[120:123], v[164:167], v[188:191], v[120:123]
	v_mfma_f32_16x16x32_bf16 v[108:111], v[156:159], v[200:203], v[108:111]
	v_mfma_f32_16x16x32_bf16 v[104:107], v[164:167], v[200:203], v[104:107]
	v_mfma_f32_16x16x32_bf16 v[92:95], v[156:159], v[208:211], v[92:95]
	v_mfma_f32_16x16x32_bf16 v[88:91], v[164:167], v[208:211], v[88:91]
	v_mfma_f32_16x16x32_bf16 v[76:79], v[156:159], v[216:219], v[76:79]
	v_mfma_f32_16x16x32_bf16 v[72:75], v[164:167], v[216:219], v[72:75]
	v_mfma_f32_16x16x32_bf16 v[116:119], v[168:171], v[184:187], v[116:119]
	v_mfma_f32_16x16x32_bf16 v[112:115], v[176:179], v[184:187], v[112:115]
	v_mfma_f32_16x16x32_bf16 v[100:103], v[168:171], v[196:199], v[100:103]
	v_mfma_f32_16x16x32_bf16 v[96:99], v[176:179], v[196:199], v[96:99]
	v_mfma_f32_16x16x32_bf16 v[84:87], v[168:171], v[204:207], v[84:87]
	v_mfma_f32_16x16x32_bf16 v[80:83], v[176:179], v[204:207], v[80:83]
	v_mfma_f32_16x16x32_bf16 v[68:71], v[168:171], v[212:215], v[68:71]
	v_mfma_f32_16x16x32_bf16 v[64:67], v[176:179], v[212:215], v[64:67]
	v_mfma_f32_16x16x32_bf16 v[116:119], v[172:175], v[188:191], v[116:119]
	v_mfma_f32_16x16x32_bf16 v[112:115], v[180:183], v[188:191], v[112:115]
	v_mfma_f32_16x16x32_bf16 v[100:103], v[172:175], v[200:203], v[100:103]
	v_mfma_f32_16x16x32_bf16 v[96:99], v[180:183], v[200:203], v[96:99]
	v_mfma_f32_16x16x32_bf16 v[84:87], v[172:175], v[208:211], v[84:87]
	v_mfma_f32_16x16x32_bf16 v[80:83], v[180:183], v[208:211], v[80:83]
	v_mfma_f32_16x16x32_bf16 v[68:71], v[172:175], v[216:219], v[68:71]
	v_mfma_f32_16x16x32_bf16 v[64:67], v[180:183], v[216:219], v[64:67]
	s_setprio 0
	s_barrier
	s_add_i32 s24, s63, s39
	v_lshl_add_u64 v[192:193], v[192:193], 0, s[16:17]
	s_mov_b32 m0, s24
	ds_read_b128 v[184:187], v150 offset:49152
	ds_read_b128 v[188:191], v150 offset:50176
	ds_read_b128 v[196:199], v150 offset:51200
	ds_read_b128 v[200:203], v150 offset:52224
	ds_read_b128 v[204:207], v150 offset:53248
	ds_read_b128 v[208:211], v150 offset:54272
	ds_read_b128 v[212:215], v150 offset:55296
	ds_read_b128 v[216:219], v150 offset:56320
	global_load_lds_dwordx4 v[192:193], off
	s_add_i32 m0, s24, 0x2000
	s_add_u32 s24, s28, 0x30080
	v_lshl_add_u64 v[192:193], v[220:221], 0, s[16:17]
	s_addc_u32 s25, s29, 0
	s_add_i32 s28, s70, s39
	global_load_lds_dwordx4 v[192:193], off
	v_lshl_add_u64 v[192:193], s[24:25], 0, v[132:133]
	s_mov_b32 m0, s28
	s_nop 0
	global_load_lds_dwordx4 v[192:193], off
	v_lshl_add_u64 v[192:193], s[24:25], 0, v[128:129]
	s_add_i32 m0, s28, 0x2000
	s_nop 0
	global_load_lds_dwordx4 v[192:193], off
	s_waitcnt vmcnt(6)
	s_waitcnt lgkmcnt(0)
	s_barrier
	s_setprio 1
	s_waitcnt lgkmcnt(0)
	v_mfma_f32_16x16x32_bf16 v[60:63], v[152:155], v[184:187], v[60:63]
	v_mfma_f32_16x16x32_bf16 v[56:59], v[160:163], v[184:187], v[56:59]
	v_mfma_f32_16x16x32_bf16 v[44:47], v[152:155], v[196:199], v[44:47]
	v_mfma_f32_16x16x32_bf16 v[40:43], v[160:163], v[196:199], v[40:43]
	v_mfma_f32_16x16x32_bf16 v[28:31], v[152:155], v[204:207], v[28:31]
	v_mfma_f32_16x16x32_bf16 v[24:27], v[160:163], v[204:207], v[24:27]
	v_mfma_f32_16x16x32_bf16 v[12:15], v[152:155], v[212:215], v[12:15]
	v_mfma_f32_16x16x32_bf16 v[8:11], v[160:163], v[212:215], v[8:11]
	v_mfma_f32_16x16x32_bf16 v[60:63], v[156:159], v[188:191], v[60:63]
	v_mfma_f32_16x16x32_bf16 v[56:59], v[164:167], v[188:191], v[56:59]
	v_mfma_f32_16x16x32_bf16 v[44:47], v[156:159], v[200:203], v[44:47]
	v_mfma_f32_16x16x32_bf16 v[40:43], v[164:167], v[200:203], v[40:43]
	v_mfma_f32_16x16x32_bf16 v[28:31], v[156:159], v[208:211], v[28:31]
	v_mfma_f32_16x16x32_bf16 v[24:27], v[164:167], v[208:211], v[24:27]
	v_mfma_f32_16x16x32_bf16 v[12:15], v[156:159], v[216:219], v[12:15]
	v_mfma_f32_16x16x32_bf16 v[8:11], v[164:167], v[216:219], v[8:11]
	v_mfma_f32_16x16x32_bf16 v[52:55], v[168:171], v[184:187], v[52:55]
	v_mfma_f32_16x16x32_bf16 v[48:51], v[176:179], v[184:187], v[48:51]
	v_mfma_f32_16x16x32_bf16 v[36:39], v[168:171], v[196:199], v[36:39]
	v_mfma_f32_16x16x32_bf16 v[32:35], v[176:179], v[196:199], v[32:35]
	v_mfma_f32_16x16x32_bf16 v[20:23], v[168:171], v[204:207], v[20:23]
	v_mfma_f32_16x16x32_bf16 v[16:19], v[176:179], v[204:207], v[16:19]
	v_mfma_f32_16x16x32_bf16 v[4:7], v[168:171], v[212:215], v[4:7]
	v_mfma_f32_16x16x32_bf16 v[0:3], v[176:179], v[212:215], v[0:3]
	v_mfma_f32_16x16x32_bf16 v[52:55], v[172:175], v[188:191], v[52:55]
	v_mfma_f32_16x16x32_bf16 v[48:51], v[180:183], v[188:191], v[48:51]
	v_mfma_f32_16x16x32_bf16 v[36:39], v[172:175], v[200:203], v[36:39]
	v_mfma_f32_16x16x32_bf16 v[32:35], v[180:183], v[200:203], v[32:35]
	v_mfma_f32_16x16x32_bf16 v[20:23], v[172:175], v[208:211], v[20:23]
	v_mfma_f32_16x16x32_bf16 v[16:19], v[180:183], v[208:211], v[16:19]
	v_mfma_f32_16x16x32_bf16 v[4:7], v[172:175], v[216:219], v[4:7]
	v_mfma_f32_16x16x32_bf16 v[0:3], v[180:183], v[216:219], v[0:3]
	s_setprio 0
	s_barrier
	v_lshl_add_u64 v[222:223], v[222:223], 0, s[16:17]
	s_mov_b32 m0, s45
	s_nop 0
	global_load_lds_dwordx4 v[222:223], off
	v_lshl_add_u64 v[224:225], v[224:225], 0, s[16:17]
	s_mov_b32 m0, s48
	s_nop 0
	global_load_lds_dwordx4 v[224:225], off
	s_add_i32 s62, s62, 2
	s_add_u32 s60, s60, 0x100
	s_addc_u32 s61, s61, 0
	s_cmp_gt_u32 s62, 9
	s_mov_b64 s[24:25], s[26:27]
	s_cbranch_scc0 .LBB0_2533
	s_and_b64 vcc, exec, s[18:19]
	s_cbranch_vccz .LBB0_2536
	s_barrier

.LBB0_2557:
	ds_read_b128 v[144:147], v153
	ds_read_b128 v[158:161], v153 offset:1024
	ds_read_b128 v[162:165], v153 offset:2048
	ds_read_b128 v[166:169], v153 offset:3072
	ds_read_b128 v[170:173], v154
	ds_read_b128 v[174:177], v154 offset:1024
	ds_read_b128 v[178:181], v154 offset:2048
	ds_read_b128 v[182:185], v154 offset:3072
	s_add_u32 s36, s34, 0xfffc0080
	s_addc_u32 s37, s35, -1
	s_cmp_eq_u32 s73, 12
	s_cselect_b32 s39, s27, s37
	s_cselect_b32 s38, s63, s36
	s_cselect_b32 s37, s25, s72
	s_cselect_b32 s36, s70, s71
	v_lshl_add_u64 v[148:149], s[34:35], 0, v[136:137]
	s_add_i32 m0, s51, 0xc000
	ds_read_b128 v[186:189], v155
	ds_read_b128 v[190:193], v155 offset:1024
	ds_read_b128 v[196:199], v155 offset:2048
	ds_read_b128 v[200:203], v155 offset:3072
	ds_read_b128 v[204:207], v155 offset:4096
	ds_read_b128 v[208:211], v155 offset:5120
	ds_read_b128 v[212:215], v155 offset:6144
	ds_read_b128 v[216:219], v155 offset:7168
	global_load_lds_dwordx4 v[148:149], off
	v_lshl_add_u64 v[148:149], s[34:35], 0, v[138:139]
	s_add_i32 m0, s51, 0xe000
	s_nop 0
	global_load_lds_dwordx4 v[148:149], off
	s_waitcnt vmcnt(8)
	s_waitcnt lgkmcnt(0)
	s_barrier
	s_setprio 1
	s_waitcnt lgkmcnt(0)
	v_mfma_f32_16x16x32_bf16 v[124:127], v[144:147], v[186:189], v[124:127]
	v_mfma_f32_16x16x32_bf16 v[120:123], v[162:165], v[186:189], v[120:123]
	v_mfma_f32_16x16x32_bf16 v[108:111], v[144:147], v[196:199], v[108:111]
	v_mfma_f32_16x16x32_bf16 v[104:107], v[162:165], v[196:199], v[104:107]
	v_mfma_f32_16x16x32_bf16 v[92:95], v[144:147], v[204:207], v[92:95]
	v_mfma_f32_16x16x32_bf16 v[88:91], v[162:165], v[204:207], v[88:91]
	v_mfma_f32_16x16x32_bf16 v[76:79], v[144:147], v[212:215], v[76:79]
	v_mfma_f32_16x16x32_bf16 v[72:75], v[162:165], v[212:215], v[72:75]
	v_mfma_f32_16x16x32_bf16 v[124:127], v[158:161], v[190:193], v[124:127]
	v_mfma_f32_16x16x32_bf16 v[120:123], v[166:169], v[190:193], v[120:123]
	v_mfma_f32_16x16x32_bf16 v[108:111], v[158:161], v[200:203], v[108:111]
	v_mfma_f32_16x16x32_bf16 v[104:107], v[166:169], v[200:203], v[104:107]
	v_mfma_f32_16x16x32_bf16 v[92:95], v[158:161], v[208:211], v[92:95]
	v_mfma_f32_16x16x32_bf16 v[88:91], v[166:169], v[208:211], v[88:91]
	v_mfma_f32_16x16x32_bf16 v[76:79], v[158:161], v[216:219], v[76:79]
	v_mfma_f32_16x16x32_bf16 v[72:75], v[166:169], v[216:219], v[72:75]
	v_mfma_f32_16x16x32_bf16 v[116:119], v[170:173], v[186:189], v[116:119]
	v_mfma_f32_16x16x32_bf16 v[112:115], v[178:181], v[186:189], v[112:115]
	v_mfma_f32_16x16x32_bf16 v[100:103], v[170:173], v[196:199], v[100:103]
	v_mfma_f32_16x16x32_bf16 v[96:99], v[178:181], v[196:199], v[96:99]
	v_mfma_f32_16x16x32_bf16 v[84:87], v[170:173], v[204:207], v[84:87]
	v_mfma_f32_16x16x32_bf16 v[80:83], v[178:181], v[204:207], v[80:83]
	v_mfma_f32_16x16x32_bf16 v[68:71], v[170:173], v[212:215], v[68:71]
	v_mfma_f32_16x16x32_bf16 v[64:67], v[178:181], v[212:215], v[64:67]
	v_mfma_f32_16x16x32_bf16 v[116:119], v[174:177], v[190:193], v[116:119]
	v_mfma_f32_16x16x32_bf16 v[112:115], v[182:185], v[190:193], v[112:115]
	v_mfma_f32_16x16x32_bf16 v[100:103], v[174:177], v[200:203], v[100:103]
	v_mfma_f32_16x16x32_bf16 v[96:99], v[182:185], v[200:203], v[96:99]
	v_mfma_f32_16x16x32_bf16 v[84:87], v[174:177], v[208:211], v[84:87]
	v_mfma_f32_16x16x32_bf16 v[80:83], v[182:185], v[208:211], v[80:83]
	v_mfma_f32_16x16x32_bf16 v[68:71], v[174:177], v[216:219], v[68:71]
	v_mfma_f32_16x16x32_bf16 v[64:67], v[182:185], v[216:219], v[64:67]
	s_setprio 0
	s_barrier
	s_add_i32 s77, s59, s49
	v_lshl_add_u64 v[148:149], s[36:37], 0, v[130:131]
	s_mov_b32 m0, s77
	ds_read_b128 v[186:189], v155 offset:16384
	ds_read_b128 v[190:193], v155 offset:17408
	ds_read_b128 v[196:199], v155 offset:18432
	ds_read_b128 v[200:203], v155 offset:19456
	ds_read_b128 v[204:207], v155 offset:20480
	ds_read_b128 v[208:211], v155 offset:21504
	ds_read_b128 v[212:215], v155 offset:22528
	ds_read_b128 v[216:219], v155 offset:23552
	global_load_lds_dwordx4 v[148:149], off
	s_add_i32 m0, s77, 0x2000
	s_add_u32 s78, s36, 0x40000
	v_lshl_add_u64 v[220:221], s[36:37], 0, v[134:135]
	s_addc_u32 s79, s37, 0
	s_add_i32 s77, s60, s49
	global_load_lds_dwordx4 v[220:221], off
	v_lshl_add_u64 v[222:223], s[78:79], 0, v[130:131]
	s_mov_b32 m0, s77
	v_lshl_add_u64 v[224:225], s[38:39], 0, v[132:133]
	global_load_lds_dwordx4 v[222:223], off
	v_lshl_add_u64 v[222:223], s[78:79], 0, v[134:135]
	s_add_i32 m0, s77, 0x2000
	s_nop 0
	global_load_lds_dwordx4 v[222:223], off
	v_lshl_add_u64 v[222:223], s[38:39], 0, v[128:129]
	s_waitcnt vmcnt(6)
	s_waitcnt lgkmcnt(0)
	s_barrier
	s_setprio 1
	s_waitcnt lgkmcnt(0)
	v_mfma_f32_16x16x32_bf16 v[60:63], v[144:147], v[186:189], v[60:63]
	v_mfma_f32_16x16x32_bf16 v[56:59], v[162:165], v[186:189], v[56:59]
	v_mfma_f32_16x16x32_bf16 v[44:47], v[144:147], v[196:199], v[44:47]
	v_mfma_f32_16x16x32_bf16 v[40:43], v[162:165], v[196:199], v[40:43]
	v_mfma_f32_16x16x32_bf16 v[28:31], v[144:147], v[204:207], v[28:31]
	v_mfma_f32_16x16x32_bf16 v[24:27], v[162:165], v[204:207], v[24:27]
	v_mfma_f32_16x16x32_bf16 v[12:15], v[144:147], v[212:215], v[12:15]
	v_mfma_f32_16x16x32_bf16 v[8:11], v[162:165], v[212:215], v[8:11]
	v_mfma_f32_16x16x32_bf16 v[60:63], v[158:161], v[190:193], v[60:63]
	v_mfma_f32_16x16x32_bf16 v[56:59], v[166:169], v[190:193], v[56:59]
	v_mfma_f32_16x16x32_bf16 v[44:47], v[158:161], v[200:203], v[44:47]
	v_mfma_f32_16x16x32_bf16 v[40:43], v[166:169], v[200:203], v[40:43]
	v_mfma_f32_16x16x32_bf16 v[28:31], v[158:161], v[208:211], v[28:31]
	v_mfma_f32_16x16x32_bf16 v[24:27], v[166:169], v[208:211], v[24:27]
	v_mfma_f32_16x16x32_bf16 v[12:15], v[158:161], v[216:219], v[12:15]
	v_mfma_f32_16x16x32_bf16 v[8:11], v[166:169], v[216:219], v[8:11]
	v_mfma_f32_16x16x32_bf16 v[52:55], v[170:173], v[186:189], v[52:55]
	v_mfma_f32_16x16x32_bf16 v[48:51], v[178:181], v[186:189], v[48:51]
	v_mfma_f32_16x16x32_bf16 v[36:39], v[170:173], v[196:199], v[36:39]
	v_mfma_f32_16x16x32_bf16 v[32:35], v[178:181], v[196:199], v[32:35]
	v_mfma_f32_16x16x32_bf16 v[20:23], v[170:173], v[204:207], v[20:23]
	v_mfma_f32_16x16x32_bf16 v[16:19], v[178:181], v[204:207], v[16:19]
	v_mfma_f32_16x16x32_bf16 v[4:7], v[170:173], v[212:215], v[4:7]
	v_mfma_f32_16x16x32_bf16 v[0:3], v[178:181], v[212:215], v[0:3]
	v_mfma_f32_16x16x32_bf16 v[52:55], v[174:177], v[190:193], v[52:55]
	v_mfma_f32_16x16x32_bf16 v[48:51], v[182:185], v[190:193], v[48:51]
	v_mfma_f32_16x16x32_bf16 v[36:39], v[174:177], v[200:203], v[36:39]
	v_mfma_f32_16x16x32_bf16 v[32:35], v[182:185], v[200:203], v[32:35]
	v_mfma_f32_16x16x32_bf16 v[20:23], v[174:177], v[208:211], v[20:23]
	v_mfma_f32_16x16x32_bf16 v[16:19], v[182:185], v[208:211], v[16:19]
	v_mfma_f32_16x16x32_bf16 v[4:7], v[174:177], v[216:219], v[4:7]
	v_mfma_f32_16x16x32_bf16 v[0:3], v[182:185], v[216:219], v[0:3]
	s_setprio 0
	s_barrier
	s_add_i32 s77, 0, 0x18000
	v_add_u32_e32 v157, s77, v151
	s_add_i32 s78, 0, 0x1c000
	ds_read_b128 v[144:147], v157
	ds_read_b128 v[158:161], v157 offset:1024
	ds_read_b128 v[162:165], v157 offset:2048
	ds_read_b128 v[166:169], v157 offset:3072
	v_add_u32_e32 v157, s78, v151
	ds_read_b128 v[170:173], v157
	ds_read_b128 v[174:177], v157 offset:1024
	ds_read_b128 v[178:181], v157 offset:2048
	ds_read_b128 v[182:185], v157 offset:3072
	s_add_u32 s38, s38, 0x40000
	s_addc_u32 s39, s39, 0
	v_lshl_add_u64 v[226:227], s[38:39], 0, v[128:129]
	ds_read_b128 v[186:189], v155 offset:32768
	ds_read_b128 v[190:193], v155 offset:33792
	ds_read_b128 v[196:199], v155 offset:34816
	ds_read_b128 v[200:203], v155 offset:35840
	ds_read_b128 v[204:207], v155 offset:36864
	ds_read_b128 v[208:211], v155 offset:37888
	ds_read_b128 v[212:215], v155 offset:38912
	ds_read_b128 v[216:219], v155 offset:39936
	s_mov_b32 m0, s51
	s_nop 0
	global_load_lds_dwordx4 v[222:223], off
	s_mov_b32 m0, s52
	s_nop 0
	global_load_lds_dwordx4 v[224:225], off
	s_mov_b32 m0, s53
	s_nop 0
	global_load_lds_dwordx4 v[226:227], off
	v_lshl_add_u64 v[226:227], s[38:39], 0, v[132:133]
	s_mov_b32 m0, s54
	s_nop 0
	global_load_lds_dwordx4 v[226:227], off
	s_waitcnt vmcnt(8)
	s_waitcnt lgkmcnt(0)
	s_barrier
	s_setprio 1
	s_waitcnt lgkmcnt(0)
	v_mfma_f32_16x16x32_bf16 v[124:127], v[144:147], v[186:189], v[124:127]
	v_mfma_f32_16x16x32_bf16 v[120:123], v[162:165], v[186:189], v[120:123]
	v_mfma_f32_16x16x32_bf16 v[108:111], v[144:147], v[196:199], v[108:111]
	v_mfma_f32_16x16x32_bf16 v[104:107], v[162:165], v[196:199], v[104:107]
	v_mfma_f32_16x16x32_bf16 v[92:95], v[144:147], v[204:207], v[92:95]
	v_mfma_f32_16x16x32_bf16 v[88:91], v[162:165], v[204:207], v[88:91]
	v_mfma_f32_16x16x32_bf16 v[76:79], v[144:147], v[212:215], v[76:79]
	v_mfma_f32_16x16x32_bf16 v[72:75], v[162:165], v[212:215], v[72:75]
	v_mfma_f32_16x16x32_bf16 v[124:127], v[158:161], v[190:193], v[124:127]
	v_mfma_f32_16x16x32_bf16 v[120:123], v[166:169], v[190:193], v[120:123]
	v_mfma_f32_16x16x32_bf16 v[108:111], v[158:161], v[200:203], v[108:111]
	v_mfma_f32_16x16x32_bf16 v[104:107], v[166:169], v[200:203], v[104:107]
	v_mfma_f32_16x16x32_bf16 v[92:95], v[158:161], v[208:211], v[92:95]
	v_mfma_f32_16x16x32_bf16 v[88:91], v[166:169], v[208:211], v[88:91]
	v_mfma_f32_16x16x32_bf16 v[76:79], v[158:161], v[216:219], v[76:79]
	v_mfma_f32_16x16x32_bf16 v[72:75], v[166:169], v[216:219], v[72:75]
	v_mfma_f32_16x16x32_bf16 v[116:119], v[170:173], v[186:189], v[116:119]
	v_mfma_f32_16x16x32_bf16 v[112:115], v[178:181], v[186:189], v[112:115]
	v_mfma_f32_16x16x32_bf16 v[100:103], v[170:173], v[196:199], v[100:103]
	v_mfma_f32_16x16x32_bf16 v[96:99], v[178:181], v[196:199], v[96:99]
	v_mfma_f32_16x16x32_bf16 v[84:87], v[170:173], v[204:207], v[84:87]
	v_mfma_f32_16x16x32_bf16 v[80:83], v[178:181], v[204:207], v[80:83]
	v_mfma_f32_16x16x32_bf16 v[68:71], v[170:173], v[212:215], v[68:71]
	v_mfma_f32_16x16x32_bf16 v[64:67], v[178:181], v[212:215], v[64:67]
	v_mfma_f32_16x16x32_bf16 v[116:119], v[174:177], v[190:193], v[116:119]
	v_mfma_f32_16x16x32_bf16 v[112:115], v[182:185], v[190:193], v[112:115]
	v_mfma_f32_16x16x32_bf16 v[100:103], v[174:177], v[200:203], v[100:103]
	v_mfma_f32_16x16x32_bf16 v[96:99], v[182:185], v[200:203], v[96:99]
	v_mfma_f32_16x16x32_bf16 v[84:87], v[174:177], v[208:211], v[84:87]
	v_mfma_f32_16x16x32_bf16 v[80:83], v[182:185], v[208:211], v[80:83]
	v_mfma_f32_16x16x32_bf16 v[68:71], v[174:177], v[216:219], v[68:71]
	v_mfma_f32_16x16x32_bf16 v[64:67], v[182:185], v[216:219], v[64:67]
	s_setprio 0
	s_barrier
	s_add_i32 s38, s77, s49
	v_lshl_add_u64 v[148:149], v[148:149], 0, s[20:21]
	s_mov_b32 m0, s38
	ds_read_b128 v[186:189], v155 offset:49152
	ds_read_b128 v[190:193], v155 offset:50176
	ds_read_b128 v[196:199], v155 offset:51200
	ds_read_b128 v[200:203], v155 offset:52224
	ds_read_b128 v[204:207], v155 offset:53248
	ds_read_b128 v[208:211], v155 offset:54272
	ds_read_b128 v[212:215], v155 offset:55296
	ds_read_b128 v[216:219], v155 offset:56320
	global_load_lds_dwordx4 v[148:149], off
	s_add_i32 m0, s38, 0x2000
	s_add_u32 s36, s36, 0x40080
	v_lshl_add_u64 v[148:149], v[220:221], 0, s[20:21]
	s_addc_u32 s37, s37, 0
	s_add_i32 s38, s78, s49
	global_load_lds_dwordx4 v[148:149], off
	v_lshl_add_u64 v[148:149], s[36:37], 0, v[130:131]
	s_mov_b32 m0, s38
	s_nop 0
	global_load_lds_dwordx4 v[148:149], off
	v_lshl_add_u64 v[148:149], s[36:37], 0, v[134:135]
	s_add_i32 m0, s38, 0x2000
	s_nop 0
	global_load_lds_dwordx4 v[148:149], off
	s_waitcnt vmcnt(6)
	s_waitcnt lgkmcnt(0)
	s_barrier
	s_setprio 1
	s_waitcnt lgkmcnt(0)
	v_mfma_f32_16x16x32_bf16 v[60:63], v[144:147], v[186:189], v[60:63]
	v_mfma_f32_16x16x32_bf16 v[56:59], v[162:165], v[186:189], v[56:59]
	v_mfma_f32_16x16x32_bf16 v[44:47], v[144:147], v[196:199], v[44:47]
	v_mfma_f32_16x16x32_bf16 v[40:43], v[162:165], v[196:199], v[40:43]
	v_mfma_f32_16x16x32_bf16 v[28:31], v[144:147], v[204:207], v[28:31]
	v_mfma_f32_16x16x32_bf16 v[24:27], v[162:165], v[204:207], v[24:27]
	v_mfma_f32_16x16x32_bf16 v[12:15], v[144:147], v[212:215], v[12:15]
	v_mfma_f32_16x16x32_bf16 v[8:11], v[162:165], v[212:215], v[8:11]
	v_mfma_f32_16x16x32_bf16 v[60:63], v[158:161], v[190:193], v[60:63]
	v_mfma_f32_16x16x32_bf16 v[56:59], v[166:169], v[190:193], v[56:59]
	v_mfma_f32_16x16x32_bf16 v[44:47], v[158:161], v[200:203], v[44:47]
	v_mfma_f32_16x16x32_bf16 v[40:43], v[166:169], v[200:203], v[40:43]
	v_mfma_f32_16x16x32_bf16 v[28:31], v[158:161], v[208:211], v[28:31]
	v_mfma_f32_16x16x32_bf16 v[24:27], v[166:169], v[208:211], v[24:27]
	v_mfma_f32_16x16x32_bf16 v[12:15], v[158:161], v[216:219], v[12:15]
	v_mfma_f32_16x16x32_bf16 v[8:11], v[166:169], v[216:219], v[8:11]
	v_mfma_f32_16x16x32_bf16 v[52:55], v[170:173], v[186:189], v[52:55]
	v_mfma_f32_16x16x32_bf16 v[48:51], v[178:181], v[186:189], v[48:51]
	v_mfma_f32_16x16x32_bf16 v[36:39], v[170:173], v[196:199], v[36:39]
	v_mfma_f32_16x16x32_bf16 v[32:35], v[178:181], v[196:199], v[32:35]
	v_mfma_f32_16x16x32_bf16 v[20:23], v[170:173], v[204:207], v[20:23]
	v_mfma_f32_16x16x32_bf16 v[16:19], v[178:181], v[204:207], v[16:19]
	v_mfma_f32_16x16x32_bf16 v[4:7], v[170:173], v[212:215], v[4:7]
	v_mfma_f32_16x16x32_bf16 v[0:3], v[178:181], v[212:215], v[0:3]
	v_mfma_f32_16x16x32_bf16 v[52:55], v[174:177], v[190:193], v[52:55]
	v_mfma_f32_16x16x32_bf16 v[48:51], v[182:185], v[190:193], v[48:51]
	v_mfma_f32_16x16x32_bf16 v[36:39], v[174:177], v[200:203], v[36:39]
	v_mfma_f32_16x16x32_bf16 v[32:35], v[182:185], v[200:203], v[32:35]
	v_mfma_f32_16x16x32_bf16 v[20:23], v[174:177], v[208:211], v[20:23]
	v_mfma_f32_16x16x32_bf16 v[16:19], v[182:185], v[208:211], v[16:19]
	v_mfma_f32_16x16x32_bf16 v[4:7], v[174:177], v[216:219], v[4:7]
	v_mfma_f32_16x16x32_bf16 v[0:3], v[182:185], v[216:219], v[0:3]
	s_setprio 0
	s_barrier
	v_lshl_add_u64 v[222:223], v[222:223], 0, s[20:21]
	s_mov_b32 m0, s56
	s_nop 0
	global_load_lds_dwordx4 v[222:223], off
	v_lshl_add_u64 v[224:225], v[224:225], 0, s[20:21]
	s_mov_b32 m0, s57
	s_nop 0
	global_load_lds_dwordx4 v[224:225], off
	s_add_i32 s73, s73, 2
	s_add_u32 s34, s34, 0x100
	s_addc_u32 s35, s35, 0
	s_add_u32 s71, s71, 0x100
	s_addc_u32 s72, s72, 0
	s_cmp_gt_u32 s73, 13
	s_cbranch_scc0 .LBB0_2557
	s_and_b64 vcc, exec, s[22:23]
	s_cbranch_vccz .LBB0_2560
	s_barrier

.LBB0_2633:
	ds_read_b128 v[144:147], v153
	ds_read_b128 v[156:159], v153 offset:1024
	ds_read_b128 v[160:163], v153 offset:2048
	ds_read_b128 v[164:167], v153 offset:3072
	ds_read_b128 v[168:171], v154
	ds_read_b128 v[172:175], v154 offset:1024
	ds_read_b128 v[176:179], v154 offset:2048
	ds_read_b128 v[180:183], v154 offset:3072
	s_add_u32 s42, s40, 0xfffe0080
	s_addc_u32 s43, s41, -1
	s_cmp_eq_u32 s73, 4
	s_cselect_b32 s45, s31, s43
	s_cselect_b32 s44, s63, s42
	s_cselect_b32 s43, s29, s72
	s_cselect_b32 s42, s70, s71
	v_lshl_add_u64 v[148:149], s[40:41], 0, v[136:137]
	s_add_i32 m0, s39, 0xc000
	ds_read_b128 v[184:187], v155
	ds_read_b128 v[188:191], v155 offset:1024
	ds_read_b128 v[196:199], v155 offset:2048
	ds_read_b128 v[200:203], v155 offset:3072
	ds_read_b128 v[204:207], v155 offset:4096
	ds_read_b128 v[208:211], v155 offset:5120
	ds_read_b128 v[212:215], v155 offset:6144
	ds_read_b128 v[216:219], v155 offset:7168
	global_load_lds_dwordx4 v[148:149], off
	v_lshl_add_u64 v[148:149], s[40:41], 0, v[138:139]
	s_add_i32 m0, s39, 0xe000
	s_nop 0
	global_load_lds_dwordx4 v[148:149], off
	s_waitcnt vmcnt(8)
	s_waitcnt lgkmcnt(0)
	s_barrier
	s_setprio 1
	s_waitcnt lgkmcnt(0)
	v_mfma_f32_16x16x32_bf16 v[124:127], v[144:147], v[184:187], v[124:127]
	v_mfma_f32_16x16x32_bf16 v[120:123], v[160:163], v[184:187], v[120:123]
	v_mfma_f32_16x16x32_bf16 v[108:111], v[144:147], v[196:199], v[108:111]
	v_mfma_f32_16x16x32_bf16 v[104:107], v[160:163], v[196:199], v[104:107]
	v_mfma_f32_16x16x32_bf16 v[92:95], v[144:147], v[204:207], v[92:95]
	v_mfma_f32_16x16x32_bf16 v[88:91], v[160:163], v[204:207], v[88:91]
	v_mfma_f32_16x16x32_bf16 v[76:79], v[144:147], v[212:215], v[76:79]
	v_mfma_f32_16x16x32_bf16 v[72:75], v[160:163], v[212:215], v[72:75]
	v_mfma_f32_16x16x32_bf16 v[124:127], v[156:159], v[188:191], v[124:127]
	v_mfma_f32_16x16x32_bf16 v[120:123], v[164:167], v[188:191], v[120:123]
	v_mfma_f32_16x16x32_bf16 v[108:111], v[156:159], v[200:203], v[108:111]
	v_mfma_f32_16x16x32_bf16 v[104:107], v[164:167], v[200:203], v[104:107]
	v_mfma_f32_16x16x32_bf16 v[92:95], v[156:159], v[208:211], v[92:95]
	v_mfma_f32_16x16x32_bf16 v[88:91], v[164:167], v[208:211], v[88:91]
	v_mfma_f32_16x16x32_bf16 v[76:79], v[156:159], v[216:219], v[76:79]
	v_mfma_f32_16x16x32_bf16 v[72:75], v[164:167], v[216:219], v[72:75]
	v_mfma_f32_16x16x32_bf16 v[116:119], v[168:171], v[184:187], v[116:119]
	v_mfma_f32_16x16x32_bf16 v[112:115], v[176:179], v[184:187], v[112:115]
	v_mfma_f32_16x16x32_bf16 v[100:103], v[168:171], v[196:199], v[100:103]
	v_mfma_f32_16x16x32_bf16 v[96:99], v[176:179], v[196:199], v[96:99]
	v_mfma_f32_16x16x32_bf16 v[84:87], v[168:171], v[204:207], v[84:87]
	v_mfma_f32_16x16x32_bf16 v[80:83], v[176:179], v[204:207], v[80:83]
	v_mfma_f32_16x16x32_bf16 v[68:71], v[168:171], v[212:215], v[68:71]
	v_mfma_f32_16x16x32_bf16 v[64:67], v[176:179], v[212:215], v[64:67]
	v_mfma_f32_16x16x32_bf16 v[116:119], v[172:175], v[188:191], v[116:119]
	v_mfma_f32_16x16x32_bf16 v[112:115], v[180:183], v[188:191], v[112:115]
	v_mfma_f32_16x16x32_bf16 v[100:103], v[172:175], v[200:203], v[100:103]
	v_mfma_f32_16x16x32_bf16 v[96:99], v[180:183], v[200:203], v[96:99]
	v_mfma_f32_16x16x32_bf16 v[84:87], v[172:175], v[208:211], v[84:87]
	v_mfma_f32_16x16x32_bf16 v[80:83], v[180:183], v[208:211], v[80:83]
	v_mfma_f32_16x16x32_bf16 v[68:71], v[172:175], v[216:219], v[68:71]
	v_mfma_f32_16x16x32_bf16 v[64:67], v[180:183], v[216:219], v[64:67]
	s_setprio 0
	s_barrier
	s_add_i32 s77, s60, s52
	v_lshl_add_u64 v[148:149], s[42:43], 0, v[130:131]
	s_mov_b32 m0, s77
	ds_read_b128 v[184:187], v155 offset:16384
	ds_read_b128 v[188:191], v155 offset:17408
	ds_read_b128 v[196:199], v155 offset:18432
	ds_read_b128 v[200:203], v155 offset:19456
	ds_read_b128 v[204:207], v155 offset:20480
	ds_read_b128 v[208:211], v155 offset:21504
	ds_read_b128 v[212:215], v155 offset:22528
	ds_read_b128 v[216:219], v155 offset:23552
	global_load_lds_dwordx4 v[148:149], off
	s_add_i32 m0, s77, 0x2000
	s_add_u32 s78, s42, 0x20000
	v_lshl_add_u64 v[192:193], s[42:43], 0, v[134:135]
	s_addc_u32 s79, s43, 0
	s_add_i32 s77, s61, s52
	global_load_lds_dwordx4 v[192:193], off
	v_lshl_add_u64 v[220:221], s[78:79], 0, v[130:131]
	s_mov_b32 m0, s77
	v_lshl_add_u64 v[222:223], s[44:45], 0, v[132:133]
	global_load_lds_dwordx4 v[220:221], off
	v_lshl_add_u64 v[220:221], s[78:79], 0, v[134:135]
	s_add_i32 m0, s77, 0x2000
	s_nop 0
	global_load_lds_dwordx4 v[220:221], off
	v_lshl_add_u64 v[220:221], s[44:45], 0, v[128:129]
	s_waitcnt vmcnt(6)
	s_waitcnt lgkmcnt(0)
	s_barrier
	s_setprio 1
	s_waitcnt lgkmcnt(0)
	v_mfma_f32_16x16x32_bf16 v[60:63], v[144:147], v[184:187], v[60:63]
	v_mfma_f32_16x16x32_bf16 v[56:59], v[160:163], v[184:187], v[56:59]
	v_mfma_f32_16x16x32_bf16 v[44:47], v[144:147], v[196:199], v[44:47]
	v_mfma_f32_16x16x32_bf16 v[40:43], v[160:163], v[196:199], v[40:43]
	v_mfma_f32_16x16x32_bf16 v[28:31], v[144:147], v[204:207], v[28:31]
	v_mfma_f32_16x16x32_bf16 v[24:27], v[160:163], v[204:207], v[24:27]
	v_mfma_f32_16x16x32_bf16 v[12:15], v[144:147], v[212:215], v[12:15]
	v_mfma_f32_16x16x32_bf16 v[8:11], v[160:163], v[212:215], v[8:11]
	v_mfma_f32_16x16x32_bf16 v[60:63], v[156:159], v[188:191], v[60:63]
	v_mfma_f32_16x16x32_bf16 v[56:59], v[164:167], v[188:191], v[56:59]
	v_mfma_f32_16x16x32_bf16 v[44:47], v[156:159], v[200:203], v[44:47]
	v_mfma_f32_16x16x32_bf16 v[40:43], v[164:167], v[200:203], v[40:43]
	v_mfma_f32_16x16x32_bf16 v[28:31], v[156:159], v[208:211], v[28:31]
	v_mfma_f32_16x16x32_bf16 v[24:27], v[164:167], v[208:211], v[24:27]
	v_mfma_f32_16x16x32_bf16 v[12:15], v[156:159], v[216:219], v[12:15]
	v_mfma_f32_16x16x32_bf16 v[8:11], v[164:167], v[216:219], v[8:11]
	v_mfma_f32_16x16x32_bf16 v[52:55], v[168:171], v[184:187], v[52:55]
	v_mfma_f32_16x16x32_bf16 v[48:51], v[176:179], v[184:187], v[48:51]
	v_mfma_f32_16x16x32_bf16 v[36:39], v[168:171], v[196:199], v[36:39]
	v_mfma_f32_16x16x32_bf16 v[32:35], v[176:179], v[196:199], v[32:35]
	v_mfma_f32_16x16x32_bf16 v[20:23], v[168:171], v[204:207], v[20:23]
	v_mfma_f32_16x16x32_bf16 v[16:19], v[176:179], v[204:207], v[16:19]
	v_mfma_f32_16x16x32_bf16 v[4:7], v[168:171], v[212:215], v[4:7]
	v_mfma_f32_16x16x32_bf16 v[0:3], v[176:179], v[212:215], v[0:3]
	v_mfma_f32_16x16x32_bf16 v[52:55], v[172:175], v[188:191], v[52:55]
	v_mfma_f32_16x16x32_bf16 v[48:51], v[180:183], v[188:191], v[48:51]
	v_mfma_f32_16x16x32_bf16 v[36:39], v[172:175], v[200:203], v[36:39]
	v_mfma_f32_16x16x32_bf16 v[32:35], v[180:183], v[200:203], v[32:35]
	v_mfma_f32_16x16x32_bf16 v[20:23], v[172:175], v[208:211], v[20:23]
	v_mfma_f32_16x16x32_bf16 v[16:19], v[180:183], v[208:211], v[16:19]
	v_mfma_f32_16x16x32_bf16 v[4:7], v[172:175], v[216:219], v[4:7]
	v_mfma_f32_16x16x32_bf16 v[0:3], v[180:183], v[216:219], v[0:3]
	s_setprio 0
	s_barrier
	s_add_i32 s77, 0, 0x18000
	s_add_i32 s78, 0, 0x1c000
	v_add_u32_e32 v164, s77, v151
	v_add_u32_e32 v180, s78, v151
	ds_read_b128 v[144:147], v164
	ds_read_b128 v[156:159], v164 offset:1024
	ds_read_b128 v[160:163], v164 offset:2048
	ds_read_b128 v[164:167], v164 offset:3072
	ds_read_b128 v[168:171], v180
	ds_read_b128 v[172:175], v180 offset:1024
	ds_read_b128 v[176:179], v180 offset:2048
	ds_read_b128 v[180:183], v180 offset:3072
	s_add_u32 s44, s44, 0x20000
	s_addc_u32 s45, s45, 0
	v_lshl_add_u64 v[224:225], s[44:45], 0, v[128:129]
	ds_read_b128 v[184:187], v155 offset:32768
	ds_read_b128 v[188:191], v155 offset:33792
	ds_read_b128 v[196:199], v155 offset:34816
	ds_read_b128 v[200:203], v155 offset:35840
	ds_read_b128 v[204:207], v155 offset:36864
	ds_read_b128 v[208:211], v155 offset:37888
	ds_read_b128 v[212:215], v155 offset:38912
	ds_read_b128 v[216:219], v155 offset:39936
	s_mov_b32 m0, s39
	s_nop 0
	global_load_lds_dwordx4 v[220:221], off
	s_mov_b32 m0, s53
	s_nop 0
	global_load_lds_dwordx4 v[222:223], off
	s_mov_b32 m0, s54
	s_nop 0
	global_load_lds_dwordx4 v[224:225], off
	v_lshl_add_u64 v[224:225], s[44:45], 0, v[132:133]
	s_mov_b32 m0, s55
	s_nop 0
	global_load_lds_dwordx4 v[224:225], off
	s_waitcnt vmcnt(8)
	s_waitcnt lgkmcnt(0)
	s_barrier
	s_setprio 1
	s_waitcnt lgkmcnt(0)
	v_mfma_f32_16x16x32_bf16 v[124:127], v[144:147], v[184:187], v[124:127]
	v_mfma_f32_16x16x32_bf16 v[120:123], v[160:163], v[184:187], v[120:123]
	v_mfma_f32_16x16x32_bf16 v[108:111], v[144:147], v[196:199], v[108:111]
	v_mfma_f32_16x16x32_bf16 v[104:107], v[160:163], v[196:199], v[104:107]
	v_mfma_f32_16x16x32_bf16 v[92:95], v[144:147], v[204:207], v[92:95]
	v_mfma_f32_16x16x32_bf16 v[88:91], v[160:163], v[204:207], v[88:91]
	v_mfma_f32_16x16x32_bf16 v[76:79], v[144:147], v[212:215], v[76:79]
	v_mfma_f32_16x16x32_bf16 v[72:75], v[160:163], v[212:215], v[72:75]
	v_mfma_f32_16x16x32_bf16 v[124:127], v[156:159], v[188:191], v[124:127]
	v_mfma_f32_16x16x32_bf16 v[120:123], v[164:167], v[188:191], v[120:123]
	v_mfma_f32_16x16x32_bf16 v[108:111], v[156:159], v[200:203], v[108:111]
	v_mfma_f32_16x16x32_bf16 v[104:107], v[164:167], v[200:203], v[104:107]
	v_mfma_f32_16x16x32_bf16 v[92:95], v[156:159], v[208:211], v[92:95]
	v_mfma_f32_16x16x32_bf16 v[88:91], v[164:167], v[208:211], v[88:91]
	v_mfma_f32_16x16x32_bf16 v[76:79], v[156:159], v[216:219], v[76:79]
	v_mfma_f32_16x16x32_bf16 v[72:75], v[164:167], v[216:219], v[72:75]
	v_mfma_f32_16x16x32_bf16 v[116:119], v[168:171], v[184:187], v[116:119]
	v_mfma_f32_16x16x32_bf16 v[112:115], v[176:179], v[184:187], v[112:115]
	v_mfma_f32_16x16x32_bf16 v[100:103], v[168:171], v[196:199], v[100:103]
	v_mfma_f32_16x16x32_bf16 v[96:99], v[176:179], v[196:199], v[96:99]
	v_mfma_f32_16x16x32_bf16 v[84:87], v[168:171], v[204:207], v[84:87]
	v_mfma_f32_16x16x32_bf16 v[80:83], v[176:179], v[204:207], v[80:83]
	v_mfma_f32_16x16x32_bf16 v[68:71], v[168:171], v[212:215], v[68:71]
	v_mfma_f32_16x16x32_bf16 v[64:67], v[176:179], v[212:215], v[64:67]
	v_mfma_f32_16x16x32_bf16 v[116:119], v[172:175], v[188:191], v[116:119]
	v_mfma_f32_16x16x32_bf16 v[112:115], v[180:183], v[188:191], v[112:115]
	v_mfma_f32_16x16x32_bf16 v[100:103], v[172:175], v[200:203], v[100:103]
	v_mfma_f32_16x16x32_bf16 v[96:99], v[180:183], v[200:203], v[96:99]
	v_mfma_f32_16x16x32_bf16 v[84:87], v[172:175], v[208:211], v[84:87]
	v_mfma_f32_16x16x32_bf16 v[80:83], v[180:183], v[208:211], v[80:83]
	v_mfma_f32_16x16x32_bf16 v[68:71], v[172:175], v[216:219], v[68:71]
	v_mfma_f32_16x16x32_bf16 v[64:67], v[180:183], v[216:219], v[64:67]
	s_setprio 0
	s_barrier
	s_add_i32 s44, s77, s52
	v_lshl_add_u64 v[148:149], v[148:149], 0, s[18:19]
	s_mov_b32 m0, s44
	ds_read_b128 v[184:187], v155 offset:49152
	ds_read_b128 v[188:191], v155 offset:50176
	ds_read_b128 v[196:199], v155 offset:51200
	ds_read_b128 v[200:203], v155 offset:52224
	ds_read_b128 v[204:207], v155 offset:53248
	ds_read_b128 v[208:211], v155 offset:54272
	ds_read_b128 v[212:215], v155 offset:55296
	ds_read_b128 v[216:219], v155 offset:56320
	global_load_lds_dwordx4 v[148:149], off
	s_add_i32 m0, s44, 0x2000
	s_add_u32 s42, s42, 0x20080
	v_lshl_add_u64 v[148:149], v[192:193], 0, s[18:19]
	s_addc_u32 s43, s43, 0
	s_add_i32 s44, s78, s52
	global_load_lds_dwordx4 v[148:149], off
	v_lshl_add_u64 v[148:149], s[42:43], 0, v[130:131]
	s_mov_b32 m0, s44
	s_nop 0
	global_load_lds_dwordx4 v[148:149], off
	v_lshl_add_u64 v[148:149], s[42:43], 0, v[134:135]
	s_add_i32 m0, s44, 0x2000
	s_nop 0
	global_load_lds_dwordx4 v[148:149], off
	s_waitcnt vmcnt(6)
	s_waitcnt lgkmcnt(0)
	s_barrier
	s_setprio 1
	s_waitcnt lgkmcnt(0)
	v_mfma_f32_16x16x32_bf16 v[60:63], v[144:147], v[184:187], v[60:63]
	v_mfma_f32_16x16x32_bf16 v[56:59], v[160:163], v[184:187], v[56:59]
	v_mfma_f32_16x16x32_bf16 v[44:47], v[144:147], v[196:199], v[44:47]
	v_mfma_f32_16x16x32_bf16 v[40:43], v[160:163], v[196:199], v[40:43]
	v_mfma_f32_16x16x32_bf16 v[28:31], v[144:147], v[204:207], v[28:31]
	v_mfma_f32_16x16x32_bf16 v[24:27], v[160:163], v[204:207], v[24:27]
	v_mfma_f32_16x16x32_bf16 v[12:15], v[144:147], v[212:215], v[12:15]
	v_mfma_f32_16x16x32_bf16 v[8:11], v[160:163], v[212:215], v[8:11]
	v_mfma_f32_16x16x32_bf16 v[60:63], v[156:159], v[188:191], v[60:63]
	v_mfma_f32_16x16x32_bf16 v[56:59], v[164:167], v[188:191], v[56:59]
	v_mfma_f32_16x16x32_bf16 v[44:47], v[156:159], v[200:203], v[44:47]
	v_mfma_f32_16x16x32_bf16 v[40:43], v[164:167], v[200:203], v[40:43]
	v_mfma_f32_16x16x32_bf16 v[28:31], v[156:159], v[208:211], v[28:31]
	v_mfma_f32_16x16x32_bf16 v[24:27], v[164:167], v[208:211], v[24:27]
	v_mfma_f32_16x16x32_bf16 v[12:15], v[156:159], v[216:219], v[12:15]
	v_mfma_f32_16x16x32_bf16 v[8:11], v[164:167], v[216:219], v[8:11]
	v_mfma_f32_16x16x32_bf16 v[52:55], v[168:171], v[184:187], v[52:55]
	v_mfma_f32_16x16x32_bf16 v[48:51], v[176:179], v[184:187], v[48:51]
	v_mfma_f32_16x16x32_bf16 v[36:39], v[168:171], v[196:199], v[36:39]
	v_mfma_f32_16x16x32_bf16 v[32:35], v[176:179], v[196:199], v[32:35]
	v_mfma_f32_16x16x32_bf16 v[20:23], v[168:171], v[204:207], v[20:23]
	v_mfma_f32_16x16x32_bf16 v[16:19], v[176:179], v[204:207], v[16:19]
	v_mfma_f32_16x16x32_bf16 v[4:7], v[168:171], v[212:215], v[4:7]
	v_mfma_f32_16x16x32_bf16 v[0:3], v[176:179], v[212:215], v[0:3]
	v_mfma_f32_16x16x32_bf16 v[52:55], v[172:175], v[188:191], v[52:55]
	v_mfma_f32_16x16x32_bf16 v[48:51], v[180:183], v[188:191], v[48:51]
	v_mfma_f32_16x16x32_bf16 v[36:39], v[172:175], v[200:203], v[36:39]
	v_mfma_f32_16x16x32_bf16 v[32:35], v[180:183], v[200:203], v[32:35]
	v_mfma_f32_16x16x32_bf16 v[20:23], v[172:175], v[208:211], v[20:23]
	v_mfma_f32_16x16x32_bf16 v[16:19], v[180:183], v[208:211], v[16:19]
	v_mfma_f32_16x16x32_bf16 v[4:7], v[172:175], v[216:219], v[4:7]
	v_mfma_f32_16x16x32_bf16 v[0:3], v[180:183], v[216:219], v[0:3]
	s_setprio 0
	s_barrier
	v_lshl_add_u64 v[220:221], v[220:221], 0, s[18:19]
	s_mov_b32 m0, s57
	s_nop 0
	global_load_lds_dwordx4 v[220:221], off
	v_lshl_add_u64 v[222:223], v[222:223], 0, s[18:19]
	s_mov_b32 m0, s58
	s_nop 0
	global_load_lds_dwordx4 v[222:223], off
	s_add_i32 s73, s73, 2
	s_add_u32 s40, s40, 0x100
	s_addc_u32 s41, s41, 0
	s_add_u32 s71, s71, 0x100
	s_addc_u32 s72, s72, 0
	s_cmp_gt_u32 s73, 5
	s_cbranch_scc0 .LBB0_2633
	s_and_b64 vcc, exec, s[20:21]
	s_cbranch_vccz .LBB0_2636
	s_barrier

.LBB0_2657:
	ds_read_b128 v[144:147], v153
	ds_read_b128 v[158:161], v153 offset:1024
	ds_read_b128 v[162:165], v153 offset:2048
	ds_read_b128 v[166:169], v153 offset:3072
	ds_read_b128 v[170:173], v154
	ds_read_b128 v[174:177], v154 offset:1024
	ds_read_b128 v[178:181], v154 offset:2048
	ds_read_b128 v[182:185], v154 offset:3072
	s_add_u32 s34, s30, 0xfffc0080
	s_addc_u32 s35, s31, -1
	s_cmp_eq_u32 s70, 12
	s_cselect_b32 s37, s25, s35
	s_cselect_b32 s36, s60, s34
	s_cselect_b32 s35, s23, s63
	s_cselect_b32 s34, s61, s62
	v_lshl_add_u64 v[148:149], s[30:31], 0, v[136:137]
	s_add_i32 m0, s48, 0xc000
	ds_read_b128 v[186:189], v155
	ds_read_b128 v[190:193], v155 offset:1024
	ds_read_b128 v[196:199], v155 offset:2048
	ds_read_b128 v[200:203], v155 offset:3072
	ds_read_b128 v[204:207], v155 offset:4096
	ds_read_b128 v[208:211], v155 offset:5120
	ds_read_b128 v[212:215], v155 offset:6144
	ds_read_b128 v[216:219], v155 offset:7168
	global_load_lds_dwordx4 v[148:149], off
	v_lshl_add_u64 v[148:149], s[30:31], 0, v[138:139]
	s_add_i32 m0, s48, 0xe000
	s_nop 0
	global_load_lds_dwordx4 v[148:149], off
	s_waitcnt vmcnt(8)
	s_waitcnt lgkmcnt(0)
	s_barrier
	s_setprio 1
	s_waitcnt lgkmcnt(0)
	v_mfma_f32_16x16x32_bf16 v[124:127], v[144:147], v[186:189], v[124:127]
	v_mfma_f32_16x16x32_bf16 v[120:123], v[162:165], v[186:189], v[120:123]
	v_mfma_f32_16x16x32_bf16 v[108:111], v[144:147], v[196:199], v[108:111]
	v_mfma_f32_16x16x32_bf16 v[104:107], v[162:165], v[196:199], v[104:107]
	v_mfma_f32_16x16x32_bf16 v[92:95], v[144:147], v[204:207], v[92:95]
	v_mfma_f32_16x16x32_bf16 v[88:91], v[162:165], v[204:207], v[88:91]
	v_mfma_f32_16x16x32_bf16 v[76:79], v[144:147], v[212:215], v[76:79]
	v_mfma_f32_16x16x32_bf16 v[72:75], v[162:165], v[212:215], v[72:75]
	v_mfma_f32_16x16x32_bf16 v[124:127], v[158:161], v[190:193], v[124:127]
	v_mfma_f32_16x16x32_bf16 v[120:123], v[166:169], v[190:193], v[120:123]
	v_mfma_f32_16x16x32_bf16 v[108:111], v[158:161], v[200:203], v[108:111]
	v_mfma_f32_16x16x32_bf16 v[104:107], v[166:169], v[200:203], v[104:107]
	v_mfma_f32_16x16x32_bf16 v[92:95], v[158:161], v[208:211], v[92:95]
	v_mfma_f32_16x16x32_bf16 v[88:91], v[166:169], v[208:211], v[88:91]
	v_mfma_f32_16x16x32_bf16 v[76:79], v[158:161], v[216:219], v[76:79]
	v_mfma_f32_16x16x32_bf16 v[72:75], v[166:169], v[216:219], v[72:75]
	v_mfma_f32_16x16x32_bf16 v[116:119], v[170:173], v[186:189], v[116:119]
	v_mfma_f32_16x16x32_bf16 v[112:115], v[178:181], v[186:189], v[112:115]
	v_mfma_f32_16x16x32_bf16 v[100:103], v[170:173], v[196:199], v[100:103]
	v_mfma_f32_16x16x32_bf16 v[96:99], v[178:181], v[196:199], v[96:99]
	v_mfma_f32_16x16x32_bf16 v[84:87], v[170:173], v[204:207], v[84:87]
	v_mfma_f32_16x16x32_bf16 v[80:83], v[178:181], v[204:207], v[80:83]
	v_mfma_f32_16x16x32_bf16 v[68:71], v[170:173], v[212:215], v[68:71]
	v_mfma_f32_16x16x32_bf16 v[64:67], v[178:181], v[212:215], v[64:67]
	v_mfma_f32_16x16x32_bf16 v[116:119], v[174:177], v[190:193], v[116:119]
	v_mfma_f32_16x16x32_bf16 v[112:115], v[182:185], v[190:193], v[112:115]
	v_mfma_f32_16x16x32_bf16 v[100:103], v[174:177], v[200:203], v[100:103]
	v_mfma_f32_16x16x32_bf16 v[96:99], v[182:185], v[200:203], v[96:99]
	v_mfma_f32_16x16x32_bf16 v[84:87], v[174:177], v[208:211], v[84:87]
	v_mfma_f32_16x16x32_bf16 v[80:83], v[182:185], v[208:211], v[80:83]
	v_mfma_f32_16x16x32_bf16 v[68:71], v[174:177], v[216:219], v[68:71]
	v_mfma_f32_16x16x32_bf16 v[64:67], v[182:185], v[216:219], v[64:67]
	s_setprio 0
	s_barrier
	s_add_i32 s71, s56, s45
	v_lshl_add_u64 v[148:149], s[34:35], 0, v[130:131]
	s_mov_b32 m0, s71
	ds_read_b128 v[186:189], v155 offset:16384
	ds_read_b128 v[190:193], v155 offset:17408
	ds_read_b128 v[196:199], v155 offset:18432
	ds_read_b128 v[200:203], v155 offset:19456
	ds_read_b128 v[204:207], v155 offset:20480
	ds_read_b128 v[208:211], v155 offset:21504
	ds_read_b128 v[212:215], v155 offset:22528
	ds_read_b128 v[216:219], v155 offset:23552
	global_load_lds_dwordx4 v[148:149], off
	s_add_i32 m0, s71, 0x2000
	s_add_u32 s72, s34, 0x40000
	v_lshl_add_u64 v[220:221], s[34:35], 0, v[134:135]
	s_addc_u32 s73, s35, 0
	s_add_i32 s71, s57, s45
	global_load_lds_dwordx4 v[220:221], off
	v_lshl_add_u64 v[222:223], s[72:73], 0, v[130:131]
	s_mov_b32 m0, s71
	v_lshl_add_u64 v[224:225], s[36:37], 0, v[132:133]
	global_load_lds_dwordx4 v[222:223], off
	v_lshl_add_u64 v[222:223], s[72:73], 0, v[134:135]
	s_add_i32 m0, s71, 0x2000
	s_nop 0
	global_load_lds_dwordx4 v[222:223], off
	v_lshl_add_u64 v[222:223], s[36:37], 0, v[128:129]
	s_waitcnt vmcnt(6)
	s_waitcnt lgkmcnt(0)
	s_barrier
	s_setprio 1
	s_waitcnt lgkmcnt(0)
	v_mfma_f32_16x16x32_bf16 v[60:63], v[144:147], v[186:189], v[60:63]
	v_mfma_f32_16x16x32_bf16 v[56:59], v[162:165], v[186:189], v[56:59]
	v_mfma_f32_16x16x32_bf16 v[44:47], v[144:147], v[196:199], v[44:47]
	v_mfma_f32_16x16x32_bf16 v[40:43], v[162:165], v[196:199], v[40:43]
	v_mfma_f32_16x16x32_bf16 v[28:31], v[144:147], v[204:207], v[28:31]
	v_mfma_f32_16x16x32_bf16 v[24:27], v[162:165], v[204:207], v[24:27]
	v_mfma_f32_16x16x32_bf16 v[12:15], v[144:147], v[212:215], v[12:15]
	v_mfma_f32_16x16x32_bf16 v[8:11], v[162:165], v[212:215], v[8:11]
	v_mfma_f32_16x16x32_bf16 v[60:63], v[158:161], v[190:193], v[60:63]
	v_mfma_f32_16x16x32_bf16 v[56:59], v[166:169], v[190:193], v[56:59]
	v_mfma_f32_16x16x32_bf16 v[44:47], v[158:161], v[200:203], v[44:47]
	v_mfma_f32_16x16x32_bf16 v[40:43], v[166:169], v[200:203], v[40:43]
	v_mfma_f32_16x16x32_bf16 v[28:31], v[158:161], v[208:211], v[28:31]
	v_mfma_f32_16x16x32_bf16 v[24:27], v[166:169], v[208:211], v[24:27]
	v_mfma_f32_16x16x32_bf16 v[12:15], v[158:161], v[216:219], v[12:15]
	v_mfma_f32_16x16x32_bf16 v[8:11], v[166:169], v[216:219], v[8:11]
	v_mfma_f32_16x16x32_bf16 v[52:55], v[170:173], v[186:189], v[52:55]
	v_mfma_f32_16x16x32_bf16 v[48:51], v[178:181], v[186:189], v[48:51]
	v_mfma_f32_16x16x32_bf16 v[36:39], v[170:173], v[196:199], v[36:39]
	v_mfma_f32_16x16x32_bf16 v[32:35], v[178:181], v[196:199], v[32:35]
	v_mfma_f32_16x16x32_bf16 v[20:23], v[170:173], v[204:207], v[20:23]
	v_mfma_f32_16x16x32_bf16 v[16:19], v[178:181], v[204:207], v[16:19]
	v_mfma_f32_16x16x32_bf16 v[4:7], v[170:173], v[212:215], v[4:7]
	v_mfma_f32_16x16x32_bf16 v[0:3], v[178:181], v[212:215], v[0:3]
	v_mfma_f32_16x16x32_bf16 v[52:55], v[174:177], v[190:193], v[52:55]
	v_mfma_f32_16x16x32_bf16 v[48:51], v[182:185], v[190:193], v[48:51]
	v_mfma_f32_16x16x32_bf16 v[36:39], v[174:177], v[200:203], v[36:39]
	v_mfma_f32_16x16x32_bf16 v[32:35], v[182:185], v[200:203], v[32:35]
	v_mfma_f32_16x16x32_bf16 v[20:23], v[174:177], v[208:211], v[20:23]
	v_mfma_f32_16x16x32_bf16 v[16:19], v[182:185], v[208:211], v[16:19]
	v_mfma_f32_16x16x32_bf16 v[4:7], v[174:177], v[216:219], v[4:7]
	v_mfma_f32_16x16x32_bf16 v[0:3], v[182:185], v[216:219], v[0:3]
	s_setprio 0
	s_barrier
	s_add_i32 s71, 0, 0x18000
	v_add_u32_e32 v157, s71, v151
	s_add_i32 s72, 0, 0x1c000
	ds_read_b128 v[144:147], v157
	ds_read_b128 v[158:161], v157 offset:1024
	ds_read_b128 v[162:165], v157 offset:2048
	ds_read_b128 v[166:169], v157 offset:3072
	v_add_u32_e32 v157, s72, v151
	ds_read_b128 v[170:173], v157
	ds_read_b128 v[174:177], v157 offset:1024
	ds_read_b128 v[178:181], v157 offset:2048
	ds_read_b128 v[182:185], v157 offset:3072
	s_add_u32 s36, s36, 0x40000
	s_addc_u32 s37, s37, 0
	v_lshl_add_u64 v[226:227], s[36:37], 0, v[128:129]
	ds_read_b128 v[186:189], v155 offset:32768
	ds_read_b128 v[190:193], v155 offset:33792
	ds_read_b128 v[196:199], v155 offset:34816
	ds_read_b128 v[200:203], v155 offset:35840
	ds_read_b128 v[204:207], v155 offset:36864
	ds_read_b128 v[208:211], v155 offset:37888
	ds_read_b128 v[212:215], v155 offset:38912
	ds_read_b128 v[216:219], v155 offset:39936
	s_mov_b32 m0, s48
	s_nop 0
	global_load_lds_dwordx4 v[222:223], off
	s_mov_b32 m0, s49
	s_nop 0
	global_load_lds_dwordx4 v[224:225], off
	s_mov_b32 m0, s50
	s_nop 0
	global_load_lds_dwordx4 v[226:227], off
	v_lshl_add_u64 v[226:227], s[36:37], 0, v[132:133]
	s_mov_b32 m0, s51
	s_nop 0
	global_load_lds_dwordx4 v[226:227], off
	s_waitcnt vmcnt(8)
	s_waitcnt lgkmcnt(0)
	s_barrier
	s_setprio 1
	s_waitcnt lgkmcnt(0)
	v_mfma_f32_16x16x32_bf16 v[124:127], v[144:147], v[186:189], v[124:127]
	v_mfma_f32_16x16x32_bf16 v[120:123], v[162:165], v[186:189], v[120:123]
	v_mfma_f32_16x16x32_bf16 v[108:111], v[144:147], v[196:199], v[108:111]
	v_mfma_f32_16x16x32_bf16 v[104:107], v[162:165], v[196:199], v[104:107]
	v_mfma_f32_16x16x32_bf16 v[92:95], v[144:147], v[204:207], v[92:95]
	v_mfma_f32_16x16x32_bf16 v[88:91], v[162:165], v[204:207], v[88:91]
	v_mfma_f32_16x16x32_bf16 v[76:79], v[144:147], v[212:215], v[76:79]
	v_mfma_f32_16x16x32_bf16 v[72:75], v[162:165], v[212:215], v[72:75]
	v_mfma_f32_16x16x32_bf16 v[124:127], v[158:161], v[190:193], v[124:127]
	v_mfma_f32_16x16x32_bf16 v[120:123], v[166:169], v[190:193], v[120:123]
	v_mfma_f32_16x16x32_bf16 v[108:111], v[158:161], v[200:203], v[108:111]
	v_mfma_f32_16x16x32_bf16 v[104:107], v[166:169], v[200:203], v[104:107]
	v_mfma_f32_16x16x32_bf16 v[92:95], v[158:161], v[208:211], v[92:95]
	v_mfma_f32_16x16x32_bf16 v[88:91], v[166:169], v[208:211], v[88:91]
	v_mfma_f32_16x16x32_bf16 v[76:79], v[158:161], v[216:219], v[76:79]
	v_mfma_f32_16x16x32_bf16 v[72:75], v[166:169], v[216:219], v[72:75]
	v_mfma_f32_16x16x32_bf16 v[116:119], v[170:173], v[186:189], v[116:119]
	v_mfma_f32_16x16x32_bf16 v[112:115], v[178:181], v[186:189], v[112:115]
	v_mfma_f32_16x16x32_bf16 v[100:103], v[170:173], v[196:199], v[100:103]
	v_mfma_f32_16x16x32_bf16 v[96:99], v[178:181], v[196:199], v[96:99]
	v_mfma_f32_16x16x32_bf16 v[84:87], v[170:173], v[204:207], v[84:87]
	v_mfma_f32_16x16x32_bf16 v[80:83], v[178:181], v[204:207], v[80:83]
	v_mfma_f32_16x16x32_bf16 v[68:71], v[170:173], v[212:215], v[68:71]
	v_mfma_f32_16x16x32_bf16 v[64:67], v[178:181], v[212:215], v[64:67]
	v_mfma_f32_16x16x32_bf16 v[116:119], v[174:177], v[190:193], v[116:119]
	v_mfma_f32_16x16x32_bf16 v[112:115], v[182:185], v[190:193], v[112:115]
	v_mfma_f32_16x16x32_bf16 v[100:103], v[174:177], v[200:203], v[100:103]
	v_mfma_f32_16x16x32_bf16 v[96:99], v[182:185], v[200:203], v[96:99]
	v_mfma_f32_16x16x32_bf16 v[84:87], v[174:177], v[208:211], v[84:87]
	v_mfma_f32_16x16x32_bf16 v[80:83], v[182:185], v[208:211], v[80:83]
	v_mfma_f32_16x16x32_bf16 v[68:71], v[174:177], v[216:219], v[68:71]
	v_mfma_f32_16x16x32_bf16 v[64:67], v[182:185], v[216:219], v[64:67]
	s_setprio 0
	s_barrier
	s_add_i32 s36, s71, s45
	v_lshl_add_u64 v[148:149], v[148:149], 0, s[18:19]
	s_mov_b32 m0, s36
	ds_read_b128 v[186:189], v155 offset:49152
	ds_read_b128 v[190:193], v155 offset:50176
	ds_read_b128 v[196:199], v155 offset:51200
	ds_read_b128 v[200:203], v155 offset:52224
	ds_read_b128 v[204:207], v155 offset:53248
	ds_read_b128 v[208:211], v155 offset:54272
	ds_read_b128 v[212:215], v155 offset:55296
	ds_read_b128 v[216:219], v155 offset:56320
	global_load_lds_dwordx4 v[148:149], off
	s_add_i32 m0, s36, 0x2000
	s_add_u32 s34, s34, 0x40080
	v_lshl_add_u64 v[148:149], v[220:221], 0, s[18:19]
	s_addc_u32 s35, s35, 0
	s_add_i32 s36, s72, s45
	global_load_lds_dwordx4 v[148:149], off
	v_lshl_add_u64 v[148:149], s[34:35], 0, v[130:131]
	s_mov_b32 m0, s36
	s_nop 0
	global_load_lds_dwordx4 v[148:149], off
	v_lshl_add_u64 v[148:149], s[34:35], 0, v[134:135]
	s_add_i32 m0, s36, 0x2000
	s_nop 0
	global_load_lds_dwordx4 v[148:149], off
	s_waitcnt vmcnt(6)
	s_waitcnt lgkmcnt(0)
	s_barrier
	s_setprio 1
	s_waitcnt lgkmcnt(0)
	v_mfma_f32_16x16x32_bf16 v[60:63], v[144:147], v[186:189], v[60:63]
	v_mfma_f32_16x16x32_bf16 v[56:59], v[162:165], v[186:189], v[56:59]
	v_mfma_f32_16x16x32_bf16 v[44:47], v[144:147], v[196:199], v[44:47]
	v_mfma_f32_16x16x32_bf16 v[40:43], v[162:165], v[196:199], v[40:43]
	v_mfma_f32_16x16x32_bf16 v[28:31], v[144:147], v[204:207], v[28:31]
	v_mfma_f32_16x16x32_bf16 v[24:27], v[162:165], v[204:207], v[24:27]
	v_mfma_f32_16x16x32_bf16 v[12:15], v[144:147], v[212:215], v[12:15]
	v_mfma_f32_16x16x32_bf16 v[8:11], v[162:165], v[212:215], v[8:11]
	v_mfma_f32_16x16x32_bf16 v[60:63], v[158:161], v[190:193], v[60:63]
	v_mfma_f32_16x16x32_bf16 v[56:59], v[166:169], v[190:193], v[56:59]
	v_mfma_f32_16x16x32_bf16 v[44:47], v[158:161], v[200:203], v[44:47]
	v_mfma_f32_16x16x32_bf16 v[40:43], v[166:169], v[200:203], v[40:43]
	v_mfma_f32_16x16x32_bf16 v[28:31], v[158:161], v[208:211], v[28:31]
	v_mfma_f32_16x16x32_bf16 v[24:27], v[166:169], v[208:211], v[24:27]
	v_mfma_f32_16x16x32_bf16 v[12:15], v[158:161], v[216:219], v[12:15]
	v_mfma_f32_16x16x32_bf16 v[8:11], v[166:169], v[216:219], v[8:11]
	v_mfma_f32_16x16x32_bf16 v[52:55], v[170:173], v[186:189], v[52:55]
	v_mfma_f32_16x16x32_bf16 v[48:51], v[178:181], v[186:189], v[48:51]
	v_mfma_f32_16x16x32_bf16 v[36:39], v[170:173], v[196:199], v[36:39]
	v_mfma_f32_16x16x32_bf16 v[32:35], v[178:181], v[196:199], v[32:35]
	v_mfma_f32_16x16x32_bf16 v[20:23], v[170:173], v[204:207], v[20:23]
	v_mfma_f32_16x16x32_bf16 v[16:19], v[178:181], v[204:207], v[16:19]
	v_mfma_f32_16x16x32_bf16 v[4:7], v[170:173], v[212:215], v[4:7]
	v_mfma_f32_16x16x32_bf16 v[0:3], v[178:181], v[212:215], v[0:3]
	v_mfma_f32_16x16x32_bf16 v[52:55], v[174:177], v[190:193], v[52:55]
	v_mfma_f32_16x16x32_bf16 v[48:51], v[182:185], v[190:193], v[48:51]
	v_mfma_f32_16x16x32_bf16 v[36:39], v[174:177], v[200:203], v[36:39]
	v_mfma_f32_16x16x32_bf16 v[32:35], v[182:185], v[200:203], v[32:35]
	v_mfma_f32_16x16x32_bf16 v[20:23], v[174:177], v[208:211], v[20:23]
	v_mfma_f32_16x16x32_bf16 v[16:19], v[182:185], v[208:211], v[16:19]
	v_mfma_f32_16x16x32_bf16 v[4:7], v[174:177], v[216:219], v[4:7]
	v_mfma_f32_16x16x32_bf16 v[0:3], v[182:185], v[216:219], v[0:3]
	s_setprio 0
	s_barrier
	v_lshl_add_u64 v[222:223], v[222:223], 0, s[18:19]
	s_mov_b32 m0, s53
	s_nop 0
	global_load_lds_dwordx4 v[222:223], off
	v_lshl_add_u64 v[224:225], v[224:225], 0, s[18:19]
	s_mov_b32 m0, s54
	s_nop 0
	global_load_lds_dwordx4 v[224:225], off
	s_add_i32 s70, s70, 2
	s_add_u32 s30, s30, 0x100
	s_addc_u32 s31, s31, 0
	s_add_u32 s62, s62, 0x100
	s_addc_u32 s63, s63, 0
	s_cmp_gt_u32 s70, 13
	s_cbranch_scc0 .LBB0_2657
	s_and_b64 vcc, exec, s[20:21]
	s_cbranch_vccz .LBB0_2660
	s_barrier

.LBB0_3031:
	ds_read_b128 v[146:149], v155
	ds_read_b128 v[160:163], v155 offset:1024
	ds_read_b128 v[164:167], v155 offset:2048
	ds_read_b128 v[168:171], v155 offset:3072
	ds_read_b128 v[172:175], v156
	ds_read_b128 v[176:179], v156 offset:1024
	ds_read_b128 v[180:183], v156 offset:2048
	ds_read_b128 v[184:187], v156 offset:3072
	s_add_u32 s36, s0, 0xfffc0080
	s_addc_u32 s37, s1, -1
	s_cmp_eq_u32 s60, 12
	s_cselect_b32 s39, s21, s37
	s_cselect_b32 s38, s23, s36
	s_cselect_b32 s37, s27, s59
	s_cselect_b32 s36, s26, s25
	v_lshl_add_u64 v[150:151], s[0:1], 0, v[138:139]
	s_add_i32 m0, s35, 0xc000
	ds_read_b128 v[188:191], v157
	ds_read_b128 v[196:199], v157 offset:1024
	ds_read_b128 v[200:203], v157 offset:2048
	ds_read_b128 v[204:207], v157 offset:3072
	ds_read_b128 v[208:211], v157 offset:4096
	ds_read_b128 v[212:215], v157 offset:5120
	ds_read_b128 v[216:219], v157 offset:6144
	ds_read_b128 v[220:223], v157 offset:7168
	global_load_lds_dwordx4 v[150:151], off
	v_lshl_add_u64 v[150:151], s[0:1], 0, v[140:141]
	s_add_i32 m0, s35, 0xe000
	s_nop 0
	global_load_lds_dwordx4 v[150:151], off
	s_waitcnt vmcnt(8)
	s_waitcnt lgkmcnt(0)
	s_barrier
	s_setprio 1
	s_waitcnt lgkmcnt(0)
	v_mfma_f32_16x16x32_bf16 v[124:127], v[146:149], v[188:191], v[124:127]
	v_mfma_f32_16x16x32_bf16 v[120:123], v[164:167], v[188:191], v[120:123]
	v_mfma_f32_16x16x32_bf16 v[108:111], v[146:149], v[200:203], v[108:111]
	v_mfma_f32_16x16x32_bf16 v[104:107], v[164:167], v[200:203], v[104:107]
	v_mfma_f32_16x16x32_bf16 v[92:95], v[146:149], v[208:211], v[92:95]
	v_mfma_f32_16x16x32_bf16 v[88:91], v[164:167], v[208:211], v[88:91]
	v_mfma_f32_16x16x32_bf16 v[76:79], v[146:149], v[216:219], v[76:79]
	v_mfma_f32_16x16x32_bf16 v[72:75], v[164:167], v[216:219], v[72:75]
	v_mfma_f32_16x16x32_bf16 v[124:127], v[160:163], v[196:199], v[124:127]
	v_mfma_f32_16x16x32_bf16 v[120:123], v[168:171], v[196:199], v[120:123]
	v_mfma_f32_16x16x32_bf16 v[108:111], v[160:163], v[204:207], v[108:111]
	v_mfma_f32_16x16x32_bf16 v[104:107], v[168:171], v[204:207], v[104:107]
	v_mfma_f32_16x16x32_bf16 v[92:95], v[160:163], v[212:215], v[92:95]
	v_mfma_f32_16x16x32_bf16 v[88:91], v[168:171], v[212:215], v[88:91]
	v_mfma_f32_16x16x32_bf16 v[76:79], v[160:163], v[220:223], v[76:79]
	v_mfma_f32_16x16x32_bf16 v[72:75], v[168:171], v[220:223], v[72:75]
	v_mfma_f32_16x16x32_bf16 v[116:119], v[172:175], v[188:191], v[116:119]
	v_mfma_f32_16x16x32_bf16 v[112:115], v[180:183], v[188:191], v[112:115]
	v_mfma_f32_16x16x32_bf16 v[100:103], v[172:175], v[200:203], v[100:103]
	v_mfma_f32_16x16x32_bf16 v[96:99], v[180:183], v[200:203], v[96:99]
	v_mfma_f32_16x16x32_bf16 v[84:87], v[172:175], v[208:211], v[84:87]
	v_mfma_f32_16x16x32_bf16 v[80:83], v[180:183], v[208:211], v[80:83]
	v_mfma_f32_16x16x32_bf16 v[68:71], v[172:175], v[216:219], v[68:71]
	v_mfma_f32_16x16x32_bf16 v[64:67], v[180:183], v[216:219], v[64:67]
	v_mfma_f32_16x16x32_bf16 v[116:119], v[176:179], v[196:199], v[116:119]
	v_mfma_f32_16x16x32_bf16 v[112:115], v[184:187], v[196:199], v[112:115]
	v_mfma_f32_16x16x32_bf16 v[100:103], v[176:179], v[204:207], v[100:103]
	v_mfma_f32_16x16x32_bf16 v[96:99], v[184:187], v[204:207], v[96:99]
	v_mfma_f32_16x16x32_bf16 v[84:87], v[176:179], v[212:215], v[84:87]
	v_mfma_f32_16x16x32_bf16 v[80:83], v[184:187], v[212:215], v[80:83]
	v_mfma_f32_16x16x32_bf16 v[68:71], v[176:179], v[220:223], v[68:71]
	v_mfma_f32_16x16x32_bf16 v[64:67], v[184:187], v[220:223], v[64:67]
	s_setprio 0
	s_barrier
	s_add_i32 s61, s55, s44
	v_lshl_add_u64 v[150:151], s[36:37], 0, v[130:131]
	s_mov_b32 m0, s61
	ds_read_b128 v[188:191], v157 offset:16384
	ds_read_b128 v[196:199], v157 offset:17408
	ds_read_b128 v[200:203], v157 offset:18432
	ds_read_b128 v[204:207], v157 offset:19456
	ds_read_b128 v[208:211], v157 offset:20480
	ds_read_b128 v[212:215], v157 offset:21504
	ds_read_b128 v[216:219], v157 offset:22528
	ds_read_b128 v[220:223], v157 offset:23552
	global_load_lds_dwordx4 v[150:151], off
	s_add_i32 m0, s61, 0x2000
	s_add_u32 s62, s36, 0x40000
	v_lshl_add_u64 v[192:193], s[36:37], 0, v[134:135]
	s_addc_u32 s63, s37, 0
	s_add_i32 s61, s56, s44
	global_load_lds_dwordx4 v[192:193], off
	v_lshl_add_u64 v[224:225], s[62:63], 0, v[130:131]
	s_mov_b32 m0, s61
	v_lshl_add_u64 v[226:227], s[38:39], 0, v[132:133]
	global_load_lds_dwordx4 v[224:225], off
	v_lshl_add_u64 v[224:225], s[62:63], 0, v[134:135]
	s_add_i32 m0, s61, 0x2000
	s_nop 0
	global_load_lds_dwordx4 v[224:225], off
	v_lshl_add_u64 v[224:225], s[38:39], 0, v[128:129]
	s_waitcnt vmcnt(6)
	s_waitcnt lgkmcnt(0)
	s_barrier
	s_setprio 1
	s_waitcnt lgkmcnt(0)
	v_mfma_f32_16x16x32_bf16 v[60:63], v[146:149], v[188:191], v[60:63]
	v_mfma_f32_16x16x32_bf16 v[56:59], v[164:167], v[188:191], v[56:59]
	v_mfma_f32_16x16x32_bf16 v[44:47], v[146:149], v[200:203], v[44:47]
	v_mfma_f32_16x16x32_bf16 v[40:43], v[164:167], v[200:203], v[40:43]
	v_mfma_f32_16x16x32_bf16 v[28:31], v[146:149], v[208:211], v[28:31]
	v_mfma_f32_16x16x32_bf16 v[24:27], v[164:167], v[208:211], v[24:27]
	v_mfma_f32_16x16x32_bf16 v[12:15], v[146:149], v[216:219], v[12:15]
	v_mfma_f32_16x16x32_bf16 v[8:11], v[164:167], v[216:219], v[8:11]
	v_mfma_f32_16x16x32_bf16 v[60:63], v[160:163], v[196:199], v[60:63]
	v_mfma_f32_16x16x32_bf16 v[56:59], v[168:171], v[196:199], v[56:59]
	v_mfma_f32_16x16x32_bf16 v[44:47], v[160:163], v[204:207], v[44:47]
	v_mfma_f32_16x16x32_bf16 v[40:43], v[168:171], v[204:207], v[40:43]
	v_mfma_f32_16x16x32_bf16 v[28:31], v[160:163], v[212:215], v[28:31]
	v_mfma_f32_16x16x32_bf16 v[24:27], v[168:171], v[212:215], v[24:27]
	v_mfma_f32_16x16x32_bf16 v[12:15], v[160:163], v[220:223], v[12:15]
	v_mfma_f32_16x16x32_bf16 v[8:11], v[168:171], v[220:223], v[8:11]
	v_mfma_f32_16x16x32_bf16 v[52:55], v[172:175], v[188:191], v[52:55]
	v_mfma_f32_16x16x32_bf16 v[48:51], v[180:183], v[188:191], v[48:51]
	v_mfma_f32_16x16x32_bf16 v[36:39], v[172:175], v[200:203], v[36:39]
	v_mfma_f32_16x16x32_bf16 v[32:35], v[180:183], v[200:203], v[32:35]
	v_mfma_f32_16x16x32_bf16 v[20:23], v[172:175], v[208:211], v[20:23]
	v_mfma_f32_16x16x32_bf16 v[16:19], v[180:183], v[208:211], v[16:19]
	v_mfma_f32_16x16x32_bf16 v[4:7], v[172:175], v[216:219], v[4:7]
	v_mfma_f32_16x16x32_bf16 v[0:3], v[180:183], v[216:219], v[0:3]
	v_mfma_f32_16x16x32_bf16 v[52:55], v[176:179], v[196:199], v[52:55]
	v_mfma_f32_16x16x32_bf16 v[48:51], v[184:187], v[196:199], v[48:51]
	v_mfma_f32_16x16x32_bf16 v[36:39], v[176:179], v[204:207], v[36:39]
	v_mfma_f32_16x16x32_bf16 v[32:35], v[184:187], v[204:207], v[32:35]
	v_mfma_f32_16x16x32_bf16 v[20:23], v[176:179], v[212:215], v[20:23]
	v_mfma_f32_16x16x32_bf16 v[16:19], v[184:187], v[212:215], v[16:19]
	v_mfma_f32_16x16x32_bf16 v[4:7], v[176:179], v[220:223], v[4:7]
	v_mfma_f32_16x16x32_bf16 v[0:3], v[184:187], v[220:223], v[0:3]
	s_setprio 0
	s_barrier
	s_add_i32 s61, 0, 0x18000
	v_add_u32_e32 v159, s61, v153
	s_add_i32 s62, 0, 0x1c000
	ds_read_b128 v[146:149], v159
	ds_read_b128 v[160:163], v159 offset:1024
	ds_read_b128 v[164:167], v159 offset:2048
	ds_read_b128 v[168:171], v159 offset:3072
	v_add_u32_e32 v159, s62, v153
	ds_read_b128 v[172:175], v159
	ds_read_b128 v[176:179], v159 offset:1024
	ds_read_b128 v[180:183], v159 offset:2048
	ds_read_b128 v[184:187], v159 offset:3072
	s_add_u32 s38, s38, 0x40000
	s_addc_u32 s39, s39, 0
	v_lshl_add_u64 v[228:229], s[38:39], 0, v[128:129]
	ds_read_b128 v[188:191], v157 offset:32768
	ds_read_b128 v[196:199], v157 offset:33792
	ds_read_b128 v[200:203], v157 offset:34816
	ds_read_b128 v[204:207], v157 offset:35840
	ds_read_b128 v[208:211], v157 offset:36864
	ds_read_b128 v[212:215], v157 offset:37888
	ds_read_b128 v[216:219], v157 offset:38912
	ds_read_b128 v[220:223], v157 offset:39936
	s_mov_b32 m0, s35
	s_nop 0
	global_load_lds_dwordx4 v[224:225], off
	s_mov_b32 m0, s45
	s_nop 0
	global_load_lds_dwordx4 v[226:227], off
	s_mov_b32 m0, s48
	s_nop 0
	global_load_lds_dwordx4 v[228:229], off
	v_lshl_add_u64 v[228:229], s[38:39], 0, v[132:133]
	s_mov_b32 m0, s49
	s_nop 0
	global_load_lds_dwordx4 v[228:229], off
	s_waitcnt vmcnt(8)
	s_waitcnt lgkmcnt(0)
	s_barrier
	s_setprio 1
	s_waitcnt lgkmcnt(0)
	v_mfma_f32_16x16x32_bf16 v[124:127], v[146:149], v[188:191], v[124:127]
	v_mfma_f32_16x16x32_bf16 v[120:123], v[164:167], v[188:191], v[120:123]
	v_mfma_f32_16x16x32_bf16 v[108:111], v[146:149], v[200:203], v[108:111]
	v_mfma_f32_16x16x32_bf16 v[104:107], v[164:167], v[200:203], v[104:107]
	v_mfma_f32_16x16x32_bf16 v[92:95], v[146:149], v[208:211], v[92:95]
	v_mfma_f32_16x16x32_bf16 v[88:91], v[164:167], v[208:211], v[88:91]
	v_mfma_f32_16x16x32_bf16 v[76:79], v[146:149], v[216:219], v[76:79]
	v_mfma_f32_16x16x32_bf16 v[72:75], v[164:167], v[216:219], v[72:75]
	v_mfma_f32_16x16x32_bf16 v[124:127], v[160:163], v[196:199], v[124:127]
	v_mfma_f32_16x16x32_bf16 v[120:123], v[168:171], v[196:199], v[120:123]
	v_mfma_f32_16x16x32_bf16 v[108:111], v[160:163], v[204:207], v[108:111]
	v_mfma_f32_16x16x32_bf16 v[104:107], v[168:171], v[204:207], v[104:107]
	v_mfma_f32_16x16x32_bf16 v[92:95], v[160:163], v[212:215], v[92:95]
	v_mfma_f32_16x16x32_bf16 v[88:91], v[168:171], v[212:215], v[88:91]
	v_mfma_f32_16x16x32_bf16 v[76:79], v[160:163], v[220:223], v[76:79]
	v_mfma_f32_16x16x32_bf16 v[72:75], v[168:171], v[220:223], v[72:75]
	v_mfma_f32_16x16x32_bf16 v[116:119], v[172:175], v[188:191], v[116:119]
	v_mfma_f32_16x16x32_bf16 v[112:115], v[180:183], v[188:191], v[112:115]
	v_mfma_f32_16x16x32_bf16 v[100:103], v[172:175], v[200:203], v[100:103]
	v_mfma_f32_16x16x32_bf16 v[96:99], v[180:183], v[200:203], v[96:99]
	v_mfma_f32_16x16x32_bf16 v[84:87], v[172:175], v[208:211], v[84:87]
	v_mfma_f32_16x16x32_bf16 v[80:83], v[180:183], v[208:211], v[80:83]
	v_mfma_f32_16x16x32_bf16 v[68:71], v[172:175], v[216:219], v[68:71]
	v_mfma_f32_16x16x32_bf16 v[64:67], v[180:183], v[216:219], v[64:67]
	v_mfma_f32_16x16x32_bf16 v[116:119], v[176:179], v[196:199], v[116:119]
	v_mfma_f32_16x16x32_bf16 v[112:115], v[184:187], v[196:199], v[112:115]
	v_mfma_f32_16x16x32_bf16 v[100:103], v[176:179], v[204:207], v[100:103]
	v_mfma_f32_16x16x32_bf16 v[96:99], v[184:187], v[204:207], v[96:99]
	v_mfma_f32_16x16x32_bf16 v[84:87], v[176:179], v[212:215], v[84:87]
	v_mfma_f32_16x16x32_bf16 v[80:83], v[184:187], v[212:215], v[80:83]
	v_mfma_f32_16x16x32_bf16 v[68:71], v[176:179], v[220:223], v[68:71]
	v_mfma_f32_16x16x32_bf16 v[64:67], v[184:187], v[220:223], v[64:67]
	s_setprio 0
	s_barrier
	s_add_i32 s38, s61, s44
	v_lshl_add_u64 v[150:151], v[150:151], 0, s[16:17]
	s_mov_b32 m0, s38
	ds_read_b128 v[188:191], v157 offset:49152
	ds_read_b128 v[196:199], v157 offset:50176
	ds_read_b128 v[200:203], v157 offset:51200
	ds_read_b128 v[204:207], v157 offset:52224
	ds_read_b128 v[208:211], v157 offset:53248
	ds_read_b128 v[212:215], v157 offset:54272
	ds_read_b128 v[216:219], v157 offset:55296
	ds_read_b128 v[220:223], v157 offset:56320
	global_load_lds_dwordx4 v[150:151], off
	s_add_i32 m0, s38, 0x2000
	s_add_u32 s36, s36, 0x40080
	v_lshl_add_u64 v[150:151], v[192:193], 0, s[16:17]
	s_addc_u32 s37, s37, 0
	s_add_i32 s38, s62, s44
	global_load_lds_dwordx4 v[150:151], off
	v_lshl_add_u64 v[150:151], s[36:37], 0, v[130:131]
	s_mov_b32 m0, s38
	s_nop 0
	global_load_lds_dwordx4 v[150:151], off
	v_lshl_add_u64 v[150:151], s[36:37], 0, v[134:135]
	s_add_i32 m0, s38, 0x2000
	s_nop 0
	global_load_lds_dwordx4 v[150:151], off
	s_waitcnt vmcnt(6)
	s_waitcnt lgkmcnt(0)
	s_barrier
	s_setprio 1
	s_waitcnt lgkmcnt(0)
	v_mfma_f32_16x16x32_bf16 v[60:63], v[146:149], v[188:191], v[60:63]
	v_mfma_f32_16x16x32_bf16 v[56:59], v[164:167], v[188:191], v[56:59]
	v_mfma_f32_16x16x32_bf16 v[44:47], v[146:149], v[200:203], v[44:47]
	v_mfma_f32_16x16x32_bf16 v[40:43], v[164:167], v[200:203], v[40:43]
	v_mfma_f32_16x16x32_bf16 v[28:31], v[146:149], v[208:211], v[28:31]
	v_mfma_f32_16x16x32_bf16 v[24:27], v[164:167], v[208:211], v[24:27]
	v_mfma_f32_16x16x32_bf16 v[12:15], v[146:149], v[216:219], v[12:15]
	v_mfma_f32_16x16x32_bf16 v[8:11], v[164:167], v[216:219], v[8:11]
	v_mfma_f32_16x16x32_bf16 v[60:63], v[160:163], v[196:199], v[60:63]
	v_mfma_f32_16x16x32_bf16 v[56:59], v[168:171], v[196:199], v[56:59]
	v_mfma_f32_16x16x32_bf16 v[44:47], v[160:163], v[204:207], v[44:47]
	v_mfma_f32_16x16x32_bf16 v[40:43], v[168:171], v[204:207], v[40:43]
	v_mfma_f32_16x16x32_bf16 v[28:31], v[160:163], v[212:215], v[28:31]
	v_mfma_f32_16x16x32_bf16 v[24:27], v[168:171], v[212:215], v[24:27]
	v_mfma_f32_16x16x32_bf16 v[12:15], v[160:163], v[220:223], v[12:15]
	v_mfma_f32_16x16x32_bf16 v[8:11], v[168:171], v[220:223], v[8:11]
	v_mfma_f32_16x16x32_bf16 v[52:55], v[172:175], v[188:191], v[52:55]
	v_mfma_f32_16x16x32_bf16 v[48:51], v[180:183], v[188:191], v[48:51]
	v_mfma_f32_16x16x32_bf16 v[36:39], v[172:175], v[200:203], v[36:39]
	v_mfma_f32_16x16x32_bf16 v[32:35], v[180:183], v[200:203], v[32:35]
	v_mfma_f32_16x16x32_bf16 v[20:23], v[172:175], v[208:211], v[20:23]
	v_mfma_f32_16x16x32_bf16 v[16:19], v[180:183], v[208:211], v[16:19]
	v_mfma_f32_16x16x32_bf16 v[4:7], v[172:175], v[216:219], v[4:7]
	v_mfma_f32_16x16x32_bf16 v[0:3], v[180:183], v[216:219], v[0:3]
	v_mfma_f32_16x16x32_bf16 v[52:55], v[176:179], v[196:199], v[52:55]
	v_mfma_f32_16x16x32_bf16 v[48:51], v[184:187], v[196:199], v[48:51]
	v_mfma_f32_16x16x32_bf16 v[36:39], v[176:179], v[204:207], v[36:39]
	v_mfma_f32_16x16x32_bf16 v[32:35], v[184:187], v[204:207], v[32:35]
	v_mfma_f32_16x16x32_bf16 v[20:23], v[176:179], v[212:215], v[20:23]
	v_mfma_f32_16x16x32_bf16 v[16:19], v[184:187], v[212:215], v[16:19]
	v_mfma_f32_16x16x32_bf16 v[4:7], v[176:179], v[220:223], v[4:7]
	v_mfma_f32_16x16x32_bf16 v[0:3], v[184:187], v[220:223], v[0:3]
	s_setprio 0
	s_barrier
	v_lshl_add_u64 v[224:225], v[224:225], 0, s[16:17]
	s_mov_b32 m0, s50
	s_nop 0
	global_load_lds_dwordx4 v[224:225], off
	v_lshl_add_u64 v[226:227], v[226:227], 0, s[16:17]
	s_mov_b32 m0, s51
	s_nop 0
	global_load_lds_dwordx4 v[226:227], off
	s_add_i32 s60, s60, 2
	s_add_u32 s0, s0, 0x100
	s_addc_u32 s1, s1, 0
	s_add_u32 s25, s25, 0x100
	s_addc_u32 s59, s59, 0
	s_cmp_gt_u32 s60, 13
	s_cbranch_scc0 .LBB0_3031
	s_and_b64 vcc, exec, s[18:19]
	s_cbranch_vccz .LBB0_3034
	s_barrier

.LBB0_3061:
	ds_read_b128 v[144:147], v159
	ds_read_b128 v[148:151], v159 offset:1024
	ds_read_b128 v[152:155], v159 offset:2048
	ds_read_b128 v[162:165], v159 offset:3072
	ds_read_b128 v[166:169], v160
	ds_read_b128 v[170:173], v160 offset:1024
	ds_read_b128 v[174:177], v160 offset:2048
	ds_read_b128 v[178:181], v160 offset:3072
	s_add_u32 s37, s42, 0xfffe0080
	s_addc_u32 s39, s43, -1
	s_cmp_eq_u32 s35, 4
	s_cselect_b32 s51, s1, s39
	s_cselect_b32 s50, s0, s37
	s_cselect_b32 s49, s41, s13
	s_cselect_b32 s48, s40, s11
	v_lshl_add_u64 v[216:217], s[42:43], 0, v[136:137]
	s_add_i32 m0, s60, 0xc000
	ds_read_b128 v[182:185], v161
	ds_read_b128 v[186:189], v161 offset:1024
	ds_read_b128 v[190:193], v161 offset:2048
	ds_read_b128 v[196:199], v161 offset:3072
	ds_read_b128 v[200:203], v161 offset:4096
	ds_read_b128 v[204:207], v161 offset:5120
	ds_read_b128 v[208:211], v161 offset:6144
	ds_read_b128 v[212:215], v161 offset:7168
	global_load_lds_dwordx4 v[216:217], off
	v_lshl_add_u64 v[216:217], s[42:43], 0, v[138:139]
	s_add_i32 m0, s60, 0xe000
	s_nop 0
	global_load_lds_dwordx4 v[216:217], off
	s_waitcnt vmcnt(8)
	s_waitcnt lgkmcnt(0)
	s_barrier
	s_setprio 1
	s_waitcnt lgkmcnt(0)
	v_mfma_f32_16x16x32_bf16 v[124:127], v[144:147], v[182:185], v[124:127]
	v_mfma_f32_16x16x32_bf16 v[120:123], v[152:155], v[182:185], v[120:123]
	v_mfma_f32_16x16x32_bf16 v[108:111], v[144:147], v[190:193], v[108:111]
	v_mfma_f32_16x16x32_bf16 v[104:107], v[152:155], v[190:193], v[104:107]
	v_mfma_f32_16x16x32_bf16 v[92:95], v[144:147], v[200:203], v[92:95]
	v_mfma_f32_16x16x32_bf16 v[88:91], v[152:155], v[200:203], v[88:91]
	v_mfma_f32_16x16x32_bf16 v[76:79], v[144:147], v[208:211], v[76:79]
	v_mfma_f32_16x16x32_bf16 v[72:75], v[152:155], v[208:211], v[72:75]
	v_mfma_f32_16x16x32_bf16 v[124:127], v[148:151], v[186:189], v[124:127]
	v_mfma_f32_16x16x32_bf16 v[120:123], v[162:165], v[186:189], v[120:123]
	v_mfma_f32_16x16x32_bf16 v[108:111], v[148:151], v[196:199], v[108:111]
	v_mfma_f32_16x16x32_bf16 v[104:107], v[162:165], v[196:199], v[104:107]
	v_mfma_f32_16x16x32_bf16 v[92:95], v[148:151], v[204:207], v[92:95]
	v_mfma_f32_16x16x32_bf16 v[88:91], v[162:165], v[204:207], v[88:91]
	v_mfma_f32_16x16x32_bf16 v[76:79], v[148:151], v[212:215], v[76:79]
	v_mfma_f32_16x16x32_bf16 v[72:75], v[162:165], v[212:215], v[72:75]
	v_mfma_f32_16x16x32_bf16 v[116:119], v[166:169], v[182:185], v[116:119]
	v_mfma_f32_16x16x32_bf16 v[112:115], v[174:177], v[182:185], v[112:115]
	v_mfma_f32_16x16x32_bf16 v[100:103], v[166:169], v[190:193], v[100:103]
	v_mfma_f32_16x16x32_bf16 v[96:99], v[174:177], v[190:193], v[96:99]
	v_mfma_f32_16x16x32_bf16 v[84:87], v[166:169], v[200:203], v[84:87]
	v_mfma_f32_16x16x32_bf16 v[80:83], v[174:177], v[200:203], v[80:83]
	v_mfma_f32_16x16x32_bf16 v[68:71], v[166:169], v[208:211], v[68:71]
	v_mfma_f32_16x16x32_bf16 v[64:67], v[174:177], v[208:211], v[64:67]
	v_mfma_f32_16x16x32_bf16 v[116:119], v[170:173], v[186:189], v[116:119]
	v_mfma_f32_16x16x32_bf16 v[112:115], v[178:181], v[186:189], v[112:115]
	v_mfma_f32_16x16x32_bf16 v[100:103], v[170:173], v[196:199], v[100:103]
	v_mfma_f32_16x16x32_bf16 v[96:99], v[178:181], v[196:199], v[96:99]
	v_mfma_f32_16x16x32_bf16 v[84:87], v[170:173], v[204:207], v[84:87]
	v_mfma_f32_16x16x32_bf16 v[80:83], v[178:181], v[204:207], v[80:83]
	v_mfma_f32_16x16x32_bf16 v[68:71], v[170:173], v[212:215], v[68:71]
	v_mfma_f32_16x16x32_bf16 v[64:67], v[178:181], v[212:215], v[64:67]
	s_setprio 0
	s_barrier
	s_add_i32 s37, s73, s57
	v_lshl_add_u64 v[216:217], s[48:49], 0, v[130:131]
	s_mov_b32 m0, s37
	ds_read_b128 v[182:185], v161 offset:16384
	ds_read_b128 v[186:189], v161 offset:17408
	ds_read_b128 v[190:193], v161 offset:18432
	ds_read_b128 v[196:199], v161 offset:19456
	ds_read_b128 v[200:203], v161 offset:20480
	ds_read_b128 v[204:207], v161 offset:21504
	ds_read_b128 v[208:211], v161 offset:22528
	ds_read_b128 v[212:215], v161 offset:23552
	global_load_lds_dwordx4 v[216:217], off
	s_add_i32 m0, s37, 0x2000
	s_add_u32 s80, s48, 0x20000
	v_lshl_add_u64 v[218:219], s[48:49], 0, v[134:135]
	s_addc_u32 s81, s49, 0
	s_add_i32 s37, s77, s57
	global_load_lds_dwordx4 v[218:219], off
	v_lshl_add_u64 v[220:221], s[80:81], 0, v[130:131]
	s_mov_b32 m0, s37
	v_lshl_add_u64 v[222:223], s[50:51], 0, v[132:133]
	global_load_lds_dwordx4 v[220:221], off
	v_lshl_add_u64 v[220:221], s[80:81], 0, v[134:135]
	s_add_i32 m0, s37, 0x2000
	s_nop 0
	global_load_lds_dwordx4 v[220:221], off
	v_lshl_add_u64 v[220:221], s[50:51], 0, v[128:129]
	s_waitcnt vmcnt(6)
	s_waitcnt lgkmcnt(0)
	s_barrier
	s_setprio 1
	s_waitcnt lgkmcnt(0)
	v_mfma_f32_16x16x32_bf16 v[60:63], v[144:147], v[182:185], v[60:63]
	v_mfma_f32_16x16x32_bf16 v[56:59], v[152:155], v[182:185], v[56:59]
	v_mfma_f32_16x16x32_bf16 v[44:47], v[144:147], v[190:193], v[44:47]
	v_mfma_f32_16x16x32_bf16 v[40:43], v[152:155], v[190:193], v[40:43]
	v_mfma_f32_16x16x32_bf16 v[28:31], v[144:147], v[200:203], v[28:31]
	v_mfma_f32_16x16x32_bf16 v[24:27], v[152:155], v[200:203], v[24:27]
	v_mfma_f32_16x16x32_bf16 v[12:15], v[144:147], v[208:211], v[12:15]
	v_mfma_f32_16x16x32_bf16 v[8:11], v[152:155], v[208:211], v[8:11]
	v_mfma_f32_16x16x32_bf16 v[60:63], v[148:151], v[186:189], v[60:63]
	v_mfma_f32_16x16x32_bf16 v[56:59], v[162:165], v[186:189], v[56:59]
	v_mfma_f32_16x16x32_bf16 v[44:47], v[148:151], v[196:199], v[44:47]
	v_mfma_f32_16x16x32_bf16 v[40:43], v[162:165], v[196:199], v[40:43]
	v_mfma_f32_16x16x32_bf16 v[28:31], v[148:151], v[204:207], v[28:31]
	v_mfma_f32_16x16x32_bf16 v[24:27], v[162:165], v[204:207], v[24:27]
	v_mfma_f32_16x16x32_bf16 v[12:15], v[148:151], v[212:215], v[12:15]
	v_mfma_f32_16x16x32_bf16 v[8:11], v[162:165], v[212:215], v[8:11]
	v_mfma_f32_16x16x32_bf16 v[52:55], v[166:169], v[182:185], v[52:55]
	v_mfma_f32_16x16x32_bf16 v[48:51], v[174:177], v[182:185], v[48:51]
	v_mfma_f32_16x16x32_bf16 v[36:39], v[166:169], v[190:193], v[36:39]
	v_mfma_f32_16x16x32_bf16 v[32:35], v[174:177], v[190:193], v[32:35]
	v_mfma_f32_16x16x32_bf16 v[20:23], v[166:169], v[200:203], v[20:23]
	v_mfma_f32_16x16x32_bf16 v[16:19], v[174:177], v[200:203], v[16:19]
	v_mfma_f32_16x16x32_bf16 v[4:7], v[166:169], v[208:211], v[4:7]
	v_mfma_f32_16x16x32_bf16 v[0:3], v[174:177], v[208:211], v[0:3]
	v_mfma_f32_16x16x32_bf16 v[52:55], v[170:173], v[186:189], v[52:55]
	v_mfma_f32_16x16x32_bf16 v[48:51], v[178:181], v[186:189], v[48:51]
	v_mfma_f32_16x16x32_bf16 v[36:39], v[170:173], v[196:199], v[36:39]
	v_mfma_f32_16x16x32_bf16 v[32:35], v[178:181], v[196:199], v[32:35]
	v_mfma_f32_16x16x32_bf16 v[20:23], v[170:173], v[204:207], v[20:23]
	v_mfma_f32_16x16x32_bf16 v[16:19], v[178:181], v[204:207], v[16:19]
	v_mfma_f32_16x16x32_bf16 v[4:7], v[170:173], v[212:215], v[4:7]
	v_mfma_f32_16x16x32_bf16 v[0:3], v[178:181], v[212:215], v[0:3]
	s_setprio 0
	s_barrier
	s_add_i32 s37, 0, 0x18000
	s_add_i32 s39, 0, 0x1c000
	v_add_u32_e32 v162, s37, v157
	v_add_u32_e32 v178, s39, v157
	ds_read_b128 v[144:147], v162
	ds_read_b128 v[148:151], v162 offset:1024
	ds_read_b128 v[152:155], v162 offset:2048
	ds_read_b128 v[162:165], v162 offset:3072
	ds_read_b128 v[166:169], v178
	ds_read_b128 v[170:173], v178 offset:1024
	ds_read_b128 v[174:177], v178 offset:2048
	ds_read_b128 v[178:181], v178 offset:3072
	s_add_u32 s50, s50, 0x20000
	s_addc_u32 s51, s51, 0
	v_lshl_add_u64 v[224:225], s[50:51], 0, v[128:129]
	ds_read_b128 v[182:185], v161 offset:32768
	ds_read_b128 v[186:189], v161 offset:33792
	ds_read_b128 v[190:193], v161 offset:34816
	ds_read_b128 v[196:199], v161 offset:35840
	ds_read_b128 v[200:203], v161 offset:36864
	ds_read_b128 v[204:207], v161 offset:37888
	ds_read_b128 v[208:211], v161 offset:38912
	ds_read_b128 v[212:215], v161 offset:39936
	s_mov_b32 m0, s60
	s_nop 0
	global_load_lds_dwordx4 v[220:221], off
	s_mov_b32 m0, s61
	s_nop 0
	global_load_lds_dwordx4 v[222:223], off
	s_mov_b32 m0, s62
	s_nop 0
	global_load_lds_dwordx4 v[224:225], off
	v_lshl_add_u64 v[224:225], s[50:51], 0, v[132:133]
	s_mov_b32 m0, s63
	s_nop 0
	global_load_lds_dwordx4 v[224:225], off
	s_waitcnt vmcnt(8)
	s_waitcnt lgkmcnt(0)
	s_barrier
	s_setprio 1
	s_waitcnt lgkmcnt(0)
	v_mfma_f32_16x16x32_bf16 v[124:127], v[144:147], v[182:185], v[124:127]
	v_mfma_f32_16x16x32_bf16 v[120:123], v[152:155], v[182:185], v[120:123]
	v_mfma_f32_16x16x32_bf16 v[108:111], v[144:147], v[190:193], v[108:111]
	v_mfma_f32_16x16x32_bf16 v[104:107], v[152:155], v[190:193], v[104:107]
	v_mfma_f32_16x16x32_bf16 v[92:95], v[144:147], v[200:203], v[92:95]
	v_mfma_f32_16x16x32_bf16 v[88:91], v[152:155], v[200:203], v[88:91]
	v_mfma_f32_16x16x32_bf16 v[76:79], v[144:147], v[208:211], v[76:79]
	v_mfma_f32_16x16x32_bf16 v[72:75], v[152:155], v[208:211], v[72:75]
	v_mfma_f32_16x16x32_bf16 v[124:127], v[148:151], v[186:189], v[124:127]
	v_mfma_f32_16x16x32_bf16 v[120:123], v[162:165], v[186:189], v[120:123]
	v_mfma_f32_16x16x32_bf16 v[108:111], v[148:151], v[196:199], v[108:111]
	v_mfma_f32_16x16x32_bf16 v[104:107], v[162:165], v[196:199], v[104:107]
	v_mfma_f32_16x16x32_bf16 v[92:95], v[148:151], v[204:207], v[92:95]
	v_mfma_f32_16x16x32_bf16 v[88:91], v[162:165], v[204:207], v[88:91]
	v_mfma_f32_16x16x32_bf16 v[76:79], v[148:151], v[212:215], v[76:79]
	v_mfma_f32_16x16x32_bf16 v[72:75], v[162:165], v[212:215], v[72:75]
	v_mfma_f32_16x16x32_bf16 v[116:119], v[166:169], v[182:185], v[116:119]
	v_mfma_f32_16x16x32_bf16 v[112:115], v[174:177], v[182:185], v[112:115]
	v_mfma_f32_16x16x32_bf16 v[100:103], v[166:169], v[190:193], v[100:103]
	v_mfma_f32_16x16x32_bf16 v[96:99], v[174:177], v[190:193], v[96:99]
	v_mfma_f32_16x16x32_bf16 v[84:87], v[166:169], v[200:203], v[84:87]
	v_mfma_f32_16x16x32_bf16 v[80:83], v[174:177], v[200:203], v[80:83]
	v_mfma_f32_16x16x32_bf16 v[68:71], v[166:169], v[208:211], v[68:71]
	v_mfma_f32_16x16x32_bf16 v[64:67], v[174:177], v[208:211], v[64:67]
	v_mfma_f32_16x16x32_bf16 v[116:119], v[170:173], v[186:189], v[116:119]
	v_mfma_f32_16x16x32_bf16 v[112:115], v[178:181], v[186:189], v[112:115]
	v_mfma_f32_16x16x32_bf16 v[100:103], v[170:173], v[196:199], v[100:103]
	v_mfma_f32_16x16x32_bf16 v[96:99], v[178:181], v[196:199], v[96:99]
	v_mfma_f32_16x16x32_bf16 v[84:87], v[170:173], v[204:207], v[84:87]
	v_mfma_f32_16x16x32_bf16 v[80:83], v[178:181], v[204:207], v[80:83]
	v_mfma_f32_16x16x32_bf16 v[68:71], v[170:173], v[212:215], v[68:71]
	v_mfma_f32_16x16x32_bf16 v[64:67], v[178:181], v[212:215], v[64:67]
	s_setprio 0
	s_barrier
	s_add_i32 s37, s37, s57
	v_lshl_add_u64 v[216:217], v[216:217], 0, s[22:23]
	s_mov_b32 m0, s37
	ds_read_b128 v[182:185], v161 offset:49152
	ds_read_b128 v[186:189], v161 offset:50176
	ds_read_b128 v[190:193], v161 offset:51200
	ds_read_b128 v[196:199], v161 offset:52224
	ds_read_b128 v[200:203], v161 offset:53248
	ds_read_b128 v[204:207], v161 offset:54272
	ds_read_b128 v[208:211], v161 offset:55296
	ds_read_b128 v[212:215], v161 offset:56320
	global_load_lds_dwordx4 v[216:217], off
	s_add_i32 m0, s37, 0x2000
	s_add_u32 s48, s48, 0x20080
	v_lshl_add_u64 v[216:217], v[218:219], 0, s[22:23]
	s_addc_u32 s49, s49, 0
	s_add_i32 s37, s39, s57
	global_load_lds_dwordx4 v[216:217], off
	v_lshl_add_u64 v[216:217], s[48:49], 0, v[130:131]
	s_mov_b32 m0, s37
	s_nop 0
	global_load_lds_dwordx4 v[216:217], off
	v_lshl_add_u64 v[216:217], s[48:49], 0, v[134:135]
	s_add_i32 m0, s37, 0x2000
	s_nop 0
	global_load_lds_dwordx4 v[216:217], off
	s_waitcnt vmcnt(6)
	s_waitcnt lgkmcnt(0)
	s_barrier
	s_setprio 1
	s_waitcnt lgkmcnt(0)
	v_mfma_f32_16x16x32_bf16 v[60:63], v[144:147], v[182:185], v[60:63]
	v_mfma_f32_16x16x32_bf16 v[56:59], v[152:155], v[182:185], v[56:59]
	v_mfma_f32_16x16x32_bf16 v[44:47], v[144:147], v[190:193], v[44:47]
	v_mfma_f32_16x16x32_bf16 v[40:43], v[152:155], v[190:193], v[40:43]
	v_mfma_f32_16x16x32_bf16 v[28:31], v[144:147], v[200:203], v[28:31]
	v_mfma_f32_16x16x32_bf16 v[24:27], v[152:155], v[200:203], v[24:27]
	v_mfma_f32_16x16x32_bf16 v[12:15], v[144:147], v[208:211], v[12:15]
	v_mfma_f32_16x16x32_bf16 v[8:11], v[152:155], v[208:211], v[8:11]
	v_mfma_f32_16x16x32_bf16 v[60:63], v[148:151], v[186:189], v[60:63]
	v_mfma_f32_16x16x32_bf16 v[56:59], v[162:165], v[186:189], v[56:59]
	v_mfma_f32_16x16x32_bf16 v[44:47], v[148:151], v[196:199], v[44:47]
	v_mfma_f32_16x16x32_bf16 v[40:43], v[162:165], v[196:199], v[40:43]
	v_mfma_f32_16x16x32_bf16 v[28:31], v[148:151], v[204:207], v[28:31]
	v_mfma_f32_16x16x32_bf16 v[24:27], v[162:165], v[204:207], v[24:27]
	v_mfma_f32_16x16x32_bf16 v[12:15], v[148:151], v[212:215], v[12:15]
	v_mfma_f32_16x16x32_bf16 v[8:11], v[162:165], v[212:215], v[8:11]
	v_mfma_f32_16x16x32_bf16 v[52:55], v[166:169], v[182:185], v[52:55]
	v_mfma_f32_16x16x32_bf16 v[48:51], v[174:177], v[182:185], v[48:51]
	v_mfma_f32_16x16x32_bf16 v[36:39], v[166:169], v[190:193], v[36:39]
	v_mfma_f32_16x16x32_bf16 v[32:35], v[174:177], v[190:193], v[32:35]
	v_mfma_f32_16x16x32_bf16 v[20:23], v[166:169], v[200:203], v[20:23]
	v_mfma_f32_16x16x32_bf16 v[16:19], v[174:177], v[200:203], v[16:19]
	v_mfma_f32_16x16x32_bf16 v[4:7], v[166:169], v[208:211], v[4:7]
	v_mfma_f32_16x16x32_bf16 v[0:3], v[174:177], v[208:211], v[0:3]
	v_mfma_f32_16x16x32_bf16 v[52:55], v[170:173], v[186:189], v[52:55]
	v_mfma_f32_16x16x32_bf16 v[48:51], v[178:181], v[186:189], v[48:51]
	v_mfma_f32_16x16x32_bf16 v[36:39], v[170:173], v[196:199], v[36:39]
	v_mfma_f32_16x16x32_bf16 v[32:35], v[178:181], v[196:199], v[32:35]
	v_mfma_f32_16x16x32_bf16 v[20:23], v[170:173], v[204:207], v[20:23]
	v_mfma_f32_16x16x32_bf16 v[16:19], v[178:181], v[204:207], v[16:19]
	v_mfma_f32_16x16x32_bf16 v[4:7], v[170:173], v[212:215], v[4:7]
	v_mfma_f32_16x16x32_bf16 v[0:3], v[178:181], v[212:215], v[0:3]
	s_setprio 0
	s_barrier
	v_lshl_add_u64 v[220:221], v[220:221], 0, s[22:23]
	s_mov_b32 m0, s70
	s_nop 0
	global_load_lds_dwordx4 v[220:221], off
	v_lshl_add_u64 v[222:223], v[222:223], 0, s[22:23]
	s_mov_b32 m0, s71
	s_nop 0
	global_load_lds_dwordx4 v[222:223], off
	s_add_i32 s35, s35, 2
	s_add_u32 s42, s42, 0x100
	s_addc_u32 s43, s43, 0
	s_add_u32 s11, s11, 0x100
	s_addc_u32 s13, s13, 0
	s_cmp_gt_u32 s35, 5
	s_cbranch_scc0 .LBB0_3061
	s_and_b64 vcc, exec, s[24:25]
	s_cbranch_vccz .LBB0_3064
	s_barrier

.LBB0_3235:
	ds_read_b128 v[144:147], v151
	ds_read_b128 v[156:159], v151 offset:1024
	ds_read_b128 v[160:163], v151 offset:2048
	ds_read_b128 v[164:167], v151 offset:3072
	ds_read_b128 v[168:171], v152
	ds_read_b128 v[172:175], v152 offset:1024
	ds_read_b128 v[176:179], v152 offset:2048
	ds_read_b128 v[180:183], v152 offset:3072
	s_add_u32 s38, s36, 0xfffc0080
	s_addc_u32 s39, s37, -1
	s_cmp_eq_u32 s70, 12
	s_cselect_b32 s41, s27, s39
	s_cselect_b32 s40, s35, s38
	s_cselect_b32 s39, s25, s63
	s_cselect_b32 s38, s61, s62
	v_lshl_add_u64 v[192:193], s[36:37], 0, v[136:137]
	s_add_i32 m0, s50, 0xc000
	ds_read_b128 v[184:187], v153
	ds_read_b128 v[188:191], v153 offset:1024
	ds_read_b128 v[196:199], v153 offset:2048
	ds_read_b128 v[200:203], v153 offset:3072
	ds_read_b128 v[204:207], v153 offset:4096
	ds_read_b128 v[208:211], v153 offset:5120
	ds_read_b128 v[212:215], v153 offset:6144
	ds_read_b128 v[216:219], v153 offset:7168
	global_load_lds_dwordx4 v[192:193], off
	v_lshl_add_u64 v[192:193], s[36:37], 0, v[138:139]
	s_add_i32 m0, s50, 0xe000
	s_nop 0
	global_load_lds_dwordx4 v[192:193], off
	s_waitcnt vmcnt(8)
	s_waitcnt lgkmcnt(0)
	s_barrier
	s_setprio 1
	s_waitcnt lgkmcnt(0)
	v_mfma_f32_16x16x32_bf16 v[124:127], v[144:147], v[184:187], v[124:127]
	v_mfma_f32_16x16x32_bf16 v[120:123], v[160:163], v[184:187], v[120:123]
	v_mfma_f32_16x16x32_bf16 v[108:111], v[144:147], v[196:199], v[108:111]
	v_mfma_f32_16x16x32_bf16 v[104:107], v[160:163], v[196:199], v[104:107]
	v_mfma_f32_16x16x32_bf16 v[92:95], v[144:147], v[204:207], v[92:95]
	v_mfma_f32_16x16x32_bf16 v[88:91], v[160:163], v[204:207], v[88:91]
	v_mfma_f32_16x16x32_bf16 v[76:79], v[144:147], v[212:215], v[76:79]
	v_mfma_f32_16x16x32_bf16 v[72:75], v[160:163], v[212:215], v[72:75]
	v_mfma_f32_16x16x32_bf16 v[124:127], v[156:159], v[188:191], v[124:127]
	v_mfma_f32_16x16x32_bf16 v[120:123], v[164:167], v[188:191], v[120:123]
	v_mfma_f32_16x16x32_bf16 v[108:111], v[156:159], v[200:203], v[108:111]
	v_mfma_f32_16x16x32_bf16 v[104:107], v[164:167], v[200:203], v[104:107]
	v_mfma_f32_16x16x32_bf16 v[92:95], v[156:159], v[208:211], v[92:95]
	v_mfma_f32_16x16x32_bf16 v[88:91], v[164:167], v[208:211], v[88:91]
	v_mfma_f32_16x16x32_bf16 v[76:79], v[156:159], v[216:219], v[76:79]
	v_mfma_f32_16x16x32_bf16 v[72:75], v[164:167], v[216:219], v[72:75]
	v_mfma_f32_16x16x32_bf16 v[116:119], v[168:171], v[184:187], v[116:119]
	v_mfma_f32_16x16x32_bf16 v[112:115], v[176:179], v[184:187], v[112:115]
	v_mfma_f32_16x16x32_bf16 v[100:103], v[168:171], v[196:199], v[100:103]
	v_mfma_f32_16x16x32_bf16 v[96:99], v[176:179], v[196:199], v[96:99]
	v_mfma_f32_16x16x32_bf16 v[84:87], v[168:171], v[204:207], v[84:87]
	v_mfma_f32_16x16x32_bf16 v[80:83], v[176:179], v[204:207], v[80:83]
	v_mfma_f32_16x16x32_bf16 v[68:71], v[168:171], v[212:215], v[68:71]
	v_mfma_f32_16x16x32_bf16 v[64:67], v[176:179], v[212:215], v[64:67]
	v_mfma_f32_16x16x32_bf16 v[116:119], v[172:175], v[188:191], v[116:119]
	v_mfma_f32_16x16x32_bf16 v[112:115], v[180:183], v[188:191], v[112:115]
	v_mfma_f32_16x16x32_bf16 v[100:103], v[172:175], v[200:203], v[100:103]
	v_mfma_f32_16x16x32_bf16 v[96:99], v[180:183], v[200:203], v[96:99]
	v_mfma_f32_16x16x32_bf16 v[84:87], v[172:175], v[208:211], v[84:87]
	v_mfma_f32_16x16x32_bf16 v[80:83], v[180:183], v[208:211], v[80:83]
	v_mfma_f32_16x16x32_bf16 v[68:71], v[172:175], v[216:219], v[68:71]
	v_mfma_f32_16x16x32_bf16 v[64:67], v[180:183], v[216:219], v[64:67]
	s_setprio 0
	s_barrier
	s_add_i32 s71, s58, s49
	v_lshl_add_u64 v[192:193], s[38:39], 0, v[130:131]
	s_mov_b32 m0, s71
	ds_read_b128 v[184:187], v153 offset:16384
	ds_read_b128 v[188:191], v153 offset:17408
	ds_read_b128 v[196:199], v153 offset:18432
	ds_read_b128 v[200:203], v153 offset:19456
	ds_read_b128 v[204:207], v153 offset:20480
	ds_read_b128 v[208:211], v153 offset:21504
	ds_read_b128 v[212:215], v153 offset:22528
	ds_read_b128 v[216:219], v153 offset:23552
	global_load_lds_dwordx4 v[192:193], off
	s_add_i32 m0, s71, 0x2000
	s_add_u32 s72, s38, 0x40000
	v_lshl_add_u64 v[220:221], s[38:39], 0, v[134:135]
	s_addc_u32 s73, s39, 0
	s_add_i32 s71, s59, s49
	global_load_lds_dwordx4 v[220:221], off
	v_lshl_add_u64 v[222:223], s[72:73], 0, v[130:131]
	s_mov_b32 m0, s71
	v_lshl_add_u64 v[224:225], s[40:41], 0, v[132:133]
	global_load_lds_dwordx4 v[222:223], off
	v_lshl_add_u64 v[222:223], s[72:73], 0, v[134:135]
	s_add_i32 m0, s71, 0x2000
	s_nop 0
	global_load_lds_dwordx4 v[222:223], off
	v_lshl_add_u64 v[222:223], s[40:41], 0, v[128:129]
	s_waitcnt vmcnt(6)
	s_waitcnt lgkmcnt(0)
	s_barrier
	s_setprio 1
	s_waitcnt lgkmcnt(0)
	v_mfma_f32_16x16x32_bf16 v[60:63], v[144:147], v[184:187], v[60:63]
	v_mfma_f32_16x16x32_bf16 v[56:59], v[160:163], v[184:187], v[56:59]
	v_mfma_f32_16x16x32_bf16 v[44:47], v[144:147], v[196:199], v[44:47]
	v_mfma_f32_16x16x32_bf16 v[40:43], v[160:163], v[196:199], v[40:43]
	v_mfma_f32_16x16x32_bf16 v[28:31], v[144:147], v[204:207], v[28:31]
	v_mfma_f32_16x16x32_bf16 v[24:27], v[160:163], v[204:207], v[24:27]
	v_mfma_f32_16x16x32_bf16 v[12:15], v[144:147], v[212:215], v[12:15]
	v_mfma_f32_16x16x32_bf16 v[8:11], v[160:163], v[212:215], v[8:11]
	v_mfma_f32_16x16x32_bf16 v[60:63], v[156:159], v[188:191], v[60:63]
	v_mfma_f32_16x16x32_bf16 v[56:59], v[164:167], v[188:191], v[56:59]
	v_mfma_f32_16x16x32_bf16 v[44:47], v[156:159], v[200:203], v[44:47]
	v_mfma_f32_16x16x32_bf16 v[40:43], v[164:167], v[200:203], v[40:43]
	v_mfma_f32_16x16x32_bf16 v[28:31], v[156:159], v[208:211], v[28:31]
	v_mfma_f32_16x16x32_bf16 v[24:27], v[164:167], v[208:211], v[24:27]
	v_mfma_f32_16x16x32_bf16 v[12:15], v[156:159], v[216:219], v[12:15]
	v_mfma_f32_16x16x32_bf16 v[8:11], v[164:167], v[216:219], v[8:11]
	v_mfma_f32_16x16x32_bf16 v[52:55], v[168:171], v[184:187], v[52:55]
	v_mfma_f32_16x16x32_bf16 v[48:51], v[176:179], v[184:187], v[48:51]
	v_mfma_f32_16x16x32_bf16 v[36:39], v[168:171], v[196:199], v[36:39]
	v_mfma_f32_16x16x32_bf16 v[32:35], v[176:179], v[196:199], v[32:35]
	v_mfma_f32_16x16x32_bf16 v[20:23], v[168:171], v[204:207], v[20:23]
	v_mfma_f32_16x16x32_bf16 v[16:19], v[176:179], v[204:207], v[16:19]
	v_mfma_f32_16x16x32_bf16 v[4:7], v[168:171], v[212:215], v[4:7]
	v_mfma_f32_16x16x32_bf16 v[0:3], v[176:179], v[212:215], v[0:3]
	v_mfma_f32_16x16x32_bf16 v[52:55], v[172:175], v[188:191], v[52:55]
	v_mfma_f32_16x16x32_bf16 v[48:51], v[180:183], v[188:191], v[48:51]
	v_mfma_f32_16x16x32_bf16 v[36:39], v[172:175], v[200:203], v[36:39]
	v_mfma_f32_16x16x32_bf16 v[32:35], v[180:183], v[200:203], v[32:35]
	v_mfma_f32_16x16x32_bf16 v[20:23], v[172:175], v[208:211], v[20:23]
	v_mfma_f32_16x16x32_bf16 v[16:19], v[180:183], v[208:211], v[16:19]
	v_mfma_f32_16x16x32_bf16 v[4:7], v[172:175], v[216:219], v[4:7]
	v_mfma_f32_16x16x32_bf16 v[0:3], v[180:183], v[216:219], v[0:3]
	s_setprio 0
	s_barrier
	s_add_i32 s71, 0, 0x18000
	v_add_u32_e32 v155, s71, v149
	s_add_i32 s72, 0, 0x1c000
	ds_read_b128 v[144:147], v155
	ds_read_b128 v[156:159], v155 offset:1024
	ds_read_b128 v[160:163], v155 offset:2048
	ds_read_b128 v[164:167], v155 offset:3072
	v_add_u32_e32 v155, s72, v149
	ds_read_b128 v[168:171], v155
	ds_read_b128 v[172:175], v155 offset:1024
	ds_read_b128 v[176:179], v155 offset:2048
	ds_read_b128 v[180:183], v155 offset:3072
	s_add_u32 s40, s40, 0x40000
	s_addc_u32 s41, s41, 0
	v_lshl_add_u64 v[226:227], s[40:41], 0, v[128:129]
	ds_read_b128 v[184:187], v153 offset:32768
	ds_read_b128 v[188:191], v153 offset:33792
	ds_read_b128 v[196:199], v153 offset:34816
	ds_read_b128 v[200:203], v153 offset:35840
	ds_read_b128 v[204:207], v153 offset:36864
	ds_read_b128 v[208:211], v153 offset:37888
	ds_read_b128 v[212:215], v153 offset:38912
	ds_read_b128 v[216:219], v153 offset:39936
	s_mov_b32 m0, s50
	s_nop 0
	global_load_lds_dwordx4 v[222:223], off
	s_mov_b32 m0, s51
	s_nop 0
	global_load_lds_dwordx4 v[224:225], off
	s_mov_b32 m0, s52
	s_nop 0
	global_load_lds_dwordx4 v[226:227], off
	v_lshl_add_u64 v[226:227], s[40:41], 0, v[132:133]
	s_mov_b32 m0, s53
	s_nop 0
	global_load_lds_dwordx4 v[226:227], off
	s_waitcnt vmcnt(8)
	s_waitcnt lgkmcnt(0)
	s_barrier
	s_setprio 1
	s_waitcnt lgkmcnt(0)
	v_mfma_f32_16x16x32_bf16 v[124:127], v[144:147], v[184:187], v[124:127]
	v_mfma_f32_16x16x32_bf16 v[120:123], v[160:163], v[184:187], v[120:123]
	v_mfma_f32_16x16x32_bf16 v[108:111], v[144:147], v[196:199], v[108:111]
	v_mfma_f32_16x16x32_bf16 v[104:107], v[160:163], v[196:199], v[104:107]
	v_mfma_f32_16x16x32_bf16 v[92:95], v[144:147], v[204:207], v[92:95]
	v_mfma_f32_16x16x32_bf16 v[88:91], v[160:163], v[204:207], v[88:91]
	v_mfma_f32_16x16x32_bf16 v[76:79], v[144:147], v[212:215], v[76:79]
	v_mfma_f32_16x16x32_bf16 v[72:75], v[160:163], v[212:215], v[72:75]
	v_mfma_f32_16x16x32_bf16 v[124:127], v[156:159], v[188:191], v[124:127]
	v_mfma_f32_16x16x32_bf16 v[120:123], v[164:167], v[188:191], v[120:123]
	v_mfma_f32_16x16x32_bf16 v[108:111], v[156:159], v[200:203], v[108:111]
	v_mfma_f32_16x16x32_bf16 v[104:107], v[164:167], v[200:203], v[104:107]
	v_mfma_f32_16x16x32_bf16 v[92:95], v[156:159], v[208:211], v[92:95]
	v_mfma_f32_16x16x32_bf16 v[88:91], v[164:167], v[208:211], v[88:91]
	v_mfma_f32_16x16x32_bf16 v[76:79], v[156:159], v[216:219], v[76:79]
	v_mfma_f32_16x16x32_bf16 v[72:75], v[164:167], v[216:219], v[72:75]
	v_mfma_f32_16x16x32_bf16 v[116:119], v[168:171], v[184:187], v[116:119]
	v_mfma_f32_16x16x32_bf16 v[112:115], v[176:179], v[184:187], v[112:115]
	v_mfma_f32_16x16x32_bf16 v[100:103], v[168:171], v[196:199], v[100:103]
	v_mfma_f32_16x16x32_bf16 v[96:99], v[176:179], v[196:199], v[96:99]
	v_mfma_f32_16x16x32_bf16 v[84:87], v[168:171], v[204:207], v[84:87]
	v_mfma_f32_16x16x32_bf16 v[80:83], v[176:179], v[204:207], v[80:83]
	v_mfma_f32_16x16x32_bf16 v[68:71], v[168:171], v[212:215], v[68:71]
	v_mfma_f32_16x16x32_bf16 v[64:67], v[176:179], v[212:215], v[64:67]
	v_mfma_f32_16x16x32_bf16 v[116:119], v[172:175], v[188:191], v[116:119]
	v_mfma_f32_16x16x32_bf16 v[112:115], v[180:183], v[188:191], v[112:115]
	v_mfma_f32_16x16x32_bf16 v[100:103], v[172:175], v[200:203], v[100:103]
	v_mfma_f32_16x16x32_bf16 v[96:99], v[180:183], v[200:203], v[96:99]
	v_mfma_f32_16x16x32_bf16 v[84:87], v[172:175], v[208:211], v[84:87]
	v_mfma_f32_16x16x32_bf16 v[80:83], v[180:183], v[208:211], v[80:83]
	v_mfma_f32_16x16x32_bf16 v[68:71], v[172:175], v[216:219], v[68:71]
	v_mfma_f32_16x16x32_bf16 v[64:67], v[180:183], v[216:219], v[64:67]
	s_setprio 0
	s_barrier
	s_add_i32 s40, s71, s49
	v_lshl_add_u64 v[192:193], v[192:193], 0, s[20:21]
	s_mov_b32 m0, s40
	ds_read_b128 v[184:187], v153 offset:49152
	ds_read_b128 v[188:191], v153 offset:50176
	ds_read_b128 v[196:199], v153 offset:51200
	ds_read_b128 v[200:203], v153 offset:52224
	ds_read_b128 v[204:207], v153 offset:53248
	ds_read_b128 v[208:211], v153 offset:54272
	ds_read_b128 v[212:215], v153 offset:55296
	ds_read_b128 v[216:219], v153 offset:56320
	global_load_lds_dwordx4 v[192:193], off
	s_add_i32 m0, s40, 0x2000
	s_add_u32 s38, s38, 0x40080
	v_lshl_add_u64 v[192:193], v[220:221], 0, s[20:21]
	s_addc_u32 s39, s39, 0
	s_add_i32 s40, s72, s49
	global_load_lds_dwordx4 v[192:193], off
	v_lshl_add_u64 v[192:193], s[38:39], 0, v[130:131]
	s_mov_b32 m0, s40
	s_nop 0
	global_load_lds_dwordx4 v[192:193], off
	v_lshl_add_u64 v[192:193], s[38:39], 0, v[134:135]
	s_add_i32 m0, s40, 0x2000
	s_nop 0
	global_load_lds_dwordx4 v[192:193], off
	s_waitcnt vmcnt(6)
	s_waitcnt lgkmcnt(0)
	s_barrier
	s_setprio 1
	s_waitcnt lgkmcnt(0)
	v_mfma_f32_16x16x32_bf16 v[60:63], v[144:147], v[184:187], v[60:63]
	v_mfma_f32_16x16x32_bf16 v[56:59], v[160:163], v[184:187], v[56:59]
	v_mfma_f32_16x16x32_bf16 v[44:47], v[144:147], v[196:199], v[44:47]
	v_mfma_f32_16x16x32_bf16 v[40:43], v[160:163], v[196:199], v[40:43]
	v_mfma_f32_16x16x32_bf16 v[28:31], v[144:147], v[204:207], v[28:31]
	v_mfma_f32_16x16x32_bf16 v[24:27], v[160:163], v[204:207], v[24:27]
	v_mfma_f32_16x16x32_bf16 v[12:15], v[144:147], v[212:215], v[12:15]
	v_mfma_f32_16x16x32_bf16 v[8:11], v[160:163], v[212:215], v[8:11]
	v_mfma_f32_16x16x32_bf16 v[60:63], v[156:159], v[188:191], v[60:63]
	v_mfma_f32_16x16x32_bf16 v[56:59], v[164:167], v[188:191], v[56:59]
	v_mfma_f32_16x16x32_bf16 v[44:47], v[156:159], v[200:203], v[44:47]
	v_mfma_f32_16x16x32_bf16 v[40:43], v[164:167], v[200:203], v[40:43]
	v_mfma_f32_16x16x32_bf16 v[28:31], v[156:159], v[208:211], v[28:31]
	v_mfma_f32_16x16x32_bf16 v[24:27], v[164:167], v[208:211], v[24:27]
	v_mfma_f32_16x16x32_bf16 v[12:15], v[156:159], v[216:219], v[12:15]
	v_mfma_f32_16x16x32_bf16 v[8:11], v[164:167], v[216:219], v[8:11]
	v_mfma_f32_16x16x32_bf16 v[52:55], v[168:171], v[184:187], v[52:55]
	v_mfma_f32_16x16x32_bf16 v[48:51], v[176:179], v[184:187], v[48:51]
	v_mfma_f32_16x16x32_bf16 v[36:39], v[168:171], v[196:199], v[36:39]
	v_mfma_f32_16x16x32_bf16 v[32:35], v[176:179], v[196:199], v[32:35]
	v_mfma_f32_16x16x32_bf16 v[20:23], v[168:171], v[204:207], v[20:23]
	v_mfma_f32_16x16x32_bf16 v[16:19], v[176:179], v[204:207], v[16:19]
	v_mfma_f32_16x16x32_bf16 v[4:7], v[168:171], v[212:215], v[4:7]
	v_mfma_f32_16x16x32_bf16 v[0:3], v[176:179], v[212:215], v[0:3]
	v_mfma_f32_16x16x32_bf16 v[52:55], v[172:175], v[188:191], v[52:55]
	v_mfma_f32_16x16x32_bf16 v[48:51], v[180:183], v[188:191], v[48:51]
	v_mfma_f32_16x16x32_bf16 v[36:39], v[172:175], v[200:203], v[36:39]
	v_mfma_f32_16x16x32_bf16 v[32:35], v[180:183], v[200:203], v[32:35]
	v_mfma_f32_16x16x32_bf16 v[20:23], v[172:175], v[208:211], v[20:23]
	v_mfma_f32_16x16x32_bf16 v[16:19], v[180:183], v[208:211], v[16:19]
	v_mfma_f32_16x16x32_bf16 v[4:7], v[172:175], v[216:219], v[4:7]
	v_mfma_f32_16x16x32_bf16 v[0:3], v[180:183], v[216:219], v[0:3]
	s_setprio 0
	s_barrier
	v_lshl_add_u64 v[222:223], v[222:223], 0, s[20:21]
	s_mov_b32 m0, s55
	s_nop 0
	global_load_lds_dwordx4 v[222:223], off
	v_lshl_add_u64 v[224:225], v[224:225], 0, s[20:21]
	s_mov_b32 m0, s56
	s_nop 0
	global_load_lds_dwordx4 v[224:225], off
	s_add_i32 s70, s70, 2
	s_add_u32 s36, s36, 0x100
	s_addc_u32 s37, s37, 0
	s_add_u32 s62, s62, 0x100
	s_addc_u32 s63, s63, 0
	s_cmp_gt_u32 s70, 13
	s_cbranch_scc0 .LBB0_3235
	s_and_b64 vcc, exec, s[22:23]
	s_cbranch_vccz .LBB0_3238
	s_barrier

.LBB0_3319:
	ds_read_b128 v[154:157], v149
	ds_read_b128 v[158:161], v149 offset:1024
	ds_read_b128 v[162:165], v149 offset:2048
	ds_read_b128 v[166:169], v149 offset:3072
	ds_read_b128 v[170:173], v150
	ds_read_b128 v[174:177], v150 offset:1024
	ds_read_b128 v[178:181], v150 offset:2048
	ds_read_b128 v[182:185], v150 offset:3072
	s_add_u32 s28, s26, 0xfffc0080
	s_addc_u32 s29, s27, -1
	s_cmp_eq_u32 s59, 12
	s_cselect_b32 s31, s19, s29
	s_cselect_b32 s30, s55, s28
	s_cselect_b32 s29, s17, s58
	s_cselect_b32 s28, s56, s57
	v_lshl_add_u64 v[144:145], s[26:27], 0, v[136:137]
	s_add_i32 m0, s25, 0xc000
	ds_read_b128 v[186:189], v151
	ds_read_b128 v[190:193], v151 offset:1024
	ds_read_b128 v[196:199], v151 offset:2048
	ds_read_b128 v[200:203], v151 offset:3072
	ds_read_b128 v[204:207], v151 offset:4096
	ds_read_b128 v[208:211], v151 offset:5120
	ds_read_b128 v[212:215], v151 offset:6144
	ds_read_b128 v[216:219], v151 offset:7168
	global_load_lds_dwordx4 v[144:145], off
	v_lshl_add_u64 v[144:145], s[26:27], 0, v[138:139]
	s_add_i32 m0, s25, 0xe000
	s_nop 0
	global_load_lds_dwordx4 v[144:145], off
	s_waitcnt vmcnt(8)
	s_waitcnt lgkmcnt(0)
	s_barrier
	s_setprio 1
	s_waitcnt lgkmcnt(0)
	v_mfma_f32_16x16x32_bf16 v[116:119], v[154:157], v[186:189], v[116:119]
	v_mfma_f32_16x16x32_bf16 v[112:115], v[162:165], v[186:189], v[112:115]
	v_mfma_f32_16x16x32_bf16 v[100:103], v[154:157], v[196:199], v[100:103]
	v_mfma_f32_16x16x32_bf16 v[96:99], v[162:165], v[196:199], v[96:99]
	v_mfma_f32_16x16x32_bf16 v[84:87], v[154:157], v[204:207], v[84:87]
	v_mfma_f32_16x16x32_bf16 v[80:83], v[162:165], v[204:207], v[80:83]
	v_mfma_f32_16x16x32_bf16 v[68:71], v[154:157], v[212:215], v[68:71]
	v_mfma_f32_16x16x32_bf16 v[64:67], v[162:165], v[212:215], v[64:67]
	v_mfma_f32_16x16x32_bf16 v[116:119], v[158:161], v[190:193], v[116:119]
	v_mfma_f32_16x16x32_bf16 v[112:115], v[166:169], v[190:193], v[112:115]
	v_mfma_f32_16x16x32_bf16 v[100:103], v[158:161], v[200:203], v[100:103]
	v_mfma_f32_16x16x32_bf16 v[96:99], v[166:169], v[200:203], v[96:99]
	v_mfma_f32_16x16x32_bf16 v[84:87], v[158:161], v[208:211], v[84:87]
	v_mfma_f32_16x16x32_bf16 v[80:83], v[166:169], v[208:211], v[80:83]
	v_mfma_f32_16x16x32_bf16 v[68:71], v[158:161], v[216:219], v[68:71]
	v_mfma_f32_16x16x32_bf16 v[64:67], v[166:169], v[216:219], v[64:67]
	v_mfma_f32_16x16x32_bf16 v[124:127], v[170:173], v[186:189], v[124:127]
	v_mfma_f32_16x16x32_bf16 v[120:123], v[178:181], v[186:189], v[120:123]
	v_mfma_f32_16x16x32_bf16 v[108:111], v[170:173], v[196:199], v[108:111]
	v_mfma_f32_16x16x32_bf16 v[104:107], v[178:181], v[196:199], v[104:107]
	v_mfma_f32_16x16x32_bf16 v[92:95], v[170:173], v[204:207], v[92:95]
	v_mfma_f32_16x16x32_bf16 v[88:91], v[178:181], v[204:207], v[88:91]
	v_mfma_f32_16x16x32_bf16 v[76:79], v[170:173], v[212:215], v[76:79]
	v_mfma_f32_16x16x32_bf16 v[72:75], v[178:181], v[212:215], v[72:75]
	v_mfma_f32_16x16x32_bf16 v[124:127], v[174:177], v[190:193], v[124:127]
	v_mfma_f32_16x16x32_bf16 v[120:123], v[182:185], v[190:193], v[120:123]
	v_mfma_f32_16x16x32_bf16 v[108:111], v[174:177], v[200:203], v[108:111]
	v_mfma_f32_16x16x32_bf16 v[104:107], v[182:185], v[200:203], v[104:107]
	v_mfma_f32_16x16x32_bf16 v[92:95], v[174:177], v[208:211], v[92:95]
	v_mfma_f32_16x16x32_bf16 v[88:91], v[182:185], v[208:211], v[88:91]
	v_mfma_f32_16x16x32_bf16 v[76:79], v[174:177], v[216:219], v[76:79]
	v_mfma_f32_16x16x32_bf16 v[72:75], v[182:185], v[216:219], v[72:75]
	s_setprio 0
	s_barrier
	s_add_i32 s60, s50, s39
	v_lshl_add_u64 v[144:145], s[28:29], 0, v[132:133]
	s_mov_b32 m0, s60
	ds_read_b128 v[186:189], v151 offset:16384
	ds_read_b128 v[190:193], v151 offset:17408
	ds_read_b128 v[196:199], v151 offset:18432
	ds_read_b128 v[200:203], v151 offset:19456
	ds_read_b128 v[204:207], v151 offset:20480
	ds_read_b128 v[208:211], v151 offset:21504
	ds_read_b128 v[212:215], v151 offset:22528
	ds_read_b128 v[216:219], v151 offset:23552
	global_load_lds_dwordx4 v[144:145], off
	s_add_i32 m0, s60, 0x2000
	s_add_u32 s60, s28, 0x40000
	v_lshl_add_u64 v[220:221], s[28:29], 0, v[128:129]
	s_addc_u32 s61, s29, 0
	s_add_i32 s62, s51, s39
	global_load_lds_dwordx4 v[220:221], off
	v_lshl_add_u64 v[222:223], s[60:61], 0, v[132:133]
	s_mov_b32 m0, s62
	v_lshl_add_u64 v[224:225], s[30:31], 0, v[130:131]
	global_load_lds_dwordx4 v[222:223], off
	v_lshl_add_u64 v[222:223], s[60:61], 0, v[128:129]
	s_add_i32 m0, s62, 0x2000
	s_nop 0
	global_load_lds_dwordx4 v[222:223], off
	v_lshl_add_u64 v[222:223], s[30:31], 0, v[134:135]
	s_waitcnt vmcnt(6)
	s_waitcnt lgkmcnt(0)
	s_barrier
	s_setprio 1
	s_waitcnt lgkmcnt(0)
	v_mfma_f32_16x16x32_bf16 v[52:55], v[154:157], v[186:189], v[52:55]
	v_mfma_f32_16x16x32_bf16 v[48:51], v[162:165], v[186:189], v[48:51]
	v_mfma_f32_16x16x32_bf16 v[36:39], v[154:157], v[196:199], v[36:39]
	v_mfma_f32_16x16x32_bf16 v[32:35], v[162:165], v[196:199], v[32:35]
	v_mfma_f32_16x16x32_bf16 v[20:23], v[154:157], v[204:207], v[20:23]
	v_mfma_f32_16x16x32_bf16 v[16:19], v[162:165], v[204:207], v[16:19]
	v_mfma_f32_16x16x32_bf16 v[4:7], v[154:157], v[212:215], v[4:7]
	v_mfma_f32_16x16x32_bf16 v[0:3], v[162:165], v[212:215], v[0:3]
	v_mfma_f32_16x16x32_bf16 v[52:55], v[158:161], v[190:193], v[52:55]
	v_mfma_f32_16x16x32_bf16 v[48:51], v[166:169], v[190:193], v[48:51]
	v_mfma_f32_16x16x32_bf16 v[36:39], v[158:161], v[200:203], v[36:39]
	v_mfma_f32_16x16x32_bf16 v[32:35], v[166:169], v[200:203], v[32:35]
	v_mfma_f32_16x16x32_bf16 v[20:23], v[158:161], v[208:211], v[20:23]
	v_mfma_f32_16x16x32_bf16 v[16:19], v[166:169], v[208:211], v[16:19]
	v_mfma_f32_16x16x32_bf16 v[4:7], v[158:161], v[216:219], v[4:7]
	v_mfma_f32_16x16x32_bf16 v[0:3], v[166:169], v[216:219], v[0:3]
	v_mfma_f32_16x16x32_bf16 v[60:63], v[170:173], v[186:189], v[60:63]
	v_mfma_f32_16x16x32_bf16 v[56:59], v[178:181], v[186:189], v[56:59]
	v_mfma_f32_16x16x32_bf16 v[44:47], v[170:173], v[196:199], v[44:47]
	v_mfma_f32_16x16x32_bf16 v[40:43], v[178:181], v[196:199], v[40:43]
	v_mfma_f32_16x16x32_bf16 v[28:31], v[170:173], v[204:207], v[28:31]
	v_mfma_f32_16x16x32_bf16 v[24:27], v[178:181], v[204:207], v[24:27]
	v_mfma_f32_16x16x32_bf16 v[12:15], v[170:173], v[212:215], v[12:15]
	v_mfma_f32_16x16x32_bf16 v[8:11], v[178:181], v[212:215], v[8:11]
	v_mfma_f32_16x16x32_bf16 v[60:63], v[174:177], v[190:193], v[60:63]
	v_mfma_f32_16x16x32_bf16 v[56:59], v[182:185], v[190:193], v[56:59]
	v_mfma_f32_16x16x32_bf16 v[44:47], v[174:177], v[200:203], v[44:47]
	v_mfma_f32_16x16x32_bf16 v[40:43], v[182:185], v[200:203], v[40:43]
	v_mfma_f32_16x16x32_bf16 v[28:31], v[174:177], v[208:211], v[28:31]
	v_mfma_f32_16x16x32_bf16 v[24:27], v[182:185], v[208:211], v[24:27]
	v_mfma_f32_16x16x32_bf16 v[12:15], v[174:177], v[216:219], v[12:15]
	v_mfma_f32_16x16x32_bf16 v[8:11], v[182:185], v[216:219], v[8:11]
	s_setprio 0
	s_barrier
	s_add_i32 s60, 0, 0x18000
	v_add_u32_e32 v153, s60, v147
	s_add_i32 s61, 0, 0x1c000
	ds_read_b128 v[154:157], v153
	ds_read_b128 v[158:161], v153 offset:1024
	ds_read_b128 v[162:165], v153 offset:2048
	ds_read_b128 v[166:169], v153 offset:3072
	v_add_u32_e32 v153, s61, v147
	ds_read_b128 v[170:173], v153
	ds_read_b128 v[174:177], v153 offset:1024
	ds_read_b128 v[178:181], v153 offset:2048
	ds_read_b128 v[182:185], v153 offset:3072
	s_add_u32 s30, s30, 0x40000
	s_addc_u32 s31, s31, 0
	v_lshl_add_u64 v[226:227], s[30:31], 0, v[134:135]
	ds_read_b128 v[186:189], v151 offset:32768
	ds_read_b128 v[190:193], v151 offset:33792
	ds_read_b128 v[196:199], v151 offset:34816
	ds_read_b128 v[200:203], v151 offset:35840
	ds_read_b128 v[204:207], v151 offset:36864
	ds_read_b128 v[208:211], v151 offset:37888
	ds_read_b128 v[212:215], v151 offset:38912
	ds_read_b128 v[216:219], v151 offset:39936
	s_mov_b32 m0, s25
	s_nop 0
	global_load_lds_dwordx4 v[222:223], off
	s_mov_b32 m0, s41
	s_nop 0
	global_load_lds_dwordx4 v[224:225], off
	s_mov_b32 m0, s42
	s_nop 0
	global_load_lds_dwordx4 v[226:227], off
	v_lshl_add_u64 v[226:227], s[30:31], 0, v[130:131]
	s_mov_b32 m0, s43
	s_nop 0
	global_load_lds_dwordx4 v[226:227], off
	s_waitcnt vmcnt(8)
	s_waitcnt lgkmcnt(0)
	s_barrier
	s_setprio 1
	s_waitcnt lgkmcnt(0)
	v_mfma_f32_16x16x32_bf16 v[116:119], v[154:157], v[186:189], v[116:119]
	v_mfma_f32_16x16x32_bf16 v[112:115], v[162:165], v[186:189], v[112:115]
	v_mfma_f32_16x16x32_bf16 v[100:103], v[154:157], v[196:199], v[100:103]
	v_mfma_f32_16x16x32_bf16 v[96:99], v[162:165], v[196:199], v[96:99]
	v_mfma_f32_16x16x32_bf16 v[84:87], v[154:157], v[204:207], v[84:87]
	v_mfma_f32_16x16x32_bf16 v[80:83], v[162:165], v[204:207], v[80:83]
	v_mfma_f32_16x16x32_bf16 v[68:71], v[154:157], v[212:215], v[68:71]
	v_mfma_f32_16x16x32_bf16 v[64:67], v[162:165], v[212:215], v[64:67]
	v_mfma_f32_16x16x32_bf16 v[116:119], v[158:161], v[190:193], v[116:119]
	v_mfma_f32_16x16x32_bf16 v[112:115], v[166:169], v[190:193], v[112:115]
	v_mfma_f32_16x16x32_bf16 v[100:103], v[158:161], v[200:203], v[100:103]
	v_mfma_f32_16x16x32_bf16 v[96:99], v[166:169], v[200:203], v[96:99]
	v_mfma_f32_16x16x32_bf16 v[84:87], v[158:161], v[208:211], v[84:87]
	v_mfma_f32_16x16x32_bf16 v[80:83], v[166:169], v[208:211], v[80:83]
	v_mfma_f32_16x16x32_bf16 v[68:71], v[158:161], v[216:219], v[68:71]
	v_mfma_f32_16x16x32_bf16 v[64:67], v[166:169], v[216:219], v[64:67]
	v_mfma_f32_16x16x32_bf16 v[124:127], v[170:173], v[186:189], v[124:127]
	v_mfma_f32_16x16x32_bf16 v[120:123], v[178:181], v[186:189], v[120:123]
	v_mfma_f32_16x16x32_bf16 v[108:111], v[170:173], v[196:199], v[108:111]
	v_mfma_f32_16x16x32_bf16 v[104:107], v[178:181], v[196:199], v[104:107]
	v_mfma_f32_16x16x32_bf16 v[92:95], v[170:173], v[204:207], v[92:95]
	v_mfma_f32_16x16x32_bf16 v[88:91], v[178:181], v[204:207], v[88:91]
	v_mfma_f32_16x16x32_bf16 v[76:79], v[170:173], v[212:215], v[76:79]
	v_mfma_f32_16x16x32_bf16 v[72:75], v[178:181], v[212:215], v[72:75]
	v_mfma_f32_16x16x32_bf16 v[124:127], v[174:177], v[190:193], v[124:127]
	v_mfma_f32_16x16x32_bf16 v[120:123], v[182:185], v[190:193], v[120:123]
	v_mfma_f32_16x16x32_bf16 v[108:111], v[174:177], v[200:203], v[108:111]
	v_mfma_f32_16x16x32_bf16 v[104:107], v[182:185], v[200:203], v[104:107]
	v_mfma_f32_16x16x32_bf16 v[92:95], v[174:177], v[208:211], v[92:95]
	v_mfma_f32_16x16x32_bf16 v[88:91], v[182:185], v[208:211], v[88:91]
	v_mfma_f32_16x16x32_bf16 v[76:79], v[174:177], v[216:219], v[76:79]
	v_mfma_f32_16x16x32_bf16 v[72:75], v[182:185], v[216:219], v[72:75]
	s_setprio 0
	s_barrier
	s_add_i32 s30, s60, s39
	v_lshl_add_u64 v[144:145], v[144:145], 0, s[12:13]
	s_mov_b32 m0, s30
	ds_read_b128 v[186:189], v151 offset:49152
	ds_read_b128 v[190:193], v151 offset:50176
	ds_read_b128 v[196:199], v151 offset:51200
	ds_read_b128 v[200:203], v151 offset:52224
	ds_read_b128 v[204:207], v151 offset:53248
	ds_read_b128 v[208:211], v151 offset:54272
	ds_read_b128 v[212:215], v151 offset:55296
	ds_read_b128 v[216:219], v151 offset:56320
	global_load_lds_dwordx4 v[144:145], off
	s_add_i32 m0, s30, 0x2000
	s_add_u32 s28, s28, 0x40080
	v_lshl_add_u64 v[144:145], v[220:221], 0, s[12:13]
	s_addc_u32 s29, s29, 0
	s_add_i32 s30, s61, s39
	global_load_lds_dwordx4 v[144:145], off
	v_lshl_add_u64 v[144:145], s[28:29], 0, v[132:133]
	s_mov_b32 m0, s30
	s_nop 0
	global_load_lds_dwordx4 v[144:145], off
	v_lshl_add_u64 v[144:145], s[28:29], 0, v[128:129]
	s_add_i32 m0, s30, 0x2000
	s_nop 0
	global_load_lds_dwordx4 v[144:145], off
	s_waitcnt vmcnt(6)
	s_waitcnt lgkmcnt(0)
	s_barrier
	s_setprio 1
	s_waitcnt lgkmcnt(0)
	v_mfma_f32_16x16x32_bf16 v[52:55], v[154:157], v[186:189], v[52:55]
	v_mfma_f32_16x16x32_bf16 v[48:51], v[162:165], v[186:189], v[48:51]
	v_mfma_f32_16x16x32_bf16 v[36:39], v[154:157], v[196:199], v[36:39]
	v_mfma_f32_16x16x32_bf16 v[32:35], v[162:165], v[196:199], v[32:35]
	v_mfma_f32_16x16x32_bf16 v[20:23], v[154:157], v[204:207], v[20:23]
	v_mfma_f32_16x16x32_bf16 v[16:19], v[162:165], v[204:207], v[16:19]
	v_mfma_f32_16x16x32_bf16 v[4:7], v[154:157], v[212:215], v[4:7]
	v_mfma_f32_16x16x32_bf16 v[0:3], v[162:165], v[212:215], v[0:3]
	v_mfma_f32_16x16x32_bf16 v[52:55], v[158:161], v[190:193], v[52:55]
	v_mfma_f32_16x16x32_bf16 v[48:51], v[166:169], v[190:193], v[48:51]
	v_mfma_f32_16x16x32_bf16 v[36:39], v[158:161], v[200:203], v[36:39]
	v_mfma_f32_16x16x32_bf16 v[32:35], v[166:169], v[200:203], v[32:35]
	v_mfma_f32_16x16x32_bf16 v[20:23], v[158:161], v[208:211], v[20:23]
	v_mfma_f32_16x16x32_bf16 v[16:19], v[166:169], v[208:211], v[16:19]
	v_mfma_f32_16x16x32_bf16 v[4:7], v[158:161], v[216:219], v[4:7]
	v_mfma_f32_16x16x32_bf16 v[0:3], v[166:169], v[216:219], v[0:3]
	v_mfma_f32_16x16x32_bf16 v[60:63], v[170:173], v[186:189], v[60:63]
	v_mfma_f32_16x16x32_bf16 v[56:59], v[178:181], v[186:189], v[56:59]
	v_mfma_f32_16x16x32_bf16 v[44:47], v[170:173], v[196:199], v[44:47]
	v_mfma_f32_16x16x32_bf16 v[40:43], v[178:181], v[196:199], v[40:43]
	v_mfma_f32_16x16x32_bf16 v[28:31], v[170:173], v[204:207], v[28:31]
	v_mfma_f32_16x16x32_bf16 v[24:27], v[178:181], v[204:207], v[24:27]
	v_mfma_f32_16x16x32_bf16 v[12:15], v[170:173], v[212:215], v[12:15]
	v_mfma_f32_16x16x32_bf16 v[8:11], v[178:181], v[212:215], v[8:11]
	v_mfma_f32_16x16x32_bf16 v[60:63], v[174:177], v[190:193], v[60:63]
	v_mfma_f32_16x16x32_bf16 v[56:59], v[182:185], v[190:193], v[56:59]
	v_mfma_f32_16x16x32_bf16 v[44:47], v[174:177], v[200:203], v[44:47]
	v_mfma_f32_16x16x32_bf16 v[40:43], v[182:185], v[200:203], v[40:43]
	v_mfma_f32_16x16x32_bf16 v[28:31], v[174:177], v[208:211], v[28:31]
	v_mfma_f32_16x16x32_bf16 v[24:27], v[182:185], v[208:211], v[24:27]
	v_mfma_f32_16x16x32_bf16 v[12:15], v[174:177], v[216:219], v[12:15]
	v_mfma_f32_16x16x32_bf16 v[8:11], v[182:185], v[216:219], v[8:11]
	s_setprio 0
	s_barrier
	v_lshl_add_u64 v[222:223], v[222:223], 0, s[12:13]
	s_mov_b32 m0, s45
	s_nop 0
	global_load_lds_dwordx4 v[222:223], off
	v_lshl_add_u64 v[224:225], v[224:225], 0, s[12:13]
	s_mov_b32 m0, s48
	s_nop 0
	global_load_lds_dwordx4 v[224:225], off
	s_add_i32 s59, s59, 2
	s_add_u32 s26, s26, 0x100
	s_addc_u32 s27, s27, 0
	s_add_u32 s57, s57, 0x100
	s_addc_u32 s58, s58, 0
	s_cmp_gt_u32 s59, 13
	s_cbranch_scc0 .LBB0_3319
	s_and_b64 vcc, exec, s[14:15]
	s_cbranch_vccz .LBB0_3322
	s_barrier

.LBB0_3401:
	ds_read_b128 v[144:147], v151
	ds_read_b128 v[156:159], v151 offset:1024
	ds_read_b128 v[160:163], v151 offset:2048
	ds_read_b128 v[164:167], v151 offset:3072
	ds_read_b128 v[168:171], v152
	ds_read_b128 v[172:175], v152 offset:1024
	ds_read_b128 v[176:179], v152 offset:2048
	ds_read_b128 v[180:183], v152 offset:3072
	s_add_u32 s24, s22, 0x100
	s_addc_u32 s25, s23, 0
	s_cmp_eq_u32 s56, 40
	s_cselect_b32 s29, s1, s25
	s_cselect_b32 s28, s0, s24
	s_cselect_b32 s27, s21, s55
	s_cselect_b32 s26, s20, s54
	v_lshl_add_u64 v[192:193], s[22:23], 0, v[136:137]
	s_add_i32 m0, s38, 0xc000
	ds_read_b128 v[184:187], v153
	ds_read_b128 v[188:191], v153 offset:1024
	ds_read_b128 v[196:199], v153 offset:2048
	ds_read_b128 v[200:203], v153 offset:3072
	ds_read_b128 v[204:207], v153 offset:4096
	ds_read_b128 v[208:211], v153 offset:5120
	ds_read_b128 v[212:215], v153 offset:6144
	ds_read_b128 v[216:219], v153 offset:7168
	global_load_lds_dwordx4 v[192:193], off
	v_lshl_add_u64 v[192:193], s[22:23], 0, v[138:139]
	s_add_i32 m0, s38, 0xe000
	s_nop 0
	global_load_lds_dwordx4 v[192:193], off
	s_waitcnt vmcnt(8)
	s_waitcnt lgkmcnt(0)
	s_barrier
	s_setprio 1
	s_waitcnt lgkmcnt(0)
	v_mfma_f32_16x16x32_bf16 v[124:127], v[144:147], v[184:187], v[124:127]
	v_mfma_f32_16x16x32_bf16 v[120:123], v[160:163], v[184:187], v[120:123]
	v_mfma_f32_16x16x32_bf16 v[108:111], v[144:147], v[196:199], v[108:111]
	v_mfma_f32_16x16x32_bf16 v[104:107], v[160:163], v[196:199], v[104:107]
	v_mfma_f32_16x16x32_bf16 v[92:95], v[144:147], v[204:207], v[92:95]
	v_mfma_f32_16x16x32_bf16 v[88:91], v[160:163], v[204:207], v[88:91]
	v_mfma_f32_16x16x32_bf16 v[76:79], v[144:147], v[212:215], v[76:79]
	v_mfma_f32_16x16x32_bf16 v[72:75], v[160:163], v[212:215], v[72:75]
	v_mfma_f32_16x16x32_bf16 v[124:127], v[156:159], v[188:191], v[124:127]
	v_mfma_f32_16x16x32_bf16 v[120:123], v[164:167], v[188:191], v[120:123]
	v_mfma_f32_16x16x32_bf16 v[108:111], v[156:159], v[200:203], v[108:111]
	v_mfma_f32_16x16x32_bf16 v[104:107], v[164:167], v[200:203], v[104:107]
	v_mfma_f32_16x16x32_bf16 v[92:95], v[156:159], v[208:211], v[92:95]
	v_mfma_f32_16x16x32_bf16 v[88:91], v[164:167], v[208:211], v[88:91]
	v_mfma_f32_16x16x32_bf16 v[76:79], v[156:159], v[216:219], v[76:79]
	v_mfma_f32_16x16x32_bf16 v[72:75], v[164:167], v[216:219], v[72:75]
	v_mfma_f32_16x16x32_bf16 v[116:119], v[168:171], v[184:187], v[116:119]
	v_mfma_f32_16x16x32_bf16 v[112:115], v[176:179], v[184:187], v[112:115]
	v_mfma_f32_16x16x32_bf16 v[100:103], v[168:171], v[196:199], v[100:103]
	v_mfma_f32_16x16x32_bf16 v[96:99], v[176:179], v[196:199], v[96:99]
	v_mfma_f32_16x16x32_bf16 v[84:87], v[168:171], v[204:207], v[84:87]
	v_mfma_f32_16x16x32_bf16 v[80:83], v[176:179], v[204:207], v[80:83]
	v_mfma_f32_16x16x32_bf16 v[68:71], v[168:171], v[212:215], v[68:71]
	v_mfma_f32_16x16x32_bf16 v[64:67], v[176:179], v[212:215], v[64:67]
	v_mfma_f32_16x16x32_bf16 v[116:119], v[172:175], v[188:191], v[116:119]
	v_mfma_f32_16x16x32_bf16 v[112:115], v[180:183], v[188:191], v[112:115]
	v_mfma_f32_16x16x32_bf16 v[100:103], v[172:175], v[200:203], v[100:103]
	v_mfma_f32_16x16x32_bf16 v[96:99], v[180:183], v[200:203], v[96:99]
	v_mfma_f32_16x16x32_bf16 v[84:87], v[172:175], v[208:211], v[84:87]
	v_mfma_f32_16x16x32_bf16 v[80:83], v[180:183], v[208:211], v[80:83]
	v_mfma_f32_16x16x32_bf16 v[68:71], v[172:175], v[216:219], v[68:71]
	v_mfma_f32_16x16x32_bf16 v[64:67], v[180:183], v[216:219], v[64:67]
	s_setprio 0
	s_barrier
	s_add_i32 s22, s48, s37
	v_lshl_add_u64 v[192:193], s[26:27], 0, v[130:131]
	s_mov_b32 m0, s22
	ds_read_b128 v[184:187], v153 offset:16384
	ds_read_b128 v[188:191], v153 offset:17408
	ds_read_b128 v[196:199], v153 offset:18432
	ds_read_b128 v[200:203], v153 offset:19456
	ds_read_b128 v[204:207], v153 offset:20480
	ds_read_b128 v[208:211], v153 offset:21504
	ds_read_b128 v[212:215], v153 offset:22528
	ds_read_b128 v[216:219], v153 offset:23552
	global_load_lds_dwordx4 v[192:193], off
	s_add_i32 m0, s22, 0x2000
	s_add_u32 s22, s26, 0xb0000
	v_lshl_add_u64 v[220:221], s[26:27], 0, v[134:135]
	s_addc_u32 s23, s27, 0
	s_add_i32 s57, s49, s37
	global_load_lds_dwordx4 v[220:221], off
	v_lshl_add_u64 v[222:223], s[22:23], 0, v[130:131]
	s_mov_b32 m0, s57
	v_lshl_add_u64 v[224:225], s[28:29], 0, v[132:133]
	global_load_lds_dwordx4 v[222:223], off
	v_lshl_add_u64 v[222:223], s[22:23], 0, v[134:135]
	s_add_i32 m0, s57, 0x2000
	s_nop 0
	global_load_lds_dwordx4 v[222:223], off
	v_lshl_add_u64 v[222:223], s[28:29], 0, v[128:129]
	s_waitcnt vmcnt(6)
	s_waitcnt lgkmcnt(0)
	s_barrier
	s_setprio 1
	s_waitcnt lgkmcnt(0)
	v_mfma_f32_16x16x32_bf16 v[60:63], v[144:147], v[184:187], v[60:63]
	v_mfma_f32_16x16x32_bf16 v[56:59], v[160:163], v[184:187], v[56:59]
	v_mfma_f32_16x16x32_bf16 v[44:47], v[144:147], v[196:199], v[44:47]
	v_mfma_f32_16x16x32_bf16 v[40:43], v[160:163], v[196:199], v[40:43]
	v_mfma_f32_16x16x32_bf16 v[28:31], v[144:147], v[204:207], v[28:31]
	v_mfma_f32_16x16x32_bf16 v[24:27], v[160:163], v[204:207], v[24:27]
	v_mfma_f32_16x16x32_bf16 v[12:15], v[144:147], v[212:215], v[12:15]
	v_mfma_f32_16x16x32_bf16 v[8:11], v[160:163], v[212:215], v[8:11]
	v_mfma_f32_16x16x32_bf16 v[60:63], v[156:159], v[188:191], v[60:63]
	v_mfma_f32_16x16x32_bf16 v[56:59], v[164:167], v[188:191], v[56:59]
	v_mfma_f32_16x16x32_bf16 v[44:47], v[156:159], v[200:203], v[44:47]
	v_mfma_f32_16x16x32_bf16 v[40:43], v[164:167], v[200:203], v[40:43]
	v_mfma_f32_16x16x32_bf16 v[28:31], v[156:159], v[208:211], v[28:31]
	v_mfma_f32_16x16x32_bf16 v[24:27], v[164:167], v[208:211], v[24:27]
	v_mfma_f32_16x16x32_bf16 v[12:15], v[156:159], v[216:219], v[12:15]
	v_mfma_f32_16x16x32_bf16 v[8:11], v[164:167], v[216:219], v[8:11]
	v_mfma_f32_16x16x32_bf16 v[52:55], v[168:171], v[184:187], v[52:55]
	v_mfma_f32_16x16x32_bf16 v[48:51], v[176:179], v[184:187], v[48:51]
	v_mfma_f32_16x16x32_bf16 v[36:39], v[168:171], v[196:199], v[36:39]
	v_mfma_f32_16x16x32_bf16 v[32:35], v[176:179], v[196:199], v[32:35]
	v_mfma_f32_16x16x32_bf16 v[20:23], v[168:171], v[204:207], v[20:23]
	v_mfma_f32_16x16x32_bf16 v[16:19], v[176:179], v[204:207], v[16:19]
	v_mfma_f32_16x16x32_bf16 v[4:7], v[168:171], v[212:215], v[4:7]
	v_mfma_f32_16x16x32_bf16 v[0:3], v[176:179], v[212:215], v[0:3]
	v_mfma_f32_16x16x32_bf16 v[52:55], v[172:175], v[188:191], v[52:55]
	v_mfma_f32_16x16x32_bf16 v[48:51], v[180:183], v[188:191], v[48:51]
	v_mfma_f32_16x16x32_bf16 v[36:39], v[172:175], v[200:203], v[36:39]
	v_mfma_f32_16x16x32_bf16 v[32:35], v[180:183], v[200:203], v[32:35]
	v_mfma_f32_16x16x32_bf16 v[20:23], v[172:175], v[208:211], v[20:23]
	v_mfma_f32_16x16x32_bf16 v[16:19], v[180:183], v[208:211], v[16:19]
	v_mfma_f32_16x16x32_bf16 v[4:7], v[172:175], v[216:219], v[4:7]
	v_mfma_f32_16x16x32_bf16 v[0:3], v[180:183], v[216:219], v[0:3]
	s_setprio 0
	s_barrier
	s_add_i32 s57, 0, 0x18000
	v_add_u32_e32 v155, s57, v149
	s_add_i32 s58, 0, 0x1c000
	ds_read_b128 v[144:147], v155
	ds_read_b128 v[156:159], v155 offset:1024
	ds_read_b128 v[160:163], v155 offset:2048
	ds_read_b128 v[164:167], v155 offset:3072
	v_add_u32_e32 v155, s58, v149
	ds_read_b128 v[168:171], v155
	ds_read_b128 v[172:175], v155 offset:1024
	ds_read_b128 v[176:179], v155 offset:2048
	ds_read_b128 v[180:183], v155 offset:3072
	s_add_u32 s22, s28, 0xb0000
	s_addc_u32 s23, s29, 0
	v_lshl_add_u64 v[226:227], s[22:23], 0, v[128:129]
	ds_read_b128 v[184:187], v153 offset:32768
	ds_read_b128 v[188:191], v153 offset:33792
	ds_read_b128 v[196:199], v153 offset:34816
	ds_read_b128 v[200:203], v153 offset:35840
	ds_read_b128 v[204:207], v153 offset:36864
	ds_read_b128 v[208:211], v153 offset:37888
	ds_read_b128 v[212:215], v153 offset:38912
	ds_read_b128 v[216:219], v153 offset:39936
	s_mov_b32 m0, s38
	s_nop 0
	global_load_lds_dwordx4 v[222:223], off
	s_mov_b32 m0, s39
	s_nop 0
	global_load_lds_dwordx4 v[224:225], off
	s_mov_b32 m0, s40
	s_nop 0
	global_load_lds_dwordx4 v[226:227], off
	v_lshl_add_u64 v[226:227], s[22:23], 0, v[132:133]
	s_mov_b32 m0, s41
	s_nop 0
	global_load_lds_dwordx4 v[226:227], off
	s_waitcnt vmcnt(8)
	s_waitcnt lgkmcnt(0)
	s_barrier
	s_setprio 1
	s_waitcnt lgkmcnt(0)
	v_mfma_f32_16x16x32_bf16 v[124:127], v[144:147], v[184:187], v[124:127]
	v_mfma_f32_16x16x32_bf16 v[120:123], v[160:163], v[184:187], v[120:123]
	v_mfma_f32_16x16x32_bf16 v[108:111], v[144:147], v[196:199], v[108:111]
	v_mfma_f32_16x16x32_bf16 v[104:107], v[160:163], v[196:199], v[104:107]
	v_mfma_f32_16x16x32_bf16 v[92:95], v[144:147], v[204:207], v[92:95]
	v_mfma_f32_16x16x32_bf16 v[88:91], v[160:163], v[204:207], v[88:91]
	v_mfma_f32_16x16x32_bf16 v[76:79], v[144:147], v[212:215], v[76:79]
	v_mfma_f32_16x16x32_bf16 v[72:75], v[160:163], v[212:215], v[72:75]
	v_mfma_f32_16x16x32_bf16 v[124:127], v[156:159], v[188:191], v[124:127]
	v_mfma_f32_16x16x32_bf16 v[120:123], v[164:167], v[188:191], v[120:123]
	v_mfma_f32_16x16x32_bf16 v[108:111], v[156:159], v[200:203], v[108:111]
	v_mfma_f32_16x16x32_bf16 v[104:107], v[164:167], v[200:203], v[104:107]
	v_mfma_f32_16x16x32_bf16 v[92:95], v[156:159], v[208:211], v[92:95]
	v_mfma_f32_16x16x32_bf16 v[88:91], v[164:167], v[208:211], v[88:91]
	v_mfma_f32_16x16x32_bf16 v[76:79], v[156:159], v[216:219], v[76:79]
	v_mfma_f32_16x16x32_bf16 v[72:75], v[164:167], v[216:219], v[72:75]
	v_mfma_f32_16x16x32_bf16 v[116:119], v[168:171], v[184:187], v[116:119]
	v_mfma_f32_16x16x32_bf16 v[112:115], v[176:179], v[184:187], v[112:115]
	v_mfma_f32_16x16x32_bf16 v[100:103], v[168:171], v[196:199], v[100:103]
	v_mfma_f32_16x16x32_bf16 v[96:99], v[176:179], v[196:199], v[96:99]
	v_mfma_f32_16x16x32_bf16 v[84:87], v[168:171], v[204:207], v[84:87]
	v_mfma_f32_16x16x32_bf16 v[80:83], v[176:179], v[204:207], v[80:83]
	v_mfma_f32_16x16x32_bf16 v[68:71], v[168:171], v[212:215], v[68:71]
	v_mfma_f32_16x16x32_bf16 v[64:67], v[176:179], v[212:215], v[64:67]
	v_mfma_f32_16x16x32_bf16 v[116:119], v[172:175], v[188:191], v[116:119]
	v_mfma_f32_16x16x32_bf16 v[112:115], v[180:183], v[188:191], v[112:115]
	v_mfma_f32_16x16x32_bf16 v[100:103], v[172:175], v[200:203], v[100:103]
	v_mfma_f32_16x16x32_bf16 v[96:99], v[180:183], v[200:203], v[96:99]
	v_mfma_f32_16x16x32_bf16 v[84:87], v[172:175], v[208:211], v[84:87]
	v_mfma_f32_16x16x32_bf16 v[80:83], v[180:183], v[208:211], v[80:83]
	v_mfma_f32_16x16x32_bf16 v[68:71], v[172:175], v[216:219], v[68:71]
	v_mfma_f32_16x16x32_bf16 v[64:67], v[180:183], v[216:219], v[64:67]
	s_setprio 0
	s_barrier
	s_add_i32 s22, s57, s37
	v_lshl_add_u64 v[192:193], v[192:193], 0, s[16:17]
	s_mov_b32 m0, s22
	ds_read_b128 v[184:187], v153 offset:49152
	ds_read_b128 v[188:191], v153 offset:50176
	ds_read_b128 v[196:199], v153 offset:51200
	ds_read_b128 v[200:203], v153 offset:52224
	ds_read_b128 v[204:207], v153 offset:53248
	ds_read_b128 v[208:211], v153 offset:54272
	ds_read_b128 v[212:215], v153 offset:55296
	ds_read_b128 v[216:219], v153 offset:56320
	global_load_lds_dwordx4 v[192:193], off
	s_add_i32 m0, s22, 0x2000
	s_add_u32 s22, s26, 0xb0080
	v_lshl_add_u64 v[192:193], v[220:221], 0, s[16:17]
	s_addc_u32 s23, s27, 0
	s_add_i32 s26, s58, s37
	global_load_lds_dwordx4 v[192:193], off
	v_lshl_add_u64 v[192:193], s[22:23], 0, v[130:131]
	s_mov_b32 m0, s26
	s_nop 0
	global_load_lds_dwordx4 v[192:193], off
	v_lshl_add_u64 v[192:193], s[22:23], 0, v[134:135]
	s_add_i32 m0, s26, 0x2000
	s_nop 0
	global_load_lds_dwordx4 v[192:193], off
	s_waitcnt vmcnt(6)
	s_waitcnt lgkmcnt(0)
	s_barrier
	s_setprio 1
	s_waitcnt lgkmcnt(0)
	v_mfma_f32_16x16x32_bf16 v[60:63], v[144:147], v[184:187], v[60:63]
	v_mfma_f32_16x16x32_bf16 v[56:59], v[160:163], v[184:187], v[56:59]
	v_mfma_f32_16x16x32_bf16 v[44:47], v[144:147], v[196:199], v[44:47]
	v_mfma_f32_16x16x32_bf16 v[40:43], v[160:163], v[196:199], v[40:43]
	v_mfma_f32_16x16x32_bf16 v[28:31], v[144:147], v[204:207], v[28:31]
	v_mfma_f32_16x16x32_bf16 v[24:27], v[160:163], v[204:207], v[24:27]
	v_mfma_f32_16x16x32_bf16 v[12:15], v[144:147], v[212:215], v[12:15]
	v_mfma_f32_16x16x32_bf16 v[8:11], v[160:163], v[212:215], v[8:11]
	v_mfma_f32_16x16x32_bf16 v[60:63], v[156:159], v[188:191], v[60:63]
	v_mfma_f32_16x16x32_bf16 v[56:59], v[164:167], v[188:191], v[56:59]
	v_mfma_f32_16x16x32_bf16 v[44:47], v[156:159], v[200:203], v[44:47]
	v_mfma_f32_16x16x32_bf16 v[40:43], v[164:167], v[200:203], v[40:43]
	v_mfma_f32_16x16x32_bf16 v[28:31], v[156:159], v[208:211], v[28:31]
	v_mfma_f32_16x16x32_bf16 v[24:27], v[164:167], v[208:211], v[24:27]
	v_mfma_f32_16x16x32_bf16 v[12:15], v[156:159], v[216:219], v[12:15]
	v_mfma_f32_16x16x32_bf16 v[8:11], v[164:167], v[216:219], v[8:11]
	v_mfma_f32_16x16x32_bf16 v[52:55], v[168:171], v[184:187], v[52:55]
	v_mfma_f32_16x16x32_bf16 v[48:51], v[176:179], v[184:187], v[48:51]
	v_mfma_f32_16x16x32_bf16 v[36:39], v[168:171], v[196:199], v[36:39]
	v_mfma_f32_16x16x32_bf16 v[32:35], v[176:179], v[196:199], v[32:35]
	v_mfma_f32_16x16x32_bf16 v[20:23], v[168:171], v[204:207], v[20:23]
	v_mfma_f32_16x16x32_bf16 v[16:19], v[176:179], v[204:207], v[16:19]
	v_mfma_f32_16x16x32_bf16 v[4:7], v[168:171], v[212:215], v[4:7]
	v_mfma_f32_16x16x32_bf16 v[0:3], v[176:179], v[212:215], v[0:3]
	v_mfma_f32_16x16x32_bf16 v[52:55], v[172:175], v[188:191], v[52:55]
	v_mfma_f32_16x16x32_bf16 v[48:51], v[180:183], v[188:191], v[48:51]
	v_mfma_f32_16x16x32_bf16 v[36:39], v[172:175], v[200:203], v[36:39]
	v_mfma_f32_16x16x32_bf16 v[32:35], v[180:183], v[200:203], v[32:35]
	v_mfma_f32_16x16x32_bf16 v[20:23], v[172:175], v[208:211], v[20:23]
	v_mfma_f32_16x16x32_bf16 v[16:19], v[180:183], v[208:211], v[16:19]
	v_mfma_f32_16x16x32_bf16 v[4:7], v[172:175], v[216:219], v[4:7]
	v_mfma_f32_16x16x32_bf16 v[0:3], v[180:183], v[216:219], v[0:3]
	s_setprio 0
	s_barrier
	v_lshl_add_u64 v[222:223], v[222:223], 0, s[16:17]
	s_mov_b32 m0, s43
	s_nop 0
	global_load_lds_dwordx4 v[222:223], off
	v_lshl_add_u64 v[224:225], v[224:225], 0, s[16:17]
	s_mov_b32 m0, s44
	s_nop 0
	global_load_lds_dwordx4 v[224:225], off
	s_add_i32 s56, s56, 2
	s_add_u32 s54, s54, 0x100
	s_addc_u32 s55, s55, 0
	s_cmp_gt_u32 s56, 41
	s_mov_b64 s[22:23], s[24:25]
	s_cbranch_scc0 .LBB0_3401
	s_and_b64 vcc, exec, s[18:19]
	s_cbranch_vccz .LBB0_3404
	s_barrier
